# PEER: integer-domain cross-lane reduction (exact), pre-shifted expert indices in pass 2
# baseline (speedup 1.0000x reference)
.LBB0_538:
	v_cmp_gt_i32_e32 vcc, s33, v2
	s_or_b64 s[16:17], s[16:17], exec
	s_and_saveexec_b64 s[18:19], vcc
	s_cbranch_execz .LBB0_537
	v_ashrrev_i32_e32 v3, 31, v2
	v_lshlrev_b64 v[4:5], 11, v[2:3]
	v_lshl_add_u64 v[8:9], v[60:61], 0, v[4:5]
	global_load_dwordx4 v[4:7], v[8:9], off offset:16
	s_nop 0
	global_load_dwordx4 v[8:11], v[8:9], off
	v_lshlrev_b64 v[110:111], 9, v[2:3]
	v_lshl_add_u64 v[110:111], v[62:63], 0, v[110:111]
	global_load_dword v112, v[110:111], off
	global_load_dword v113, v[110:111], off offset:64
	global_load_dword v114, v[110:111], off offset:128
	global_load_dword v115, v[110:111], off offset:192
	global_load_dword v116, v[110:111], off offset:256
	global_load_dword v117, v[110:111], off offset:320
	global_load_dword v118, v[110:111], off offset:384
	global_load_dword v119, v[110:111], off offset:448
	s_waitcnt lgkmcnt(0)
	v_add_u32_e32 v109, s20, v193
	s_waitcnt vmcnt(9)
	v_lshlrev_b32_e32 v13, 16, v4
	s_waitcnt vmcnt(8)
	v_lshlrev_b32_e32 v12, 16, v8
	v_and_b32_e32 v8, 0xffff0000, v8
	v_lshlrev_b32_e32 v14, 16, v9
	v_and_b32_e32 v15, 0xffff0000, v9
	v_max3_f32 v0, |v12|, 0, |v8|
	v_lshlrev_b32_e32 v17, 16, v10
	v_and_b32_e32 v10, 0xffff0000, v10
	v_max3_f32 v0, v0, |v14|, |v15|
	v_lshlrev_b32_e32 v19, 16, v11
	v_and_b32_e32 v11, 0xffff0000, v11
	v_max3_f32 v0, v0, |v17|, |v10|
	v_and_b32_e32 v4, 0xffff0000, v4
	v_max3_f32 v0, v0, |v19|, |v11|
	v_lshlrev_b32_e32 v16, 16, v5
	v_and_b32_e32 v5, 0xffff0000, v5
	v_max3_f32 v0, v0, |v13|, |v4|
	v_lshlrev_b32_e32 v18, 16, v6
	v_and_b32_e32 v6, 0xffff0000, v6
	v_max3_f32 v0, v0, |v16|, |v5|
	v_lshlrev_b32_e32 v20, 16, v7
	v_and_b32_e32 v7, 0xffff0000, v7
	v_max3_f32 v0, v0, |v18|, |v6|
	v_max3_f32 v9, v0, |v20|, |v7|
	v_and_b32_e32 v0, 64, v219
	v_add_u32_e32 v21, 64, v0
	v_xor_b32_e32 v0, 32, v219
	v_cmp_lt_i32_e32 vcc, v0, v21
	s_nop 1
	v_cndmask_b32_e32 v0, v219, v0, vcc
	v_lshlrev_b32_e32 v0, 2, v0
	ds_bpermute_b32 v22, v0, v9
	s_waitcnt lgkmcnt(0)
	v_max_f32_e32 v22, v22, v22
	v_max_f32_e32 v9, v9, v22
	v_xor_b32_e32 v22, 16, v219
	v_cmp_lt_i32_e32 vcc, v22, v21
	s_nop 1
	v_cndmask_b32_e32 v22, v219, v22, vcc
	v_lshlrev_b32_e32 v22, 2, v22
	ds_bpermute_b32 v22, v22, v9
	s_waitcnt lgkmcnt(0)
	v_max_f32_e32 v22, v22, v22
	v_max_f32_e32 v9, v9, v22
	v_xor_b32_e32 v22, 8, v219
	v_cmp_lt_i32_e32 vcc, v22, v21
	s_nop 1
	v_cndmask_b32_e32 v22, v219, v22, vcc
	v_lshlrev_b32_e32 v22, 2, v22
	ds_bpermute_b32 v22, v22, v9
	s_waitcnt lgkmcnt(0)
	v_max_f32_e32 v22, v22, v22
	v_max_f32_e32 v9, v9, v22
	v_xor_b32_e32 v22, 4, v219
	v_cmp_lt_i32_e32 vcc, v22, v21
	s_nop 1
	v_cndmask_b32_e32 v22, v219, v22, vcc
	v_lshlrev_b32_e32 v22, 2, v22
	ds_bpermute_b32 v22, v22, v9
	s_waitcnt lgkmcnt(0)
	v_max_f32_e32 v22, v22, v22
	v_max_f32_e32 v9, v9, v22
	v_xor_b32_e32 v22, 2, v219
	v_cmp_lt_i32_e32 vcc, v22, v21
	s_nop 1
	v_cndmask_b32_e32 v22, v219, v22, vcc
	v_lshlrev_b32_e32 v22, 2, v22
	ds_bpermute_b32 v22, v22, v9
	s_waitcnt lgkmcnt(0)
	v_max_f32_e32 v22, v22, v22
	v_max_f32_e32 v9, v9, v22
	v_xor_b32_e32 v22, 1, v219
	v_cmp_lt_i32_e32 vcc, v22, v21
	s_nop 1
	v_cndmask_b32_e32 v21, v219, v22, vcc
	v_lshlrev_b32_e32 v21, 2, v21
	ds_bpermute_b32 v21, v21, v9
	s_waitcnt lgkmcnt(0)
	v_max_f32_e32 v21, v21, v21
	v_max_f32_e32 v9, v9, v21
	v_div_scale_f32 v21, s[22:23], v9, v9, s69
	v_rcp_f32_e32 v22, v21
	v_cmp_lt_f32_e64 s[0:1], 0, v9
	v_fma_f32 v23, -v21, v22, 1.0
	v_fmac_f32_e32 v22, v23, v22
	v_div_scale_f32 v23, vcc, s69, v9, s69
	v_mul_f32_e32 v24, v23, v22
	v_fma_f32 v25, -v21, v24, v23
	v_fmac_f32_e32 v24, v25, v22
	v_fma_f32 v21, -v21, v24, v23
	v_div_fmas_f32 v21, v21, v22, v24
	v_div_fixup_f32 v21, v21, v9, s69
	v_cndmask_b32_e64 v21, 0, v21, s[0:1]
	v_mul_f32_e32 v12, v21, v12
	v_mul_f32_e32 v8, v21, v8
	v_rndne_f32_e32 v12, v12
	v_rndne_f32_e32 v8, v8
	v_cvt_i32_f32_e32 v12, v12
	v_cvt_i32_f32_e32 v8, v8
	v_mul_f32_e32 v14, v21, v14
	v_mul_f32_e32 v15, v21, v15
	v_rndne_f32_e32 v14, v14
	v_rndne_f32_e32 v15, v15
	v_cvt_i32_f32_e32 v14, v14
	v_cvt_i32_f32_e32 v15, v15
	v_mul_f32_e32 v17, v21, v17
	v_mul_f32_e32 v10, v21, v10
	v_rndne_f32_e32 v17, v17
	v_rndne_f32_e32 v10, v10
	v_add_u32_e32 v22, 8, v12
	v_add_u32_e32 v23, 8, v8
	v_cvt_i32_f32_e32 v17, v17
	v_cvt_i32_f32_e32 v10, v10
	v_mul_f32_e32 v11, v21, v11
	v_lshrrev_b32_e32 v22, 4, v22
	v_and_b32_e32 v23, 0xf0, v23
	v_mul_f32_e32 v19, v21, v19
	v_rndne_f32_e32 v11, v11
	v_and_or_b32 v22, v22, 15, v23
	v_lshl_add_u32 v23, v14, 4, v222
	v_lshl_add_u32 v24, v15, 8, v223
	v_rndne_f32_e32 v19, v19
	v_cvt_i32_f32_e32 v11, v11
	v_and_b32_e32 v23, 0xf00, v23
	v_and_b32_e32 v24, 0xf000, v24
	v_cvt_i32_f32_e32 v19, v19
	v_or3_b32 v22, v22, v23, v24
	v_lshl_add_u32 v23, v17, 12, v224
	v_lshl_add_u32 v24, v10, 16, v225
	v_and_b32_e32 v12, 15, v12
	v_lshlrev_b32_e32 v8, 4, v8
	v_lshlrev_b32_e32 v14, 8, v14
	v_and_b32_e32 v23, 0xf0000, v23
	v_and_b32_e32 v24, 0xf00000, v24
	v_and_b32_e32 v8, 0xf0, v8
	v_and_b32_e32 v14, 0xf00, v14
	v_lshlrev_b32_e32 v15, 12, v15
	v_lshlrev_b32_e32 v17, 16, v17
	v_or3_b32 v22, v22, v23, v24
	v_lshl_add_u32 v24, v11, 24, v227
	v_lshl_or_b32 v11, v11, 28, v12
	v_and_b32_e32 v15, 0xf000, v15
	v_and_b32_e32 v17, 0xf0000, v17
	v_lshlrev_b32_e32 v10, 20, v10
	v_lshl_add_u32 v23, v19, 20, v226
	v_lshlrev_b32_e32 v19, 24, v19
	v_or3_b32 v8, v11, v8, v14
	v_and_b32_e32 v10, 0xf00000, v10
	v_and_b32_e32 v19, 0xf000000, v19
	v_or3_b32 v8, v8, v15, v17
	v_or3_b32 v75, v8, v10, v19
	v_mul_f32_e32 v8, v21, v13
	v_mul_f32_e32 v4, v21, v4
	v_rndne_f32_e32 v8, v8
	v_rndne_f32_e32 v4, v4
	v_cvt_i32_f32_e32 v8, v8
	v_cvt_i32_f32_e32 v4, v4
	v_mul_f32_e32 v5, v21, v5
	v_rndne_f32_e32 v5, v5
	v_add_u32_e32 v10, 8, v8
	v_add_u32_e32 v11, 8, v4
	v_lshrrev_b32_e32 v10, 4, v10
	v_and_b32_e32 v11, 0xf0, v11
	v_and_or_b32 v10, v10, 15, v11
	v_mul_f32_e32 v11, v21, v16
	v_rndne_f32_e32 v11, v11
	v_cvt_i32_f32_e32 v11, v11
	v_cvt_i32_f32_e32 v5, v5
	v_mul_f32_e32 v6, v21, v6
	v_rndne_f32_e32 v6, v6
	v_lshl_add_u32 v12, v11, 4, v222
	v_lshl_add_u32 v13, v5, 8, v223
	v_and_b32_e32 v12, 0xf00, v12
	v_and_b32_e32 v13, 0xf000, v13
	v_or3_b32 v10, v10, v12, v13
	v_mul_f32_e32 v12, v21, v18
	v_rndne_f32_e32 v12, v12
	v_cvt_i32_f32_e32 v12, v12
	v_cvt_i32_f32_e32 v6, v6
	v_mul_f32_e32 v7, v21, v7
	v_rndne_f32_e32 v7, v7
	v_lshl_add_u32 v13, v12, 12, v224
	v_lshl_add_u32 v14, v6, 16, v225
	v_and_b32_e32 v13, 0xf0000, v13
	v_and_b32_e32 v14, 0xf00000, v14
	v_or3_b32 v10, v10, v13, v14
	v_mul_f32_e32 v13, v21, v20
	v_rndne_f32_e32 v13, v13
	v_cvt_i32_f32_e32 v7, v7
	v_cvt_i32_f32_e32 v13, v13
	v_and_b32_e32 v8, 15, v8
	v_lshlrev_b32_e32 v4, 4, v4
	v_lshlrev_b32_e32 v11, 8, v11
	v_and_b32_e32 v4, 0xf0, v4
	v_and_b32_e32 v11, 0xf00, v11
	v_lshlrev_b32_e32 v5, 12, v5
	v_lshlrev_b32_e32 v12, 16, v12
	v_lshl_add_u32 v15, v7, 24, v227
	v_lshl_or_b32 v7, v7, 28, v8
	v_and_b32_e32 v5, 0xf000, v5
	v_and_b32_e32 v12, 0xf0000, v12
	v_lshlrev_b32_e32 v6, 20, v6
	v_lshl_add_u32 v14, v13, 20, v226
	v_lshlrev_b32_e32 v13, 24, v13
	v_or3_b32 v4, v7, v4, v11
	v_and_b32_e32 v6, 0xf00000, v6
	v_and_b32_e32 v13, 0xf000000, v13
	v_or3_b32 v4, v4, v5, v12
	v_or3_b32 v108, v4, v6, v13
	v_lshlrev_b64 v[6:7], 9, v[2:3]
	v_and_b32_e32 v14, 0xf000000, v14
	v_and_b32_e32 v15, 0xf0000000, v15
	v_lshl_add_u64 v[4:5], v[62:63], 0, v[6:7]
	v_or3_b32 v77, v10, v14, v15
	s_waitcnt vmcnt(7)
	v_mov_b32_e32 v20, v112
	s_waitcnt vmcnt(6)
	v_mov_b32_e32 v18, v113
	s_waitcnt vmcnt(5)
	v_mov_b32_e32 v16, v114
	s_waitcnt vmcnt(4)
	v_mov_b32_e32 v14, v115
	s_waitcnt vmcnt(3)
	v_mov_b32_e32 v12, v116
	s_waitcnt vmcnt(2)
	v_mov_b32_e32 v10, v117
	s_waitcnt vmcnt(1)
	v_mov_b32_e32 v8, v118
	s_nop 0
	s_waitcnt vmcnt(0)
	v_mov_b32_e32 v4, v119
	v_and_b32_e32 v23, 0xf000000, v23
	v_and_b32_e32 v24, 0xf0000000, v24
	v_or3_b32 v73, v22, v23, v24
	v_mul_f32_e32 v3, 0x3c09ae41, v9
	v_lshl_add_u64 v[6:7], v[64:65], 0, v[6:7]
	v_readlane_b32 s0, v20, 0
	s_lshl_b32 s0, s0, 9
	s_nop 3
	buffer_load_dwordx2 v[100:101], v192, s[52:55], s0 offen
	v_readlane_b32 s0, v20, 1
	s_lshl_b32 s0, s0, 9
	s_nop 3
	buffer_load_dwordx2 v[102:103], v192, s[52:55], s0 offen
	v_readlane_b32 s0, v20, 2
	s_lshl_b32 s0, s0, 9
	s_nop 3
	buffer_load_dwordx2 v[98:99], v192, s[52:55], s0 offen
	v_readlane_b32 s0, v20, 3
	s_lshl_b32 s0, s0, 9
	s_nop 3
	buffer_load_dwordx2 v[104:105], v192, s[52:55], s0 offen
	v_readlane_b32 s0, v20, 4
	s_lshl_b32 s0, s0, 9
	s_nop 3
	buffer_load_dwordx2 v[94:95], v192, s[52:55], s0 offen
	v_readlane_b32 s0, v20, 5
	s_lshl_b32 s0, s0, 9
	s_nop 3
	buffer_load_dwordx2 v[86:87], v192, s[52:55], s0 offen
	v_readlane_b32 s0, v20, 6
	s_lshl_b32 s0, s0, 9
	s_nop 3
	buffer_load_dwordx2 v[84:85], v192, s[52:55], s0 offen
	v_readlane_b32 s0, v20, 7
	s_lshl_b32 s0, s0, 9
	s_nop 3
	buffer_load_dwordx2 v[90:91], v192, s[52:55], s0 offen
	v_readlane_b32 s0, v20, 8
	s_lshl_b32 s0, s0, 9
	s_nop 3
	buffer_load_dwordx2 v[78:79], v192, s[52:55], s0 offen
	v_readlane_b32 s0, v20, 9
	s_lshl_b32 s0, s0, 9
	s_nop 3
	buffer_load_dwordx2 v[50:51], v192, s[52:55], s0 offen
	v_readlane_b32 s0, v20, 10
	s_lshl_b32 s0, s0, 9
	s_nop 3
	buffer_load_dwordx2 v[48:49], v192, s[52:55], s0 offen
	v_readlane_b32 s0, v20, 11
	s_lshl_b32 s0, s0, 9
	s_nop 3
	buffer_load_dwordx2 v[54:55], v192, s[52:55], s0 offen
	v_readlane_b32 s0, v20, 12
	s_lshl_b32 s0, s0, 9
	s_nop 3
	buffer_load_dwordx2 v[42:43], v192, s[52:55], s0 offen
	v_readlane_b32 s0, v20, 13
	s_lshl_b32 s0, s0, 9
	s_nop 3
	buffer_load_dwordx2 v[34:35], v192, s[52:55], s0 offen
	v_readlane_b32 s0, v20, 14
	s_lshl_b32 s0, s0, 9
	s_nop 3
	buffer_load_dwordx2 v[32:33], v192, s[52:55], s0 offen
	v_readlane_b32 s0, v20, 15
	s_lshl_b32 s0, s0, 9
	s_nop 3
	buffer_load_dwordx2 v[38:39], v192, s[52:55], s0 offen
	v_lshlrev_b32_e32 v120, 2, v20
	v_lshlrev_b32_e32 v121, 2, v18
	v_lshlrev_b32_e32 v122, 2, v16
	v_lshlrev_b32_e32 v123, 2, v14
	v_lshlrev_b32_e32 v124, 2, v12
	v_lshlrev_b32_e32 v125, 2, v10
	v_lshlrev_b32_e32 v126, 2, v8
	v_lshlrev_b32_e32 v127, 2, v4
	global_load_dword v128, v120, s[8:9]
	global_load_dword v136, v120, s[10:11]
	global_load_dword v144, v[6:7], off
	global_load_dword v129, v121, s[8:9]
	global_load_dword v137, v121, s[10:11]
	global_load_dword v145, v[6:7], off offset:64
	global_load_dword v130, v122, s[8:9]
	global_load_dword v138, v122, s[10:11]
	global_load_dword v146, v[6:7], off offset:128
	global_load_dword v131, v123, s[8:9]
	global_load_dword v139, v123, s[10:11]
	global_load_dword v147, v[6:7], off offset:192
	global_load_dword v132, v124, s[8:9]
	global_load_dword v140, v124, s[10:11]
	global_load_dword v148, v[6:7], off offset:256
	global_load_dword v133, v125, s[8:9]
	global_load_dword v141, v125, s[10:11]
	global_load_dword v149, v[6:7], off offset:320
	global_load_dword v134, v126, s[8:9]
	global_load_dword v142, v126, s[10:11]
	global_load_dword v150, v[6:7], off offset:384
	global_load_dword v135, v127, s[8:9]
	global_load_dword v143, v127, s[10:11]
	global_load_dword v151, v[6:7], off offset:448
	s_nop 3
	s_waitcnt vmcnt(39)
	v_dot8_i32_i4 v5, v100, v73, 0
	s_nop 1
	v_dot8_i32_i4 v9, v100, v75, 0
	v_dot8_i32_i4 v5, v101, v77, v5
	v_dot8_i32_i4 v9, v101, v108, v9
	s_waitcnt vmcnt(38)
	v_dot8_i32_i4 v11, v102, v75, 0
	s_nop 0
	v_lshl_add_u32 v5, v5, 4, v9
	v_dot8_i32_i4 v9, v102, v73, 0
	v_dot8_i32_i4 v9, v103, v77, v9
	v_dot8_i32_i4 v11, v103, v108, v11
	s_waitcnt vmcnt(37)
	v_dot8_i32_i4 v13, v98, v75, 0
	s_nop 0
	v_lshl_add_u32 v9, v9, 4, v11
	v_dot8_i32_i4 v11, v98, v73, 0
	v_dot8_i32_i4 v11, v99, v77, v11
	v_dot8_i32_i4 v13, v99, v108, v13
	s_waitcnt vmcnt(36)
	v_dot8_i32_i4 v15, v104, v75, 0
	v_dot8_i32_i4 v15, v105, v108, v15
	v_lshl_add_u32 v11, v11, 4, v13
	v_dot8_i32_i4 v13, v104, v73, 0
	v_dot8_i32_i4 v13, v105, v77, v13
	s_nop 1
	s_nop 0
	v_lshl_add_u32 v13, v13, 4, v15
	s_nop 0
	s_waitcnt vmcnt(35)
	v_dot8_i32_i4 v15, v94, v73, 0
	s_nop 1
	v_dot8_i32_i4 v17, v94, v75, 0
	v_dot8_i32_i4 v15, v95, v77, v15
	v_dot8_i32_i4 v17, v95, v108, v17
	s_waitcnt vmcnt(34)
	v_dot8_i32_i4 v19, v86, v75, 0
	s_nop 0
	v_lshl_add_u32 v15, v15, 4, v17
	v_dot8_i32_i4 v17, v86, v73, 0
	v_dot8_i32_i4 v17, v87, v77, v17
	v_dot8_i32_i4 v19, v87, v108, v19
	s_waitcnt vmcnt(33)
	v_dot8_i32_i4 v21, v84, v75, 0
	v_dot8_i32_i4 v21, v85, v108, v21
	v_lshl_add_u32 v17, v17, 4, v19
	v_dot8_i32_i4 v19, v84, v73, 0
	v_dot8_i32_i4 v19, v85, v77, v19
	s_nop 1
	s_nop 0
	v_lshl_add_u32 v19, v19, 4, v21
	s_waitcnt vmcnt(32)
	v_dot8_i32_i4 v21, v90, v73, 0
	v_dot8_i32_i4 v84, v90, v75, 0
	v_dot8_i32_i4 v21, v91, v77, v21
	v_dot8_i32_i4 v84, v91, v108, v84
	v_readlane_b32 s0, v18, 0
	s_lshl_b32 s0, s0, 9
	s_nop 0
	v_lshl_add_u32 v21, v21, 4, v84
	s_waitcnt vmcnt(31)
	v_dot8_i32_i4 v84, v78, v73, 0
	v_dot8_i32_i4 v85, v78, v75, 0
	buffer_load_dwordx2 v[96:97], v192, s[52:55], s0 offen
	v_readlane_b32 s0, v18, 1
	s_lshl_b32 s0, s0, 9
	v_dot8_i32_i4 v84, v79, v77, v84
	v_dot8_i32_i4 v85, v79, v108, v85
	buffer_load_dwordx2 v[88:89], v192, s[52:55], s0 offen
	v_readlane_b32 s0, v18, 2
	s_lshl_b32 s0, s0, 9
	v_lshl_add_u32 v78, v84, 4, v85
	buffer_load_dwordx2 v[82:83], v192, s[52:55], s0 offen
	v_readlane_b32 s0, v18, 3
	s_lshl_b32 s0, s0, 9
	s_waitcnt vmcnt(33)
	v_dot8_i32_i4 v79, v50, v73, 0
	s_nop 0
	buffer_load_dwordx2 v[92:93], v192, s[52:55], s0 offen
	v_readlane_b32 s0, v18, 4
	s_lshl_b32 s0, s0, 9
	v_dot8_i32_i4 v84, v50, v75, 0
	v_dot8_i32_i4 v79, v51, v77, v79
	v_dot8_i32_i4 v84, v51, v108, v84
	buffer_load_dwordx2 v[80:81], v192, s[52:55], s0 offen
	v_readlane_b32 s0, v18, 5
	s_lshl_b32 s0, s0, 9
	v_lshl_add_u32 v50, v79, 4, v84
	s_waitcnt vmcnt(34)
	v_dot8_i32_i4 v51, v48, v73, 0
	v_dot8_i32_i4 v79, v48, v75, 0
	buffer_load_dwordx2 v[52:53], v192, s[52:55], s0 offen
	v_readlane_b32 s0, v18, 6
	s_lshl_b32 s0, s0, 9
	v_dot8_i32_i4 v51, v49, v77, v51
	v_dot8_i32_i4 v79, v49, v108, v79
	s_waitcnt vmcnt(34)
	v_dot8_i32_i4 v49, v54, v73, 0
	buffer_load_dwordx2 v[46:47], v192, s[52:55], s0 offen
	v_readlane_b32 s0, v18, 7
	s_lshl_b32 s0, s0, 9
	v_lshl_add_u32 v48, v51, 4, v79
	v_dot8_i32_i4 v51, v54, v75, 0
	v_dot8_i32_i4 v49, v55, v77, v49
	buffer_load_dwordx2 v[56:57], v192, s[52:55], s0 offen
	v_readlane_b32 s0, v18, 8
	s_lshl_b32 s0, s0, 9
	v_dot8_i32_i4 v51, v55, v108, v51
	s_waitcnt vmcnt(35)
	v_dot8_i32_i4 v54, v42, v75, 0
	v_dot8_i32_i4 v54, v43, v108, v54
	buffer_load_dwordx2 v[44:45], v192, s[52:55], s0 offen
	v_readlane_b32 s0, v18, 9
	s_lshl_b32 s0, s0, 9
	v_lshl_add_u32 v49, v49, 4, v51
	v_dot8_i32_i4 v51, v42, v73, 0
	v_dot8_i32_i4 v51, v43, v77, v51
	buffer_load_dwordx2 v[36:37], v192, s[52:55], s0 offen
	v_readlane_b32 s0, v18, 10
	s_lshl_b32 s0, s0, 9
	v_lshl_add_u32 v42, v51, 4, v54
	s_waitcnt vmcnt(36)
	v_dot8_i32_i4 v43, v34, v73, 0
	buffer_load_dwordx2 v[30:31], v192, s[52:55], s0 offen
	v_readlane_b32 s0, v18, 11
	s_lshl_b32 s0, s0, 9
	v_dot8_i32_i4 v51, v34, v75, 0
	v_dot8_i32_i4 v43, v35, v77, v43
	v_dot8_i32_i4 v51, v35, v108, v51
	buffer_load_dwordx2 v[40:41], v192, s[52:55], s0 offen
	v_readlane_b32 s0, v18, 12
	s_lshl_b32 s0, s0, 9
	v_lshl_add_u32 v34, v43, 4, v51
	s_waitcnt vmcnt(37)
	v_dot8_i32_i4 v35, v32, v73, 0
	v_dot8_i32_i4 v43, v32, v75, 0
	buffer_load_dwordx2 v[28:29], v192, s[52:55], s0 offen
	v_readlane_b32 s0, v18, 13
	s_lshl_b32 s0, s0, 9
	v_dot8_i32_i4 v35, v33, v77, v35
	v_dot8_i32_i4 v43, v33, v108, v43
	s_waitcnt vmcnt(37)
	v_dot8_i32_i4 v33, v38, v73, 0
	buffer_load_dwordx2 v[24:25], v192, s[52:55], s0 offen
	v_readlane_b32 s0, v18, 14
	s_lshl_b32 s0, s0, 9
	v_lshl_add_u32 v32, v35, 4, v43
	v_dot8_i32_i4 v35, v38, v75, 0
	v_dot8_i32_i4 v33, v39, v77, v33
	buffer_load_dwordx2 v[22:23], v192, s[52:55], s0 offen
	v_readlane_b32 s0, v18, 15
	s_lshl_b32 s0, s0, 9
	v_dot8_i32_i4 v35, v39, v108, v35
	buffer_load_dwordx2 v[26:27], v192, s[52:55], s0 offen
	s_nop 1
	v_lshl_add_u32 v33, v33, 4, v35
	s_nop 0
	v_cndmask_b32_e64 v35, v9, v5, s[40:41]
	v_cndmask_b32_e64 v5, v5, v9, s[40:41]
	v_cndmask_b32_e64 v9, v13, v11, s[40:41]
	v_cndmask_b32_e64 v11, v11, v13, s[40:41]
	ds_swizzle_b32 v11, v11 offset:swizzle(SWAP,1)
	v_cndmask_b32_e64 v13, v15, v17, s[40:41]
	ds_swizzle_b32 v13, v13 offset:swizzle(SWAP,1)
	s_waitcnt lgkmcnt(1)
	v_add_u32_e32 v9, v9, v11
	v_cndmask_b32_e64 v11, v17, v15, s[40:41]
	v_cndmask_b32_e64 v15, v19, v21, s[40:41]
	ds_swizzle_b32 v15, v15 offset:swizzle(SWAP,1)
	v_cndmask_b32_e64 v17, v78, v50, s[40:41]
	s_waitcnt lgkmcnt(1)
	v_add_u32_e32 v11, v11, v13
	v_cndmask_b32_e64 v13, v21, v19, s[40:41]
	ds_swizzle_b32 v17, v17 offset:swizzle(SWAP,1)
	v_cndmask_b32_e64 v19, v48, v49, s[40:41]
	ds_swizzle_b32 v19, v19 offset:swizzle(SWAP,1)
	v_cndmask_b32_e64 v21, v42, v34, s[40:41]
	ds_swizzle_b32 v21, v21 offset:swizzle(SWAP,1)
	s_waitcnt lgkmcnt(3)
	v_add_u32_e32 v13, v13, v15
	v_cndmask_b32_e64 v15, v50, v78, s[40:41]
	s_waitcnt lgkmcnt(2)
	v_add_u32_e32 v15, v15, v17
	v_cndmask_b32_e64 v17, v49, v48, s[40:41]
	s_waitcnt lgkmcnt(1)
	v_add_u32_e32 v17, v17, v19
	v_cndmask_b32_e64 v19, v34, v42, s[40:41]
	ds_swizzle_b32 v5, v5 offset:swizzle(SWAP,1)
	s_waitcnt lgkmcnt(1)
	v_add_u32_e32 v19, v19, v21
	v_cndmask_b32_e64 v21, v33, v32, s[40:41]
	v_cndmask_b32_e64 v32, v32, v33, s[40:41]
	ds_swizzle_b32 v32, v32 offset:swizzle(SWAP,1)
	s_waitcnt lgkmcnt(1)
	v_add_u32_e32 v5, v35, v5
	s_waitcnt lgkmcnt(0)
	v_add_u32_e32 v21, v21, v32
	v_cndmask_b32_e64 v32, v9, v5, s[42:43]
	v_cndmask_b32_e64 v5, v5, v9, s[42:43]
	v_cndmask_b32_e64 v9, v13, v11, s[42:43]
	v_cndmask_b32_e64 v11, v11, v13, s[42:43]
	ds_swizzle_b32 v11, v11 offset:swizzle(SWAP,2)
	v_cndmask_b32_e64 v13, v15, v17, s[42:43]
	ds_swizzle_b32 v13, v13 offset:swizzle(SWAP,2)
	ds_swizzle_b32 v5, v5 offset:swizzle(SWAP,2)
	s_waitcnt lgkmcnt(2)
	v_add_u32_e32 v9, v9, v11
	v_cndmask_b32_e64 v11, v17, v15, s[42:43]
	v_cndmask_b32_e64 v15, v19, v21, s[42:43]
	ds_swizzle_b32 v15, v15 offset:swizzle(SWAP,2)
	s_waitcnt lgkmcnt(2)
	v_add_u32_e32 v11, v11, v13
	v_cndmask_b32_e64 v13, v21, v19, s[42:43]
	s_waitcnt lgkmcnt(1)
	v_add_u32_e32 v5, v32, v5
	s_waitcnt lgkmcnt(0)
	v_add_u32_e32 v13, v13, v15
	v_cndmask_b32_e64 v15, v9, v5, s[44:45]
	v_cndmask_b32_e64 v5, v5, v9, s[44:45]
	v_cndmask_b32_e64 v9, v13, v11, s[44:45]
	v_cndmask_b32_e64 v11, v11, v13, s[44:45]
	ds_swizzle_b32 v5, v5 offset:swizzle(SWAP,4)
	ds_swizzle_b32 v11, v11 offset:swizzle(SWAP,4)
	s_waitcnt lgkmcnt(1)
	v_add_u32_e32 v5, v15, v5
	s_waitcnt lgkmcnt(0)
	v_add_u32_e32 v9, v9, v11
	v_cndmask_b32_e64 v11, v9, v5, s[46:47]
	v_cndmask_b32_e64 v5, v5, v9, s[46:47]
	ds_swizzle_b32 v5, v5 offset:swizzle(SWAP,8)
	s_waitcnt lgkmcnt(0)
	v_add_u32_e32 v5, v11, v5
	ds_swizzle_b32 v9, v5 offset:swizzle(SWAP,16)
	s_waitcnt lgkmcnt(0)
	v_add_u32_e32 v5, v5, v9
	ds_bpermute_b32 v9, v0, v5
	s_and_saveexec_b64 s[0:1], s[48:49]
	s_cbranch_execz .LBB0_541
	v_ashrrev_i32_e32 v21, 31, v20
	v_lshlrev_b64 v[20:21], 2, v[20:21]
	v_lshl_add_u64 v[32:33], s[8:9], 0, v[20:21]
	s_waitcnt vmcnt(39)
	v_mov_b32_e32 v11, v128
	v_lshl_add_u64 v[20:21], s[10:11], 0, v[20:21]
	s_waitcnt vmcnt(37)
	v_mov_b32_e32 v13, v144
	v_mov_b32_e32 v15, v136
	s_waitcnt lgkmcnt(0)
	v_add_u32_e32 v5, v5, v9
	v_cvt_f32_i32_e32 v5, v5
	v_mul_f32_e32 v5, v5, v11
	v_mul_f32_e32 v5, v3, v5
	v_mul_f32_e32 v11, 0x3d372713, v5
	v_mul_f32_e32 v11, v5, v11
	v_mul_f32_e32 v9, 0.5, v5
	v_fmac_f32_e32 v5, v5, v11
	v_mul_f32_e32 v5, 0x3f4c422a, v5
	v_add_f32_e32 v5, v5, v5
	v_mul_f32_e32 v5, 0x3fb8aa3b, v5
	v_exp_f32_e32 v5, v5
	s_nop 0
	v_add_f32_e32 v5, 1.0, v5
	v_rcp_f32_e32 v5, v5
	s_nop 0
	v_fma_f32 v5, v5, -2.0, 1.0
	v_add_f32_e32 v5, 1.0, v5
	v_mul_f32_e32 v5, v9, v5
	v_mul_f32_e32 v5, v13, v5
	v_mul_f32_e32 v5, v15, v5
	ds_write_b32 v109, v5
.LBB0_541:
	s_or_b64 exec, exec, s[0:1]
	v_readlane_b32 s0, v16, 0
	s_lshl_b32 s0, s0, 9
	s_waitcnt lgkmcnt(0)
	s_waitcnt vmcnt(15)
	v_dot8_i32_i4 v5, v96, v73, 0
	v_dot8_i32_i4 v9, v96, v75, 0
	buffer_load_dwordx2 v[102:103], v192, s[52:55], s0 offen
	v_readlane_b32 s0, v16, 1
	s_lshl_b32 s0, s0, 9
	v_dot8_i32_i4 v5, v97, v77, v5
	v_dot8_i32_i4 v9, v97, v108, v9
	s_waitcnt vmcnt(15)
	v_dot8_i32_i4 v11, v88, v75, 0
	buffer_load_dwordx2 v[98:99], v192, s[52:55], s0 offen
	v_readlane_b32 s0, v16, 2
	s_lshl_b32 s0, s0, 9
	v_lshl_add_u32 v5, v5, 4, v9
	v_dot8_i32_i4 v9, v88, v73, 0
	v_dot8_i32_i4 v9, v89, v77, v9
	buffer_load_dwordx2 v[94:95], v192, s[52:55], s0 offen
	v_readlane_b32 s0, v16, 3
	s_lshl_b32 s0, s0, 9
	v_dot8_i32_i4 v11, v89, v108, v11
	s_waitcnt vmcnt(16)
	v_dot8_i32_i4 v13, v82, v75, 0
	v_dot8_i32_i4 v13, v83, v108, v13
	buffer_load_dwordx2 v[100:101], v192, s[52:55], s0 offen
	v_readlane_b32 s0, v16, 4
	s_lshl_b32 s0, s0, 9
	v_lshl_add_u32 v9, v9, 4, v11
	v_dot8_i32_i4 v11, v82, v73, 0
	v_dot8_i32_i4 v11, v83, v77, v11
	buffer_load_dwordx2 v[90:91], v192, s[52:55], s0 offen
	v_readlane_b32 s0, v16, 5
	s_lshl_b32 s0, s0, 9
	v_lshl_add_u32 v11, v11, 4, v13
	s_waitcnt vmcnt(17)
	v_dot8_i32_i4 v13, v92, v73, 0
	buffer_load_dwordx2 v[84:85], v192, s[52:55], s0 offen
	v_readlane_b32 s0, v16, 6
	s_lshl_b32 s0, s0, 9
	v_dot8_i32_i4 v15, v92, v75, 0
	v_dot8_i32_i4 v13, v93, v77, v13
	v_dot8_i32_i4 v15, v93, v108, v15
	buffer_load_dwordx2 v[78:79], v192, s[52:55], s0 offen
	v_readlane_b32 s0, v16, 7
	s_lshl_b32 s0, s0, 9
	v_lshl_add_u32 v13, v13, 4, v15
	s_waitcnt vmcnt(18)
	v_dot8_i32_i4 v15, v80, v73, 0
	v_dot8_i32_i4 v17, v80, v75, 0
	buffer_load_dwordx2 v[86:87], v192, s[52:55], s0 offen
	v_readlane_b32 s0, v16, 8
	s_lshl_b32 s0, s0, 9
	v_dot8_i32_i4 v15, v81, v77, v15
	v_dot8_i32_i4 v17, v81, v108, v17
	s_waitcnt vmcnt(18)
	v_dot8_i32_i4 v19, v52, v75, 0
	buffer_load_dwordx2 v[54:55], v192, s[52:55], s0 offen
	v_readlane_b32 s0, v16, 9
	s_lshl_b32 s0, s0, 9
	v_lshl_add_u32 v15, v15, 4, v17
	v_dot8_i32_i4 v17, v52, v73, 0
	v_dot8_i32_i4 v17, v53, v77, v17
	buffer_load_dwordx2 v[48:49], v192, s[52:55], s0 offen
	v_readlane_b32 s0, v16, 10
	s_lshl_b32 s0, s0, 9
	v_dot8_i32_i4 v19, v53, v108, v19
	s_waitcnt vmcnt(19)
	v_dot8_i32_i4 v52, v46, v75, 0
	v_dot8_i32_i4 v52, v47, v108, v52
	buffer_load_dwordx2 v[42:43], v192, s[52:55], s0 offen
	v_readlane_b32 s0, v16, 11
	s_lshl_b32 s0, s0, 9
	v_lshl_add_u32 v17, v17, 4, v19
	v_dot8_i32_i4 v19, v46, v73, 0
	v_dot8_i32_i4 v19, v47, v77, v19
	buffer_load_dwordx2 v[50:51], v192, s[52:55], s0 offen
	v_readlane_b32 s0, v16, 12
	s_lshl_b32 s0, s0, 9
	s_waitcnt vmcnt(20)
	v_dot8_i32_i4 v46, v56, v73, 0
	v_dot8_i32_i4 v47, v56, v75, 0
	buffer_load_dwordx2 v[38:39], v192, s[52:55], s0 offen
	v_readlane_b32 s0, v16, 13
	s_lshl_b32 s0, s0, 9
	v_dot8_i32_i4 v46, v57, v77, v46
	v_dot8_i32_i4 v47, v57, v108, v47
	v_lshl_add_u32 v19, v19, 4, v52
	buffer_load_dwordx2 v[32:33], v192, s[52:55], s0 offen
	v_readlane_b32 s0, v16, 14
	s_lshl_b32 s0, s0, 9
	v_lshl_add_u32 v46, v46, 4, v47
	s_waitcnt vmcnt(21)
	v_dot8_i32_i4 v47, v44, v73, 0
	v_dot8_i32_i4 v52, v44, v75, 0
	buffer_load_dwordx2 v[20:21], v192, s[52:55], s0 offen
	v_readlane_b32 s0, v16, 15
	s_lshl_b32 s0, s0, 9
	v_dot8_i32_i4 v47, v45, v77, v47
	v_dot8_i32_i4 v52, v45, v108, v52
	s_waitcnt vmcnt(21)
	v_dot8_i32_i4 v45, v36, v73, 0
	buffer_load_dwordx2 v[34:35], v192, s[52:55], s0 offen
	v_lshl_add_u32 v44, v47, 4, v52
	v_dot8_i32_i4 v47, v36, v75, 0
	v_dot8_i32_i4 v45, v37, v77, v45
	v_dot8_i32_i4 v47, v37, v108, v47
	s_waitcnt vmcnt(21)
	v_dot8_i32_i4 v37, v30, v73, 0
	v_dot8_i32_i4 v37, v31, v77, v37
	v_lshl_add_u32 v36, v45, 4, v47
	v_dot8_i32_i4 v45, v30, v75, 0
	v_dot8_i32_i4 v45, v31, v108, v45
	s_waitcnt vmcnt(20)
	v_dot8_i32_i4 v31, v40, v73, 0
	v_dot8_i32_i4 v31, v41, v77, v31
	v_lshl_add_u32 v30, v37, 4, v45
	v_dot8_i32_i4 v37, v40, v75, 0
	v_dot8_i32_i4 v37, v41, v108, v37
	s_waitcnt vmcnt(19)
	v_dot8_i32_i4 v40, v28, v75, 0
	v_dot8_i32_i4 v40, v29, v108, v40
	v_lshl_add_u32 v31, v31, 4, v37
	v_dot8_i32_i4 v37, v28, v73, 0
	v_dot8_i32_i4 v37, v29, v77, v37
	s_waitcnt vmcnt(18)
	v_dot8_i32_i4 v29, v24, v73, 0
	v_dot8_i32_i4 v29, v25, v77, v29
	v_lshl_add_u32 v28, v37, 4, v40
	v_dot8_i32_i4 v37, v24, v75, 0
	v_dot8_i32_i4 v37, v25, v108, v37
	s_waitcnt vmcnt(17)
	v_dot8_i32_i4 v25, v22, v73, 0
	s_nop 0
	v_lshl_add_u32 v24, v29, 4, v37
	v_dot8_i32_i4 v29, v22, v75, 0
	v_dot8_i32_i4 v25, v23, v77, v25
	v_dot8_i32_i4 v29, v23, v108, v29
	s_nop 0
	s_nop 0
	s_nop 0
	v_lshl_add_u32 v22, v25, 4, v29
	s_waitcnt vmcnt(16)
	v_dot8_i32_i4 v23, v26, v73, 0
	v_dot8_i32_i4 v25, v26, v75, 0
	v_dot8_i32_i4 v23, v27, v77, v23
	v_dot8_i32_i4 v25, v27, v108, v25
	s_nop 0
	s_nop 0
	s_nop 0
	v_lshl_add_u32 v23, v23, 4, v25
	s_nop 1
	v_cndmask_b32_e64 v25, v9, v5, s[40:41]
	v_cndmask_b32_e64 v5, v5, v9, s[40:41]
	v_cndmask_b32_e64 v9, v13, v11, s[40:41]
	v_cndmask_b32_e64 v11, v11, v13, s[40:41]
	ds_swizzle_b32 v11, v11 offset:swizzle(SWAP,1)
	v_cndmask_b32_e64 v13, v15, v17, s[40:41]
	ds_swizzle_b32 v13, v13 offset:swizzle(SWAP,1)
	s_waitcnt lgkmcnt(1)
	v_add_u32_e32 v9, v9, v11
	v_cndmask_b32_e64 v11, v17, v15, s[40:41]
	v_cndmask_b32_e64 v15, v19, v46, s[40:41]
	ds_swizzle_b32 v15, v15 offset:swizzle(SWAP,1)
	v_cndmask_b32_e64 v17, v44, v36, s[40:41]
	s_waitcnt lgkmcnt(1)
	v_add_u32_e32 v11, v11, v13
	v_cndmask_b32_e64 v13, v46, v19, s[40:41]
	ds_swizzle_b32 v17, v17 offset:swizzle(SWAP,1)
	v_cndmask_b32_e64 v19, v30, v31, s[40:41]
	ds_swizzle_b32 v19, v19 offset:swizzle(SWAP,1)
	s_waitcnt lgkmcnt(2)
	v_add_u32_e32 v13, v13, v15
	v_cndmask_b32_e64 v15, v36, v44, s[40:41]
	s_waitcnt lgkmcnt(1)
	v_add_u32_e32 v15, v15, v17
	v_cndmask_b32_e64 v17, v31, v30, s[40:41]
	s_waitcnt lgkmcnt(0)
	v_add_u32_e32 v17, v17, v19
	v_cndmask_b32_e64 v19, v24, v28, s[40:41]
	v_cndmask_b32_e64 v24, v28, v24, s[40:41]
	ds_swizzle_b32 v5, v5 offset:swizzle(SWAP,1)
	ds_swizzle_b32 v24, v24 offset:swizzle(SWAP,1)
	s_waitcnt lgkmcnt(1)
	v_add_u32_e32 v5, v25, v5
	s_waitcnt lgkmcnt(0)
	v_add_u32_e32 v19, v19, v24
	v_cndmask_b32_e64 v24, v23, v22, s[40:41]
	v_cndmask_b32_e64 v22, v22, v23, s[40:41]
	ds_swizzle_b32 v22, v22 offset:swizzle(SWAP,1)
	v_cndmask_b32_e64 v23, v9, v5, s[42:43]
	v_cndmask_b32_e64 v5, v5, v9, s[42:43]
	v_cndmask_b32_e64 v9, v13, v11, s[42:43]
	v_cndmask_b32_e64 v11, v11, v13, s[42:43]
	ds_swizzle_b32 v11, v11 offset:swizzle(SWAP,2)
	s_waitcnt lgkmcnt(1)
	v_add_u32_e32 v22, v24, v22
	v_cndmask_b32_e64 v13, v15, v17, s[42:43]
	ds_swizzle_b32 v13, v13 offset:swizzle(SWAP,2)
	ds_swizzle_b32 v5, v5 offset:swizzle(SWAP,2)
	s_waitcnt lgkmcnt(2)
	v_add_u32_e32 v9, v9, v11
	v_cndmask_b32_e64 v11, v17, v15, s[42:43]
	v_cndmask_b32_e64 v15, v19, v22, s[42:43]
	ds_swizzle_b32 v15, v15 offset:swizzle(SWAP,2)
	s_waitcnt lgkmcnt(2)
	v_add_u32_e32 v11, v11, v13
	v_cndmask_b32_e64 v13, v22, v19, s[42:43]
	s_waitcnt lgkmcnt(1)
	v_add_u32_e32 v5, v23, v5
	s_waitcnt lgkmcnt(0)
	v_add_u32_e32 v13, v13, v15
	v_cndmask_b32_e64 v15, v9, v5, s[44:45]
	v_cndmask_b32_e64 v5, v5, v9, s[44:45]
	v_cndmask_b32_e64 v9, v13, v11, s[44:45]
	v_cndmask_b32_e64 v11, v11, v13, s[44:45]
	ds_swizzle_b32 v5, v5 offset:swizzle(SWAP,4)
	ds_swizzle_b32 v11, v11 offset:swizzle(SWAP,4)
	s_waitcnt lgkmcnt(1)
	v_add_u32_e32 v5, v15, v5
	s_waitcnt lgkmcnt(0)
	v_add_u32_e32 v9, v9, v11
	v_cndmask_b32_e64 v11, v9, v5, s[46:47]
	v_cndmask_b32_e64 v5, v5, v9, s[46:47]
	ds_swizzle_b32 v5, v5 offset:swizzle(SWAP,8)
	s_waitcnt lgkmcnt(0)
	v_add_u32_e32 v5, v11, v5
	ds_swizzle_b32 v9, v5 offset:swizzle(SWAP,16)
	s_waitcnt lgkmcnt(0)
	v_add_u32_e32 v5, v5, v9
	ds_bpermute_b32 v9, v0, v5
	s_and_saveexec_b64 s[0:1], s[48:49]
	s_cbranch_execz .LBB0_543
	v_ashrrev_i32_e32 v19, 31, v18
	v_lshlrev_b64 v[18:19], 2, v[18:19]
	v_lshl_add_u64 v[22:23], s[8:9], 0, v[18:19]
	v_mov_b32_e32 v11, v129
	v_lshl_add_u64 v[18:19], s[10:11], 0, v[18:19]
	v_mov_b32_e32 v13, v145
	v_mov_b32_e32 v15, v137
	s_waitcnt lgkmcnt(0)
	v_add_u32_e32 v5, v5, v9
	v_cvt_f32_i32_e32 v5, v5
	v_mul_f32_e32 v5, v5, v11
	v_mul_f32_e32 v5, v3, v5
	v_mul_f32_e32 v11, 0x3d372713, v5
	v_mul_f32_e32 v11, v5, v11
	v_mul_f32_e32 v9, 0.5, v5
	v_fmac_f32_e32 v5, v5, v11
	v_mul_f32_e32 v5, 0x3f4c422a, v5
	v_add_f32_e32 v5, v5, v5
	v_mul_f32_e32 v5, 0x3fb8aa3b, v5
	v_exp_f32_e32 v5, v5
	s_nop 0
	v_add_f32_e32 v5, 1.0, v5
	v_rcp_f32_e32 v5, v5
	s_nop 0
	v_fma_f32 v5, v5, -2.0, 1.0
	v_add_f32_e32 v5, 1.0, v5
	v_mul_f32_e32 v5, v9, v5
	v_mul_f32_e32 v5, v13, v5
	v_mul_f32_e32 v5, v15, v5
	ds_write_b32 v109, v5 offset:64
.LBB0_543:
	s_or_b64 exec, exec, s[0:1]
	v_readlane_b32 s0, v14, 0
	s_lshl_b32 s0, s0, 9
	s_waitcnt lgkmcnt(0)
	s_waitcnt vmcnt(15)
	v_dot8_i32_i4 v5, v102, v73, 0
	v_dot8_i32_i4 v9, v102, v75, 0
	buffer_load_dwordx2 v[96:97], v192, s[52:55], s0 offen
	v_readlane_b32 s0, v14, 1
	s_lshl_b32 s0, s0, 9
	v_dot8_i32_i4 v5, v103, v77, v5
	v_dot8_i32_i4 v9, v103, v108, v9
	s_waitcnt vmcnt(15)
	v_dot8_i32_i4 v11, v98, v75, 0
	buffer_load_dwordx2 v[104:105], v192, s[52:55], s0 offen
	v_readlane_b32 s0, v14, 2
	s_lshl_b32 s0, s0, 9
	v_lshl_add_u32 v5, v5, 4, v9
	v_dot8_i32_i4 v9, v98, v73, 0
	v_dot8_i32_i4 v9, v99, v77, v9
	buffer_load_dwordx2 v[92:93], v192, s[52:55], s0 offen
	v_readlane_b32 s0, v14, 3
	s_lshl_b32 s0, s0, 9
	v_dot8_i32_i4 v11, v99, v108, v11
	s_waitcnt vmcnt(16)
	v_dot8_i32_i4 v13, v94, v75, 0
	v_dot8_i32_i4 v13, v95, v108, v13
	buffer_load_dwordx2 v[106:107], v192, s[52:55], s0 offen
	v_readlane_b32 s0, v14, 4
	s_lshl_b32 s0, s0, 9
	v_lshl_add_u32 v9, v9, 4, v11
	v_dot8_i32_i4 v11, v94, v73, 0
	v_dot8_i32_i4 v11, v95, v77, v11
	buffer_load_dwordx2 v[88:89], v192, s[52:55], s0 offen
	v_readlane_b32 s0, v14, 5
	s_lshl_b32 s0, s0, 9
	v_lshl_add_u32 v11, v11, 4, v13
	s_waitcnt vmcnt(17)
	v_dot8_i32_i4 v13, v100, v73, 0
	buffer_load_dwordx2 v[80:81], v192, s[52:55], s0 offen
	v_readlane_b32 s0, v14, 6
	s_lshl_b32 s0, s0, 9
	v_dot8_i32_i4 v15, v100, v75, 0
	v_dot8_i32_i4 v13, v101, v77, v13
	v_dot8_i32_i4 v15, v101, v108, v15
	buffer_load_dwordx2 v[56:57], v192, s[52:55], s0 offen
	v_readlane_b32 s0, v14, 7
	s_lshl_b32 s0, s0, 9
	v_lshl_add_u32 v13, v13, 4, v15
	s_waitcnt vmcnt(18)
	v_dot8_i32_i4 v15, v90, v73, 0
	v_dot8_i32_i4 v17, v90, v75, 0
	buffer_load_dwordx2 v[82:83], v192, s[52:55], s0 offen
	v_readlane_b32 s0, v14, 8
	s_lshl_b32 s0, s0, 9
	v_dot8_i32_i4 v15, v91, v77, v15
	v_dot8_i32_i4 v17, v91, v108, v17
	s_waitcnt vmcnt(18)
	v_dot8_i32_i4 v22, v84, v75, 0
	buffer_load_dwordx2 v[52:53], v192, s[52:55], s0 offen
	v_readlane_b32 s0, v14, 9
	s_lshl_b32 s0, s0, 9
	v_lshl_add_u32 v15, v15, 4, v17
	v_dot8_i32_i4 v17, v84, v73, 0
	v_dot8_i32_i4 v17, v85, v77, v17
	buffer_load_dwordx2 v[44:45], v192, s[52:55], s0 offen
	v_readlane_b32 s0, v14, 10
	s_lshl_b32 s0, s0, 9
	v_dot8_i32_i4 v22, v85, v108, v22
	s_waitcnt vmcnt(19)
	v_dot8_i32_i4 v23, v78, v75, 0
	v_dot8_i32_i4 v23, v79, v108, v23
	buffer_load_dwordx2 v[40:41], v192, s[52:55], s0 offen
	v_readlane_b32 s0, v14, 11
	s_lshl_b32 s0, s0, 9
	v_lshl_add_u32 v17, v17, 4, v22
	v_dot8_i32_i4 v22, v78, v73, 0
	v_dot8_i32_i4 v22, v79, v77, v22
	buffer_load_dwordx2 v[46:47], v192, s[52:55], s0 offen
	v_readlane_b32 s0, v14, 12
	s_lshl_b32 s0, s0, 9
	v_lshl_add_u32 v22, v22, 4, v23
	s_waitcnt vmcnt(20)
	v_dot8_i32_i4 v23, v86, v73, 0
	buffer_load_dwordx2 v[36:37], v192, s[52:55], s0 offen
	v_readlane_b32 s0, v14, 13
	s_lshl_b32 s0, s0, 9
	v_dot8_i32_i4 v26, v86, v75, 0
	v_dot8_i32_i4 v23, v87, v77, v23
	v_dot8_i32_i4 v26, v87, v108, v26
	buffer_load_dwordx2 v[24:25], v192, s[52:55], s0 offen
	v_readlane_b32 s0, v14, 14
	s_lshl_b32 s0, s0, 9
	v_lshl_add_u32 v23, v23, 4, v26
	s_waitcnt vmcnt(21)
	v_dot8_i32_i4 v26, v54, v73, 0
	v_dot8_i32_i4 v27, v54, v75, 0
	buffer_load_dwordx2 v[18:19], v192, s[52:55], s0 offen
	v_readlane_b32 s0, v14, 15
	s_lshl_b32 s0, s0, 9
	v_dot8_i32_i4 v26, v55, v77, v26
	v_dot8_i32_i4 v27, v55, v108, v27
	s_waitcnt vmcnt(21)
	v_dot8_i32_i4 v30, v48, v75, 0
	buffer_load_dwordx2 v[28:29], v192, s[52:55], s0 offen
	v_lshl_add_u32 v26, v26, 4, v27
	v_dot8_i32_i4 v27, v48, v73, 0
	v_dot8_i32_i4 v27, v49, v77, v27
	v_dot8_i32_i4 v30, v49, v108, v30
	s_waitcnt vmcnt(21)
	v_dot8_i32_i4 v31, v42, v75, 0
	v_dot8_i32_i4 v31, v43, v108, v31
	v_lshl_add_u32 v27, v27, 4, v30
	v_dot8_i32_i4 v30, v42, v73, 0
	v_dot8_i32_i4 v30, v43, v77, v30
	s_waitcnt vmcnt(20)
	v_dot8_i32_i4 v42, v50, v75, 0
	v_dot8_i32_i4 v42, v51, v108, v42
	v_lshl_add_u32 v30, v30, 4, v31
	v_dot8_i32_i4 v31, v50, v73, 0
	v_dot8_i32_i4 v31, v51, v77, v31
	s_waitcnt vmcnt(19)
	v_dot8_i32_i4 v43, v38, v75, 0
	v_dot8_i32_i4 v43, v39, v108, v43
	v_lshl_add_u32 v31, v31, 4, v42
	v_dot8_i32_i4 v42, v38, v73, 0
	v_dot8_i32_i4 v42, v39, v77, v42
	s_waitcnt vmcnt(18)
	v_dot8_i32_i4 v39, v32, v73, 0
	v_dot8_i32_i4 v39, v33, v77, v39
	v_lshl_add_u32 v38, v42, 4, v43
	v_dot8_i32_i4 v42, v32, v75, 0
	v_dot8_i32_i4 v42, v33, v108, v42
	s_waitcnt vmcnt(17)
	v_dot8_i32_i4 v33, v20, v73, 0
	s_nop 0
	v_lshl_add_u32 v32, v39, 4, v42
	v_dot8_i32_i4 v39, v20, v75, 0
	v_dot8_i32_i4 v33, v21, v77, v33
	v_dot8_i32_i4 v39, v21, v108, v39
	s_nop 0
	s_nop 0
	s_nop 0
	v_lshl_add_u32 v20, v33, 4, v39
	s_waitcnt vmcnt(16)
	v_dot8_i32_i4 v21, v34, v73, 0
	v_dot8_i32_i4 v33, v34, v75, 0
	v_dot8_i32_i4 v21, v35, v77, v21
	v_dot8_i32_i4 v33, v35, v108, v33
	s_nop 0
	s_nop 0
	s_nop 0
	v_lshl_add_u32 v21, v21, 4, v33
	s_nop 1
	v_cndmask_b32_e64 v33, v9, v5, s[40:41]
	v_cndmask_b32_e64 v5, v5, v9, s[40:41]
	v_cndmask_b32_e64 v9, v13, v11, s[40:41]
	v_cndmask_b32_e64 v11, v11, v13, s[40:41]
	ds_swizzle_b32 v11, v11 offset:swizzle(SWAP,1)
	v_cndmask_b32_e64 v13, v15, v17, s[40:41]
	ds_swizzle_b32 v13, v13 offset:swizzle(SWAP,1)
	s_waitcnt lgkmcnt(1)
	v_add_u32_e32 v9, v9, v11
	v_cndmask_b32_e64 v11, v17, v15, s[40:41]
	v_cndmask_b32_e64 v15, v22, v23, s[40:41]
	ds_swizzle_b32 v15, v15 offset:swizzle(SWAP,1)
	v_cndmask_b32_e64 v17, v26, v27, s[40:41]
	s_waitcnt lgkmcnt(1)
	v_add_u32_e32 v11, v11, v13
	v_cndmask_b32_e64 v13, v23, v22, s[40:41]
	ds_swizzle_b32 v17, v17 offset:swizzle(SWAP,1)
	v_cndmask_b32_e64 v22, v30, v31, s[40:41]
	ds_swizzle_b32 v22, v22 offset:swizzle(SWAP,1)
	v_cndmask_b32_e64 v23, v38, v32, s[40:41]
	ds_swizzle_b32 v5, v5 offset:swizzle(SWAP,1)
	ds_swizzle_b32 v23, v23 offset:swizzle(SWAP,1)
	s_waitcnt lgkmcnt(4)
	v_add_u32_e32 v13, v13, v15
	v_cndmask_b32_e64 v15, v27, v26, s[40:41]
	s_waitcnt lgkmcnt(3)
	v_add_u32_e32 v15, v15, v17
	v_cndmask_b32_e64 v17, v31, v30, s[40:41]
	s_waitcnt lgkmcnt(2)
	v_add_u32_e32 v17, v17, v22
	v_cndmask_b32_e64 v22, v32, v38, s[40:41]
	s_waitcnt lgkmcnt(1)
	v_add_u32_e32 v5, v33, v5
	s_waitcnt lgkmcnt(0)
	v_add_u32_e32 v22, v22, v23
	v_cndmask_b32_e64 v23, v21, v20, s[40:41]
	v_cndmask_b32_e64 v20, v20, v21, s[40:41]
	ds_swizzle_b32 v20, v20 offset:swizzle(SWAP,1)
	v_cndmask_b32_e64 v21, v9, v5, s[42:43]
	v_cndmask_b32_e64 v5, v5, v9, s[42:43]
	v_cndmask_b32_e64 v9, v13, v11, s[42:43]
	v_cndmask_b32_e64 v11, v11, v13, s[42:43]
	ds_swizzle_b32 v11, v11 offset:swizzle(SWAP,2)
	s_waitcnt lgkmcnt(1)
	v_add_u32_e32 v20, v23, v20
	v_cndmask_b32_e64 v13, v15, v17, s[42:43]
	ds_swizzle_b32 v13, v13 offset:swizzle(SWAP,2)
	ds_swizzle_b32 v5, v5 offset:swizzle(SWAP,2)
	s_waitcnt lgkmcnt(2)
	v_add_u32_e32 v9, v9, v11
	v_cndmask_b32_e64 v11, v17, v15, s[42:43]
	v_cndmask_b32_e64 v15, v22, v20, s[42:43]
	ds_swizzle_b32 v15, v15 offset:swizzle(SWAP,2)
	s_waitcnt lgkmcnt(2)
	v_add_u32_e32 v11, v11, v13
	v_cndmask_b32_e64 v13, v20, v22, s[42:43]
	s_waitcnt lgkmcnt(1)
	v_add_u32_e32 v5, v21, v5
	s_waitcnt lgkmcnt(0)
	v_add_u32_e32 v13, v13, v15
	v_cndmask_b32_e64 v15, v9, v5, s[44:45]
	v_cndmask_b32_e64 v5, v5, v9, s[44:45]
	v_cndmask_b32_e64 v9, v13, v11, s[44:45]
	v_cndmask_b32_e64 v11, v11, v13, s[44:45]
	ds_swizzle_b32 v5, v5 offset:swizzle(SWAP,4)
	ds_swizzle_b32 v11, v11 offset:swizzle(SWAP,4)
	s_waitcnt lgkmcnt(1)
	v_add_u32_e32 v5, v15, v5
	s_waitcnt lgkmcnt(0)
	v_add_u32_e32 v9, v9, v11
	v_cndmask_b32_e64 v11, v9, v5, s[46:47]
	v_cndmask_b32_e64 v5, v5, v9, s[46:47]
	ds_swizzle_b32 v5, v5 offset:swizzle(SWAP,8)
	s_waitcnt lgkmcnt(0)
	v_add_u32_e32 v5, v11, v5
	ds_swizzle_b32 v9, v5 offset:swizzle(SWAP,16)
	s_waitcnt lgkmcnt(0)
	v_add_u32_e32 v5, v5, v9
	ds_bpermute_b32 v9, v0, v5
	s_and_saveexec_b64 s[0:1], s[48:49]
	s_cbranch_execz .LBB0_545
	v_ashrrev_i32_e32 v17, 31, v16
	v_lshlrev_b64 v[16:17], 2, v[16:17]
	v_lshl_add_u64 v[20:21], s[8:9], 0, v[16:17]
	v_mov_b32_e32 v11, v130
	v_lshl_add_u64 v[16:17], s[10:11], 0, v[16:17]
	v_mov_b32_e32 v13, v146
	v_mov_b32_e32 v15, v138
	s_waitcnt lgkmcnt(0)
	v_add_u32_e32 v5, v5, v9
	v_cvt_f32_i32_e32 v5, v5
	v_mul_f32_e32 v5, v5, v11
	v_mul_f32_e32 v5, v3, v5
	v_mul_f32_e32 v11, 0x3d372713, v5
	v_mul_f32_e32 v11, v5, v11
	v_mul_f32_e32 v9, 0.5, v5
	v_fmac_f32_e32 v5, v5, v11
	v_mul_f32_e32 v5, 0x3f4c422a, v5
	v_add_f32_e32 v5, v5, v5
	v_mul_f32_e32 v5, 0x3fb8aa3b, v5
	v_exp_f32_e32 v5, v5
	s_nop 0
	v_add_f32_e32 v5, 1.0, v5
	v_rcp_f32_e32 v5, v5
	s_nop 0
	v_fma_f32 v5, v5, -2.0, 1.0
	v_add_f32_e32 v5, 1.0, v5
	v_mul_f32_e32 v5, v9, v5
	v_mul_f32_e32 v5, v13, v5
	v_mul_f32_e32 v5, v15, v5
	ds_write_b32 v109, v5 offset:128
.LBB0_545:
	s_or_b64 exec, exec, s[0:1]
	v_readlane_b32 s0, v12, 0
	s_lshl_b32 s0, s0, 9
	s_waitcnt lgkmcnt(0)
	s_waitcnt vmcnt(15)
	v_dot8_i32_i4 v5, v96, v73, 0
	v_dot8_i32_i4 v9, v96, v75, 0
	buffer_load_dwordx2 v[94:95], v192, s[52:55], s0 offen
	v_readlane_b32 s0, v12, 1
	s_lshl_b32 s0, s0, 9
	v_dot8_i32_i4 v5, v97, v77, v5
	v_dot8_i32_i4 v9, v97, v108, v9
	s_waitcnt vmcnt(15)
	v_dot8_i32_i4 v11, v104, v75, 0
	buffer_load_dwordx2 v[86:87], v192, s[52:55], s0 offen
	v_readlane_b32 s0, v12, 2
	s_lshl_b32 s0, s0, 9
	v_lshl_add_u32 v5, v5, 4, v9
	v_dot8_i32_i4 v9, v104, v73, 0
	v_dot8_i32_i4 v9, v105, v77, v9
	buffer_load_dwordx2 v[84:85], v192, s[52:55], s0 offen
	v_readlane_b32 s0, v12, 3
	s_lshl_b32 s0, s0, 9
	v_dot8_i32_i4 v11, v105, v108, v11
	s_waitcnt vmcnt(16)
	v_dot8_i32_i4 v13, v92, v75, 0
	v_dot8_i32_i4 v13, v93, v108, v13
	buffer_load_dwordx2 v[90:91], v192, s[52:55], s0 offen
	v_readlane_b32 s0, v12, 4
	s_lshl_b32 s0, s0, 9
	v_lshl_add_u32 v9, v9, 4, v11
	v_dot8_i32_i4 v11, v92, v73, 0
	v_dot8_i32_i4 v11, v93, v77, v11
	buffer_load_dwordx2 v[78:79], v192, s[52:55], s0 offen
	v_readlane_b32 s0, v12, 5
	s_lshl_b32 s0, s0, 9
	v_lshl_add_u32 v11, v11, 4, v13
	s_waitcnt vmcnt(17)
	v_dot8_i32_i4 v13, v106, v73, 0
	buffer_load_dwordx2 v[50:51], v192, s[52:55], s0 offen
	v_readlane_b32 s0, v12, 6
	s_lshl_b32 s0, s0, 9
	v_dot8_i32_i4 v15, v106, v75, 0
	v_dot8_i32_i4 v13, v107, v77, v13
	v_dot8_i32_i4 v15, v107, v108, v15
	buffer_load_dwordx2 v[48:49], v192, s[52:55], s0 offen
	v_readlane_b32 s0, v12, 7
	s_lshl_b32 s0, s0, 9
	v_lshl_add_u32 v13, v13, 4, v15
	s_waitcnt vmcnt(18)
	v_dot8_i32_i4 v15, v88, v73, 0
	v_dot8_i32_i4 v32, v88, v75, 0
	buffer_load_dwordx2 v[54:55], v192, s[52:55], s0 offen
	v_readlane_b32 s0, v12, 8
	s_lshl_b32 s0, s0, 9
	v_dot8_i32_i4 v15, v89, v77, v15
	v_dot8_i32_i4 v32, v89, v108, v32
	s_waitcnt vmcnt(18)
	v_dot8_i32_i4 v33, v80, v75, 0
	buffer_load_dwordx2 v[42:43], v192, s[52:55], s0 offen
	v_readlane_b32 s0, v12, 9
	s_lshl_b32 s0, s0, 9
	v_lshl_add_u32 v15, v15, 4, v32
	v_dot8_i32_i4 v32, v80, v73, 0
	v_dot8_i32_i4 v32, v81, v77, v32
	buffer_load_dwordx2 v[34:35], v192, s[52:55], s0 offen
	v_readlane_b32 s0, v12, 10
	s_lshl_b32 s0, s0, 9
	v_dot8_i32_i4 v33, v81, v108, v33
	s_waitcnt vmcnt(19)
	v_dot8_i32_i4 v80, v56, v75, 0
	v_dot8_i32_i4 v80, v57, v108, v80
	buffer_load_dwordx2 v[30:31], v192, s[52:55], s0 offen
	v_readlane_b32 s0, v12, 11
	s_lshl_b32 s0, s0, 9
	v_lshl_add_u32 v32, v32, 4, v33
	v_dot8_i32_i4 v33, v56, v73, 0
	v_dot8_i32_i4 v33, v57, v77, v33
	buffer_load_dwordx2 v[38:39], v192, s[52:55], s0 offen
	v_readlane_b32 s0, v12, 12
	s_lshl_b32 s0, s0, 9
	s_waitcnt vmcnt(20)
	v_dot8_i32_i4 v56, v82, v73, 0
	v_dot8_i32_i4 v57, v82, v75, 0
	buffer_load_dwordx2 v[26:27], v192, s[52:55], s0 offen
	v_readlane_b32 s0, v12, 13
	s_lshl_b32 s0, s0, 9
	v_dot8_i32_i4 v56, v83, v77, v56
	v_dot8_i32_i4 v57, v83, v108, v57
	v_lshl_add_u32 v33, v33, 4, v80
	buffer_load_dwordx2 v[20:21], v192, s[52:55], s0 offen
	v_readlane_b32 s0, v12, 14
	s_lshl_b32 s0, s0, 9
	v_lshl_add_u32 v56, v56, 4, v57
	s_waitcnt vmcnt(21)
	v_dot8_i32_i4 v57, v52, v73, 0
	v_dot8_i32_i4 v80, v52, v75, 0
	buffer_load_dwordx2 v[16:17], v192, s[52:55], s0 offen
	v_readlane_b32 s0, v12, 15
	s_lshl_b32 s0, s0, 9
	v_dot8_i32_i4 v57, v53, v77, v57
	v_dot8_i32_i4 v80, v53, v108, v80
	s_waitcnt vmcnt(21)
	v_dot8_i32_i4 v53, v44, v73, 0
	buffer_load_dwordx2 v[22:23], v192, s[52:55], s0 offen
	v_lshl_add_u32 v52, v57, 4, v80
	v_dot8_i32_i4 v57, v44, v75, 0
	v_dot8_i32_i4 v53, v45, v77, v53
	v_dot8_i32_i4 v57, v45, v108, v57
	s_waitcnt vmcnt(21)
	v_dot8_i32_i4 v45, v40, v73, 0
	v_dot8_i32_i4 v45, v41, v77, v45
	v_lshl_add_u32 v44, v53, 4, v57
	v_dot8_i32_i4 v53, v40, v75, 0
	v_dot8_i32_i4 v53, v41, v108, v53
	s_waitcnt vmcnt(20)
	v_dot8_i32_i4 v41, v46, v73, 0
	v_dot8_i32_i4 v41, v47, v77, v41
	v_lshl_add_u32 v40, v45, 4, v53
	v_dot8_i32_i4 v45, v46, v75, 0
	v_dot8_i32_i4 v45, v47, v108, v45
	s_waitcnt vmcnt(19)
	v_dot8_i32_i4 v46, v36, v75, 0
	v_dot8_i32_i4 v46, v37, v108, v46
	v_lshl_add_u32 v41, v41, 4, v45
	v_dot8_i32_i4 v45, v36, v73, 0
	v_dot8_i32_i4 v45, v37, v77, v45
	s_waitcnt vmcnt(18)
	v_dot8_i32_i4 v37, v24, v73, 0
	v_dot8_i32_i4 v37, v25, v77, v37
	v_lshl_add_u32 v36, v45, 4, v46
	v_dot8_i32_i4 v45, v24, v75, 0
	v_dot8_i32_i4 v45, v25, v108, v45
	s_waitcnt vmcnt(17)
	v_dot8_i32_i4 v25, v18, v73, 0
	s_nop 0
	v_lshl_add_u32 v24, v37, 4, v45
	v_dot8_i32_i4 v37, v18, v75, 0
	v_dot8_i32_i4 v25, v19, v77, v25
	v_dot8_i32_i4 v37, v19, v108, v37
	s_waitcnt vmcnt(16)
	v_dot8_i32_i4 v19, v28, v73, 0
	v_dot8_i32_i4 v19, v29, v77, v19
	v_lshl_add_u32 v18, v25, 4, v37
	v_dot8_i32_i4 v25, v28, v75, 0
	v_dot8_i32_i4 v25, v29, v108, v25
	s_nop 1
	s_nop 0
	v_lshl_add_u32 v19, v19, 4, v25
	s_nop 0
	v_cndmask_b32_e64 v25, v9, v5, s[40:41]
	v_cndmask_b32_e64 v5, v5, v9, s[40:41]
	v_cndmask_b32_e64 v9, v13, v11, s[40:41]
	v_cndmask_b32_e64 v11, v11, v13, s[40:41]
	ds_swizzle_b32 v11, v11 offset:swizzle(SWAP,1)
	ds_swizzle_b32 v5, v5 offset:swizzle(SWAP,1)
	v_cndmask_b32_e64 v13, v15, v32, s[40:41]
	s_waitcnt lgkmcnt(1)
	v_add_u32_e32 v9, v9, v11
	v_cndmask_b32_e64 v11, v32, v15, s[40:41]
	ds_swizzle_b32 v13, v13 offset:swizzle(SWAP,1)
	v_cndmask_b32_e64 v15, v33, v56, s[40:41]
	s_waitcnt lgkmcnt(1)
	v_add_u32_e32 v5, v25, v5
	ds_swizzle_b32 v15, v15 offset:swizzle(SWAP,1)
	v_cndmask_b32_e64 v25, v52, v44, s[40:41]
	ds_swizzle_b32 v25, v25 offset:swizzle(SWAP,1)
	v_cndmask_b32_e64 v28, v40, v41, s[40:41]
	ds_swizzle_b32 v28, v28 offset:swizzle(SWAP,1)
	s_waitcnt lgkmcnt(3)
	v_add_u32_e32 v11, v11, v13
	v_cndmask_b32_e64 v13, v56, v33, s[40:41]
	s_waitcnt lgkmcnt(2)
	v_add_u32_e32 v13, v13, v15
	v_cndmask_b32_e64 v15, v44, v52, s[40:41]
	s_waitcnt lgkmcnt(1)
	v_add_u32_e32 v15, v15, v25
	v_cndmask_b32_e64 v25, v41, v40, s[40:41]
	s_waitcnt lgkmcnt(0)
	v_add_u32_e32 v25, v25, v28
	v_cndmask_b32_e64 v28, v24, v36, s[40:41]
	v_cndmask_b32_e64 v24, v36, v24, s[40:41]
	ds_swizzle_b32 v24, v24 offset:swizzle(SWAP,1)
	s_waitcnt lgkmcnt(0)
	v_add_u32_e32 v24, v28, v24
	v_cndmask_b32_e64 v28, v19, v18, s[40:41]
	v_cndmask_b32_e64 v18, v18, v19, s[40:41]
	ds_swizzle_b32 v18, v18 offset:swizzle(SWAP,1)
	v_cndmask_b32_e64 v19, v9, v5, s[42:43]
	v_cndmask_b32_e64 v5, v5, v9, s[42:43]
	v_cndmask_b32_e64 v9, v13, v11, s[42:43]
	v_cndmask_b32_e64 v11, v11, v13, s[42:43]
	ds_swizzle_b32 v11, v11 offset:swizzle(SWAP,2)
	s_waitcnt lgkmcnt(1)
	v_add_u32_e32 v18, v28, v18
	v_cndmask_b32_e64 v13, v15, v25, s[42:43]
	ds_swizzle_b32 v13, v13 offset:swizzle(SWAP,2)
	ds_swizzle_b32 v5, v5 offset:swizzle(SWAP,2)
	s_waitcnt lgkmcnt(2)
	v_add_u32_e32 v9, v9, v11
	v_cndmask_b32_e64 v11, v25, v15, s[42:43]
	v_cndmask_b32_e64 v15, v24, v18, s[42:43]
	ds_swizzle_b32 v15, v15 offset:swizzle(SWAP,2)
	s_waitcnt lgkmcnt(2)
	v_add_u32_e32 v11, v11, v13
	v_cndmask_b32_e64 v13, v18, v24, s[42:43]
	s_waitcnt lgkmcnt(1)
	v_add_u32_e32 v5, v19, v5
	s_waitcnt lgkmcnt(0)
	v_add_u32_e32 v13, v13, v15
	v_cndmask_b32_e64 v15, v9, v5, s[44:45]
	v_cndmask_b32_e64 v5, v5, v9, s[44:45]
	v_cndmask_b32_e64 v9, v13, v11, s[44:45]
	v_cndmask_b32_e64 v11, v11, v13, s[44:45]
	ds_swizzle_b32 v5, v5 offset:swizzle(SWAP,4)
	ds_swizzle_b32 v11, v11 offset:swizzle(SWAP,4)
	s_waitcnt lgkmcnt(1)
	v_add_u32_e32 v5, v15, v5
	s_waitcnt lgkmcnt(0)
	v_add_u32_e32 v9, v9, v11
	v_cndmask_b32_e64 v11, v9, v5, s[46:47]
	v_cndmask_b32_e64 v5, v5, v9, s[46:47]
	ds_swizzle_b32 v5, v5 offset:swizzle(SWAP,8)
	s_waitcnt lgkmcnt(0)
	v_add_u32_e32 v5, v11, v5
	ds_swizzle_b32 v9, v5 offset:swizzle(SWAP,16)
	s_waitcnt lgkmcnt(0)
	v_add_u32_e32 v5, v5, v9
	ds_bpermute_b32 v9, v0, v5
	s_and_saveexec_b64 s[0:1], s[48:49]
	s_cbranch_execz .LBB0_547
	v_ashrrev_i32_e32 v15, 31, v14
	v_lshlrev_b64 v[14:15], 2, v[14:15]
	v_lshl_add_u64 v[18:19], s[8:9], 0, v[14:15]
	v_mov_b32_e32 v11, v131
	v_lshl_add_u64 v[14:15], s[10:11], 0, v[14:15]
	v_mov_b32_e32 v13, v147
	s_nop 0
	v_mov_b32_e32 v14, v139
	s_waitcnt lgkmcnt(0)
	v_add_u32_e32 v5, v5, v9
	v_cvt_f32_i32_e32 v5, v5
	v_mul_f32_e32 v5, v5, v11
	v_mul_f32_e32 v5, v3, v5
	v_mul_f32_e32 v11, 0x3d372713, v5
	v_mul_f32_e32 v11, v5, v11
	v_mul_f32_e32 v9, 0.5, v5
	v_fmac_f32_e32 v5, v5, v11
	v_mul_f32_e32 v5, 0x3f4c422a, v5
	v_add_f32_e32 v5, v5, v5
	v_mul_f32_e32 v5, 0x3fb8aa3b, v5
	v_exp_f32_e32 v5, v5
	s_nop 0
	v_add_f32_e32 v5, 1.0, v5
	v_rcp_f32_e32 v5, v5
	s_nop 0
	v_fma_f32 v5, v5, -2.0, 1.0
	v_add_f32_e32 v5, 1.0, v5
	v_mul_f32_e32 v5, v9, v5
	v_mul_f32_e32 v5, v13, v5
	v_mul_f32_e32 v5, v14, v5
	ds_write_b32 v109, v5 offset:192
.LBB0_547:
	s_or_b64 exec, exec, s[0:1]
	v_readlane_b32 s0, v10, 0
	s_lshl_b32 s0, s0, 9
	s_waitcnt lgkmcnt(0)
	s_waitcnt vmcnt(15)
	v_dot8_i32_i4 v5, v94, v73, 0
	v_dot8_i32_i4 v9, v94, v75, 0
	buffer_load_dwordx2 v[92:93], v192, s[52:55], s0 offen
	v_readlane_b32 s0, v10, 1
	s_lshl_b32 s0, s0, 9
	v_dot8_i32_i4 v5, v95, v77, v5
	v_dot8_i32_i4 v9, v95, v108, v9
	s_waitcnt vmcnt(15)
	v_dot8_i32_i4 v11, v86, v75, 0
	buffer_load_dwordx2 v[96:97], v192, s[52:55], s0 offen
	v_readlane_b32 s0, v10, 2
	s_lshl_b32 s0, s0, 9
	v_lshl_add_u32 v5, v5, 4, v9
	v_dot8_i32_i4 v9, v86, v73, 0
	v_dot8_i32_i4 v9, v87, v77, v9
	buffer_load_dwordx2 v[88:89], v192, s[52:55], s0 offen
	v_readlane_b32 s0, v10, 3
	s_lshl_b32 s0, s0, 9
	v_dot8_i32_i4 v11, v87, v108, v11
	s_waitcnt vmcnt(16)
	v_dot8_i32_i4 v13, v84, v75, 0
	v_dot8_i32_i4 v13, v85, v108, v13
	buffer_load_dwordx2 v[98:99], v192, s[52:55], s0 offen
	v_readlane_b32 s0, v10, 4
	s_lshl_b32 s0, s0, 9
	v_lshl_add_u32 v9, v9, 4, v11
	v_dot8_i32_i4 v11, v84, v73, 0
	v_dot8_i32_i4 v11, v85, v77, v11
	buffer_load_dwordx2 v[82:83], v192, s[52:55], s0 offen
	v_readlane_b32 s0, v10, 5
	s_lshl_b32 s0, s0, 9
	v_lshl_add_u32 v11, v11, 4, v13
	s_waitcnt vmcnt(17)
	v_dot8_i32_i4 v13, v90, v73, 0
	buffer_load_dwordx2 v[56:57], v192, s[52:55], s0 offen
	v_readlane_b32 s0, v10, 6
	s_lshl_b32 s0, s0, 9
	v_dot8_i32_i4 v18, v90, v75, 0
	v_dot8_i32_i4 v13, v91, v77, v13
	v_dot8_i32_i4 v18, v91, v108, v18
	buffer_load_dwordx2 v[52:53], v192, s[52:55], s0 offen
	v_readlane_b32 s0, v10, 7
	s_lshl_b32 s0, s0, 9
	v_lshl_add_u32 v13, v13, 4, v18
	s_waitcnt vmcnt(18)
	v_dot8_i32_i4 v18, v78, v73, 0
	v_dot8_i32_i4 v19, v78, v75, 0
	buffer_load_dwordx2 v[80:81], v192, s[52:55], s0 offen
	v_readlane_b32 s0, v10, 8
	s_lshl_b32 s0, s0, 9
	v_dot8_i32_i4 v18, v79, v77, v18
	v_dot8_i32_i4 v19, v79, v108, v19
	s_waitcnt vmcnt(18)
	v_dot8_i32_i4 v78, v50, v75, 0
	buffer_load_dwordx2 v[46:47], v192, s[52:55], s0 offen
	v_readlane_b32 s0, v10, 9
	s_lshl_b32 s0, s0, 9
	v_lshl_add_u32 v18, v18, 4, v19
	v_dot8_i32_i4 v19, v50, v73, 0
	v_dot8_i32_i4 v19, v51, v77, v19
	buffer_load_dwordx2 v[40:41], v192, s[52:55], s0 offen
	v_readlane_b32 s0, v10, 10
	s_lshl_b32 s0, s0, 9
	v_dot8_i32_i4 v78, v51, v108, v78
	s_waitcnt vmcnt(19)
	v_dot8_i32_i4 v50, v48, v73, 0
	buffer_load_dwordx2 v[36:37], v192, s[52:55], s0 offen
	v_readlane_b32 s0, v10, 11
	s_lshl_b32 s0, s0, 9
	v_dot8_i32_i4 v51, v48, v75, 0
	v_dot8_i32_i4 v50, v49, v77, v50
	v_dot8_i32_i4 v51, v49, v108, v51
	buffer_load_dwordx2 v[44:45], v192, s[52:55], s0 offen
	v_readlane_b32 s0, v10, 12
	s_lshl_b32 s0, s0, 9
	v_lshl_add_u32 v48, v50, 4, v51
	s_waitcnt vmcnt(20)
	v_dot8_i32_i4 v49, v54, v73, 0
	v_dot8_i32_i4 v50, v54, v75, 0
	buffer_load_dwordx2 v[32:33], v192, s[52:55], s0 offen
	v_readlane_b32 s0, v10, 13
	s_lshl_b32 s0, s0, 9
	v_dot8_i32_i4 v49, v55, v77, v49
	v_dot8_i32_i4 v50, v55, v108, v50
	s_waitcnt vmcnt(20)
	v_dot8_i32_i4 v51, v42, v75, 0
	buffer_load_dwordx2 v[24:25], v192, s[52:55], s0 offen
	v_readlane_b32 s0, v10, 14
	s_lshl_b32 s0, s0, 9
	v_lshl_add_u32 v49, v49, 4, v50
	v_dot8_i32_i4 v50, v42, v73, 0
	v_dot8_i32_i4 v50, v43, v77, v50
	buffer_load_dwordx2 v[14:15], v192, s[52:55], s0 offen
	v_readlane_b32 s0, v10, 15
	s_lshl_b32 s0, s0, 9
	v_dot8_i32_i4 v51, v43, v108, v51
	s_waitcnt vmcnt(21)
	v_dot8_i32_i4 v43, v34, v73, 0
	v_dot8_i32_i4 v43, v35, v77, v43
	buffer_load_dwordx2 v[28:29], v192, s[52:55], s0 offen
	v_lshl_add_u32 v42, v50, 4, v51
	v_dot8_i32_i4 v50, v34, v75, 0
	v_dot8_i32_i4 v50, v35, v108, v50
	s_waitcnt vmcnt(21)
	v_dot8_i32_i4 v35, v30, v73, 0
	v_dot8_i32_i4 v35, v31, v77, v35
	v_lshl_add_u32 v34, v43, 4, v50
	v_dot8_i32_i4 v43, v30, v75, 0
	v_dot8_i32_i4 v43, v31, v108, v43
	s_waitcnt vmcnt(20)
	v_dot8_i32_i4 v31, v38, v73, 0
	v_dot8_i32_i4 v31, v39, v77, v31
	v_lshl_add_u32 v30, v35, 4, v43
	v_dot8_i32_i4 v35, v38, v75, 0
	v_dot8_i32_i4 v35, v39, v108, v35
	s_waitcnt vmcnt(19)
	v_dot8_i32_i4 v38, v26, v75, 0
	v_dot8_i32_i4 v38, v27, v108, v38
	v_lshl_add_u32 v31, v31, 4, v35
	v_dot8_i32_i4 v35, v26, v73, 0
	v_dot8_i32_i4 v35, v27, v77, v35
	s_waitcnt vmcnt(18)
	v_dot8_i32_i4 v27, v20, v73, 0
	v_dot8_i32_i4 v27, v21, v77, v27
	v_lshl_add_u32 v26, v35, 4, v38
	v_dot8_i32_i4 v35, v20, v75, 0
	v_dot8_i32_i4 v35, v21, v108, v35
	s_waitcnt vmcnt(17)
	v_dot8_i32_i4 v21, v16, v73, 0
	s_nop 0
	v_lshl_add_u32 v20, v27, 4, v35
	v_dot8_i32_i4 v27, v16, v75, 0
	v_dot8_i32_i4 v21, v17, v77, v21
	v_dot8_i32_i4 v27, v17, v108, v27
	s_waitcnt vmcnt(16)
	v_dot8_i32_i4 v17, v22, v73, 0
	v_dot8_i32_i4 v17, v23, v77, v17
	v_lshl_add_u32 v16, v21, 4, v27
	v_dot8_i32_i4 v21, v22, v75, 0
	v_dot8_i32_i4 v21, v23, v108, v21
	v_lshl_add_u32 v19, v19, 4, v78
	s_nop 0
	s_nop 0
	v_lshl_add_u32 v17, v17, 4, v21
	s_nop 0
	v_cndmask_b32_e64 v21, v9, v5, s[40:41]
	v_cndmask_b32_e64 v5, v5, v9, s[40:41]
	v_cndmask_b32_e64 v9, v13, v11, s[40:41]
	v_cndmask_b32_e64 v11, v11, v13, s[40:41]
	ds_swizzle_b32 v11, v11 offset:swizzle(SWAP,1)
	ds_swizzle_b32 v5, v5 offset:swizzle(SWAP,1)
	v_cndmask_b32_e64 v13, v18, v19, s[40:41]
	s_waitcnt lgkmcnt(1)
	v_add_u32_e32 v9, v9, v11
	v_cndmask_b32_e64 v11, v19, v18, s[40:41]
	ds_swizzle_b32 v13, v13 offset:swizzle(SWAP,1)
	v_cndmask_b32_e64 v18, v48, v49, s[40:41]
	ds_swizzle_b32 v18, v18 offset:swizzle(SWAP,1)
	v_cndmask_b32_e64 v19, v42, v34, s[40:41]
	s_waitcnt lgkmcnt(2)
	v_add_u32_e32 v5, v21, v5
	ds_swizzle_b32 v19, v19 offset:swizzle(SWAP,1)
	v_cndmask_b32_e64 v21, v30, v31, s[40:41]
	ds_swizzle_b32 v21, v21 offset:swizzle(SWAP,1)
	s_waitcnt lgkmcnt(3)
	v_add_u32_e32 v11, v11, v13
	v_cndmask_b32_e64 v13, v49, v48, s[40:41]
	s_waitcnt lgkmcnt(2)
	v_add_u32_e32 v13, v13, v18
	v_cndmask_b32_e64 v18, v34, v42, s[40:41]
	s_waitcnt lgkmcnt(1)
	v_add_u32_e32 v18, v18, v19
	v_cndmask_b32_e64 v19, v31, v30, s[40:41]
	s_waitcnt lgkmcnt(0)
	v_add_u32_e32 v19, v19, v21
	v_cndmask_b32_e64 v21, v20, v26, s[40:41]
	v_cndmask_b32_e64 v20, v26, v20, s[40:41]
	ds_swizzle_b32 v20, v20 offset:swizzle(SWAP,1)
	s_waitcnt lgkmcnt(0)
	v_add_u32_e32 v20, v21, v20
	v_cndmask_b32_e64 v21, v17, v16, s[40:41]
	v_cndmask_b32_e64 v16, v16, v17, s[40:41]
	v_cndmask_b32_e64 v17, v9, v5, s[42:43]
	v_cndmask_b32_e64 v5, v5, v9, s[42:43]
	v_cndmask_b32_e64 v9, v13, v11, s[42:43]
	v_cndmask_b32_e64 v11, v11, v13, s[42:43]
	ds_swizzle_b32 v16, v16 offset:swizzle(SWAP,1)
	ds_swizzle_b32 v11, v11 offset:swizzle(SWAP,2)
	v_cndmask_b32_e64 v13, v18, v19, s[42:43]
	ds_swizzle_b32 v13, v13 offset:swizzle(SWAP,2)
	ds_swizzle_b32 v5, v5 offset:swizzle(SWAP,2)
	s_waitcnt lgkmcnt(3)
	v_add_u32_e32 v16, v21, v16
	s_waitcnt lgkmcnt(2)
	v_add_u32_e32 v9, v9, v11
	v_cndmask_b32_e64 v11, v19, v18, s[42:43]
	s_waitcnt lgkmcnt(1)
	v_add_u32_e32 v11, v11, v13
	v_cndmask_b32_e64 v13, v16, v20, s[42:43]
	v_cndmask_b32_e64 v16, v20, v16, s[42:43]
	ds_swizzle_b32 v16, v16 offset:swizzle(SWAP,2)
	s_waitcnt lgkmcnt(1)
	v_add_u32_e32 v5, v17, v5
	s_waitcnt lgkmcnt(0)
	v_add_u32_e32 v13, v13, v16
	v_cndmask_b32_e64 v16, v9, v5, s[44:45]
	v_cndmask_b32_e64 v5, v5, v9, s[44:45]
	v_cndmask_b32_e64 v9, v13, v11, s[44:45]
	v_cndmask_b32_e64 v11, v11, v13, s[44:45]
	ds_swizzle_b32 v5, v5 offset:swizzle(SWAP,4)
	ds_swizzle_b32 v11, v11 offset:swizzle(SWAP,4)
	s_waitcnt lgkmcnt(1)
	v_add_u32_e32 v5, v16, v5
	s_waitcnt lgkmcnt(0)
	v_add_u32_e32 v9, v9, v11
	v_cndmask_b32_e64 v11, v9, v5, s[46:47]
	v_cndmask_b32_e64 v5, v5, v9, s[46:47]
	ds_swizzle_b32 v5, v5 offset:swizzle(SWAP,8)
	s_waitcnt lgkmcnt(0)
	v_add_u32_e32 v5, v11, v5
	ds_swizzle_b32 v9, v5 offset:swizzle(SWAP,16)
	s_waitcnt lgkmcnt(0)
	v_add_u32_e32 v5, v5, v9
	ds_bpermute_b32 v9, v0, v5
	s_and_saveexec_b64 s[0:1], s[48:49]
	s_cbranch_execz .LBB0_549
	v_ashrrev_i32_e32 v13, 31, v12
	v_lshlrev_b64 v[12:13], 2, v[12:13]
	v_lshl_add_u64 v[16:17], s[8:9], 0, v[12:13]
	v_mov_b32_e32 v11, v132
	v_lshl_add_u64 v[12:13], s[10:11], 0, v[12:13]
	v_mov_b32_e32 v16, v148
	s_nop 0
	v_mov_b32_e32 v12, v140
	s_waitcnt lgkmcnt(0)
	v_add_u32_e32 v5, v5, v9
	v_cvt_f32_i32_e32 v5, v5
	v_mul_f32_e32 v5, v5, v11
	v_mul_f32_e32 v5, v3, v5
	v_mul_f32_e32 v11, 0x3d372713, v5
	v_mul_f32_e32 v11, v5, v11
	v_mul_f32_e32 v9, 0.5, v5
	v_fmac_f32_e32 v5, v5, v11
	v_mul_f32_e32 v5, 0x3f4c422a, v5
	v_add_f32_e32 v5, v5, v5
	v_mul_f32_e32 v5, 0x3fb8aa3b, v5
	v_exp_f32_e32 v5, v5
	s_nop 0
	v_add_f32_e32 v5, 1.0, v5
	v_rcp_f32_e32 v5, v5
	s_nop 0
	v_fma_f32 v5, v5, -2.0, 1.0
	v_add_f32_e32 v5, 1.0, v5
	v_mul_f32_e32 v5, v9, v5
	v_mul_f32_e32 v5, v16, v5
	v_mul_f32_e32 v5, v12, v5
	ds_write_b32 v109, v5 offset:256
.LBB0_549:
	s_or_b64 exec, exec, s[0:1]
	v_readlane_b32 s0, v8, 0
	s_lshl_b32 s0, s0, 9
	s_waitcnt lgkmcnt(0)
	s_waitcnt vmcnt(15)
	v_dot8_i32_i4 v5, v92, v73, 0
	v_dot8_i32_i4 v9, v92, v75, 0
	buffer_load_dwordx2 v[86:87], v192, s[52:55], s0 offen
	v_readlane_b32 s0, v8, 1
	s_lshl_b32 s0, s0, 9
	v_dot8_i32_i4 v5, v93, v77, v5
	v_dot8_i32_i4 v9, v93, v108, v9
	s_waitcnt vmcnt(15)
	v_dot8_i32_i4 v11, v96, v75, 0
	buffer_load_dwordx2 v[78:79], v192, s[52:55], s0 offen
	v_readlane_b32 s0, v8, 2
	s_lshl_b32 s0, s0, 9
	v_lshl_add_u32 v5, v5, 4, v9
	v_dot8_i32_i4 v9, v96, v73, 0
	v_dot8_i32_i4 v9, v97, v77, v9
	buffer_load_dwordx2 v[54:55], v192, s[52:55], s0 offen
	v_readlane_b32 s0, v8, 3
	s_lshl_b32 s0, s0, 9
	v_dot8_i32_i4 v11, v97, v108, v11
	s_waitcnt vmcnt(16)
	v_dot8_i32_i4 v90, v88, v75, 0
	v_dot8_i32_i4 v90, v89, v108, v90
	buffer_load_dwordx2 v[84:85], v192, s[52:55], s0 offen
	v_readlane_b32 s0, v8, 4
	s_lshl_b32 s0, s0, 9
	v_lshl_add_u32 v9, v9, 4, v11
	v_dot8_i32_i4 v11, v88, v73, 0
	v_dot8_i32_i4 v11, v89, v77, v11
	buffer_load_dwordx2 v[50:51], v192, s[52:55], s0 offen
	v_readlane_b32 s0, v8, 5
	s_lshl_b32 s0, s0, 9
	s_waitcnt vmcnt(17)
	v_dot8_i32_i4 v88, v98, v73, 0
	v_dot8_i32_i4 v89, v98, v75, 0
	buffer_load_dwordx2 v[42:43], v192, s[52:55], s0 offen
	v_readlane_b32 s0, v8, 6
	s_lshl_b32 s0, s0, 9
	v_dot8_i32_i4 v88, v99, v77, v88
	v_dot8_i32_i4 v89, v99, v108, v89
	v_lshl_add_u32 v11, v11, 4, v90
	buffer_load_dwordx2 v[38:39], v192, s[52:55], s0 offen
	v_readlane_b32 s0, v8, 7
	s_lshl_b32 s0, s0, 9
	v_lshl_add_u32 v88, v88, 4, v89
	s_waitcnt vmcnt(18)
	v_dot8_i32_i4 v89, v82, v73, 0
	v_dot8_i32_i4 v90, v82, v75, 0
	buffer_load_dwordx2 v[48:49], v192, s[52:55], s0 offen
	v_readlane_b32 s0, v8, 8
	s_lshl_b32 s0, s0, 9
	v_dot8_i32_i4 v89, v83, v77, v89
	v_dot8_i32_i4 v90, v83, v108, v90
	s_waitcnt vmcnt(18)
	v_dot8_i32_i4 v83, v56, v73, 0
	buffer_load_dwordx2 v[34:35], v192, s[52:55], s0 offen
	v_readlane_b32 s0, v8, 9
	s_lshl_b32 s0, s0, 9
	v_lshl_add_u32 v82, v89, 4, v90
	v_dot8_i32_i4 v89, v56, v75, 0
	v_dot8_i32_i4 v83, v57, v77, v83
	buffer_load_dwordx2 v[26:27], v192, s[52:55], s0 offen
	v_readlane_b32 s0, v8, 10
	s_lshl_b32 s0, s0, 9
	v_dot8_i32_i4 v89, v57, v108, v89
	s_waitcnt vmcnt(19)
	v_dot8_i32_i4 v57, v52, v73, 0
	v_dot8_i32_i4 v57, v53, v77, v57
	buffer_load_dwordx2 v[22:23], v192, s[52:55], s0 offen
	v_readlane_b32 s0, v8, 11
	s_lshl_b32 s0, s0, 9
	v_lshl_add_u32 v56, v83, 4, v89
	v_dot8_i32_i4 v83, v52, v75, 0
	v_dot8_i32_i4 v83, v53, v108, v83
	buffer_load_dwordx2 v[30:31], v192, s[52:55], s0 offen
	v_readlane_b32 s0, v8, 12
	s_lshl_b32 s0, s0, 9
	v_lshl_add_u32 v52, v57, 4, v83
	s_waitcnt vmcnt(20)
	v_dot8_i32_i4 v53, v80, v73, 0
	buffer_load_dwordx2 v[20:21], v192, s[52:55], s0 offen
	v_readlane_b32 s0, v8, 13
	s_lshl_b32 s0, s0, 9
	v_dot8_i32_i4 v57, v80, v75, 0
	v_dot8_i32_i4 v53, v81, v77, v53
	v_dot8_i32_i4 v57, v81, v108, v57
	buffer_load_dwordx2 v[16:17], v192, s[52:55], s0 offen
	v_readlane_b32 s0, v8, 14
	s_lshl_b32 s0, s0, 9
	v_lshl_add_u32 v53, v53, 4, v57
	s_waitcnt vmcnt(21)
	v_dot8_i32_i4 v57, v46, v73, 0
	v_dot8_i32_i4 v80, v46, v75, 0
	buffer_load_dwordx2 v[12:13], v192, s[52:55], s0 offen
	v_readlane_b32 s0, v8, 15
	s_lshl_b32 s0, s0, 9
	v_dot8_i32_i4 v57, v47, v77, v57
	v_dot8_i32_i4 v80, v47, v108, v80
	s_waitcnt vmcnt(21)
	v_dot8_i32_i4 v47, v40, v73, 0
	buffer_load_dwordx2 v[18:19], v192, s[52:55], s0 offen
	v_lshl_add_u32 v46, v57, 4, v80
	v_dot8_i32_i4 v57, v40, v75, 0
	v_dot8_i32_i4 v47, v41, v77, v47
	v_dot8_i32_i4 v57, v41, v108, v57
	s_waitcnt vmcnt(21)
	v_dot8_i32_i4 v41, v36, v73, 0
	v_dot8_i32_i4 v41, v37, v77, v41
	v_lshl_add_u32 v40, v47, 4, v57
	v_dot8_i32_i4 v47, v36, v75, 0
	v_dot8_i32_i4 v47, v37, v108, v47
	s_waitcnt vmcnt(20)
	v_dot8_i32_i4 v37, v44, v73, 0
	v_dot8_i32_i4 v37, v45, v77, v37
	v_lshl_add_u32 v36, v41, 4, v47
	v_dot8_i32_i4 v41, v44, v75, 0
	v_dot8_i32_i4 v41, v45, v108, v41
	s_waitcnt vmcnt(19)
	v_dot8_i32_i4 v44, v32, v75, 0
	v_dot8_i32_i4 v44, v33, v108, v44
	v_lshl_add_u32 v37, v37, 4, v41
	v_dot8_i32_i4 v41, v32, v73, 0
	v_dot8_i32_i4 v41, v33, v77, v41
	s_waitcnt vmcnt(18)
	v_dot8_i32_i4 v33, v24, v73, 0
	v_dot8_i32_i4 v33, v25, v77, v33
	v_lshl_add_u32 v32, v41, 4, v44
	v_dot8_i32_i4 v41, v24, v75, 0
	v_dot8_i32_i4 v41, v25, v108, v41
	s_waitcnt vmcnt(17)
	v_dot8_i32_i4 v25, v14, v73, 0
	s_nop 0
	v_lshl_add_u32 v24, v33, 4, v41
	v_dot8_i32_i4 v33, v14, v75, 0
	v_dot8_i32_i4 v25, v15, v77, v25
	v_dot8_i32_i4 v33, v15, v108, v33
	s_waitcnt vmcnt(16)
	v_dot8_i32_i4 v15, v28, v73, 0
	v_dot8_i32_i4 v15, v29, v77, v15
	v_lshl_add_u32 v14, v25, 4, v33
	v_dot8_i32_i4 v25, v28, v75, 0
	v_dot8_i32_i4 v25, v29, v108, v25
	s_nop 1
	s_nop 0
	v_lshl_add_u32 v15, v15, 4, v25
	s_nop 0
	v_cndmask_b32_e64 v25, v9, v5, s[40:41]
	v_cndmask_b32_e64 v5, v5, v9, s[40:41]
	ds_swizzle_b32 v5, v5 offset:swizzle(SWAP,1)
	v_cndmask_b32_e64 v9, v88, v11, s[40:41]
	v_cndmask_b32_e64 v11, v11, v88, s[40:41]
	s_waitcnt lgkmcnt(0)
	v_add_u32_e32 v5, v25, v5
	ds_swizzle_b32 v11, v11 offset:swizzle(SWAP,1)
	v_cndmask_b32_e64 v25, v82, v56, s[40:41]
	ds_swizzle_b32 v25, v25 offset:swizzle(SWAP,1)
	v_cndmask_b32_e64 v28, v52, v53, s[40:41]
	ds_swizzle_b32 v28, v28 offset:swizzle(SWAP,1)
	v_cndmask_b32_e64 v29, v46, v40, s[40:41]
	ds_swizzle_b32 v29, v29 offset:swizzle(SWAP,1)
	v_cndmask_b32_e64 v33, v36, v37, s[40:41]
	ds_swizzle_b32 v33, v33 offset:swizzle(SWAP,1)
	s_waitcnt lgkmcnt(4)
	v_add_u32_e32 v9, v9, v11
	v_cndmask_b32_e64 v11, v56, v82, s[40:41]
	s_waitcnt lgkmcnt(3)
	v_add_u32_e32 v11, v11, v25
	v_cndmask_b32_e64 v25, v53, v52, s[40:41]
	s_waitcnt lgkmcnt(2)
	v_add_u32_e32 v25, v25, v28
	v_cndmask_b32_e64 v28, v40, v46, s[40:41]
	s_waitcnt lgkmcnt(1)
	v_add_u32_e32 v28, v28, v29
	v_cndmask_b32_e64 v29, v37, v36, s[40:41]
	s_waitcnt lgkmcnt(0)
	v_add_u32_e32 v29, v29, v33
	v_cndmask_b32_e64 v33, v24, v32, s[40:41]
	v_cndmask_b32_e64 v24, v32, v24, s[40:41]
	v_cndmask_b32_e64 v32, v15, v14, s[40:41]
	v_cndmask_b32_e64 v14, v14, v15, s[40:41]
	v_cndmask_b32_e64 v15, v9, v5, s[42:43]
	v_cndmask_b32_e64 v5, v5, v9, s[42:43]
	ds_swizzle_b32 v5, v5 offset:swizzle(SWAP,2)
	v_cndmask_b32_e64 v9, v25, v11, s[42:43]
	v_cndmask_b32_e64 v11, v11, v25, s[42:43]
	ds_swizzle_b32 v24, v24 offset:swizzle(SWAP,1)
	ds_swizzle_b32 v14, v14 offset:swizzle(SWAP,1)
	s_waitcnt lgkmcnt(2)
	v_add_u32_e32 v5, v15, v5
	ds_swizzle_b32 v11, v11 offset:swizzle(SWAP,2)
	v_cndmask_b32_e64 v15, v28, v29, s[42:43]
	ds_swizzle_b32 v15, v15 offset:swizzle(SWAP,2)
	s_waitcnt lgkmcnt(3)
	v_add_u32_e32 v24, v33, v24
	s_waitcnt lgkmcnt(2)
	v_add_u32_e32 v14, v32, v14
	s_waitcnt lgkmcnt(1)
	v_add_u32_e32 v9, v9, v11
	v_cndmask_b32_e64 v11, v29, v28, s[42:43]
	s_waitcnt lgkmcnt(0)
	v_add_u32_e32 v11, v11, v15
	v_cndmask_b32_e64 v15, v14, v24, s[42:43]
	v_cndmask_b32_e64 v14, v24, v14, s[42:43]
	ds_swizzle_b32 v14, v14 offset:swizzle(SWAP,2)
	s_waitcnt lgkmcnt(0)
	v_add_u32_e32 v14, v15, v14
	v_cndmask_b32_e64 v15, v9, v5, s[44:45]
	v_cndmask_b32_e64 v5, v5, v9, s[44:45]
	v_cndmask_b32_e64 v9, v14, v11, s[44:45]
	v_cndmask_b32_e64 v11, v11, v14, s[44:45]
	ds_swizzle_b32 v5, v5 offset:swizzle(SWAP,4)
	ds_swizzle_b32 v11, v11 offset:swizzle(SWAP,4)
	s_waitcnt lgkmcnt(1)
	v_add_u32_e32 v5, v15, v5
	s_waitcnt lgkmcnt(0)
	v_add_u32_e32 v9, v9, v11
	v_cndmask_b32_e64 v11, v9, v5, s[46:47]
	v_cndmask_b32_e64 v5, v5, v9, s[46:47]
	ds_swizzle_b32 v5, v5 offset:swizzle(SWAP,8)
	s_waitcnt lgkmcnt(0)
	v_add_u32_e32 v5, v11, v5
	ds_swizzle_b32 v9, v5 offset:swizzle(SWAP,16)
	s_waitcnt lgkmcnt(0)
	v_add_u32_e32 v5, v5, v9
	ds_bpermute_b32 v9, v0, v5
	s_and_saveexec_b64 s[0:1], s[48:49]
	s_cbranch_execz .LBB0_551
	v_ashrrev_i32_e32 v11, 31, v10
	v_lshlrev_b64 v[10:11], 2, v[10:11]
	v_lshl_add_u64 v[14:15], s[8:9], 0, v[10:11]
	v_mov_b32_e32 v14, v133
	v_lshl_add_u64 v[10:11], s[10:11], 0, v[10:11]
	v_mov_b32_e32 v15, v149
	s_nop 0
	v_mov_b32_e32 v10, v141
	s_waitcnt lgkmcnt(0)
	v_add_u32_e32 v5, v5, v9
	v_cvt_f32_i32_e32 v5, v5
	v_mul_f32_e32 v5, v5, v14
	v_mul_f32_e32 v5, v3, v5
	v_mul_f32_e32 v11, 0x3d372713, v5
	v_mul_f32_e32 v11, v5, v11
	v_mul_f32_e32 v9, 0.5, v5
	v_fmac_f32_e32 v5, v5, v11
	v_mul_f32_e32 v5, 0x3f4c422a, v5
	v_add_f32_e32 v5, v5, v5
	v_mul_f32_e32 v5, 0x3fb8aa3b, v5
	v_exp_f32_e32 v5, v5
	s_nop 0
	v_add_f32_e32 v5, 1.0, v5
	v_rcp_f32_e32 v5, v5
	s_nop 0
	v_fma_f32 v5, v5, -2.0, 1.0
	v_add_f32_e32 v5, 1.0, v5
	v_mul_f32_e32 v5, v9, v5
	v_mul_f32_e32 v5, v15, v5
	v_mul_f32_e32 v5, v10, v5
	ds_write_b32 v109, v5 offset:320
.LBB0_551:
	s_or_b64 exec, exec, s[0:1]
	s_waitcnt lgkmcnt(0)
	v_readlane_b32 s0, v4, 0
	s_waitcnt vmcnt(15)
	v_dot8_i32_i4 v5, v86, v73, 0
	v_dot8_i32_i4 v9, v86, v75, 0
	s_lshl_b32 s0, s0, 9
	v_dot8_i32_i4 v5, v87, v77, v5
	v_dot8_i32_i4 v9, v87, v108, v9
	buffer_load_dwordx2 v[88:89], v192, s[52:55], s0 offen
	v_readlane_b32 s0, v4, 1
	s_nop 0
	v_lshl_add_u32 v5, v5, 4, v9
	s_lshl_b32 s0, s0, 9
	s_waitcnt vmcnt(15)
	v_dot8_i32_i4 v9, v78, v73, 0
	v_dot8_i32_i4 v86, v78, v75, 0
	buffer_load_dwordx2 v[90:91], v192, s[52:55], s0 offen
	v_readlane_b32 s0, v4, 2
	v_dot8_i32_i4 v9, v79, v77, v9
	v_dot8_i32_i4 v86, v79, v108, v86
	s_lshl_b32 s0, s0, 9
	s_waitcnt vmcnt(15)
	v_dot8_i32_i4 v78, v54, v73, 0
	v_dot8_i32_i4 v79, v54, v75, 0
	buffer_load_dwordx2 v[82:83], v192, s[52:55], s0 offen
	v_readlane_b32 s0, v4, 3
	v_dot8_i32_i4 v78, v55, v77, v78
	v_dot8_i32_i4 v79, v55, v108, v79
	s_lshl_b32 s0, s0, 9
	s_waitcnt vmcnt(15)
	v_dot8_i32_i4 v55, v84, v73, 0
	v_lshl_add_u32 v54, v78, 4, v79
	buffer_load_dwordx2 v[92:93], v192, s[52:55], s0 offen
	v_readlane_b32 s0, v4, 4
	v_dot8_i32_i4 v78, v84, v75, 0
	s_lshl_b32 s0, s0, 9
	v_dot8_i32_i4 v55, v85, v77, v55
	v_dot8_i32_i4 v78, v85, v108, v78
	buffer_load_dwordx2 v[80:81], v192, s[52:55], s0 offen
	v_readlane_b32 s0, v4, 5
	s_nop 0
	v_lshl_add_u32 v55, v55, 4, v78
	s_lshl_b32 s0, s0, 9
	s_waitcnt vmcnt(16)
	v_dot8_i32_i4 v78, v50, v73, 0
	v_dot8_i32_i4 v79, v50, v75, 0
	buffer_load_dwordx2 v[52:53], v192, s[52:55], s0 offen
	v_readlane_b32 s0, v4, 6
	v_dot8_i32_i4 v78, v51, v77, v78
	v_dot8_i32_i4 v79, v51, v108, v79
	s_lshl_b32 s0, s0, 9
	s_waitcnt vmcnt(16)
	v_dot8_i32_i4 v51, v42, v73, 0
	v_lshl_add_u32 v50, v78, 4, v79
	buffer_load_dwordx2 v[46:47], v192, s[52:55], s0 offen
	v_readlane_b32 s0, v4, 7
	v_dot8_i32_i4 v78, v42, v75, 0
	s_lshl_b32 s0, s0, 9
	v_dot8_i32_i4 v51, v43, v77, v51
	v_dot8_i32_i4 v78, v43, v108, v78
	buffer_load_dwordx2 v[56:57], v192, s[52:55], s0 offen
	v_readlane_b32 s0, v4, 8
	s_nop 0
	v_lshl_add_u32 v42, v51, 4, v78
	s_lshl_b32 s0, s0, 9
	s_waitcnt vmcnt(17)
	v_dot8_i32_i4 v43, v38, v73, 0
	v_dot8_i32_i4 v51, v38, v75, 0
	buffer_load_dwordx2 v[44:45], v192, s[52:55], s0 offen
	v_readlane_b32 s0, v4, 9
	v_dot8_i32_i4 v43, v39, v77, v43
	v_dot8_i32_i4 v51, v39, v108, v51
	s_lshl_b32 s0, s0, 9
	s_waitcnt vmcnt(17)
	v_dot8_i32_i4 v39, v48, v73, 0
	v_lshl_add_u32 v38, v43, 4, v51
	buffer_load_dwordx2 v[36:37], v192, s[52:55], s0 offen
	v_readlane_b32 s0, v4, 10
	v_dot8_i32_i4 v43, v48, v75, 0
	s_lshl_b32 s0, s0, 9
	v_dot8_i32_i4 v39, v49, v77, v39
	v_dot8_i32_i4 v43, v49, v108, v43
	buffer_load_dwordx2 v[32:33], v192, s[52:55], s0 offen
	v_readlane_b32 s0, v4, 11
	s_nop 0
	v_lshl_add_u32 v39, v39, 4, v43
	s_lshl_b32 s0, s0, 9
	s_waitcnt vmcnt(18)
	v_dot8_i32_i4 v43, v34, v73, 0
	v_dot8_i32_i4 v48, v34, v75, 0
	buffer_load_dwordx2 v[40:41], v192, s[52:55], s0 offen
	v_readlane_b32 s0, v4, 12
	v_dot8_i32_i4 v43, v35, v77, v43
	v_dot8_i32_i4 v48, v35, v108, v48
	s_lshl_b32 s0, s0, 9
	s_waitcnt vmcnt(18)
	v_dot8_i32_i4 v35, v26, v73, 0
	v_lshl_add_u32 v34, v43, 4, v48
	buffer_load_dwordx2 v[28:29], v192, s[52:55], s0 offen
	v_readlane_b32 s0, v4, 13
	v_dot8_i32_i4 v43, v26, v75, 0
	s_lshl_b32 s0, s0, 9
	v_dot8_i32_i4 v35, v27, v77, v35
	v_dot8_i32_i4 v43, v27, v108, v43
	buffer_load_dwordx2 v[14:15], v192, s[52:55], s0 offen
	v_readlane_b32 s0, v4, 14
	s_nop 0
	v_lshl_add_u32 v26, v35, 4, v43
	s_lshl_b32 s0, s0, 9
	s_waitcnt vmcnt(19)
	v_dot8_i32_i4 v27, v22, v73, 0
	v_dot8_i32_i4 v35, v22, v75, 0
	buffer_load_dwordx2 v[10:11], v192, s[52:55], s0 offen
	v_readlane_b32 s0, v4, 15
	v_dot8_i32_i4 v27, v23, v77, v27
	v_dot8_i32_i4 v35, v23, v108, v35
	s_lshl_b32 s0, s0, 9
	s_waitcnt vmcnt(19)
	v_dot8_i32_i4 v23, v30, v73, 0
	v_lshl_add_u32 v22, v27, 4, v35
	buffer_load_dwordx2 v[24:25], v192, s[52:55], s0 offen
	v_dot8_i32_i4 v27, v30, v75, 0
	v_dot8_i32_i4 v23, v31, v77, v23
	v_dot8_i32_i4 v27, v31, v108, v27
	s_waitcnt vmcnt(19)
	v_dot8_i32_i4 v30, v20, v75, 0
	v_dot8_i32_i4 v30, v21, v108, v30
	v_lshl_add_u32 v23, v23, 4, v27
	v_dot8_i32_i4 v27, v20, v73, 0
	v_dot8_i32_i4 v27, v21, v77, v27
	s_waitcnt vmcnt(18)
	v_dot8_i32_i4 v21, v16, v73, 0
	v_dot8_i32_i4 v21, v17, v77, v21
	v_lshl_add_u32 v20, v27, 4, v30
	v_dot8_i32_i4 v27, v16, v75, 0
	v_dot8_i32_i4 v27, v17, v108, v27
	v_lshl_add_u32 v9, v9, 4, v86
	s_waitcnt vmcnt(17)
	v_dot8_i32_i4 v17, v12, v73, 0
	v_lshl_add_u32 v16, v21, 4, v27
	v_dot8_i32_i4 v21, v12, v75, 0
	v_dot8_i32_i4 v17, v13, v77, v17
	v_dot8_i32_i4 v21, v13, v108, v21
	s_waitcnt vmcnt(16)
	v_dot8_i32_i4 v13, v18, v73, 0
	v_dot8_i32_i4 v13, v19, v77, v13
	v_lshl_add_u32 v12, v17, 4, v21
	v_dot8_i32_i4 v17, v18, v75, 0
	v_dot8_i32_i4 v17, v19, v108, v17
	s_nop 1
	s_nop 0
	v_lshl_add_u32 v13, v13, 4, v17
	s_nop 0
	v_cndmask_b32_e64 v17, v9, v5, s[40:41]
	v_cndmask_b32_e64 v5, v5, v9, s[40:41]
	ds_swizzle_b32 v5, v5 offset:swizzle(SWAP,1)
	s_waitcnt lgkmcnt(0)
	v_add_u32_e32 v5, v17, v5
	v_cndmask_b32_e64 v17, v54, v55, s[40:41]
	ds_swizzle_b32 v17, v17 offset:swizzle(SWAP,1)
	v_cndmask_b32_e64 v18, v50, v42, s[40:41]
	ds_swizzle_b32 v18, v18 offset:swizzle(SWAP,1)
	v_cndmask_b32_e64 v19, v38, v39, s[40:41]
	ds_swizzle_b32 v19, v19 offset:swizzle(SWAP,1)
	v_cndmask_b32_e64 v21, v34, v26, s[40:41]
	ds_swizzle_b32 v21, v21 offset:swizzle(SWAP,1)
	v_cndmask_b32_e64 v9, v55, v54, s[40:41]
	s_waitcnt lgkmcnt(3)
	v_add_u32_e32 v9, v9, v17
	v_cndmask_b32_e64 v17, v42, v50, s[40:41]
	s_waitcnt lgkmcnt(2)
	v_add_u32_e32 v17, v17, v18
	v_cndmask_b32_e64 v18, v39, v38, s[40:41]
	s_waitcnt lgkmcnt(1)
	v_add_u32_e32 v18, v18, v19
	v_cndmask_b32_e64 v19, v26, v34, s[40:41]
	s_waitcnt lgkmcnt(0)
	v_add_u32_e32 v19, v19, v21
	v_cndmask_b32_e64 v21, v23, v22, s[40:41]
	v_cndmask_b32_e64 v22, v22, v23, s[40:41]
	ds_swizzle_b32 v22, v22 offset:swizzle(SWAP,1)
	s_waitcnt lgkmcnt(0)
	v_add_u32_e32 v21, v21, v22
	v_cndmask_b32_e64 v22, v16, v20, s[40:41]
	v_cndmask_b32_e64 v16, v20, v16, s[40:41]
	v_cndmask_b32_e64 v20, v13, v12, s[40:41]
	v_cndmask_b32_e64 v12, v12, v13, s[40:41]
	v_cndmask_b32_e64 v13, v9, v5, s[42:43]
	v_cndmask_b32_e64 v5, v5, v9, s[42:43]
	ds_swizzle_b32 v5, v5 offset:swizzle(SWAP,2)
	ds_swizzle_b32 v16, v16 offset:swizzle(SWAP,1)
	ds_swizzle_b32 v12, v12 offset:swizzle(SWAP,1)
	v_cndmask_b32_e64 v9, v18, v17, s[42:43]
	s_waitcnt lgkmcnt(2)
	v_add_u32_e32 v5, v13, v5
	v_cndmask_b32_e64 v13, v17, v18, s[42:43]
	ds_swizzle_b32 v13, v13 offset:swizzle(SWAP,2)
	v_cndmask_b32_e64 v17, v19, v21, s[42:43]
	ds_swizzle_b32 v17, v17 offset:swizzle(SWAP,2)
	s_waitcnt lgkmcnt(3)
	v_add_u32_e32 v16, v22, v16
	s_waitcnt lgkmcnt(2)
	v_add_u32_e32 v12, v20, v12
	s_waitcnt lgkmcnt(1)
	v_add_u32_e32 v9, v9, v13
	v_cndmask_b32_e64 v13, v21, v19, s[42:43]
	s_waitcnt lgkmcnt(0)
	v_add_u32_e32 v13, v13, v17
	v_cndmask_b32_e64 v17, v12, v16, s[42:43]
	v_cndmask_b32_e64 v12, v16, v12, s[42:43]
	ds_swizzle_b32 v12, v12 offset:swizzle(SWAP,2)
	v_cndmask_b32_e64 v16, v9, v5, s[44:45]
	v_cndmask_b32_e64 v5, v5, v9, s[44:45]
	ds_swizzle_b32 v5, v5 offset:swizzle(SWAP,4)
	s_waitcnt lgkmcnt(1)
	v_add_u32_e32 v12, v17, v12
	v_cndmask_b32_e64 v9, v12, v13, s[44:45]
	v_cndmask_b32_e64 v12, v13, v12, s[44:45]
	ds_swizzle_b32 v12, v12 offset:swizzle(SWAP,4)
	s_waitcnt lgkmcnt(1)
	v_add_u32_e32 v5, v16, v5
	s_waitcnt lgkmcnt(0)
	v_add_u32_e32 v9, v9, v12
	v_cndmask_b32_e64 v12, v9, v5, s[46:47]
	v_cndmask_b32_e64 v5, v5, v9, s[46:47]
	ds_swizzle_b32 v5, v5 offset:swizzle(SWAP,8)
	s_waitcnt lgkmcnt(0)
	v_add_u32_e32 v5, v12, v5
	ds_swizzle_b32 v9, v5 offset:swizzle(SWAP,16)
	s_waitcnt lgkmcnt(0)
	v_add_u32_e32 v5, v5, v9
	ds_bpermute_b32 v12, v0, v5
	s_and_saveexec_b64 s[0:1], s[48:49]
	s_cbranch_execz .LBB0_553
	v_ashrrev_i32_e32 v9, 31, v8
	v_lshlrev_b64 v[8:9], 2, v[8:9]
	v_lshl_add_u64 v[16:17], s[8:9], 0, v[8:9]
	v_mov_b32_e32 v13, v134
	v_lshl_add_u64 v[8:9], s[10:11], 0, v[8:9]
	v_mov_b32_e32 v16, v150
	s_nop 0
	v_mov_b32_e32 v8, v142
	s_waitcnt lgkmcnt(0)
	v_add_u32_e32 v5, v5, v12
	v_cvt_f32_i32_e32 v5, v5
	v_mul_f32_e32 v5, v5, v13
	v_mul_f32_e32 v5, v3, v5
	v_mul_f32_e32 v12, 0x3d372713, v5
	v_mul_f32_e32 v12, v5, v12
	v_mul_f32_e32 v9, 0.5, v5
	v_fmac_f32_e32 v5, v5, v12
	v_mul_f32_e32 v5, 0x3f4c422a, v5
	v_add_f32_e32 v5, v5, v5
	v_mul_f32_e32 v5, 0x3fb8aa3b, v5
	v_exp_f32_e32 v5, v5
	s_nop 0
	v_add_f32_e32 v5, 1.0, v5
	v_rcp_f32_e32 v5, v5
	s_nop 0
	v_fma_f32 v5, v5, -2.0, 1.0
	v_add_f32_e32 v5, 1.0, v5
	v_mul_f32_e32 v5, v9, v5
	v_mul_f32_e32 v5, v16, v5
	v_mul_f32_e32 v5, v8, v5
	ds_write_b32 v109, v5 offset:384
.LBB0_553:
	s_or_b64 exec, exec, s[0:1]
	s_waitcnt vmcnt(15)
	v_dot8_i32_i4 v5, v88, v73, 0
	v_dot8_i32_i4 v8, v88, v75, 0
	v_dot8_i32_i4 v5, v89, v77, v5
	v_dot8_i32_i4 v8, v89, v108, v8
	s_waitcnt vmcnt(14)
	v_dot8_i32_i4 v9, v90, v75, 0
	v_dot8_i32_i4 v9, v91, v108, v9
	v_lshl_add_u32 v5, v5, 4, v8
	v_dot8_i32_i4 v8, v90, v73, 0
	v_dot8_i32_i4 v8, v91, v77, v8
	s_waitcnt lgkmcnt(0)
	s_waitcnt vmcnt(13)
	v_dot8_i32_i4 v12, v82, v75, 0
	v_dot8_i32_i4 v12, v83, v108, v12
	v_lshl_add_u32 v8, v8, 4, v9
	v_dot8_i32_i4 v9, v82, v73, 0
	v_dot8_i32_i4 v9, v83, v77, v9
	s_waitcnt vmcnt(12)
	v_dot8_i32_i4 v13, v92, v75, 0
	v_dot8_i32_i4 v13, v93, v108, v13
	v_lshl_add_u32 v9, v9, 4, v12
	v_dot8_i32_i4 v12, v92, v73, 0
	v_dot8_i32_i4 v12, v93, v77, v12
	s_waitcnt vmcnt(11)
	v_dot8_i32_i4 v16, v80, v75, 0
	v_dot8_i32_i4 v16, v81, v108, v16
	v_lshl_add_u32 v12, v12, 4, v13
	v_dot8_i32_i4 v13, v80, v73, 0
	v_dot8_i32_i4 v13, v81, v77, v13
	s_waitcnt vmcnt(10)
	v_dot8_i32_i4 v17, v52, v75, 0
	v_dot8_i32_i4 v17, v53, v108, v17
	v_lshl_add_u32 v13, v13, 4, v16
	v_dot8_i32_i4 v16, v52, v73, 0
	v_dot8_i32_i4 v16, v53, v77, v16
	s_waitcnt vmcnt(9)
	v_dot8_i32_i4 v18, v46, v75, 0
	v_dot8_i32_i4 v18, v47, v108, v18
	v_lshl_add_u32 v16, v16, 4, v17
	v_dot8_i32_i4 v17, v46, v73, 0
	v_dot8_i32_i4 v17, v47, v77, v17
	s_waitcnt vmcnt(8)
	v_dot8_i32_i4 v19, v56, v75, 0
	v_dot8_i32_i4 v19, v57, v108, v19
	v_lshl_add_u32 v17, v17, 4, v18
	v_dot8_i32_i4 v18, v56, v73, 0
	v_dot8_i32_i4 v18, v57, v77, v18
	s_waitcnt vmcnt(7)
	v_dot8_i32_i4 v20, v44, v75, 0
	v_dot8_i32_i4 v20, v45, v108, v20
	v_lshl_add_u32 v18, v18, 4, v19
	v_dot8_i32_i4 v19, v44, v73, 0
	v_dot8_i32_i4 v19, v45, v77, v19
	s_waitcnt vmcnt(6)
	v_dot8_i32_i4 v21, v36, v75, 0
	v_dot8_i32_i4 v21, v37, v108, v21
	v_lshl_add_u32 v19, v19, 4, v20
	v_dot8_i32_i4 v20, v36, v73, 0
	v_dot8_i32_i4 v20, v37, v77, v20
	s_waitcnt vmcnt(5)
	v_dot8_i32_i4 v22, v32, v75, 0
	v_dot8_i32_i4 v22, v33, v108, v22
	v_lshl_add_u32 v20, v20, 4, v21
	v_dot8_i32_i4 v21, v32, v73, 0
	v_dot8_i32_i4 v21, v33, v77, v21
	s_waitcnt vmcnt(4)
	v_dot8_i32_i4 v23, v40, v75, 0
	v_dot8_i32_i4 v23, v41, v108, v23
	v_lshl_add_u32 v21, v21, 4, v22
	v_dot8_i32_i4 v22, v40, v73, 0
	v_dot8_i32_i4 v22, v41, v77, v22
	s_waitcnt vmcnt(3)
	v_dot8_i32_i4 v26, v28, v75, 0
	v_dot8_i32_i4 v26, v29, v108, v26
	v_lshl_add_u32 v22, v22, 4, v23
	v_dot8_i32_i4 v23, v28, v73, 0
	v_dot8_i32_i4 v23, v29, v77, v23
	s_waitcnt vmcnt(2)
	v_dot8_i32_i4 v27, v14, v75, 0
	v_dot8_i32_i4 v27, v15, v108, v27
	v_lshl_add_u32 v23, v23, 4, v26
	v_dot8_i32_i4 v26, v14, v73, 0
	v_dot8_i32_i4 v26, v15, v77, v26
	s_waitcnt vmcnt(1)
	v_dot8_i32_i4 v15, v10, v73, 0
	s_nop 0
	v_lshl_add_u32 v14, v26, 4, v27
	v_dot8_i32_i4 v26, v10, v75, 0
	v_dot8_i32_i4 v15, v11, v77, v15
	v_dot8_i32_i4 v26, v11, v108, v26
	s_waitcnt vmcnt(0)
	v_dot8_i32_i4 v11, v24, v73, 0
	v_dot8_i32_i4 v11, v25, v77, v11
	v_lshl_add_u32 v10, v15, 4, v26
	v_dot8_i32_i4 v15, v24, v75, 0
	v_dot8_i32_i4 v15, v25, v108, v15
	s_nop 1
	s_nop 0
	v_lshl_add_u32 v11, v11, 4, v15
	s_nop 0
	v_cndmask_b32_e64 v15, v8, v5, s[40:41]
	v_cndmask_b32_e64 v5, v5, v8, s[40:41]
	v_cndmask_b32_e64 v8, v9, v12, s[40:41]
	ds_swizzle_b32 v8, v8 offset:swizzle(SWAP,1)
	ds_swizzle_b32 v5, v5 offset:swizzle(SWAP,1)
	v_cndmask_b32_e64 v9, v12, v9, s[40:41]
	v_cndmask_b32_e64 v24, v13, v16, s[40:41]
	s_waitcnt lgkmcnt(1)
	v_add_u32_e32 v8, v9, v8
	v_cndmask_b32_e64 v9, v16, v13, s[40:41]
	v_cndmask_b32_e64 v13, v17, v18, s[40:41]
	s_waitcnt lgkmcnt(0)
	v_add_u32_e32 v5, v15, v5
	ds_swizzle_b32 v13, v13 offset:swizzle(SWAP,1)
	v_cndmask_b32_e64 v15, v19, v20, s[40:41]
	ds_swizzle_b32 v15, v15 offset:swizzle(SWAP,1)
	v_cndmask_b32_e64 v16, v21, v22, s[40:41]
	ds_swizzle_b32 v16, v16 offset:swizzle(SWAP,1)
	v_cndmask_b32_e64 v12, v18, v17, s[40:41]
	s_waitcnt lgkmcnt(2)
	v_add_u32_e32 v12, v12, v13
	v_cndmask_b32_e64 v13, v20, v19, s[40:41]
	s_waitcnt lgkmcnt(1)
	v_add_u32_e32 v13, v13, v15
	v_cndmask_b32_e64 v15, v22, v21, s[40:41]
	ds_swizzle_b32 v24, v24 offset:swizzle(SWAP,1)
	s_waitcnt lgkmcnt(1)
	v_add_u32_e32 v15, v15, v16
	v_cndmask_b32_e64 v16, v14, v23, s[40:41]
	v_cndmask_b32_e64 v14, v23, v14, s[40:41]
	v_cndmask_b32_e64 v17, v10, v11, s[40:41]
	ds_swizzle_b32 v14, v14 offset:swizzle(SWAP,1)
	ds_swizzle_b32 v17, v17 offset:swizzle(SWAP,1)
	s_waitcnt lgkmcnt(2)
	v_add_u32_e32 v9, v9, v24
	v_cndmask_b32_e64 v10, v11, v10, s[40:41]
	v_cndmask_b32_e64 v18, v5, v8, s[42:43]
	s_waitcnt lgkmcnt(1)
	v_add_u32_e32 v14, v16, v14
	s_waitcnt lgkmcnt(0)
	v_add_u32_e32 v10, v10, v17
	v_cndmask_b32_e64 v5, v8, v5, s[42:43]
	v_cndmask_b32_e64 v8, v12, v9, s[42:43]
	v_cndmask_b32_e64 v9, v9, v12, s[42:43]
	ds_swizzle_b32 v9, v9 offset:swizzle(SWAP,2)
	v_cndmask_b32_e64 v11, v13, v15, s[42:43]
	v_cndmask_b32_e64 v12, v14, v10, s[42:43]
	ds_swizzle_b32 v18, v18 offset:swizzle(SWAP,2)
	ds_swizzle_b32 v11, v11 offset:swizzle(SWAP,2)
	ds_swizzle_b32 v12, v12 offset:swizzle(SWAP,2)
	s_waitcnt lgkmcnt(3)
	v_add_u32_e32 v8, v8, v9
	v_cndmask_b32_e64 v9, v15, v13, s[42:43]
	v_cndmask_b32_e64 v10, v10, v14, s[42:43]
	s_waitcnt lgkmcnt(2)
	v_add_u32_e32 v5, v5, v18
	s_waitcnt lgkmcnt(1)
	v_add_u32_e32 v9, v9, v11
	s_waitcnt lgkmcnt(0)
	v_add_u32_e32 v10, v10, v12
	v_cndmask_b32_e64 v11, v5, v8, s[44:45]
	v_cndmask_b32_e64 v12, v9, v10, s[44:45]
	ds_swizzle_b32 v11, v11 offset:swizzle(SWAP,4)
	ds_swizzle_b32 v12, v12 offset:swizzle(SWAP,4)
	v_cndmask_b32_e64 v5, v8, v5, s[44:45]
	v_cndmask_b32_e64 v8, v10, v9, s[44:45]
	s_waitcnt lgkmcnt(1)
	v_add_u32_e32 v5, v5, v11
	s_waitcnt lgkmcnt(0)
	v_add_u32_e32 v8, v8, v12
	v_cndmask_b32_e64 v9, v5, v8, s[46:47]
	ds_swizzle_b32 v9, v9 offset:swizzle(SWAP,8)
	v_cndmask_b32_e64 v5, v8, v5, s[46:47]
	s_waitcnt lgkmcnt(0)
	v_add_u32_e32 v5, v5, v9
	ds_swizzle_b32 v8, v5 offset:swizzle(SWAP,16)
	s_waitcnt lgkmcnt(0)
	v_add_u32_e32 v8, v5, v8
	ds_bpermute_b32 v0, v0, v8
	s_and_saveexec_b64 s[0:1], s[48:49]
	s_cbranch_execz .LBB0_536
	v_ashrrev_i32_e32 v5, 31, v4
	v_lshlrev_b64 v[4:5], 2, v[4:5]
	v_lshl_add_u64 v[10:11], s[8:9], 0, v[4:5]
	v_mov_b32_e32 v9, v135
	v_lshl_add_u64 v[4:5], s[10:11], 0, v[4:5]
	v_mov_b32_e32 v6, v151
	s_nop 0
	v_mov_b32_e32 v4, v143
	s_waitcnt lgkmcnt(0)
	v_add_u32_e32 v0, v8, v0
	v_cvt_f32_i32_e32 v0, v0
	v_mul_f32_e32 v0, v0, v9
	v_mul_f32_e32 v0, v3, v0
	v_mul_f32_e32 v5, 0x3d372713, v0
	v_mul_f32_e32 v5, v0, v5
	v_mul_f32_e32 v3, 0.5, v0
	v_fmac_f32_e32 v0, v0, v5
	v_mul_f32_e32 v0, 0x3f4c422a, v0
	v_add_f32_e32 v0, v0, v0
	v_mul_f32_e32 v0, 0x3fb8aa3b, v0
	v_exp_f32_e32 v0, v0
	s_nop 0
	v_add_f32_e32 v0, 1.0, v0
	v_rcp_f32_e32 v0, v0
	s_nop 0
	v_fma_f32 v0, v0, -2.0, 1.0
	v_add_f32_e32 v0, 1.0, v0
	v_mul_f32_e32 v0, v3, v0
	v_mul_f32_e32 v0, v6, v0
	v_mul_f32_e32 v0, v4, v0
	ds_write_b32 v109, v0 offset:448
	s_branch .LBB0_536

.LBB0_558:
	v_cmp_gt_i32_e32 vcc, s33, v78
	s_or_b64 s[16:17], s[16:17], exec
	s_and_saveexec_b64 s[18:19], vcc
	s_cbranch_execz .LBB0_557
	v_ashrrev_i32_e32 v79, 31, v78
	v_lshlrev_b64 v[2:3], 9, v[78:79]
	v_lshl_add_u64 v[2:3], v[62:63], 0, v[2:3]
	global_load_dword v4, v[2:3], off
	s_mov_b32 s6, s54
	s_mov_b32 s7, s55
	global_load_dword v73, v[2:3], off offset:64
	s_waitcnt lgkmcnt(0)
	global_load_dword v51, v[2:3], off offset:128
	global_load_dword v50, v[2:3], off offset:192
	global_load_dword v49, v[2:3], off offset:256
	global_load_dword v48, v[2:3], off offset:320
	global_load_dword v46, v[2:3], off offset:384
	global_load_dword v0, v[2:3], off offset:448
	v_add_u32_e32 v47, s21, v194
	ds_read2_b32 v[2:3], v47 offset1:16
	v_mov_b32_e32 v75, v1
	v_mov_b32_e32 v77, v1
	s_waitcnt lgkmcnt(0)
	v_readlane_b32 s38, v2, 0
	v_readlane_b32 s56, v2, 1
	v_readlane_b32 s24, v2, 3
	v_readlane_b32 s28, v2, 4
	v_readlane_b32 s34, v2, 5
	v_readlane_b32 s36, v2, 6
	v_readlane_b32 s26, v2, 8
	v_readlane_b32 s30, v2, 9
	v_readlane_b32 s62, v2, 12
	s_waitcnt vmcnt(0)
	v_lshlrev_b32_e32 v4, 9, v4
	v_lshlrev_b32_e32 v73, 9, v73
	v_lshlrev_b32_e32 v51, 9, v51
	v_lshlrev_b32_e32 v50, 9, v50
	v_lshlrev_b32_e32 v49, 9, v49
	v_lshlrev_b32_e32 v48, 9, v48
	v_lshlrev_b32_e32 v46, 9, v46
	v_lshlrev_b32_e32 v0, 9, v0
	s_nop 0
	v_readlane_b32 s20, v4, 0
	v_readlane_b32 s22, v4, 6
	s_nop 1
	s_nop 1
	buffer_load_dwordx2 v[8:9], v192, s[4:7], s20 offen
	v_readlane_b32 s23, v4, 7
	s_nop 0
	buffer_load_dwordx2 v[22:23], v192, s[4:7], s22 offen
	v_readlane_b32 s20, v4, 1
	v_readlane_b32 s25, v4, 8
	s_nop 1
	buffer_load_dwordx2 v[24:25], v192, s[4:7], s23 offen
	v_readlane_b32 s23, v4, 9
	s_nop 1
	buffer_load_dwordx2 v[12:13], v192, s[4:7], s20 offen
	v_readlane_b32 s20, v4, 2
	s_nop 2
	buffer_load_dwordx2 v[28:29], v192, s[4:7], s23 offen
	buffer_load_dwordx2 v[26:27], v192, s[4:7], s25 offen
	v_readlane_b32 s27, v4, 10
	s_nop 1
	buffer_load_dwordx2 v[14:15], v192, s[4:7], s20 offen
	v_readlane_b32 s20, v4, 3
	v_readlane_b32 s29, v4, 11
	v_readlane_b32 s31, v4, 12
	v_readlane_b32 s35, v4, 13
	v_readlane_b32 s37, v4, 14
	s_nop 0
	buffer_load_dwordx2 v[16:17], v192, s[4:7], s20 offen
	v_readlane_b32 s20, v4, 4
	v_readlane_b32 s25, v4, 15
	s_nop 3
	buffer_load_dwordx2 v[18:19], v192, s[4:7], s20 offen
	v_readlane_b32 s20, v4, 5
	s_mov_b32 s23, s25
	v_readlane_b32 s22, v2, 7
	s_nop 2
	buffer_load_dwordx2 v[20:21], v192, s[4:7], s20 offen
	buffer_load_dwordx2 v[30:31], v192, s[4:7], s27 offen
	buffer_load_dwordx2 v[32:33], v192, s[4:7], s29 offen
	buffer_load_dwordx2 v[34:35], v192, s[4:7], s31 offen
	buffer_load_dwordx2 v[10:11], v192, s[4:7], s35 offen
	buffer_load_dwordx2 v[6:7], v192, s[4:7], s37 offen
	buffer_load_dwordx2 v[4:5], v192, s[4:7], s23 offen
	v_readlane_b32 s20, v2, 2
	s_waitcnt vmcnt(15)
	v_cvt_scalef32_pk_f32_fp4 v[36:37], v8, 1.0
	v_cvt_scalef32_pk_f32_fp4 v[44:45], v9, 1.0
	v_pk_fma_f32 v[36:37], v[36:37], s[38:39], 0 op_sel_hi:[1,0,0]
	v_pk_fma_f32 v[44:45], v[44:45], s[38:39], 0 op_sel_hi:[1,0,0]
	s_waitcnt vmcnt(14)
	v_cvt_scalef32_pk_f32_fp4 v[156:157], v23, 1.0
	v_cvt_scalef32_pk_f32_fp4 v[42:43], v8, 1.0 op_sel:[1,1,0]
	v_cvt_scalef32_pk_f32_fp4 v[38:39], v8, 1.0 op_sel:[1,0,0]
	s_waitcnt vmcnt(13)
	v_cvt_scalef32_pk_f32_fp4 v[170:171], v25, 1.0
	v_cvt_scalef32_pk_f32_fp4 v[40:41], v8, 1.0 op_sel:[0,1,0]
	v_cvt_scalef32_pk_f32_fp4 v[52:53], v9, 1.0 op_sel:[1,0,0]
	s_waitcnt vmcnt(12)
	v_cvt_scalef32_pk_f32_fp4 v[56:57], v12, 1.0
	v_cvt_scalef32_pk_f32_fp4 v[86:87], v13, 1.0
	v_pk_fma_f32 v[36:37], v[56:57], s[56:57], v[36:37] op_sel_hi:[1,0,1]
	v_pk_fma_f32 v[44:45], v[86:87], s[56:57], v[44:45] op_sel_hi:[1,0,1]
	v_cvt_scalef32_pk_f32_fp4 v[54:55], v9, 1.0 op_sel:[0,1,0]
	s_waitcnt vmcnt(10)
	v_cvt_scalef32_pk_f32_fp4 v[184:185], v27, 1.0
	v_cvt_scalef32_pk_f32_fp4 v[8:9], v9, 1.0 op_sel:[1,1,0]
	s_waitcnt vmcnt(9)
	v_cvt_scalef32_pk_f32_fp4 v[92:93], v14, 1.0
	v_cvt_scalef32_pk_f32_fp4 v[94:95], v14, 1.0 op_sel:[1,0,0]
	v_cvt_scalef32_pk_f32_fp4 v[96:97], v14, 1.0 op_sel:[0,1,0]
	v_cvt_scalef32_pk_f32_fp4 v[98:99], v14, 1.0 op_sel:[1,1,0]
	v_cvt_scalef32_pk_f32_fp4 v[100:101], v15, 1.0
	v_cvt_scalef32_pk_f32_fp4 v[102:103], v15, 1.0 op_sel:[1,0,0]
	v_cvt_scalef32_pk_f32_fp4 v[104:105], v15, 1.0 op_sel:[0,1,0]
	v_cvt_scalef32_pk_f32_fp4 v[106:107], v15, 1.0 op_sel:[1,1,0]
	s_waitcnt vmcnt(8)
	v_cvt_scalef32_pk_f32_fp4 v[14:15], v16, 1.0
	v_pk_fma_f32 v[36:37], v[92:93], s[20:21], v[36:37] op_sel_hi:[1,0,1]
	v_cvt_scalef32_pk_f32_fp4 v[114:115], v17, 1.0
	v_pk_fma_f32 v[14:15], v[14:15], s[24:25], v[36:37] op_sel_hi:[1,0,1]
	v_pk_fma_f32 v[36:37], v[100:101], s[20:21], v[44:45] op_sel_hi:[1,0,1]
	v_cvt_scalef32_pk_f32_fp4 v[84:85], v12, 1.0 op_sel:[1,1,0]
	s_waitcnt vmcnt(7)
	v_cvt_scalef32_pk_f32_fp4 v[128:129], v19, 1.0
	v_pk_fma_f32 v[36:37], v[114:115], s[24:25], v[36:37] op_sel_hi:[1,0,1]
	v_cvt_scalef32_pk_f32_fp4 v[202:203], v29, 1.0
	v_pk_fma_f32 v[36:37], v[128:129], s[28:29], v[36:37] op_sel_hi:[1,0,1]
	v_pk_fma_f32 v[42:43], v[42:43], s[38:39], 0 op_sel_hi:[1,0,0]
	v_cvt_scalef32_pk_f32_fp4 v[80:81], v12, 1.0 op_sel:[1,0,0]
	v_cvt_scalef32_pk_f32_fp4 v[82:83], v12, 1.0 op_sel:[0,1,0]
	s_waitcnt vmcnt(6)
	v_cvt_scalef32_pk_f32_fp4 v[142:143], v21, 1.0
	v_pk_fma_f32 v[36:37], v[142:143], s[34:35], v[36:37] op_sel_hi:[1,0,1]
	v_cvt_scalef32_pk_f32_fp4 v[88:89], v13, 1.0 op_sel:[1,0,0]
	v_pk_fma_f32 v[36:37], v[156:157], s[36:37], v[36:37] op_sel_hi:[1,0,1]
	v_cvt_scalef32_pk_f32_fp4 v[90:91], v13, 1.0 op_sel:[0,1,0]
	v_pk_fma_f32 v[36:37], v[170:171], s[22:23], v[36:37] op_sel_hi:[1,0,1]
	v_cvt_scalef32_pk_f32_fp4 v[12:13], v13, 1.0 op_sel:[1,1,0]
	v_pk_fma_f32 v[36:37], v[184:185], s[26:27], v[36:37] op_sel_hi:[1,0,1]
	v_pk_fma_f32 v[38:39], v[38:39], s[38:39], 0 op_sel_hi:[1,0,0]
	v_pk_fma_f32 v[40:41], v[40:41], s[38:39], 0 op_sel_hi:[1,0,0]
	v_pk_fma_f32 v[52:53], v[52:53], s[38:39], 0 op_sel_hi:[1,0,0]
	v_pk_fma_f32 v[54:55], v[54:55], s[38:39], 0 op_sel_hi:[1,0,0]
	v_pk_fma_f32 v[8:9], v[8:9], s[38:39], 0 op_sel_hi:[1,0,0]
	v_pk_fma_f32 v[42:43], v[84:85], s[56:57], v[42:43] op_sel_hi:[1,0,1]
	v_readlane_b32 s38, v2, 10
	s_waitcnt vmcnt(5)
	v_cvt_scalef32_pk_f32_fp4 v[84:85], v31, 1.0
	v_pk_fma_f32 v[36:37], v[202:203], s[30:31], v[36:37] op_sel_hi:[1,0,1]
	v_cvt_scalef32_pk_f32_fp4 v[108:109], v16, 1.0 op_sel:[1,0,0]
	v_cvt_scalef32_pk_f32_fp4 v[110:111], v16, 1.0 op_sel:[0,1,0]
	v_cvt_scalef32_pk_f32_fp4 v[112:113], v16, 1.0 op_sel:[1,1,0]
	v_cvt_scalef32_pk_f32_fp4 v[116:117], v17, 1.0 op_sel:[1,0,0]
	v_cvt_scalef32_pk_f32_fp4 v[118:119], v17, 1.0 op_sel:[0,1,0]
	v_cvt_scalef32_pk_f32_fp4 v[120:121], v17, 1.0 op_sel:[1,1,0]
	v_cvt_scalef32_pk_f32_fp4 v[16:17], v18, 1.0
	v_pk_fma_f32 v[38:39], v[80:81], s[56:57], v[38:39] op_sel_hi:[1,0,1]
	v_pk_fma_f32 v[40:41], v[82:83], s[56:57], v[40:41] op_sel_hi:[1,0,1]
	v_pk_fma_f32 v[52:53], v[88:89], s[56:57], v[52:53] op_sel_hi:[1,0,1]
	v_pk_fma_f32 v[54:55], v[90:91], s[56:57], v[54:55] op_sel_hi:[1,0,1]
	v_pk_fma_f32 v[56:57], v[12:13], s[56:57], v[8:9] op_sel_hi:[1,0,1]
	v_readlane_b32 s56, v2, 11
	s_waitcnt vmcnt(4)
	v_cvt_scalef32_pk_f32_fp4 v[236:237], v33, 1.0
	v_pk_fma_f32 v[36:37], v[84:85], s[38:39], v[36:37] op_sel_hi:[1,0,1]
	v_pk_fma_f32 v[14:15], v[16:17], s[28:29], v[14:15] op_sel_hi:[1,0,1]
	s_waitcnt vmcnt(3)
	v_cvt_scalef32_pk_f32_fp4 v[16:17], v35, 1.0
	v_pk_fma_f32 v[36:37], v[236:237], s[56:57], v[36:37] op_sel_hi:[1,0,1]
	v_cvt_scalef32_pk_f32_fp4 v[130:131], v19, 1.0 op_sel:[1,0,0]
	v_pk_fma_f32 v[16:17], v[16:17], s[62:63], v[36:37] op_sel_hi:[1,0,1]
	v_pk_fma_f32 v[36:37], v[102:103], s[20:21], v[52:53] op_sel_hi:[1,0,1]
	v_cvt_scalef32_pk_f32_fp4 v[144:145], v21, 1.0 op_sel:[1,0,0]
	v_pk_fma_f32 v[36:37], v[116:117], s[24:25], v[36:37] op_sel_hi:[1,0,1]
	v_cvt_scalef32_pk_f32_fp4 v[158:159], v23, 1.0 op_sel:[1,0,0]
	v_pk_fma_f32 v[36:37], v[130:131], s[28:29], v[36:37] op_sel_hi:[1,0,1]
	v_cvt_scalef32_pk_f32_fp4 v[122:123], v18, 1.0 op_sel:[1,0,0]
	v_pk_fma_f32 v[36:37], v[144:145], s[34:35], v[36:37] op_sel_hi:[1,0,1]
	v_cvt_scalef32_pk_f32_fp4 v[124:125], v18, 1.0 op_sel:[0,1,0]
	v_cvt_scalef32_pk_f32_fp4 v[126:127], v18, 1.0 op_sel:[1,1,0]
	v_cvt_scalef32_pk_f32_fp4 v[132:133], v19, 1.0 op_sel:[0,1,0]
	v_cvt_scalef32_pk_f32_fp4 v[134:135], v19, 1.0 op_sel:[1,1,0]
	v_cvt_scalef32_pk_f32_fp4 v[18:19], v20, 1.0
	v_cvt_scalef32_pk_f32_fp4 v[172:173], v25, 1.0 op_sel:[1,0,0]
	v_pk_fma_f32 v[36:37], v[158:159], s[36:37], v[36:37] op_sel_hi:[1,0,1]
	v_cvt_scalef32_pk_f32_fp4 v[136:137], v20, 1.0 op_sel:[1,0,0]
	v_cvt_scalef32_pk_f32_fp4 v[138:139], v20, 1.0 op_sel:[0,1,0]
	v_cvt_scalef32_pk_f32_fp4 v[140:141], v20, 1.0 op_sel:[1,1,0]
	v_cvt_scalef32_pk_f32_fp4 v[146:147], v21, 1.0 op_sel:[0,1,0]
	v_cvt_scalef32_pk_f32_fp4 v[148:149], v21, 1.0 op_sel:[1,1,0]
	v_cvt_scalef32_pk_f32_fp4 v[20:21], v22, 1.0
	v_cvt_scalef32_pk_f32_fp4 v[186:187], v27, 1.0 op_sel:[1,0,0]
	v_pk_fma_f32 v[14:15], v[18:19], s[34:35], v[14:15] op_sel_hi:[1,0,1]
	v_pk_fma_f32 v[36:37], v[172:173], s[22:23], v[36:37] op_sel_hi:[1,0,1]
	v_cvt_scalef32_pk_f32_fp4 v[150:151], v22, 1.0 op_sel:[1,0,0]
	v_cvt_scalef32_pk_f32_fp4 v[152:153], v22, 1.0 op_sel:[0,1,0]
	v_cvt_scalef32_pk_f32_fp4 v[154:155], v22, 1.0 op_sel:[1,1,0]
	v_cvt_scalef32_pk_f32_fp4 v[160:161], v23, 1.0 op_sel:[0,1,0]
	v_cvt_scalef32_pk_f32_fp4 v[162:163], v23, 1.0 op_sel:[1,1,0]
	v_cvt_scalef32_pk_f32_fp4 v[22:23], v24, 1.0
	v_cvt_scalef32_pk_f32_fp4 v[204:205], v29, 1.0 op_sel:[1,0,0]
	v_pk_fma_f32 v[14:15], v[20:21], s[36:37], v[14:15] op_sel_hi:[1,0,1]
	v_pk_fma_f32 v[36:37], v[186:187], s[26:27], v[36:37] op_sel_hi:[1,0,1]
	v_cvt_scalef32_pk_f32_fp4 v[176:177], v26, 1.0
	v_cvt_scalef32_pk_f32_fp4 v[86:87], v31, 1.0 op_sel:[1,0,0]
	v_pk_fma_f32 v[14:15], v[22:23], s[22:23], v[14:15] op_sel_hi:[1,0,1]
	v_pk_fma_f32 v[36:37], v[204:205], s[30:31], v[36:37] op_sel_hi:[1,0,1]
	v_cvt_scalef32_pk_f32_fp4 v[190:191], v28, 1.0
	v_cvt_scalef32_pk_f32_fp4 v[238:239], v33, 1.0 op_sel:[1,0,0]
	v_pk_fma_f32 v[14:15], v[176:177], s[26:27], v[14:15] op_sel_hi:[1,0,1]
	v_pk_fma_f32 v[36:37], v[86:87], s[38:39], v[36:37] op_sel_hi:[1,0,1]
	v_cvt_scalef32_pk_f32_fp4 v[8:9], v30, 1.0
	v_pk_fma_f32 v[14:15], v[190:191], s[30:31], v[14:15] op_sel_hi:[1,0,1]
	v_cvt_scalef32_pk_f32_fp4 v[18:19], v35, 1.0 op_sel:[1,0,0]
	v_pk_fma_f32 v[36:37], v[238:239], s[56:57], v[36:37] op_sel_hi:[1,0,1]
	v_cvt_scalef32_pk_f32_fp4 v[90:91], v32, 1.0
	v_pk_fma_f32 v[8:9], v[8:9], s[38:39], v[14:15] op_sel_hi:[1,0,1]
	v_pk_fma_f32 v[18:19], v[18:19], s[62:63], v[36:37] op_sel_hi:[1,0,1]
	v_pk_fma_f32 v[36:37], v[104:105], s[20:21], v[54:55] op_sel_hi:[1,0,1]
	v_cvt_scalef32_pk_f32_fp4 v[242:243], v34, 1.0
	v_pk_fma_f32 v[8:9], v[90:91], s[56:57], v[8:9] op_sel_hi:[1,0,1]
	v_pk_fma_f32 v[36:37], v[118:119], s[24:25], v[36:37] op_sel_hi:[1,0,1]
	v_pk_fma_f32 v[22:23], v[242:243], s[62:63], v[8:9] op_sel_hi:[1,0,1]
	v_pk_fma_f32 v[8:9], v[94:95], s[20:21], v[38:39] op_sel_hi:[1,0,1]
	v_pk_fma_f32 v[36:37], v[132:133], s[28:29], v[36:37] op_sel_hi:[1,0,1]
	v_pk_fma_f32 v[8:9], v[108:109], s[24:25], v[8:9] op_sel_hi:[1,0,1]
	v_pk_fma_f32 v[36:37], v[146:147], s[34:35], v[36:37] op_sel_hi:[1,0,1]
	v_cvt_scalef32_pk_f32_fp4 v[174:175], v25, 1.0 op_sel:[0,1,0]
	v_pk_fma_f32 v[8:9], v[122:123], s[28:29], v[8:9] op_sel_hi:[1,0,1]
	v_pk_fma_f32 v[36:37], v[160:161], s[36:37], v[36:37] op_sel_hi:[1,0,1]
	v_cvt_scalef32_pk_f32_fp4 v[188:189], v27, 1.0 op_sel:[0,1,0]
	v_pk_fma_f32 v[8:9], v[136:137], s[34:35], v[8:9] op_sel_hi:[1,0,1]
	v_pk_fma_f32 v[36:37], v[174:175], s[22:23], v[36:37] op_sel_hi:[1,0,1]
	v_cvt_scalef32_pk_f32_fp4 v[164:165], v24, 1.0 op_sel:[1,0,0]
	v_cvt_scalef32_pk_f32_fp4 v[206:207], v29, 1.0 op_sel:[0,1,0]
	v_pk_fma_f32 v[8:9], v[150:151], s[36:37], v[8:9] op_sel_hi:[1,0,1]
	v_pk_fma_f32 v[36:37], v[188:189], s[26:27], v[36:37] op_sel_hi:[1,0,1]
	v_cvt_scalef32_pk_f32_fp4 v[178:179], v26, 1.0 op_sel:[1,0,0]
	v_cvt_scalef32_pk_f32_fp4 v[88:89], v31, 1.0 op_sel:[0,1,0]
	v_pk_fma_f32 v[8:9], v[164:165], s[22:23], v[8:9] op_sel_hi:[1,0,1]
	v_pk_fma_f32 v[36:37], v[206:207], s[30:31], v[36:37] op_sel_hi:[1,0,1]
	v_cvt_scalef32_pk_f32_fp4 v[196:197], v28, 1.0 op_sel:[1,0,0]
	v_cvt_scalef32_pk_f32_fp4 v[240:241], v33, 1.0 op_sel:[0,1,0]
	v_pk_fma_f32 v[8:9], v[178:179], s[26:27], v[8:9] op_sel_hi:[1,0,1]
	v_pk_fma_f32 v[36:37], v[88:89], s[38:39], v[36:37] op_sel_hi:[1,0,1]
	v_cvt_scalef32_pk_f32_fp4 v[12:13], v30, 1.0 op_sel:[1,0,0]
	v_pk_fma_f32 v[8:9], v[196:197], s[30:31], v[8:9] op_sel_hi:[1,0,1]
	v_cvt_scalef32_pk_f32_fp4 v[20:21], v35, 1.0 op_sel:[0,1,0]
	v_pk_fma_f32 v[36:37], v[240:241], s[56:57], v[36:37] op_sel_hi:[1,0,1]
	v_pk_fma_f32 v[8:9], v[12:13], s[38:39], v[8:9] op_sel_hi:[1,0,1]
	v_pk_fma_f32 v[12:13], v[96:97], s[20:21], v[40:41] op_sel_hi:[1,0,1]
	v_pk_fma_f32 v[14:15], v[98:99], s[20:21], v[42:43] op_sel_hi:[1,0,1]
	v_pk_fma_f32 v[20:21], v[20:21], s[62:63], v[36:37] op_sel_hi:[1,0,1]
	v_pk_fma_f32 v[36:37], v[106:107], s[20:21], v[56:57] op_sel_hi:[1,0,1]
	v_pk_fma_f32 v[12:13], v[110:111], s[24:25], v[12:13] op_sel_hi:[1,0,1]
	v_pk_fma_f32 v[14:15], v[112:113], s[24:25], v[14:15] op_sel_hi:[1,0,1]
	v_pk_fma_f32 v[36:37], v[120:121], s[24:25], v[36:37] op_sel_hi:[1,0,1]
	v_pk_fma_f32 v[12:13], v[124:125], s[28:29], v[12:13] op_sel_hi:[1,0,1]
	v_pk_fma_f32 v[14:15], v[126:127], s[28:29], v[14:15] op_sel_hi:[1,0,1]
	v_pk_fma_f32 v[36:37], v[134:135], s[28:29], v[36:37] op_sel_hi:[1,0,1]
	v_pk_fma_f32 v[12:13], v[138:139], s[34:35], v[12:13] op_sel_hi:[1,0,1]
	v_pk_fma_f32 v[14:15], v[140:141], s[34:35], v[14:15] op_sel_hi:[1,0,1]
	v_pk_fma_f32 v[36:37], v[148:149], s[34:35], v[36:37] op_sel_hi:[1,0,1]
	v_cvt_scalef32_pk_f32_fp4 v[166:167], v24, 1.0 op_sel:[0,1,0]
	v_cvt_scalef32_pk_f32_fp4 v[168:169], v24, 1.0 op_sel:[1,1,0]
	v_cvt_scalef32_pk_f32_fp4 v[24:25], v25, 1.0 op_sel:[1,1,0]
	v_pk_fma_f32 v[12:13], v[152:153], s[36:37], v[12:13] op_sel_hi:[1,0,1]
	v_pk_fma_f32 v[14:15], v[154:155], s[36:37], v[14:15] op_sel_hi:[1,0,1]
	v_pk_fma_f32 v[36:37], v[162:163], s[36:37], v[36:37] op_sel_hi:[1,0,1]
	v_pk_fma_f32 v[12:13], v[166:167], s[22:23], v[12:13] op_sel_hi:[1,0,1]
	v_pk_fma_f32 v[14:15], v[168:169], s[22:23], v[14:15] op_sel_hi:[1,0,1]
	v_readlane_b32 s20, v73, 0
	v_pk_fma_f32 v[24:25], v[24:25], s[22:23], v[36:37] op_sel_hi:[1,0,1]
	v_readlane_b32 s22, v73, 2
	v_cvt_scalef32_pk_f32_fp4 v[182:183], v26, 1.0 op_sel:[1,1,0]
	v_cvt_scalef32_pk_f32_fp4 v[200:201], v28, 1.0 op_sel:[1,1,0]
	v_pk_fma_f32 v[14:15], v[182:183], s[26:27], v[14:15] op_sel_hi:[1,0,1]
	buffer_load_dwordx2 v[38:39], v192, s[4:7], s20 offen
	s_nop 0
	buffer_load_dwordx2 v[44:45], v192, s[4:7], s22 offen
	v_readlane_b32 s20, v73, 1
	v_readlane_b32 s23, v73, 3
	v_cvt_scalef32_pk_f32_fp4 v[180:181], v26, 1.0 op_sel:[0,1,0]
	v_cvt_scalef32_pk_f32_fp4 v[26:27], v27, 1.0 op_sel:[1,1,0]
	v_cvt_scalef32_pk_f32_fp4 v[82:83], v30, 1.0 op_sel:[1,1,0]
	v_pk_fma_f32 v[14:15], v[200:201], s[30:31], v[14:15] op_sel_hi:[1,0,1]
	v_pk_fma_f32 v[14:15], v[82:83], s[38:39], v[14:15] op_sel_hi:[1,0,1]
	v_pk_fma_f32 v[24:25], v[26:27], s[26:27], v[24:25] op_sel_hi:[1,0,1]
	buffer_load_dwordx2 v[26:27], v192, s[4:7], s20 offen
	buffer_load_dwordx2 v[82:83], v192, s[4:7], s23 offen
	v_readlane_b32 s23, v73, 4
	v_readlane_b32 s25, v73, 7
	v_cvt_scalef32_pk_f32_fp4 v[198:199], v28, 1.0 op_sel:[0,1,0]
	v_cvt_scalef32_pk_f32_fp4 v[28:29], v29, 1.0 op_sel:[1,1,0]
	s_nop 1
	buffer_load_dwordx2 v[96:97], v192, s[4:7], s23 offen
	v_readlane_b32 s23, v73, 5
	v_cvt_scalef32_pk_f32_fp4 v[80:81], v30, 1.0 op_sel:[0,1,0]
	v_cvt_scalef32_pk_f32_fp4 v[30:31], v31, 1.0 op_sel:[1,1,0]
	v_pk_fma_f32 v[12:13], v[180:181], s[26:27], v[12:13] op_sel_hi:[1,0,1]
	v_pk_fma_f32 v[24:25], v[28:29], s[30:31], v[24:25] op_sel_hi:[1,0,1]
	s_nop 0
	buffer_load_dwordx2 v[108:109], v192, s[4:7], s23 offen
	v_readlane_b32 s23, v73, 6
	s_nop 3
	s_nop 0
	buffer_load_dwordx2 v[116:117], v192, s[4:7], s23 offen
	buffer_load_dwordx2 v[118:119], v192, s[4:7], s25 offen
	v_readlane_b32 s23, v73, 8
	v_readlane_b32 s25, v73, 9
	v_readlane_b32 s26, v73, 10
	v_readlane_b32 s27, v73, 11
	v_cvt_scalef32_pk_f32_fp4 v[208:209], v32, 1.0 op_sel:[1,0,0]
	v_cvt_scalef32_pk_f32_fp4 v[232:233], v32, 1.0 op_sel:[0,1,0]
	v_cvt_scalef32_pk_f32_fp4 v[234:235], v32, 1.0 op_sel:[1,1,0]
	v_cvt_scalef32_pk_f32_fp4 v[32:33], v33, 1.0 op_sel:[1,1,0]
	v_pk_fma_f32 v[24:25], v[30:31], s[38:39], v[24:25] op_sel_hi:[1,0,1]
	buffer_load_dwordx2 v[120:121], v192, s[4:7], s23 offen
	buffer_load_dwordx2 v[122:123], v192, s[4:7], s25 offen
	buffer_load_dwordx2 v[124:125], v192, s[4:7], s26 offen
	buffer_load_dwordx2 v[126:127], v192, s[4:7], s27 offen
	v_readlane_b32 s23, v73, 12
	v_cvt_scalef32_pk_f32_fp4 v[244:245], v34, 1.0 op_sel:[1,0,0]
	v_cvt_scalef32_pk_f32_fp4 v[246:247], v34, 1.0 op_sel:[0,1,0]
	v_cvt_scalef32_pk_f32_fp4 v[248:249], v34, 1.0 op_sel:[1,1,0]
	v_pk_fma_f32 v[12:13], v[198:199], s[30:31], v[12:13] op_sel_hi:[1,0,1]
	v_cvt_scalef32_pk_f32_fp4 v[34:35], v35, 1.0 op_sel:[1,1,0]
	v_pk_fma_f32 v[24:25], v[32:33], s[56:57], v[24:25] op_sel_hi:[1,0,1]
	v_readlane_b32 s25, v73, 13
	v_readlane_b32 s26, v73, 14
	v_readlane_b32 s27, v73, 15
	v_pk_fma_f32 v[12:13], v[80:81], s[38:39], v[12:13] op_sel_hi:[1,0,1]
	v_pk_fma_f32 v[24:25], v[34:35], s[62:63], v[24:25] op_sel_hi:[1,0,1]
	s_waitcnt vmcnt(14)
	v_cvt_scalef32_pk_f32_fp4 v[28:29], v10, 1.0
	v_cvt_scalef32_pk_f32_fp4 v[32:33], v10, 1.0 op_sel:[1,0,0]
	v_cvt_scalef32_pk_f32_fp4 v[34:35], v10, 1.0 op_sel:[0,1,0]
	v_cvt_scalef32_pk_f32_fp4 v[36:37], v10, 1.0 op_sel:[1,1,0]
	v_cvt_scalef32_pk_f32_fp4 v[42:43], v11, 1.0
	v_cvt_scalef32_pk_f32_fp4 v[52:53], v11, 1.0 op_sel:[1,0,0]
	v_cvt_scalef32_pk_f32_fp4 v[54:55], v11, 1.0 op_sel:[0,1,0]
	v_cvt_scalef32_pk_f32_fp4 v[56:57], v11, 1.0 op_sel:[1,1,0]
	s_waitcnt vmcnt(13)
	v_cvt_scalef32_pk_f32_fp4 v[10:11], v6, 1.0
	v_cvt_scalef32_pk_f32_fp4 v[80:81], v6, 1.0 op_sel:[1,0,0]
	v_cvt_scalef32_pk_f32_fp4 v[84:85], v6, 1.0 op_sel:[0,1,0]
	v_cvt_scalef32_pk_f32_fp4 v[86:87], v6, 1.0 op_sel:[1,1,0]
	v_cvt_scalef32_pk_f32_fp4 v[88:89], v7, 1.0
	v_cvt_scalef32_pk_f32_fp4 v[90:91], v7, 1.0 op_sel:[1,0,0]
	v_cvt_scalef32_pk_f32_fp4 v[92:93], v7, 1.0 op_sel:[0,1,0]
	v_cvt_scalef32_pk_f32_fp4 v[94:95], v7, 1.0 op_sel:[1,1,0]
	s_waitcnt vmcnt(12)
	v_cvt_scalef32_pk_f32_fp4 v[98:99], v4, 1.0
	v_cvt_scalef32_pk_f32_fp4 v[100:101], v4, 1.0 op_sel:[1,0,0]
	v_cvt_scalef32_pk_f32_fp4 v[102:103], v4, 1.0 op_sel:[0,1,0]
	v_cvt_scalef32_pk_f32_fp4 v[104:105], v4, 1.0 op_sel:[1,1,0]
	v_cvt_scalef32_pk_f32_fp4 v[106:107], v5, 1.0
	v_cvt_scalef32_pk_f32_fp4 v[110:111], v5, 1.0 op_sel:[1,0,0]
	v_cvt_scalef32_pk_f32_fp4 v[112:113], v5, 1.0 op_sel:[0,1,0]
	v_cvt_scalef32_pk_f32_fp4 v[114:115], v5, 1.0 op_sel:[1,1,0]
	buffer_load_dwordx2 v[40:41], v192, s[4:7], s23 offen
	buffer_load_dwordx2 v[30:31], v192, s[4:7], s25 offen
	buffer_load_dwordx2 v[6:7], v192, s[4:7], s26 offen
	buffer_load_dwordx2 v[4:5], v192, s[4:7], s27 offen
	v_pk_fma_f32 v[8:9], v[208:209], s[56:57], v[8:9] op_sel_hi:[1,0,1]
	v_readlane_b32 s20, v2, 13
	v_pk_fma_f32 v[8:9], v[244:245], s[62:63], v[8:9] op_sel_hi:[1,0,1]
	v_readlane_b32 s22, v2, 14
	v_pk_fma_f32 v[22:23], v[28:29], s[20:21], v[22:23] op_sel_hi:[1,0,1]
	v_pk_fma_f32 v[8:9], v[32:33], s[20:21], v[8:9] op_sel_hi:[1,0,1]
	v_readlane_b32 s24, v2, 15
	v_pk_fma_f32 v[10:11], v[10:11], s[22:23], v[22:23] op_sel_hi:[1,0,1]
	v_pk_fma_f32 v[8:9], v[80:81], s[22:23], v[8:9] op_sel_hi:[1,0,1]
	v_readlane_b32 s26, v3, 0
	s_waitcnt vmcnt(15)
	v_cvt_scalef32_pk_f32_fp4 v[128:129], v38, 1.0
	v_cvt_scalef32_pk_f32_fp4 v[130:131], v38, 1.0 op_sel:[1,0,0]
	v_pk_fma_f32 v[10:11], v[98:99], s[24:25], v[10:11] op_sel_hi:[1,0,1]
	v_pk_fma_f32 v[8:9], v[100:101], s[24:25], v[8:9] op_sel_hi:[1,0,1]
	v_readlane_b32 s28, v3, 1
	s_waitcnt vmcnt(13)
	v_cvt_scalef32_pk_f32_fp4 v[142:143], v26, 1.0
	v_cvt_scalef32_pk_f32_fp4 v[144:145], v26, 1.0 op_sel:[1,0,0]
	v_pk_fma_f32 v[10:11], v[128:129], s[26:27], v[10:11] op_sel_hi:[1,0,1]
	v_pk_fma_f32 v[8:9], v[130:131], s[26:27], v[8:9] op_sel_hi:[1,0,1]
	v_cvt_scalef32_pk_f32_fp4 v[146:147], v26, 1.0 op_sel:[0,1,0]
	v_cvt_scalef32_pk_f32_fp4 v[148:149], v26, 1.0 op_sel:[1,1,0]
	v_cvt_scalef32_pk_f32_fp4 v[150:151], v27, 1.0
	v_cvt_scalef32_pk_f32_fp4 v[152:153], v27, 1.0 op_sel:[1,0,0]
	v_cvt_scalef32_pk_f32_fp4 v[154:155], v27, 1.0 op_sel:[0,1,0]
	v_cvt_scalef32_pk_f32_fp4 v[156:157], v27, 1.0 op_sel:[1,1,0]
	v_readlane_b32 s30, v3, 2
	v_cvt_scalef32_pk_f32_fp4 v[26:27], v44, 1.0
	v_cvt_scalef32_pk_f32_fp4 v[158:159], v44, 1.0 op_sel:[1,0,0]
	v_pk_fma_f32 v[10:11], v[142:143], s[28:29], v[10:11] op_sel_hi:[1,0,1]
	v_pk_fma_f32 v[8:9], v[144:145], s[28:29], v[8:9] op_sel_hi:[1,0,1]
	v_readlane_b32 s34, v3, 3
	s_waitcnt vmcnt(12)
	v_cvt_scalef32_pk_f32_fp4 v[170:171], v82, 1.0
	v_cvt_scalef32_pk_f32_fp4 v[172:173], v82, 1.0 op_sel:[1,0,0]
	v_pk_fma_f32 v[10:11], v[26:27], s[30:31], v[10:11] op_sel_hi:[1,0,1]
	v_pk_fma_f32 v[8:9], v[158:159], s[30:31], v[8:9] op_sel_hi:[1,0,1]
	v_readlane_b32 s36, v3, 4
	s_waitcnt vmcnt(11)
	v_cvt_scalef32_pk_f32_fp4 v[184:185], v96, 1.0
	v_cvt_scalef32_pk_f32_fp4 v[186:187], v96, 1.0 op_sel:[1,0,0]
	v_pk_fma_f32 v[10:11], v[170:171], s[34:35], v[10:11] op_sel_hi:[1,0,1]
	v_pk_fma_f32 v[8:9], v[172:173], s[34:35], v[8:9] op_sel_hi:[1,0,1]
	v_readlane_b32 s38, v3, 5
	s_waitcnt vmcnt(10)
	v_cvt_scalef32_pk_f32_fp4 v[202:203], v108, 1.0
	v_cvt_scalef32_pk_f32_fp4 v[204:205], v108, 1.0 op_sel:[1,0,0]
	v_pk_fma_f32 v[10:11], v[184:185], s[36:37], v[10:11] op_sel_hi:[1,0,1]
	v_pk_fma_f32 v[8:9], v[186:187], s[36:37], v[8:9] op_sel_hi:[1,0,1]
	v_pk_fma_f32 v[12:13], v[232:233], s[56:57], v[12:13] op_sel_hi:[1,0,1]
	v_pk_fma_f32 v[14:15], v[234:235], s[56:57], v[14:15] op_sel_hi:[1,0,1]
	v_readlane_b32 s56, v3, 6
	s_waitcnt vmcnt(9)
	v_cvt_scalef32_pk_f32_fp4 v[238:239], v116, 1.0
	v_cvt_scalef32_pk_f32_fp4 v[240:241], v116, 1.0 op_sel:[1,0,0]
	v_pk_fma_f32 v[10:11], v[202:203], s[38:39], v[10:11] op_sel_hi:[1,0,1]
	v_pk_fma_f32 v[8:9], v[204:205], s[38:39], v[8:9] op_sel_hi:[1,0,1]
	v_pk_fma_f32 v[12:13], v[246:247], s[62:63], v[12:13] op_sel_hi:[1,0,1]
	v_pk_fma_f32 v[14:15], v[248:249], s[62:63], v[14:15] op_sel_hi:[1,0,1]
	v_readlane_b32 s62, v3, 7
	s_waitcnt vmcnt(8)
	v_cvt_scalef32_pk_f32_fp4 v[230:231], v118, 1.0
	v_cvt_scalef32_pk_f32_fp4 v[216:217], v118, 1.0 op_sel:[1,0,0]
	v_pk_fma_f32 v[10:11], v[238:239], s[56:57], v[10:11] op_sel_hi:[1,0,1]
	v_pk_fma_f32 v[8:9], v[240:241], s[56:57], v[8:9] op_sel_hi:[1,0,1]
	v_pk_fma_f32 v[26:27], v[230:231], s[62:63], v[10:11] op_sel_hi:[1,0,1]
	v_pk_fma_f32 v[10:11], v[216:217], s[62:63], v[8:9] op_sel_hi:[1,0,1]
	v_pk_fma_f32 v[8:9], v[34:35], s[20:21], v[12:13] op_sel_hi:[1,0,1]
	v_cvt_scalef32_pk_f32_fp4 v[132:133], v38, 1.0 op_sel:[0,1,0]
	v_pk_fma_f32 v[8:9], v[84:85], s[22:23], v[8:9] op_sel_hi:[1,0,1]
	v_cvt_scalef32_pk_f32_fp4 v[160:161], v44, 1.0 op_sel:[0,1,0]
	v_pk_fma_f32 v[8:9], v[102:103], s[24:25], v[8:9] op_sel_hi:[1,0,1]
	v_cvt_scalef32_pk_f32_fp4 v[174:175], v82, 1.0 op_sel:[0,1,0]
	v_pk_fma_f32 v[8:9], v[132:133], s[26:27], v[8:9] op_sel_hi:[1,0,1]
	v_cvt_scalef32_pk_f32_fp4 v[188:189], v96, 1.0 op_sel:[0,1,0]
	v_pk_fma_f32 v[8:9], v[146:147], s[28:29], v[8:9] op_sel_hi:[1,0,1]
	v_cvt_scalef32_pk_f32_fp4 v[206:207], v108, 1.0 op_sel:[0,1,0]
	v_pk_fma_f32 v[8:9], v[160:161], s[30:31], v[8:9] op_sel_hi:[1,0,1]
	v_cvt_scalef32_pk_f32_fp4 v[242:243], v116, 1.0 op_sel:[0,1,0]
	v_pk_fma_f32 v[8:9], v[174:175], s[34:35], v[8:9] op_sel_hi:[1,0,1]
	v_cvt_scalef32_pk_f32_fp4 v[214:215], v118, 1.0 op_sel:[0,1,0]
	v_pk_fma_f32 v[8:9], v[188:189], s[36:37], v[8:9] op_sel_hi:[1,0,1]
	v_pk_fma_f32 v[16:17], v[42:43], s[20:21], v[16:17] op_sel_hi:[1,0,1]
	v_pk_fma_f32 v[8:9], v[206:207], s[38:39], v[8:9] op_sel_hi:[1,0,1]
	v_cvt_scalef32_pk_f32_fp4 v[134:135], v38, 1.0 op_sel:[1,1,0]
	v_pk_fma_f32 v[8:9], v[242:243], s[56:57], v[8:9] op_sel_hi:[1,0,1]
	v_pk_fma_f32 v[16:17], v[88:89], s[22:23], v[16:17] op_sel_hi:[1,0,1]
	v_pk_fma_f32 v[12:13], v[214:215], s[62:63], v[8:9] op_sel_hi:[1,0,1]
	v_pk_fma_f32 v[8:9], v[36:37], s[20:21], v[14:15] op_sel_hi:[1,0,1]
	v_cvt_scalef32_pk_f32_fp4 v[136:137], v39, 1.0
	v_pk_fma_f32 v[8:9], v[86:87], s[22:23], v[8:9] op_sel_hi:[1,0,1]
	v_pk_fma_f32 v[16:17], v[106:107], s[24:25], v[16:17] op_sel_hi:[1,0,1]
	v_pk_fma_f32 v[8:9], v[104:105], s[24:25], v[8:9] op_sel_hi:[1,0,1]
	v_cvt_scalef32_pk_f32_fp4 v[162:163], v44, 1.0 op_sel:[1,1,0]
	v_pk_fma_f32 v[8:9], v[134:135], s[26:27], v[8:9] op_sel_hi:[1,0,1]
	v_pk_fma_f32 v[16:17], v[136:137], s[26:27], v[16:17] op_sel_hi:[1,0,1]
	v_pk_fma_f32 v[8:9], v[148:149], s[28:29], v[8:9] op_sel_hi:[1,0,1]
	v_cvt_scalef32_pk_f32_fp4 v[164:165], v45, 1.0
	v_cvt_scalef32_pk_f32_fp4 v[176:177], v82, 1.0 op_sel:[1,1,0]
	v_pk_fma_f32 v[8:9], v[162:163], s[30:31], v[8:9] op_sel_hi:[1,0,1]
	v_pk_fma_f32 v[16:17], v[150:151], s[28:29], v[16:17] op_sel_hi:[1,0,1]
	v_cvt_scalef32_pk_f32_fp4 v[178:179], v83, 1.0
	v_cvt_scalef32_pk_f32_fp4 v[190:191], v96, 1.0 op_sel:[1,1,0]
	v_pk_fma_f32 v[8:9], v[176:177], s[34:35], v[8:9] op_sel_hi:[1,0,1]
	v_pk_fma_f32 v[16:17], v[164:165], s[30:31], v[16:17] op_sel_hi:[1,0,1]
	v_cvt_scalef32_pk_f32_fp4 v[196:197], v97, 1.0
	v_cvt_scalef32_pk_f32_fp4 v[208:209], v108, 1.0 op_sel:[1,1,0]
	v_pk_fma_f32 v[8:9], v[190:191], s[36:37], v[8:9] op_sel_hi:[1,0,1]
	v_pk_fma_f32 v[16:17], v[178:179], s[34:35], v[16:17] op_sel_hi:[1,0,1]
	v_cvt_scalef32_pk_f32_fp4 v[232:233], v109, 1.0
	v_cvt_scalef32_pk_f32_fp4 v[244:245], v116, 1.0 op_sel:[1,1,0]
	v_pk_fma_f32 v[8:9], v[208:209], s[38:39], v[8:9] op_sel_hi:[1,0,1]
	v_pk_fma_f32 v[16:17], v[196:197], s[36:37], v[16:17] op_sel_hi:[1,0,1]
	v_cvt_scalef32_pk_f32_fp4 v[246:247], v117, 1.0
	v_cvt_scalef32_pk_f32_fp4 v[210:211], v118, 1.0 op_sel:[1,1,0]
	v_pk_fma_f32 v[8:9], v[244:245], s[56:57], v[8:9] op_sel_hi:[1,0,1]
	v_pk_fma_f32 v[16:17], v[232:233], s[38:39], v[16:17] op_sel_hi:[1,0,1]
	v_pk_fma_f32 v[14:15], v[210:211], s[62:63], v[8:9] op_sel_hi:[1,0,1]
	v_cvt_scalef32_pk_f32_fp4 v[8:9], v119, 1.0
	v_pk_fma_f32 v[16:17], v[246:247], s[56:57], v[16:17] op_sel_hi:[1,0,1]
	v_cvt_scalef32_pk_f32_fp4 v[138:139], v39, 1.0 op_sel:[1,0,0]
	v_pk_fma_f32 v[16:17], v[8:9], s[62:63], v[16:17] op_sel_hi:[1,0,1]
	v_pk_fma_f32 v[8:9], v[52:53], s[20:21], v[18:19] op_sel_hi:[1,0,1]
	v_cvt_scalef32_pk_f32_fp4 v[166:167], v45, 1.0 op_sel:[1,0,0]
	v_pk_fma_f32 v[8:9], v[90:91], s[22:23], v[8:9] op_sel_hi:[1,0,1]
	v_cvt_scalef32_pk_f32_fp4 v[180:181], v83, 1.0 op_sel:[1,0,0]
	v_pk_fma_f32 v[8:9], v[110:111], s[24:25], v[8:9] op_sel_hi:[1,0,1]
	v_cvt_scalef32_pk_f32_fp4 v[198:199], v97, 1.0 op_sel:[1,0,0]
	v_pk_fma_f32 v[8:9], v[138:139], s[26:27], v[8:9] op_sel_hi:[1,0,1]
	v_cvt_scalef32_pk_f32_fp4 v[234:235], v109, 1.0 op_sel:[1,0,0]
	v_pk_fma_f32 v[8:9], v[152:153], s[28:29], v[8:9] op_sel_hi:[1,0,1]
	v_cvt_scalef32_pk_f32_fp4 v[248:249], v117, 1.0 op_sel:[1,0,0]
	v_pk_fma_f32 v[8:9], v[166:167], s[30:31], v[8:9] op_sel_hi:[1,0,1]
	v_cvt_scalef32_pk_f32_fp4 v[22:23], v119, 1.0 op_sel:[1,0,0]
	v_pk_fma_f32 v[8:9], v[180:181], s[34:35], v[8:9] op_sel_hi:[1,0,1]
	v_cvt_scalef32_pk_f32_fp4 v[140:141], v39, 1.0 op_sel:[0,1,0]
	v_pk_fma_f32 v[8:9], v[198:199], s[36:37], v[8:9] op_sel_hi:[1,0,1]
	v_cvt_scalef32_pk_f32_fp4 v[168:169], v45, 1.0 op_sel:[0,1,0]
	v_pk_fma_f32 v[8:9], v[234:235], s[38:39], v[8:9] op_sel_hi:[1,0,1]
	v_cvt_scalef32_pk_f32_fp4 v[182:183], v83, 1.0 op_sel:[0,1,0]
	v_pk_fma_f32 v[8:9], v[248:249], s[56:57], v[8:9] op_sel_hi:[1,0,1]
	v_cvt_scalef32_pk_f32_fp4 v[200:201], v97, 1.0 op_sel:[0,1,0]
	v_pk_fma_f32 v[18:19], v[22:23], s[62:63], v[8:9] op_sel_hi:[1,0,1]
	v_pk_fma_f32 v[8:9], v[54:55], s[20:21], v[20:21] op_sel_hi:[1,0,1]
	v_cvt_scalef32_pk_f32_fp4 v[236:237], v109, 1.0 op_sel:[0,1,0]
	v_pk_fma_f32 v[8:9], v[92:93], s[22:23], v[8:9] op_sel_hi:[1,0,1]
	v_cvt_scalef32_pk_f32_fp4 v[228:229], v117, 1.0 op_sel:[0,1,0]
	v_pk_fma_f32 v[8:9], v[112:113], s[24:25], v[8:9] op_sel_hi:[1,0,1]
	v_cvt_scalef32_pk_f32_fp4 v[28:29], v119, 1.0 op_sel:[0,1,0]
	v_pk_fma_f32 v[8:9], v[140:141], s[26:27], v[8:9] op_sel_hi:[1,0,1]
	v_cvt_scalef32_pk_f32_fp4 v[38:39], v39, 1.0 op_sel:[1,1,0]
	v_pk_fma_f32 v[8:9], v[154:155], s[28:29], v[8:9] op_sel_hi:[1,0,1]
	v_cvt_scalef32_pk_f32_fp4 v[44:45], v45, 1.0 op_sel:[1,1,0]
	v_pk_fma_f32 v[8:9], v[168:169], s[30:31], v[8:9] op_sel_hi:[1,0,1]
	v_cvt_scalef32_pk_f32_fp4 v[82:83], v83, 1.0 op_sel:[1,1,0]
	v_pk_fma_f32 v[8:9], v[182:183], s[34:35], v[8:9] op_sel_hi:[1,0,1]
	v_cvt_scalef32_pk_f32_fp4 v[96:97], v97, 1.0 op_sel:[1,1,0]
	v_pk_fma_f32 v[8:9], v[200:201], s[36:37], v[8:9] op_sel_hi:[1,0,1]
	v_cvt_scalef32_pk_f32_fp4 v[108:109], v109, 1.0 op_sel:[1,1,0]
	v_pk_fma_f32 v[8:9], v[236:237], s[38:39], v[8:9] op_sel_hi:[1,0,1]
	v_cvt_scalef32_pk_f32_fp4 v[116:117], v117, 1.0 op_sel:[1,1,0]
	v_pk_fma_f32 v[8:9], v[228:229], s[56:57], v[8:9] op_sel_hi:[1,0,1]
	v_cvt_scalef32_pk_f32_fp4 v[32:33], v119, 1.0 op_sel:[1,1,0]
	v_pk_fma_f32 v[20:21], v[28:29], s[62:63], v[8:9] op_sel_hi:[1,0,1]
	v_pk_fma_f32 v[8:9], v[56:57], s[20:21], v[24:25] op_sel_hi:[1,0,1]
	v_readlane_b32 s20, v3, 8
	v_pk_fma_f32 v[8:9], v[94:95], s[22:23], v[8:9] op_sel_hi:[1,0,1]
	v_readlane_b32 s23, v51, 0
	v_pk_fma_f32 v[8:9], v[114:115], s[24:25], v[8:9] op_sel_hi:[1,0,1]
	v_readlane_b32 s25, v51, 5
	v_pk_fma_f32 v[8:9], v[38:39], s[26:27], v[8:9] op_sel_hi:[1,0,1]
	v_readlane_b32 s27, v51, 6
	s_nop 0
	buffer_load_dwordx2 v[128:129], v192, s[4:7], s23 offen
	v_readlane_b32 s23, v51, 1
	v_pk_fma_f32 v[8:9], v[156:157], s[28:29], v[8:9] op_sel_hi:[1,0,1]
	v_readlane_b32 s29, v51, 7
	s_nop 2
	buffer_load_dwordx2 v[138:139], v192, s[4:7], s23 offen
	v_readlane_b32 s23, v51, 2
	v_pk_fma_f32 v[8:9], v[44:45], s[30:31], v[8:9] op_sel_hi:[1,0,1]
	v_readlane_b32 s22, v3, 9
	v_pk_fma_f32 v[8:9], v[82:83], s[34:35], v[8:9] op_sel_hi:[1,0,1]
	s_nop 1
	buffer_load_dwordx2 v[152:153], v192, s[4:7], s23 offen
	v_readlane_b32 s23, v51, 3
	v_pk_fma_f32 v[8:9], v[96:97], s[36:37], v[8:9] op_sel_hi:[1,0,1]
	v_readlane_b32 s24, v3, 10
	v_pk_fma_f32 v[8:9], v[108:109], s[38:39], v[8:9] op_sel_hi:[1,0,1]
	v_readlane_b32 s26, v3, 11
	s_nop 0
	buffer_load_dwordx2 v[188:189], v192, s[4:7], s23 offen
	v_readlane_b32 s23, v51, 4
	s_nop 3
	s_nop 0
	buffer_load_dwordx2 v[190:191], v192, s[4:7], s23 offen
	buffer_load_dwordx2 v[196:197], v192, s[4:7], s25 offen
	buffer_load_dwordx2 v[198:199], v192, s[4:7], s27 offen
	buffer_load_dwordx2 v[200:201], v192, s[4:7], s29 offen
	v_readlane_b32 s23, v51, 8
	v_readlane_b32 s25, v51, 9
	v_readlane_b32 s27, v51, 10
	v_readlane_b32 s29, v51, 11
	s_nop 1
	buffer_load_dwordx2 v[202:203], v192, s[4:7], s23 offen
	s_nop 1
	buffer_load_dwordx2 v[204:205], v192, s[4:7], s25 offen
	s_nop 1
	buffer_load_dwordx2 v[206:207], v192, s[4:7], s27 offen
	s_nop 1
	buffer_load_dwordx2 v[208:209], v192, s[4:7], s29 offen
	v_readlane_b32 s23, v51, 12
	v_pk_fma_f32 v[8:9], v[116:117], s[56:57], v[8:9] op_sel_hi:[1,0,1]
	v_readlane_b32 s25, v51, 13
	v_readlane_b32 s27, v51, 14
	v_readlane_b32 s29, v51, 15
	v_pk_fma_f32 v[22:23], v[32:33], s[62:63], v[8:9] op_sel_hi:[1,0,1]
	v_readlane_b32 s28, v3, 12
	v_readlane_b32 s30, v3, 13
	v_readlane_b32 s34, v3, 14
	s_waitcnt vmcnt(13)
	v_cvt_scalef32_pk_f32_fp4 v[156:157], v6, 1.0
	v_cvt_scalef32_pk_f32_fp4 v[158:159], v6, 1.0 op_sel:[1,0,0]
	v_cvt_scalef32_pk_f32_fp4 v[160:161], v6, 1.0 op_sel:[0,1,0]
	v_cvt_scalef32_pk_f32_fp4 v[162:163], v6, 1.0 op_sel:[1,1,0]
	v_cvt_scalef32_pk_f32_fp4 v[164:165], v7, 1.0
	v_cvt_scalef32_pk_f32_fp4 v[166:167], v7, 1.0 op_sel:[1,0,0]
	v_cvt_scalef32_pk_f32_fp4 v[168:169], v7, 1.0 op_sel:[0,1,0]
	v_cvt_scalef32_pk_f32_fp4 v[170:171], v7, 1.0 op_sel:[1,1,0]
	v_readlane_b32 s36, v3, 15
	s_waitcnt vmcnt(12)
	v_cvt_scalef32_pk_f32_fp4 v[172:173], v4, 1.0
	v_cvt_scalef32_pk_f32_fp4 v[174:175], v4, 1.0 op_sel:[1,0,0]
	v_cvt_scalef32_pk_f32_fp4 v[176:177], v4, 1.0 op_sel:[0,1,0]
	v_cvt_scalef32_pk_f32_fp4 v[178:179], v4, 1.0 op_sel:[1,1,0]
	v_cvt_scalef32_pk_f32_fp4 v[180:181], v5, 1.0
	v_cvt_scalef32_pk_f32_fp4 v[182:183], v5, 1.0 op_sel:[1,0,0]
	v_cvt_scalef32_pk_f32_fp4 v[184:185], v5, 1.0 op_sel:[0,1,0]
	v_cvt_scalef32_pk_f32_fp4 v[186:187], v5, 1.0 op_sel:[1,1,0]
	ds_read2_b32 v[2:3], v47 offset0:32 offset1:48
	buffer_load_dwordx2 v[210:211], v192, s[4:7], s23 offen
	buffer_load_dwordx2 v[8:9], v192, s[4:7], s25 offen
	buffer_load_dwordx2 v[6:7], v192, s[4:7], s27 offen
	buffer_load_dwordx2 v[4:5], v192, s[4:7], s29 offen
	v_cvt_scalef32_pk_f32_fp4 v[32:33], v121, 1.0 op_sel:[0,1,0]
	v_cvt_scalef32_pk_f32_fp4 v[36:37], v123, 1.0 op_sel:[0,1,0]
	v_pk_fma_f32 v[20:21], v[32:33], s[20:21], v[20:21] op_sel_hi:[1,0,1]
	v_cvt_scalef32_pk_f32_fp4 v[82:83], v121, 1.0
	v_cvt_scalef32_pk_f32_fp4 v[44:45], v125, 1.0 op_sel:[0,1,0]
	v_pk_fma_f32 v[20:21], v[36:37], s[22:23], v[20:21] op_sel_hi:[1,0,1]
	v_cvt_scalef32_pk_f32_fp4 v[52:53], v120, 1.0
	v_cvt_scalef32_pk_f32_fp4 v[54:55], v120, 1.0 op_sel:[1,0,0]
	v_cvt_scalef32_pk_f32_fp4 v[56:57], v120, 1.0 op_sel:[0,1,0]
	v_cvt_scalef32_pk_f32_fp4 v[80:81], v120, 1.0 op_sel:[1,1,0]
	v_cvt_scalef32_pk_f32_fp4 v[38:39], v121, 1.0 op_sel:[1,0,0]
	v_cvt_scalef32_pk_f32_fp4 v[24:25], v121, 1.0 op_sel:[1,1,0]
	v_cvt_scalef32_pk_f32_fp4 v[92:93], v123, 1.0
	v_cvt_scalef32_pk_f32_fp4 v[120:121], v127, 1.0 op_sel:[0,1,0]
	v_pk_fma_f32 v[16:17], v[82:83], s[20:21], v[16:17] op_sel_hi:[1,0,1]
	v_pk_fma_f32 v[20:21], v[44:45], s[24:25], v[20:21] op_sel_hi:[1,0,1]
	v_cvt_scalef32_pk_f32_fp4 v[94:95], v123, 1.0 op_sel:[1,0,0]
	v_cvt_scalef32_pk_f32_fp4 v[104:105], v125, 1.0
	v_cvt_scalef32_pk_f32_fp4 v[136:137], v41, 1.0 op_sel:[0,1,0]
	v_pk_fma_f32 v[16:17], v[92:93], s[22:23], v[16:17] op_sel_hi:[1,0,1]
	v_pk_fma_f32 v[18:19], v[38:39], s[20:21], v[18:19] op_sel_hi:[1,0,1]
	v_pk_fma_f32 v[20:21], v[120:121], s[26:27], v[20:21] op_sel_hi:[1,0,1]
	v_cvt_scalef32_pk_f32_fp4 v[106:107], v125, 1.0 op_sel:[1,0,0]
	v_cvt_scalef32_pk_f32_fp4 v[116:117], v127, 1.0
	v_cvt_scalef32_pk_f32_fp4 v[154:155], v31, 1.0 op_sel:[0,1,0]
	v_pk_fma_f32 v[16:17], v[104:105], s[24:25], v[16:17] op_sel_hi:[1,0,1]
	v_pk_fma_f32 v[18:19], v[94:95], s[22:23], v[18:19] op_sel_hi:[1,0,1]
	v_pk_fma_f32 v[20:21], v[136:137], s[28:29], v[20:21] op_sel_hi:[1,0,1]
	v_cvt_scalef32_pk_f32_fp4 v[118:119], v127, 1.0 op_sel:[1,0,0]
	v_cvt_scalef32_pk_f32_fp4 v[132:133], v41, 1.0
	v_pk_fma_f32 v[16:17], v[116:117], s[26:27], v[16:17] op_sel_hi:[1,0,1]
	v_pk_fma_f32 v[18:19], v[106:107], s[24:25], v[18:19] op_sel_hi:[1,0,1]
	v_pk_fma_f32 v[20:21], v[154:155], s[30:31], v[20:21] op_sel_hi:[1,0,1]
	v_cvt_scalef32_pk_f32_fp4 v[134:135], v41, 1.0 op_sel:[1,0,0]
	v_cvt_scalef32_pk_f32_fp4 v[148:149], v31, 1.0
	v_pk_fma_f32 v[16:17], v[132:133], s[28:29], v[16:17] op_sel_hi:[1,0,1]
	v_pk_fma_f32 v[18:19], v[118:119], s[26:27], v[18:19] op_sel_hi:[1,0,1]
	v_pk_fma_f32 v[20:21], v[168:169], s[34:35], v[20:21] op_sel_hi:[1,0,1]
	v_cvt_scalef32_pk_f32_fp4 v[150:151], v31, 1.0 op_sel:[1,0,0]
	s_waitcnt lgkmcnt(0)
	v_readlane_b32 s38, v2, 0
	s_waitcnt vmcnt(15)
	v_cvt_scalef32_pk_f32_fp4 v[236:237], v129, 1.0 op_sel:[0,1,0]
	v_pk_fma_f32 v[16:17], v[148:149], s[30:31], v[16:17] op_sel_hi:[1,0,1]
	v_pk_fma_f32 v[18:19], v[134:135], s[28:29], v[18:19] op_sel_hi:[1,0,1]
	v_pk_fma_f32 v[20:21], v[184:185], s[36:37], v[20:21] op_sel_hi:[1,0,1]
	v_readlane_b32 s56, v2, 1
	v_pk_fma_f32 v[26:27], v[52:53], s[20:21], v[26:27] op_sel_hi:[1,0,1]
	s_waitcnt vmcnt(14)
	v_cvt_scalef32_pk_f32_fp4 v[52:53], v139, 1.0 op_sel:[0,1,0]
	v_pk_fma_f32 v[16:17], v[164:165], s[34:35], v[16:17] op_sel_hi:[1,0,1]
	v_pk_fma_f32 v[18:19], v[150:151], s[30:31], v[18:19] op_sel_hi:[1,0,1]
	v_pk_fma_f32 v[20:21], v[236:237], s[38:39], v[20:21] op_sel_hi:[1,0,1]
	v_cvt_scalef32_pk_f32_fp4 v[84:85], v122, 1.0
	v_cvt_scalef32_pk_f32_fp4 v[232:233], v129, 1.0
	v_readlane_b32 s62, v2, 2
	v_pk_fma_f32 v[14:15], v[80:81], s[20:21], v[14:15] op_sel_hi:[1,0,1]
	s_waitcnt vmcnt(13)
	v_cvt_scalef32_pk_f32_fp4 v[80:81], v153, 1.0 op_sel:[0,1,0]
	v_pk_fma_f32 v[16:17], v[180:181], s[36:37], v[16:17] op_sel_hi:[1,0,1]
	v_pk_fma_f32 v[18:19], v[166:167], s[34:35], v[18:19] op_sel_hi:[1,0,1]
	v_pk_fma_f32 v[20:21], v[52:53], s[56:57], v[20:21] op_sel_hi:[1,0,1]
	v_cvt_scalef32_pk_f32_fp4 v[28:29], v123, 1.0 op_sel:[1,1,0]
	v_cvt_scalef32_pk_f32_fp4 v[96:97], v124, 1.0
	v_cvt_scalef32_pk_f32_fp4 v[234:235], v129, 1.0 op_sel:[1,0,0]
	v_cvt_scalef32_pk_f32_fp4 v[246:247], v139, 1.0
	v_pk_fma_f32 v[26:27], v[84:85], s[22:23], v[26:27] op_sel_hi:[1,0,1]
	v_pk_fma_f32 v[16:17], v[232:233], s[38:39], v[16:17] op_sel_hi:[1,0,1]
	v_pk_fma_f32 v[18:19], v[182:183], s[36:37], v[18:19] op_sel_hi:[1,0,1]
	v_pk_fma_f32 v[32:33], v[80:81], s[62:63], v[20:21] op_sel_hi:[1,0,1]
	v_pk_fma_f32 v[20:21], v[24:25], s[20:21], v[22:23] op_sel_hi:[1,0,1]
	v_cvt_scalef32_pk_f32_fp4 v[86:87], v122, 1.0 op_sel:[1,0,0]
	v_cvt_scalef32_pk_f32_fp4 v[34:35], v125, 1.0 op_sel:[1,1,0]
	v_cvt_scalef32_pk_f32_fp4 v[108:109], v126, 1.0
	v_cvt_scalef32_pk_f32_fp4 v[248:249], v139, 1.0 op_sel:[1,0,0]
	v_pk_fma_f32 v[26:27], v[96:97], s[24:25], v[26:27] op_sel_hi:[1,0,1]
	v_pk_fma_f32 v[10:11], v[54:55], s[20:21], v[10:11] op_sel_hi:[1,0,1]
	v_cvt_scalef32_pk_f32_fp4 v[54:55], v153, 1.0
	v_pk_fma_f32 v[16:17], v[246:247], s[56:57], v[16:17] op_sel_hi:[1,0,1]
	v_pk_fma_f32 v[18:19], v[234:235], s[38:39], v[18:19] op_sel_hi:[1,0,1]
	v_pk_fma_f32 v[20:21], v[28:29], s[22:23], v[20:21] op_sel_hi:[1,0,1]
	v_cvt_scalef32_pk_f32_fp4 v[88:89], v122, 1.0 op_sel:[0,1,0]
	v_cvt_scalef32_pk_f32_fp4 v[90:91], v122, 1.0 op_sel:[1,1,0]
	v_cvt_scalef32_pk_f32_fp4 v[98:99], v124, 1.0 op_sel:[1,0,0]
	v_cvt_scalef32_pk_f32_fp4 v[42:43], v127, 1.0 op_sel:[1,1,0]
	v_cvt_scalef32_pk_f32_fp4 v[122:123], v40, 1.0
	v_pk_fma_f32 v[26:27], v[108:109], s[26:27], v[26:27] op_sel_hi:[1,0,1]
	v_pk_fma_f32 v[10:11], v[86:87], s[22:23], v[10:11] op_sel_hi:[1,0,1]
	v_pk_fma_f32 v[12:13], v[56:57], s[20:21], v[12:13] op_sel_hi:[1,0,1]
	v_cvt_scalef32_pk_f32_fp4 v[56:57], v153, 1.0 op_sel:[1,0,0]
	v_pk_fma_f32 v[16:17], v[54:55], s[62:63], v[16:17] op_sel_hi:[1,0,1]
	v_pk_fma_f32 v[18:19], v[248:249], s[56:57], v[18:19] op_sel_hi:[1,0,1]
	v_pk_fma_f32 v[20:21], v[34:35], s[24:25], v[20:21] op_sel_hi:[1,0,1]
	v_readlane_b32 s20, v2, 3
	s_waitcnt vmcnt(12)
	v_cvt_scalef32_pk_f32_fp4 v[34:35], v189, 1.0
	v_cvt_scalef32_pk_f32_fp4 v[100:101], v124, 1.0 op_sel:[0,1,0]
	v_cvt_scalef32_pk_f32_fp4 v[102:103], v124, 1.0 op_sel:[1,1,0]
	v_cvt_scalef32_pk_f32_fp4 v[110:111], v126, 1.0 op_sel:[1,0,0]
	v_cvt_scalef32_pk_f32_fp4 v[112:113], v126, 1.0 op_sel:[0,1,0]
	v_cvt_scalef32_pk_f32_fp4 v[114:115], v126, 1.0 op_sel:[1,1,0]
	v_cvt_scalef32_pk_f32_fp4 v[124:125], v40, 1.0 op_sel:[1,0,0]
	v_cvt_scalef32_pk_f32_fp4 v[126:127], v40, 1.0 op_sel:[0,1,0]
	v_cvt_scalef32_pk_f32_fp4 v[130:131], v40, 1.0 op_sel:[1,1,0]
	v_cvt_scalef32_pk_f32_fp4 v[40:41], v41, 1.0 op_sel:[1,1,0]
	v_cvt_scalef32_pk_f32_fp4 v[140:141], v30, 1.0
	v_pk_fma_f32 v[26:27], v[122:123], s[28:29], v[26:27] op_sel_hi:[1,0,1]
	v_pk_fma_f32 v[10:11], v[98:99], s[24:25], v[10:11] op_sel_hi:[1,0,1]
	v_pk_fma_f32 v[12:13], v[88:89], s[22:23], v[12:13] op_sel_hi:[1,0,1]
	v_pk_fma_f32 v[14:15], v[90:91], s[22:23], v[14:15] op_sel_hi:[1,0,1]
	v_pk_fma_f32 v[18:19], v[56:57], s[62:63], v[18:19] op_sel_hi:[1,0,1]
	v_pk_fma_f32 v[20:21], v[42:43], s[26:27], v[20:21] op_sel_hi:[1,0,1]
	v_readlane_b32 s22, v2, 4
	s_waitcnt vmcnt(11)
	v_cvt_scalef32_pk_f32_fp4 v[56:57], v191, 1.0
	v_pk_fma_f32 v[16:17], v[34:35], s[20:21], v[16:17] op_sel_hi:[1,0,1]
	v_cvt_scalef32_pk_f32_fp4 v[142:143], v30, 1.0 op_sel:[1,0,0]
	v_cvt_scalef32_pk_f32_fp4 v[144:145], v30, 1.0 op_sel:[0,1,0]
	v_cvt_scalef32_pk_f32_fp4 v[146:147], v30, 1.0 op_sel:[1,1,0]
	v_cvt_scalef32_pk_f32_fp4 v[30:31], v31, 1.0 op_sel:[1,1,0]
	v_pk_fma_f32 v[26:27], v[140:141], s[30:31], v[26:27] op_sel_hi:[1,0,1]
	v_pk_fma_f32 v[10:11], v[110:111], s[26:27], v[10:11] op_sel_hi:[1,0,1]
	v_pk_fma_f32 v[12:13], v[100:101], s[24:25], v[12:13] op_sel_hi:[1,0,1]
	v_pk_fma_f32 v[14:15], v[102:103], s[24:25], v[14:15] op_sel_hi:[1,0,1]
	v_pk_fma_f32 v[20:21], v[40:41], s[28:29], v[20:21] op_sel_hi:[1,0,1]
	v_readlane_b32 s24, v2, 5
	s_waitcnt vmcnt(10)
	v_cvt_scalef32_pk_f32_fp4 v[94:95], v197, 1.0
	v_pk_fma_f32 v[16:17], v[56:57], s[22:23], v[16:17] op_sel_hi:[1,0,1]
	v_pk_fma_f32 v[26:27], v[156:157], s[34:35], v[26:27] op_sel_hi:[1,0,1]
	v_pk_fma_f32 v[10:11], v[124:125], s[28:29], v[10:11] op_sel_hi:[1,0,1]
	v_pk_fma_f32 v[12:13], v[112:113], s[26:27], v[12:13] op_sel_hi:[1,0,1]
	v_pk_fma_f32 v[14:15], v[114:115], s[26:27], v[14:15] op_sel_hi:[1,0,1]
	v_pk_fma_f32 v[20:21], v[30:31], s[30:31], v[20:21] op_sel_hi:[1,0,1]
	v_readlane_b32 s26, v2, 6
	s_waitcnt vmcnt(9)
	v_cvt_scalef32_pk_f32_fp4 v[110:111], v199, 1.0
	v_pk_fma_f32 v[16:17], v[94:95], s[24:25], v[16:17] op_sel_hi:[1,0,1]
	v_cvt_scalef32_pk_f32_fp4 v[214:215], v128, 1.0
	v_pk_fma_f32 v[26:27], v[172:173], s[36:37], v[26:27] op_sel_hi:[1,0,1]
	v_pk_fma_f32 v[10:11], v[142:143], s[30:31], v[10:11] op_sel_hi:[1,0,1]
	v_pk_fma_f32 v[12:13], v[126:127], s[28:29], v[12:13] op_sel_hi:[1,0,1]
	v_pk_fma_f32 v[14:15], v[130:131], s[28:29], v[14:15] op_sel_hi:[1,0,1]
	v_pk_fma_f32 v[20:21], v[170:171], s[34:35], v[20:21] op_sel_hi:[1,0,1]
	v_readlane_b32 s28, v2, 7
	s_waitcnt vmcnt(8)
	v_cvt_scalef32_pk_f32_fp4 v[126:127], v201, 1.0
	v_pk_fma_f32 v[16:17], v[110:111], s[26:27], v[16:17] op_sel_hi:[1,0,1]
	v_cvt_scalef32_pk_f32_fp4 v[216:217], v128, 1.0 op_sel:[1,0,0]
	v_cvt_scalef32_pk_f32_fp4 v[228:229], v128, 1.0 op_sel:[0,1,0]
	v_cvt_scalef32_pk_f32_fp4 v[230:231], v128, 1.0 op_sel:[1,1,0]
	v_cvt_scalef32_pk_f32_fp4 v[128:129], v129, 1.0 op_sel:[1,1,0]
	v_cvt_scalef32_pk_f32_fp4 v[238:239], v138, 1.0
	v_pk_fma_f32 v[26:27], v[214:215], s[38:39], v[26:27] op_sel_hi:[1,0,1]
	v_pk_fma_f32 v[10:11], v[158:159], s[34:35], v[10:11] op_sel_hi:[1,0,1]
	v_pk_fma_f32 v[12:13], v[144:145], s[30:31], v[12:13] op_sel_hi:[1,0,1]
	v_pk_fma_f32 v[14:15], v[146:147], s[30:31], v[14:15] op_sel_hi:[1,0,1]
	v_pk_fma_f32 v[20:21], v[186:187], s[36:37], v[20:21] op_sel_hi:[1,0,1]
	v_readlane_b32 s30, v2, 8
	s_waitcnt vmcnt(7)
	v_cvt_scalef32_pk_f32_fp4 v[142:143], v203, 1.0
	v_pk_fma_f32 v[16:17], v[126:127], s[28:29], v[16:17] op_sel_hi:[1,0,1]
	v_cvt_scalef32_pk_f32_fp4 v[240:241], v138, 1.0 op_sel:[1,0,0]
	v_cvt_scalef32_pk_f32_fp4 v[242:243], v138, 1.0 op_sel:[0,1,0]
	v_cvt_scalef32_pk_f32_fp4 v[244:245], v138, 1.0 op_sel:[1,1,0]
	v_cvt_scalef32_pk_f32_fp4 v[138:139], v139, 1.0 op_sel:[1,1,0]
	v_cvt_scalef32_pk_f32_fp4 v[84:85], v152, 1.0
	v_pk_fma_f32 v[26:27], v[238:239], s[56:57], v[26:27] op_sel_hi:[1,0,1]
	v_pk_fma_f32 v[10:11], v[174:175], s[36:37], v[10:11] op_sel_hi:[1,0,1]
	v_pk_fma_f32 v[12:13], v[160:161], s[34:35], v[12:13] op_sel_hi:[1,0,1]
	v_pk_fma_f32 v[14:15], v[162:163], s[34:35], v[14:15] op_sel_hi:[1,0,1]
	v_pk_fma_f32 v[20:21], v[128:129], s[38:39], v[20:21] op_sel_hi:[1,0,1]
	v_readlane_b32 s34, v2, 9
	s_waitcnt vmcnt(6)
	v_cvt_scalef32_pk_f32_fp4 v[158:159], v205, 1.0
	v_pk_fma_f32 v[16:17], v[142:143], s[30:31], v[16:17] op_sel_hi:[1,0,1]
	v_pk_fma_f32 v[26:27], v[84:85], s[62:63], v[26:27] op_sel_hi:[1,0,1]
	v_pk_fma_f32 v[10:11], v[216:217], s[38:39], v[10:11] op_sel_hi:[1,0,1]
	v_pk_fma_f32 v[12:13], v[176:177], s[36:37], v[12:13] op_sel_hi:[1,0,1]
	v_pk_fma_f32 v[14:15], v[178:179], s[36:37], v[14:15] op_sel_hi:[1,0,1]
	v_cvt_scalef32_pk_f32_fp4 v[84:85], v153, 1.0 op_sel:[1,1,0]
	v_pk_fma_f32 v[20:21], v[138:139], s[56:57], v[20:21] op_sel_hi:[1,0,1]
	v_readlane_b32 s36, v2, 10
	s_waitcnt vmcnt(5)
	v_cvt_scalef32_pk_f32_fp4 v[174:175], v207, 1.0
	v_pk_fma_f32 v[16:17], v[158:159], s[34:35], v[16:17] op_sel_hi:[1,0,1]
	v_cvt_scalef32_pk_f32_fp4 v[96:97], v152, 1.0 op_sel:[1,0,0]
	v_pk_fma_f32 v[10:11], v[240:241], s[56:57], v[10:11] op_sel_hi:[1,0,1]
	v_pk_fma_f32 v[12:13], v[228:229], s[38:39], v[12:13] op_sel_hi:[1,0,1]
	v_pk_fma_f32 v[14:15], v[230:231], s[38:39], v[14:15] op_sel_hi:[1,0,1]
	v_pk_fma_f32 v[22:23], v[84:85], s[62:63], v[20:21] op_sel_hi:[1,0,1]
	v_cvt_scalef32_pk_f32_fp4 v[42:43], v190, 1.0
	v_cvt_scalef32_pk_f32_fp4 v[44:45], v190, 1.0 op_sel:[1,0,0]
	v_cvt_scalef32_pk_f32_fp4 v[52:53], v190, 1.0 op_sel:[0,1,0]
	v_cvt_scalef32_pk_f32_fp4 v[54:55], v190, 1.0 op_sel:[1,1,0]
	v_cvt_scalef32_pk_f32_fp4 v[80:81], v191, 1.0 op_sel:[1,0,0]
	v_cvt_scalef32_pk_f32_fp4 v[82:83], v191, 1.0 op_sel:[0,1,0]
	v_cvt_scalef32_pk_f32_fp4 v[84:85], v191, 1.0 op_sel:[1,1,0]
	v_readlane_b32 s38, v2, 11
	s_waitcnt vmcnt(4)
	v_cvt_scalef32_pk_f32_fp4 v[190:191], v209, 1.0
	v_pk_fma_f32 v[16:17], v[174:175], s[36:37], v[16:17] op_sel_hi:[1,0,1]
	v_cvt_scalef32_pk_f32_fp4 v[108:109], v152, 1.0 op_sel:[0,1,0]
	v_cvt_scalef32_pk_f32_fp4 v[122:123], v152, 1.0 op_sel:[1,1,0]
	v_pk_fma_f32 v[10:11], v[96:97], s[62:63], v[10:11] op_sel_hi:[1,0,1]
	v_pk_fma_f32 v[12:13], v[242:243], s[56:57], v[12:13] op_sel_hi:[1,0,1]
	v_pk_fma_f32 v[14:15], v[244:245], s[56:57], v[14:15] op_sel_hi:[1,0,1]
	v_cvt_scalef32_pk_f32_fp4 v[24:25], v188, 1.0 op_sel:[1,0,0]
	v_readlane_b32 s56, v2, 12
	s_waitcnt vmcnt(3)
	v_cvt_scalef32_pk_f32_fp4 v[214:215], v211, 1.0
	v_pk_fma_f32 v[16:17], v[190:191], s[38:39], v[16:17] op_sel_hi:[1,0,1]
	v_pk_fma_f32 v[12:13], v[108:109], s[62:63], v[12:13] op_sel_hi:[1,0,1]
	v_pk_fma_f32 v[14:15], v[122:123], s[62:63], v[14:15] op_sel_hi:[1,0,1]
	v_cvt_scalef32_pk_f32_fp4 v[38:39], v189, 1.0 op_sel:[0,1,0]
	v_readlane_b32 s62, v2, 13
	v_pk_fma_f32 v[10:11], v[24:25], s[20:21], v[10:11] op_sel_hi:[1,0,1]
	s_waitcnt vmcnt(2)
	v_cvt_scalef32_pk_f32_fp4 v[24:25], v9, 1.0
	v_pk_fma_f32 v[16:17], v[214:215], s[56:57], v[16:17] op_sel_hi:[1,0,1]
	v_cvt_scalef32_pk_f32_fp4 v[98:99], v197, 1.0 op_sel:[0,1,0]
	v_pk_fma_f32 v[16:17], v[24:25], s[62:63], v[16:17] op_sel_hi:[1,0,1]
	v_pk_fma_f32 v[24:25], v[38:39], s[20:21], v[32:33] op_sel_hi:[1,0,1]
	v_cvt_scalef32_pk_f32_fp4 v[114:115], v199, 1.0 op_sel:[0,1,0]
	v_pk_fma_f32 v[24:25], v[82:83], s[22:23], v[24:25] op_sel_hi:[1,0,1]
	v_cvt_scalef32_pk_f32_fp4 v[130:131], v201, 1.0 op_sel:[0,1,0]
	v_pk_fma_f32 v[24:25], v[98:99], s[24:25], v[24:25] op_sel_hi:[1,0,1]
	v_cvt_scalef32_pk_f32_fp4 v[20:21], v188, 1.0
	v_pk_fma_f32 v[24:25], v[114:115], s[26:27], v[24:25] op_sel_hi:[1,0,1]
	v_cvt_scalef32_pk_f32_fp4 v[28:29], v188, 1.0 op_sel:[0,1,0]
	v_cvt_scalef32_pk_f32_fp4 v[30:31], v188, 1.0 op_sel:[1,1,0]
	v_cvt_scalef32_pk_f32_fp4 v[36:37], v189, 1.0 op_sel:[1,0,0]
	v_cvt_scalef32_pk_f32_fp4 v[146:147], v203, 1.0 op_sel:[0,1,0]
	v_pk_fma_f32 v[24:25], v[130:131], s[28:29], v[24:25] op_sel_hi:[1,0,1]
	v_cvt_scalef32_pk_f32_fp4 v[162:163], v205, 1.0 op_sel:[0,1,0]
	v_pk_fma_f32 v[20:21], v[20:21], s[20:21], v[26:27] op_sel_hi:[1,0,1]
	v_pk_fma_f32 v[12:13], v[28:29], s[20:21], v[12:13] op_sel_hi:[1,0,1]
	v_pk_fma_f32 v[14:15], v[30:31], s[20:21], v[14:15] op_sel_hi:[1,0,1]
	v_pk_fma_f32 v[18:19], v[36:37], s[20:21], v[18:19] op_sel_hi:[1,0,1]
	v_pk_fma_f32 v[24:25], v[146:147], s[30:31], v[24:25] op_sel_hi:[1,0,1]
	v_cvt_scalef32_pk_f32_fp4 v[40:41], v189, 1.0 op_sel:[1,1,0]
	v_cvt_scalef32_pk_f32_fp4 v[178:179], v207, 1.0 op_sel:[0,1,0]
	v_pk_fma_f32 v[20:21], v[42:43], s[22:23], v[20:21] op_sel_hi:[1,0,1]
	v_pk_fma_f32 v[10:11], v[44:45], s[22:23], v[10:11] op_sel_hi:[1,0,1]
	v_pk_fma_f32 v[12:13], v[52:53], s[22:23], v[12:13] op_sel_hi:[1,0,1]
	v_pk_fma_f32 v[14:15], v[54:55], s[22:23], v[14:15] op_sel_hi:[1,0,1]
	v_pk_fma_f32 v[18:19], v[80:81], s[22:23], v[18:19] op_sel_hi:[1,0,1]
	v_pk_fma_f32 v[24:25], v[162:163], s[34:35], v[24:25] op_sel_hi:[1,0,1]
	v_readlane_b32 s23, v50, 0
	v_cvt_scalef32_pk_f32_fp4 v[102:103], v198, 1.0
	v_cvt_scalef32_pk_f32_fp4 v[104:105], v198, 1.0 op_sel:[1,0,0]
	v_cvt_scalef32_pk_f32_fp4 v[106:107], v198, 1.0 op_sel:[0,1,0]
	v_cvt_scalef32_pk_f32_fp4 v[108:109], v198, 1.0 op_sel:[1,1,0]
	v_cvt_scalef32_pk_f32_fp4 v[112:113], v199, 1.0 op_sel:[1,0,0]
	v_cvt_scalef32_pk_f32_fp4 v[116:117], v199, 1.0 op_sel:[1,1,0]
	v_cvt_scalef32_pk_f32_fp4 v[198:199], v209, 1.0 op_sel:[0,1,0]
	v_pk_fma_f32 v[24:25], v[178:179], s[36:37], v[24:25] op_sel_hi:[1,0,1]
	v_pk_fma_f32 v[22:23], v[40:41], s[20:21], v[22:23] op_sel_hi:[1,0,1]
	v_cvt_scalef32_pk_f32_fp4 v[228:229], v211, 1.0 op_sel:[0,1,0]
	v_pk_fma_f32 v[24:25], v[198:199], s[38:39], v[24:25] op_sel_hi:[1,0,1]
	v_pk_fma_f32 v[22:23], v[84:85], s[22:23], v[22:23] op_sel_hi:[1,0,1]
	v_readlane_b32 s20, v50, 1
	v_readlane_b32 s22, v50, 3
	v_cvt_scalef32_pk_f32_fp4 v[28:29], v9, 1.0 op_sel:[0,1,0]
	v_pk_fma_f32 v[24:25], v[228:229], s[56:57], v[24:25] op_sel_hi:[1,0,1]
	buffer_load_dwordx2 v[30:31], v192, s[4:7], s23 offen
	s_nop 1
	buffer_load_dwordx2 v[38:39], v192, s[4:7], s22 offen
	v_pk_fma_f32 v[28:29], v[28:29], s[62:63], v[24:25] op_sel_hi:[1,0,1]
	buffer_load_dwordx2 v[24:25], v192, s[4:7], s20 offen
	v_readlane_b32 s20, v50, 2
	v_readlane_b32 s22, v50, 4
	v_readlane_b32 s23, v50, 5
	v_cvt_scalef32_pk_f32_fp4 v[92:93], v196, 1.0 op_sel:[1,1,0]
	s_nop 1
	buffer_load_dwordx2 v[32:33], v192, s[4:7], s20 offen
	s_nop 1
	buffer_load_dwordx2 v[80:81], v192, s[4:7], s22 offen
	v_cvt_scalef32_pk_f32_fp4 v[86:87], v196, 1.0
	v_cvt_scalef32_pk_f32_fp4 v[88:89], v196, 1.0 op_sel:[1,0,0]
	v_cvt_scalef32_pk_f32_fp4 v[90:91], v196, 1.0 op_sel:[0,1,0]
	v_cvt_scalef32_pk_f32_fp4 v[96:97], v197, 1.0 op_sel:[1,0,0]
	v_cvt_scalef32_pk_f32_fp4 v[100:101], v197, 1.0 op_sel:[1,1,0]
	v_pk_fma_f32 v[14:15], v[92:93], s[24:25], v[14:15] op_sel_hi:[1,0,1]
	buffer_load_dwordx2 v[92:93], v192, s[4:7], s23 offen
	v_readlane_b32 s23, v50, 6
	v_pk_fma_f32 v[20:21], v[86:87], s[24:25], v[20:21] op_sel_hi:[1,0,1]
	v_pk_fma_f32 v[10:11], v[88:89], s[24:25], v[10:11] op_sel_hi:[1,0,1]
	v_pk_fma_f32 v[12:13], v[90:91], s[24:25], v[12:13] op_sel_hi:[1,0,1]
	v_pk_fma_f32 v[18:19], v[96:97], s[24:25], v[18:19] op_sel_hi:[1,0,1]
	v_pk_fma_f32 v[22:23], v[100:101], s[24:25], v[22:23] op_sel_hi:[1,0,1]
	v_readlane_b32 s24, v50, 7
	v_pk_fma_f32 v[20:21], v[102:103], s[26:27], v[20:21] op_sel_hi:[1,0,1]
	buffer_load_dwordx2 v[100:101], v192, s[4:7], s23 offen
	s_nop 1
	s_nop 0
	buffer_load_dwordx2 v[102:103], v192, s[4:7], s24 offen
	v_readlane_b32 s23, v50, 8
	v_pk_fma_f32 v[10:11], v[104:105], s[26:27], v[10:11] op_sel_hi:[1,0,1]
	v_pk_fma_f32 v[12:13], v[106:107], s[26:27], v[12:13] op_sel_hi:[1,0,1]
	v_pk_fma_f32 v[14:15], v[108:109], s[26:27], v[14:15] op_sel_hi:[1,0,1]
	v_pk_fma_f32 v[18:19], v[112:113], s[26:27], v[18:19] op_sel_hi:[1,0,1]
	v_pk_fma_f32 v[22:23], v[116:117], s[26:27], v[22:23] op_sel_hi:[1,0,1]
	v_readlane_b32 s24, v50, 9
	v_readlane_b32 s25, v50, 10
	v_readlane_b32 s26, v50, 11
	buffer_load_dwordx2 v[104:105], v192, s[4:7], s23 offen
	s_nop 1
	buffer_load_dwordx2 v[106:107], v192, s[4:7], s24 offen
	s_nop 1
	buffer_load_dwordx2 v[108:109], v192, s[4:7], s25 offen
	s_nop 1
	buffer_load_dwordx2 v[110:111], v192, s[4:7], s26 offen
	v_cvt_scalef32_pk_f32_fp4 v[128:129], v201, 1.0 op_sel:[1,0,0]
	v_cvt_scalef32_pk_f32_fp4 v[132:133], v201, 1.0 op_sel:[1,1,0]
	v_cvt_scalef32_pk_f32_fp4 v[144:145], v203, 1.0 op_sel:[1,0,0]
	v_cvt_scalef32_pk_f32_fp4 v[148:149], v203, 1.0 op_sel:[1,1,0]
	v_pk_fma_f32 v[18:19], v[128:129], s[28:29], v[18:19] op_sel_hi:[1,0,1]
	v_pk_fma_f32 v[22:23], v[132:133], s[28:29], v[22:23] op_sel_hi:[1,0,1]
	v_cvt_scalef32_pk_f32_fp4 v[160:161], v205, 1.0 op_sel:[1,0,0]
	v_cvt_scalef32_pk_f32_fp4 v[164:165], v205, 1.0 op_sel:[1,1,0]
	v_pk_fma_f32 v[18:19], v[144:145], s[30:31], v[18:19] op_sel_hi:[1,0,1]
	v_pk_fma_f32 v[22:23], v[148:149], s[30:31], v[22:23] op_sel_hi:[1,0,1]
	v_cvt_scalef32_pk_f32_fp4 v[176:177], v207, 1.0 op_sel:[1,0,0]
	v_cvt_scalef32_pk_f32_fp4 v[180:181], v207, 1.0 op_sel:[1,1,0]
	v_pk_fma_f32 v[18:19], v[160:161], s[34:35], v[18:19] op_sel_hi:[1,0,1]
	v_pk_fma_f32 v[22:23], v[164:165], s[34:35], v[22:23] op_sel_hi:[1,0,1]
	v_cvt_scalef32_pk_f32_fp4 v[118:119], v200, 1.0
	v_cvt_scalef32_pk_f32_fp4 v[120:121], v200, 1.0 op_sel:[1,0,0]
	v_cvt_scalef32_pk_f32_fp4 v[122:123], v200, 1.0 op_sel:[0,1,0]
	v_cvt_scalef32_pk_f32_fp4 v[124:125], v200, 1.0 op_sel:[1,1,0]
	v_cvt_scalef32_pk_f32_fp4 v[196:197], v209, 1.0 op_sel:[1,0,0]
	v_cvt_scalef32_pk_f32_fp4 v[200:201], v209, 1.0 op_sel:[1,1,0]
	v_pk_fma_f32 v[18:19], v[176:177], s[36:37], v[18:19] op_sel_hi:[1,0,1]
	v_pk_fma_f32 v[22:23], v[180:181], s[36:37], v[22:23] op_sel_hi:[1,0,1]
	v_cvt_scalef32_pk_f32_fp4 v[134:135], v202, 1.0
	v_cvt_scalef32_pk_f32_fp4 v[136:137], v202, 1.0 op_sel:[1,0,0]
	v_cvt_scalef32_pk_f32_fp4 v[138:139], v202, 1.0 op_sel:[0,1,0]
	v_cvt_scalef32_pk_f32_fp4 v[140:141], v202, 1.0 op_sel:[1,1,0]
	v_cvt_scalef32_pk_f32_fp4 v[150:151], v204, 1.0
	v_cvt_scalef32_pk_f32_fp4 v[152:153], v204, 1.0 op_sel:[1,0,0]
	v_cvt_scalef32_pk_f32_fp4 v[154:155], v204, 1.0 op_sel:[0,1,0]
	v_cvt_scalef32_pk_f32_fp4 v[156:157], v204, 1.0 op_sel:[1,1,0]
	v_cvt_scalef32_pk_f32_fp4 v[166:167], v206, 1.0
	v_cvt_scalef32_pk_f32_fp4 v[168:169], v206, 1.0 op_sel:[1,0,0]
	v_cvt_scalef32_pk_f32_fp4 v[170:171], v206, 1.0 op_sel:[0,1,0]
	v_cvt_scalef32_pk_f32_fp4 v[172:173], v206, 1.0 op_sel:[1,1,0]
	v_cvt_scalef32_pk_f32_fp4 v[182:183], v208, 1.0
	v_cvt_scalef32_pk_f32_fp4 v[184:185], v208, 1.0 op_sel:[1,0,0]
	v_cvt_scalef32_pk_f32_fp4 v[186:187], v208, 1.0 op_sel:[0,1,0]
	v_cvt_scalef32_pk_f32_fp4 v[188:189], v208, 1.0 op_sel:[1,1,0]
	v_cvt_scalef32_pk_f32_fp4 v[202:203], v210, 1.0
	v_cvt_scalef32_pk_f32_fp4 v[204:205], v210, 1.0 op_sel:[1,0,0]
	v_cvt_scalef32_pk_f32_fp4 v[206:207], v210, 1.0 op_sel:[0,1,0]
	v_cvt_scalef32_pk_f32_fp4 v[208:209], v210, 1.0 op_sel:[1,1,0]
	v_cvt_scalef32_pk_f32_fp4 v[216:217], v211, 1.0 op_sel:[1,0,0]
	v_cvt_scalef32_pk_f32_fp4 v[210:211], v211, 1.0 op_sel:[1,1,0]
	v_pk_fma_f32 v[18:19], v[196:197], s[38:39], v[18:19] op_sel_hi:[1,0,1]
	v_pk_fma_f32 v[22:23], v[200:201], s[38:39], v[22:23] op_sel_hi:[1,0,1]
	v_readlane_b32 s23, v50, 12
	v_cvt_scalef32_pk_f32_fp4 v[230:231], v8, 1.0
	v_cvt_scalef32_pk_f32_fp4 v[232:233], v8, 1.0 op_sel:[1,0,0]
	v_cvt_scalef32_pk_f32_fp4 v[234:235], v8, 1.0 op_sel:[0,1,0]
	v_cvt_scalef32_pk_f32_fp4 v[236:237], v8, 1.0 op_sel:[1,1,0]
	v_cvt_scalef32_pk_f32_fp4 v[26:27], v9, 1.0 op_sel:[1,0,0]
	v_cvt_scalef32_pk_f32_fp4 v[8:9], v9, 1.0 op_sel:[1,1,0]
	v_pk_fma_f32 v[18:19], v[216:217], s[56:57], v[18:19] op_sel_hi:[1,0,1]
	v_pk_fma_f32 v[22:23], v[210:211], s[56:57], v[22:23] op_sel_hi:[1,0,1]
	v_readlane_b32 s24, v50, 13
	v_readlane_b32 s25, v50, 14
	v_readlane_b32 s26, v50, 15
	v_pk_fma_f32 v[18:19], v[26:27], s[62:63], v[18:19] op_sel_hi:[1,0,1]
	v_pk_fma_f32 v[22:23], v[8:9], s[62:63], v[22:23] op_sel_hi:[1,0,1]
	s_waitcnt vmcnt(13)
	v_cvt_scalef32_pk_f32_fp4 v[8:9], v6, 1.0
	v_cvt_scalef32_pk_f32_fp4 v[36:37], v6, 1.0 op_sel:[1,0,0]
	v_cvt_scalef32_pk_f32_fp4 v[40:41], v6, 1.0 op_sel:[0,1,0]
	v_cvt_scalef32_pk_f32_fp4 v[42:43], v6, 1.0 op_sel:[1,1,0]
	v_cvt_scalef32_pk_f32_fp4 v[44:45], v7, 1.0
	v_cvt_scalef32_pk_f32_fp4 v[52:53], v7, 1.0 op_sel:[1,0,0]
	v_cvt_scalef32_pk_f32_fp4 v[54:55], v7, 1.0 op_sel:[0,1,0]
	v_cvt_scalef32_pk_f32_fp4 v[56:57], v7, 1.0 op_sel:[1,1,0]
	s_waitcnt vmcnt(12)
	v_cvt_scalef32_pk_f32_fp4 v[82:83], v4, 1.0
	v_cvt_scalef32_pk_f32_fp4 v[84:85], v4, 1.0 op_sel:[1,0,0]
	v_cvt_scalef32_pk_f32_fp4 v[86:87], v4, 1.0 op_sel:[0,1,0]
	v_cvt_scalef32_pk_f32_fp4 v[88:89], v4, 1.0 op_sel:[1,1,0]
	v_cvt_scalef32_pk_f32_fp4 v[90:91], v5, 1.0
	v_cvt_scalef32_pk_f32_fp4 v[94:95], v5, 1.0 op_sel:[1,0,0]
	v_cvt_scalef32_pk_f32_fp4 v[96:97], v5, 1.0 op_sel:[0,1,0]
	v_cvt_scalef32_pk_f32_fp4 v[98:99], v5, 1.0 op_sel:[1,1,0]
	buffer_load_dwordx2 v[34:35], v192, s[4:7], s23 offen
	buffer_load_dwordx2 v[26:27], v192, s[4:7], s24 offen
	buffer_load_dwordx2 v[6:7], v192, s[4:7], s25 offen
	buffer_load_dwordx2 v[4:5], v192, s[4:7], s26 offen
	v_pk_fma_f32 v[20:21], v[118:119], s[28:29], v[20:21] op_sel_hi:[1,0,1]
	v_readlane_b32 s20, v2, 14
	v_pk_fma_f32 v[20:21], v[134:135], s[30:31], v[20:21] op_sel_hi:[1,0,1]
	v_readlane_b32 s22, v2, 15
	v_pk_fma_f32 v[20:21], v[150:151], s[34:35], v[20:21] op_sel_hi:[1,0,1]
	v_readlane_b32 s24, v3, 0
	v_pk_fma_f32 v[20:21], v[166:167], s[36:37], v[20:21] op_sel_hi:[1,0,1]
	s_waitcnt vmcnt(15)
	v_cvt_scalef32_pk_f32_fp4 v[50:51], v30, 1.0
	v_pk_fma_f32 v[20:21], v[182:183], s[38:39], v[20:21] op_sel_hi:[1,0,1]
	v_pk_fma_f32 v[16:17], v[44:45], s[20:21], v[16:17] op_sel_hi:[1,0,1]
	v_pk_fma_f32 v[20:21], v[202:203], s[56:57], v[20:21] op_sel_hi:[1,0,1]
	v_pk_fma_f32 v[10:11], v[120:121], s[28:29], v[10:11] op_sel_hi:[1,0,1]
	v_pk_fma_f32 v[20:21], v[230:231], s[62:63], v[20:21] op_sel_hi:[1,0,1]
	v_pk_fma_f32 v[12:13], v[122:123], s[28:29], v[12:13] op_sel_hi:[1,0,1]
	v_pk_fma_f32 v[8:9], v[8:9], s[20:21], v[20:21] op_sel_hi:[1,0,1]
	v_pk_fma_f32 v[14:15], v[124:125], s[28:29], v[14:15] op_sel_hi:[1,0,1]
	v_pk_fma_f32 v[8:9], v[82:83], s[22:23], v[8:9] op_sel_hi:[1,0,1]
	v_cvt_scalef32_pk_f32_fp4 v[118:119], v31, 1.0
	v_readlane_b32 s26, v3, 1
	s_waitcnt vmcnt(13)
	v_cvt_scalef32_pk_f32_fp4 v[124:125], v24, 1.0
	v_pk_fma_f32 v[8:9], v[50:51], s[24:25], v[8:9] op_sel_hi:[1,0,1]
	v_pk_fma_f32 v[16:17], v[90:91], s[22:23], v[16:17] op_sel_hi:[1,0,1]
	v_pk_fma_f32 v[10:11], v[136:137], s[30:31], v[10:11] op_sel_hi:[1,0,1]
	v_pk_fma_f32 v[12:13], v[138:139], s[30:31], v[12:13] op_sel_hi:[1,0,1]
	v_cvt_scalef32_pk_f32_fp4 v[126:127], v24, 1.0 op_sel:[1,0,0]
	v_cvt_scalef32_pk_f32_fp4 v[128:129], v24, 1.0 op_sel:[0,1,0]
	v_cvt_scalef32_pk_f32_fp4 v[130:131], v24, 1.0 op_sel:[1,1,0]
	v_cvt_scalef32_pk_f32_fp4 v[132:133], v25, 1.0
	v_cvt_scalef32_pk_f32_fp4 v[134:135], v25, 1.0 op_sel:[1,0,0]
	v_cvt_scalef32_pk_f32_fp4 v[136:137], v25, 1.0 op_sel:[0,1,0]
	v_cvt_scalef32_pk_f32_fp4 v[138:139], v25, 1.0 op_sel:[1,1,0]
	v_readlane_b32 s28, v3, 2
	s_waitcnt vmcnt(12)
	v_cvt_scalef32_pk_f32_fp4 v[24:25], v32, 1.0
	v_pk_fma_f32 v[8:9], v[124:125], s[26:27], v[8:9] op_sel_hi:[1,0,1]
	v_pk_fma_f32 v[16:17], v[118:119], s[24:25], v[16:17] op_sel_hi:[1,0,1]
	v_pk_fma_f32 v[10:11], v[152:153], s[34:35], v[10:11] op_sel_hi:[1,0,1]
	v_pk_fma_f32 v[14:15], v[140:141], s[30:31], v[14:15] op_sel_hi:[1,0,1]
	v_cvt_scalef32_pk_f32_fp4 v[146:147], v33, 1.0
	v_readlane_b32 s30, v3, 3
	v_cvt_scalef32_pk_f32_fp4 v[152:153], v38, 1.0
	v_pk_fma_f32 v[8:9], v[24:25], s[28:29], v[8:9] op_sel_hi:[1,0,1]
	v_pk_fma_f32 v[16:17], v[132:133], s[26:27], v[16:17] op_sel_hi:[1,0,1]
	v_pk_fma_f32 v[12:13], v[154:155], s[34:35], v[12:13] op_sel_hi:[1,0,1]
	v_pk_fma_f32 v[14:15], v[156:157], s[34:35], v[14:15] op_sel_hi:[1,0,1]
	v_cvt_scalef32_pk_f32_fp4 v[160:161], v39, 1.0
	v_readlane_b32 s34, v3, 4
	s_waitcnt vmcnt(11)
	v_cvt_scalef32_pk_f32_fp4 v[166:167], v80, 1.0
	v_pk_fma_f32 v[8:9], v[152:153], s[30:31], v[8:9] op_sel_hi:[1,0,1]
	v_pk_fma_f32 v[16:17], v[146:147], s[28:29], v[16:17] op_sel_hi:[1,0,1]
	v_pk_fma_f32 v[10:11], v[168:169], s[36:37], v[10:11] op_sel_hi:[1,0,1]
	v_pk_fma_f32 v[12:13], v[170:171], s[36:37], v[12:13] op_sel_hi:[1,0,1]
	v_pk_fma_f32 v[14:15], v[172:173], s[36:37], v[14:15] op_sel_hi:[1,0,1]
	v_cvt_scalef32_pk_f32_fp4 v[174:175], v81, 1.0
	v_readlane_b32 s36, v3, 5
	s_waitcnt vmcnt(10)
	v_cvt_scalef32_pk_f32_fp4 v[180:181], v92, 1.0
	v_pk_fma_f32 v[8:9], v[166:167], s[34:35], v[8:9] op_sel_hi:[1,0,1]
	v_pk_fma_f32 v[16:17], v[160:161], s[30:31], v[16:17] op_sel_hi:[1,0,1]
	v_pk_fma_f32 v[10:11], v[184:185], s[38:39], v[10:11] op_sel_hi:[1,0,1]
	v_pk_fma_f32 v[12:13], v[186:187], s[38:39], v[12:13] op_sel_hi:[1,0,1]
	v_pk_fma_f32 v[14:15], v[188:189], s[38:39], v[14:15] op_sel_hi:[1,0,1]
	v_cvt_scalef32_pk_f32_fp4 v[188:189], v93, 1.0
	v_readlane_b32 s38, v3, 6
	s_waitcnt vmcnt(9)
	v_cvt_scalef32_pk_f32_fp4 v[198:199], v100, 1.0
	v_pk_fma_f32 v[8:9], v[180:181], s[36:37], v[8:9] op_sel_hi:[1,0,1]
	v_pk_fma_f32 v[16:17], v[174:175], s[34:35], v[16:17] op_sel_hi:[1,0,1]
	v_pk_fma_f32 v[10:11], v[204:205], s[56:57], v[10:11] op_sel_hi:[1,0,1]
	v_pk_fma_f32 v[12:13], v[206:207], s[56:57], v[12:13] op_sel_hi:[1,0,1]
	v_pk_fma_f32 v[14:15], v[208:209], s[56:57], v[14:15] op_sel_hi:[1,0,1]
	v_cvt_scalef32_pk_f32_fp4 v[206:207], v101, 1.0
	v_readlane_b32 s56, v3, 7
	s_waitcnt vmcnt(8)
	v_cvt_scalef32_pk_f32_fp4 v[214:215], v102, 1.0
	v_pk_fma_f32 v[8:9], v[198:199], s[38:39], v[8:9] op_sel_hi:[1,0,1]
	v_pk_fma_f32 v[16:17], v[188:189], s[36:37], v[16:17] op_sel_hi:[1,0,1]
	v_pk_fma_f32 v[10:11], v[232:233], s[62:63], v[10:11] op_sel_hi:[1,0,1]
	v_pk_fma_f32 v[12:13], v[234:235], s[62:63], v[12:13] op_sel_hi:[1,0,1]
	v_pk_fma_f32 v[14:15], v[236:237], s[62:63], v[14:15] op_sel_hi:[1,0,1]
	v_cvt_scalef32_pk_f32_fp4 v[232:233], v103, 1.0
	v_readlane_b32 s62, v3, 8
	s_waitcnt vmcnt(7)
	v_cvt_scalef32_pk_f32_fp4 v[238:239], v104, 1.0
	v_pk_fma_f32 v[8:9], v[214:215], s[56:57], v[8:9] op_sel_hi:[1,0,1]
	v_pk_fma_f32 v[16:17], v[206:207], s[38:39], v[16:17] op_sel_hi:[1,0,1]
	v_pk_fma_f32 v[24:25], v[238:239], s[62:63], v[8:9] op_sel_hi:[1,0,1]
	v_pk_fma_f32 v[8:9], v[36:37], s[20:21], v[10:11] op_sel_hi:[1,0,1]
	v_pk_fma_f32 v[10:11], v[40:41], s[20:21], v[12:13] op_sel_hi:[1,0,1]
	v_pk_fma_f32 v[12:13], v[42:43], s[20:21], v[14:15] op_sel_hi:[1,0,1]
	v_cvt_scalef32_pk_f32_fp4 v[14:15], v105, 1.0
	v_pk_fma_f32 v[16:17], v[232:233], s[56:57], v[16:17] op_sel_hi:[1,0,1]
	v_cvt_scalef32_pk_f32_fp4 v[120:121], v31, 1.0 op_sel:[1,0,0]
	v_pk_fma_f32 v[14:15], v[14:15], s[62:63], v[16:17] op_sel_hi:[1,0,1]
	v_pk_fma_f32 v[16:17], v[52:53], s[20:21], v[18:19] op_sel_hi:[1,0,1]
	v_cvt_scalef32_pk_f32_fp4 v[148:149], v33, 1.0 op_sel:[1,0,0]
	v_pk_fma_f32 v[16:17], v[94:95], s[22:23], v[16:17] op_sel_hi:[1,0,1]
	v_cvt_scalef32_pk_f32_fp4 v[162:163], v39, 1.0 op_sel:[1,0,0]
	v_pk_fma_f32 v[16:17], v[120:121], s[24:25], v[16:17] op_sel_hi:[1,0,1]
	v_cvt_scalef32_pk_f32_fp4 v[176:177], v81, 1.0 op_sel:[1,0,0]
	v_pk_fma_f32 v[16:17], v[134:135], s[26:27], v[16:17] op_sel_hi:[1,0,1]
	v_cvt_scalef32_pk_f32_fp4 v[190:191], v93, 1.0 op_sel:[1,0,0]
	v_pk_fma_f32 v[16:17], v[148:149], s[28:29], v[16:17] op_sel_hi:[1,0,1]
	v_pk_fma_f32 v[18:19], v[54:55], s[20:21], v[28:29] op_sel_hi:[1,0,1]
	v_pk_fma_f32 v[16:17], v[162:163], s[30:31], v[16:17] op_sel_hi:[1,0,1]
	v_cvt_scalef32_pk_f32_fp4 v[122:123], v31, 1.0 op_sel:[0,1,0]
	v_pk_fma_f32 v[16:17], v[176:177], s[34:35], v[16:17] op_sel_hi:[1,0,1]
	v_cvt_scalef32_pk_f32_fp4 v[208:209], v101, 1.0 op_sel:[1,0,0]
	v_pk_fma_f32 v[16:17], v[190:191], s[36:37], v[16:17] op_sel_hi:[1,0,1]
	v_pk_fma_f32 v[18:19], v[96:97], s[22:23], v[18:19] op_sel_hi:[1,0,1]
	v_cvt_scalef32_pk_f32_fp4 v[234:235], v103, 1.0 op_sel:[1,0,0]
	v_pk_fma_f32 v[16:17], v[208:209], s[38:39], v[16:17] op_sel_hi:[1,0,1]
	v_pk_fma_f32 v[18:19], v[122:123], s[24:25], v[18:19] op_sel_hi:[1,0,1]
	v_cvt_scalef32_pk_f32_fp4 v[150:151], v33, 1.0 op_sel:[0,1,0]
	v_cvt_scalef32_pk_f32_fp4 v[20:21], v105, 1.0 op_sel:[1,0,0]
	v_pk_fma_f32 v[16:17], v[234:235], s[56:57], v[16:17] op_sel_hi:[1,0,1]
	v_pk_fma_f32 v[18:19], v[136:137], s[26:27], v[18:19] op_sel_hi:[1,0,1]
	v_cvt_scalef32_pk_f32_fp4 v[164:165], v39, 1.0 op_sel:[0,1,0]
	v_pk_fma_f32 v[16:17], v[20:21], s[62:63], v[16:17] op_sel_hi:[1,0,1]
	v_pk_fma_f32 v[18:19], v[150:151], s[28:29], v[18:19] op_sel_hi:[1,0,1]
	v_pk_fma_f32 v[20:21], v[56:57], s[20:21], v[22:23] op_sel_hi:[1,0,1]
	v_cvt_scalef32_pk_f32_fp4 v[112:113], v30, 1.0 op_sel:[1,0,0]
	v_cvt_scalef32_pk_f32_fp4 v[114:115], v30, 1.0 op_sel:[0,1,0]
	v_cvt_scalef32_pk_f32_fp4 v[116:117], v30, 1.0 op_sel:[1,1,0]
	v_cvt_scalef32_pk_f32_fp4 v[30:31], v31, 1.0 op_sel:[1,1,0]
	v_cvt_scalef32_pk_f32_fp4 v[178:179], v81, 1.0 op_sel:[0,1,0]
	v_pk_fma_f32 v[18:19], v[164:165], s[30:31], v[18:19] op_sel_hi:[1,0,1]
	v_pk_fma_f32 v[20:21], v[98:99], s[22:23], v[20:21] op_sel_hi:[1,0,1]
	v_cvt_scalef32_pk_f32_fp4 v[196:197], v93, 1.0 op_sel:[0,1,0]
	v_pk_fma_f32 v[18:19], v[178:179], s[34:35], v[18:19] op_sel_hi:[1,0,1]
	v_pk_fma_f32 v[20:21], v[30:31], s[24:25], v[20:21] op_sel_hi:[1,0,1]
	v_cvt_scalef32_pk_f32_fp4 v[140:141], v32, 1.0 op_sel:[1,0,0]
	v_cvt_scalef32_pk_f32_fp4 v[142:143], v32, 1.0 op_sel:[0,1,0]
	v_cvt_scalef32_pk_f32_fp4 v[144:145], v32, 1.0 op_sel:[1,1,0]
	v_cvt_scalef32_pk_f32_fp4 v[32:33], v33, 1.0 op_sel:[1,1,0]
	v_cvt_scalef32_pk_f32_fp4 v[210:211], v101, 1.0 op_sel:[0,1,0]
	v_pk_fma_f32 v[18:19], v[196:197], s[36:37], v[18:19] op_sel_hi:[1,0,1]
	v_pk_fma_f32 v[20:21], v[138:139], s[26:27], v[20:21] op_sel_hi:[1,0,1]
	v_cvt_scalef32_pk_f32_fp4 v[154:155], v38, 1.0 op_sel:[1,0,0]
	v_cvt_scalef32_pk_f32_fp4 v[156:157], v38, 1.0 op_sel:[0,1,0]
	v_cvt_scalef32_pk_f32_fp4 v[158:159], v38, 1.0 op_sel:[1,1,0]
	v_cvt_scalef32_pk_f32_fp4 v[38:39], v39, 1.0 op_sel:[1,1,0]
	v_cvt_scalef32_pk_f32_fp4 v[236:237], v103, 1.0 op_sel:[0,1,0]
	v_pk_fma_f32 v[8:9], v[84:85], s[22:23], v[8:9] op_sel_hi:[1,0,1]
	v_pk_fma_f32 v[10:11], v[86:87], s[22:23], v[10:11] op_sel_hi:[1,0,1]
	v_pk_fma_f32 v[12:13], v[88:89], s[22:23], v[12:13] op_sel_hi:[1,0,1]
	v_pk_fma_f32 v[18:19], v[210:211], s[38:39], v[18:19] op_sel_hi:[1,0,1]
	v_pk_fma_f32 v[20:21], v[32:33], s[28:29], v[20:21] op_sel_hi:[1,0,1]
	v_readlane_b32 s23, v49, 0
	v_cvt_scalef32_pk_f32_fp4 v[168:169], v80, 1.0 op_sel:[1,0,0]
	v_cvt_scalef32_pk_f32_fp4 v[170:171], v80, 1.0 op_sel:[0,1,0]
	v_cvt_scalef32_pk_f32_fp4 v[172:173], v80, 1.0 op_sel:[1,1,0]
	v_cvt_scalef32_pk_f32_fp4 v[80:81], v81, 1.0 op_sel:[1,1,0]
	v_cvt_scalef32_pk_f32_fp4 v[36:37], v105, 1.0 op_sel:[0,1,0]
	v_pk_fma_f32 v[18:19], v[236:237], s[56:57], v[18:19] op_sel_hi:[1,0,1]
	v_pk_fma_f32 v[20:21], v[38:39], s[30:31], v[20:21] op_sel_hi:[1,0,1]
	v_pk_fma_f32 v[18:19], v[36:37], s[62:63], v[18:19] op_sel_hi:[1,0,1]
	v_pk_fma_f32 v[20:21], v[80:81], s[34:35], v[20:21] op_sel_hi:[1,0,1]
	s_waitcnt vmcnt(5)
	v_cvt_scalef32_pk_f32_fp4 v[54:55], v108, 1.0
	v_cvt_scalef32_pk_f32_fp4 v[56:57], v108, 1.0 op_sel:[1,0,0]
	v_cvt_scalef32_pk_f32_fp4 v[80:81], v108, 1.0 op_sel:[0,1,0]
	v_cvt_scalef32_pk_f32_fp4 v[82:83], v108, 1.0 op_sel:[1,1,0]
	v_cvt_scalef32_pk_f32_fp4 v[84:85], v109, 1.0
	v_cvt_scalef32_pk_f32_fp4 v[86:87], v109, 1.0 op_sel:[1,0,0]
	v_cvt_scalef32_pk_f32_fp4 v[36:37], v109, 1.0 op_sel:[0,1,0]
	v_cvt_scalef32_pk_f32_fp4 v[28:29], v109, 1.0 op_sel:[1,1,0]
	buffer_load_dwordx2 v[108:109], v192, s[4:7], s23 offen
	v_readlane_b32 s23, v49, 1
	v_pk_fma_f32 v[10:11], v[114:115], s[24:25], v[10:11] op_sel_hi:[1,0,1]
	v_pk_fma_f32 v[12:13], v[116:117], s[24:25], v[12:13] op_sel_hi:[1,0,1]
	v_pk_fma_f32 v[10:11], v[128:129], s[26:27], v[10:11] op_sel_hi:[1,0,1]
	v_pk_fma_f32 v[8:9], v[112:113], s[24:25], v[8:9] op_sel_hi:[1,0,1]
	s_nop 0
	buffer_load_dwordx2 v[118:119], v192, s[4:7], s23 offen
	v_readlane_b32 s23, v49, 2
	v_pk_fma_f32 v[10:11], v[142:143], s[28:29], v[10:11] op_sel_hi:[1,0,1]
	v_pk_fma_f32 v[12:13], v[130:131], s[26:27], v[12:13] op_sel_hi:[1,0,1]
	v_pk_fma_f32 v[8:9], v[126:127], s[26:27], v[8:9] op_sel_hi:[1,0,1]
	v_pk_fma_f32 v[12:13], v[144:145], s[28:29], v[12:13] op_sel_hi:[1,0,1]
	s_nop 0
	buffer_load_dwordx2 v[132:133], v192, s[4:7], s23 offen
	v_readlane_b32 s23, v49, 3
	v_pk_fma_f32 v[8:9], v[140:141], s[28:29], v[8:9] op_sel_hi:[1,0,1]
	v_pk_fma_f32 v[10:11], v[156:157], s[30:31], v[10:11] op_sel_hi:[1,0,1]
	v_pk_fma_f32 v[12:13], v[158:159], s[30:31], v[12:13] op_sel_hi:[1,0,1]
	v_readlane_b32 s25, v49, 5
	s_nop 0
	buffer_load_dwordx2 v[142:143], v192, s[4:7], s23 offen
	v_readlane_b32 s23, v49, 4
	v_readlane_b32 s27, v49, 6
	v_readlane_b32 s29, v49, 7
	v_pk_fma_f32 v[10:11], v[170:171], s[34:35], v[10:11] op_sel_hi:[1,0,1]
	v_pk_fma_f32 v[12:13], v[172:173], s[34:35], v[12:13] op_sel_hi:[1,0,1]
	s_nop 0
	buffer_load_dwordx2 v[170:171], v192, s[4:7], s23 offen
	buffer_load_dwordx2 v[172:173], v192, s[4:7], s25 offen
	buffer_load_dwordx2 v[174:175], v192, s[4:7], s27 offen
	buffer_load_dwordx2 v[176:177], v192, s[4:7], s29 offen
	v_pk_fma_f32 v[8:9], v[154:155], s[30:31], v[8:9] op_sel_hi:[1,0,1]
	v_readlane_b32 s23, v49, 8
	v_cvt_scalef32_pk_f32_fp4 v[182:183], v92, 1.0 op_sel:[1,0,0]
	v_cvt_scalef32_pk_f32_fp4 v[184:185], v92, 1.0 op_sel:[0,1,0]
	v_pk_fma_f32 v[8:9], v[168:169], s[34:35], v[8:9] op_sel_hi:[1,0,1]
	v_readlane_b32 s25, v49, 9
	v_readlane_b32 s27, v49, 10
	v_readlane_b32 s29, v49, 11
	v_pk_fma_f32 v[8:9], v[182:183], s[36:37], v[8:9] op_sel_hi:[1,0,1]
	v_pk_fma_f32 v[10:11], v[184:185], s[36:37], v[10:11] op_sel_hi:[1,0,1]
	buffer_load_dwordx2 v[178:179], v192, s[4:7], s23 offen
	buffer_load_dwordx2 v[180:181], v192, s[4:7], s25 offen
	buffer_load_dwordx2 v[182:183], v192, s[4:7], s27 offen
	buffer_load_dwordx2 v[184:185], v192, s[4:7], s29 offen
	v_readlane_b32 s23, v49, 12
	v_cvt_scalef32_pk_f32_fp4 v[186:187], v92, 1.0 op_sel:[1,1,0]
	v_readlane_b32 s25, v49, 13
	v_readlane_b32 s27, v49, 14
	v_readlane_b32 s29, v49, 15
	v_pk_fma_f32 v[12:13], v[186:187], s[36:37], v[12:13] op_sel_hi:[1,0,1]
	v_readlane_b32 s20, v3, 9
	v_readlane_b32 s22, v3, 10
	v_readlane_b32 s24, v3, 11
	v_readlane_b32 s26, v3, 12
	v_readlane_b32 s28, v3, 13
	v_readlane_b32 s30, v3, 14
	s_waitcnt vmcnt(13)
	v_cvt_scalef32_pk_f32_fp4 v[136:137], v6, 1.0
	v_cvt_scalef32_pk_f32_fp4 v[138:139], v6, 1.0 op_sel:[1,0,0]
	v_cvt_scalef32_pk_f32_fp4 v[140:141], v6, 1.0 op_sel:[0,1,0]
	v_cvt_scalef32_pk_f32_fp4 v[144:145], v6, 1.0 op_sel:[1,1,0]
	v_cvt_scalef32_pk_f32_fp4 v[146:147], v7, 1.0
	v_cvt_scalef32_pk_f32_fp4 v[148:149], v7, 1.0 op_sel:[1,0,0]
	v_cvt_scalef32_pk_f32_fp4 v[150:151], v7, 1.0 op_sel:[0,1,0]
	v_cvt_scalef32_pk_f32_fp4 v[152:153], v7, 1.0 op_sel:[1,1,0]
	v_readlane_b32 s34, v3, 15
	s_waitcnt vmcnt(12)
	v_cvt_scalef32_pk_f32_fp4 v[154:155], v4, 1.0
	v_cvt_scalef32_pk_f32_fp4 v[156:157], v4, 1.0 op_sel:[1,0,0]
	v_cvt_scalef32_pk_f32_fp4 v[158:159], v4, 1.0 op_sel:[0,1,0]
	v_cvt_scalef32_pk_f32_fp4 v[160:161], v4, 1.0 op_sel:[1,1,0]
	v_cvt_scalef32_pk_f32_fp4 v[162:163], v5, 1.0
	v_cvt_scalef32_pk_f32_fp4 v[164:165], v5, 1.0 op_sel:[1,0,0]
	v_cvt_scalef32_pk_f32_fp4 v[166:167], v5, 1.0 op_sel:[0,1,0]
	v_cvt_scalef32_pk_f32_fp4 v[168:169], v5, 1.0 op_sel:[1,1,0]
	ds_read2_b32 v[2:3], v47 offset0:64 offset1:80
	buffer_load_dwordx2 v[186:187], v192, s[4:7], s23 offen
	buffer_load_dwordx2 v[188:189], v192, s[4:7], s25 offen
	buffer_load_dwordx2 v[6:7], v192, s[4:7], s27 offen
	buffer_load_dwordx2 v[4:5], v192, s[4:7], s29 offen
	v_cvt_scalef32_pk_f32_fp4 v[38:39], v107, 1.0 op_sel:[1,0,0]
	v_pk_fma_f32 v[16:17], v[38:39], s[20:21], v[16:17] op_sel_hi:[1,0,1]
	v_cvt_scalef32_pk_f32_fp4 v[98:99], v111, 1.0 op_sel:[1,0,0]
	v_pk_fma_f32 v[16:17], v[86:87], s[22:23], v[16:17] op_sel_hi:[1,0,1]
	v_cvt_scalef32_pk_f32_fp4 v[114:115], v35, 1.0 op_sel:[1,0,0]
	v_pk_fma_f32 v[16:17], v[98:99], s[24:25], v[16:17] op_sel_hi:[1,0,1]
	v_cvt_scalef32_pk_f32_fp4 v[130:131], v27, 1.0 op_sel:[1,0,0]
	v_pk_fma_f32 v[16:17], v[114:115], s[26:27], v[16:17] op_sel_hi:[1,0,1]
	v_cvt_scalef32_pk_f32_fp4 v[92:93], v93, 1.0 op_sel:[1,1,0]
	v_pk_fma_f32 v[16:17], v[130:131], s[28:29], v[16:17] op_sel_hi:[1,0,1]
	v_cvt_scalef32_pk_f32_fp4 v[200:201], v100, 1.0 op_sel:[1,0,0]
	v_cvt_scalef32_pk_f32_fp4 v[204:205], v100, 1.0 op_sel:[1,1,0]
	v_pk_fma_f32 v[16:17], v[148:149], s[30:31], v[16:17] op_sel_hi:[1,0,1]
	v_cvt_scalef32_pk_f32_fp4 v[202:203], v100, 1.0 op_sel:[0,1,0]
	v_cvt_scalef32_pk_f32_fp4 v[100:101], v101, 1.0 op_sel:[1,1,0]
	v_cvt_scalef32_pk_f32_fp4 v[216:217], v102, 1.0 op_sel:[1,0,0]
	v_cvt_scalef32_pk_f32_fp4 v[230:231], v102, 1.0 op_sel:[1,1,0]
	v_pk_fma_f32 v[8:9], v[200:201], s[38:39], v[8:9] op_sel_hi:[1,0,1]
	v_pk_fma_f32 v[12:13], v[204:205], s[38:39], v[12:13] op_sel_hi:[1,0,1]
	v_pk_fma_f32 v[20:21], v[92:93], s[36:37], v[20:21] op_sel_hi:[1,0,1]
	s_waitcnt lgkmcnt(0)
	v_readlane_b32 s36, v2, 0
	s_waitcnt vmcnt(15)
	v_cvt_scalef32_pk_f32_fp4 v[204:205], v109, 1.0 op_sel:[1,0,0]
	v_pk_fma_f32 v[16:17], v[164:165], s[34:35], v[16:17] op_sel_hi:[1,0,1]
	v_cvt_scalef32_pk_f32_fp4 v[228:229], v102, 1.0 op_sel:[0,1,0]
	v_cvt_scalef32_pk_f32_fp4 v[102:103], v103, 1.0 op_sel:[1,1,0]
	v_cvt_scalef32_pk_f32_fp4 v[240:241], v104, 1.0 op_sel:[1,0,0]
	v_cvt_scalef32_pk_f32_fp4 v[244:245], v104, 1.0 op_sel:[1,1,0]
	v_pk_fma_f32 v[8:9], v[216:217], s[56:57], v[8:9] op_sel_hi:[1,0,1]
	v_pk_fma_f32 v[10:11], v[202:203], s[38:39], v[10:11] op_sel_hi:[1,0,1]
	v_pk_fma_f32 v[12:13], v[230:231], s[56:57], v[12:13] op_sel_hi:[1,0,1]
	v_pk_fma_f32 v[20:21], v[100:101], s[38:39], v[20:21] op_sel_hi:[1,0,1]
	v_readlane_b32 s38, v2, 1
	s_waitcnt vmcnt(14)
	v_cvt_scalef32_pk_f32_fp4 v[230:231], v119, 1.0 op_sel:[1,0,0]
	v_pk_fma_f32 v[16:17], v[204:205], s[36:37], v[16:17] op_sel_hi:[1,0,1]
	v_cvt_scalef32_pk_f32_fp4 v[242:243], v104, 1.0 op_sel:[0,1,0]
	v_pk_fma_f32 v[8:9], v[240:241], s[62:63], v[8:9] op_sel_hi:[1,0,1]
	v_pk_fma_f32 v[10:11], v[228:229], s[56:57], v[10:11] op_sel_hi:[1,0,1]
	v_pk_fma_f32 v[12:13], v[244:245], s[62:63], v[12:13] op_sel_hi:[1,0,1]
	v_cvt_scalef32_pk_f32_fp4 v[40:41], v105, 1.0 op_sel:[1,1,0]
	v_pk_fma_f32 v[20:21], v[102:103], s[56:57], v[20:21] op_sel_hi:[1,0,1]
	v_cvt_scalef32_pk_f32_fp4 v[42:43], v106, 1.0 op_sel:[1,0,0]
	v_readlane_b32 s56, v2, 2
	s_waitcnt vmcnt(13)
	v_cvt_scalef32_pk_f32_fp4 v[244:245], v133, 1.0 op_sel:[1,0,0]
	v_pk_fma_f32 v[16:17], v[230:231], s[38:39], v[16:17] op_sel_hi:[1,0,1]
	v_pk_fma_f32 v[10:11], v[242:243], s[62:63], v[10:11] op_sel_hi:[1,0,1]
	v_pk_fma_f32 v[20:21], v[40:41], s[62:63], v[20:21] op_sel_hi:[1,0,1]
	v_cvt_scalef32_pk_f32_fp4 v[30:31], v107, 1.0 op_sel:[0,1,0]
	v_readlane_b32 s62, v2, 3
	v_pk_fma_f32 v[8:9], v[42:43], s[20:21], v[8:9] op_sel_hi:[1,0,1]
	s_waitcnt vmcnt(12)
	v_cvt_scalef32_pk_f32_fp4 v[42:43], v143, 1.0 op_sel:[1,0,0]
	v_pk_fma_f32 v[16:17], v[244:245], s[56:57], v[16:17] op_sel_hi:[1,0,1]
	v_cvt_scalef32_pk_f32_fp4 v[100:101], v111, 1.0 op_sel:[0,1,0]
	v_pk_fma_f32 v[38:39], v[42:43], s[62:63], v[16:17] op_sel_hi:[1,0,1]
	v_pk_fma_f32 v[16:17], v[30:31], s[20:21], v[18:19] op_sel_hi:[1,0,1]
	v_cvt_scalef32_pk_f32_fp4 v[52:53], v107, 1.0
	v_pk_fma_f32 v[16:17], v[36:37], s[22:23], v[16:17] op_sel_hi:[1,0,1]
	v_cvt_scalef32_pk_f32_fp4 v[116:117], v35, 1.0 op_sel:[0,1,0]
	v_pk_fma_f32 v[16:17], v[100:101], s[24:25], v[16:17] op_sel_hi:[1,0,1]
	v_cvt_scalef32_pk_f32_fp4 v[90:91], v110, 1.0 op_sel:[1,0,0]
	v_cvt_scalef32_pk_f32_fp4 v[134:135], v27, 1.0 op_sel:[0,1,0]
	v_pk_fma_f32 v[8:9], v[56:57], s[22:23], v[8:9] op_sel_hi:[1,0,1]
	v_pk_fma_f32 v[14:15], v[52:53], s[20:21], v[14:15] op_sel_hi:[1,0,1]
	v_pk_fma_f32 v[16:17], v[116:117], s[26:27], v[16:17] op_sel_hi:[1,0,1]
	v_cvt_scalef32_pk_f32_fp4 v[96:97], v111, 1.0
	v_cvt_scalef32_pk_f32_fp4 v[104:105], v34, 1.0 op_sel:[1,0,0]
	v_pk_fma_f32 v[8:9], v[90:91], s[24:25], v[8:9] op_sel_hi:[1,0,1]
	v_pk_fma_f32 v[14:15], v[84:85], s[22:23], v[14:15] op_sel_hi:[1,0,1]
	v_pk_fma_f32 v[16:17], v[134:135], s[28:29], v[16:17] op_sel_hi:[1,0,1]
	v_cvt_scalef32_pk_f32_fp4 v[112:113], v35, 1.0
	v_cvt_scalef32_pk_f32_fp4 v[122:123], v26, 1.0 op_sel:[1,0,0]
	v_pk_fma_f32 v[8:9], v[104:105], s[26:27], v[8:9] op_sel_hi:[1,0,1]
	v_pk_fma_f32 v[14:15], v[96:97], s[24:25], v[14:15] op_sel_hi:[1,0,1]
	v_pk_fma_f32 v[16:17], v[150:151], s[30:31], v[16:17] op_sel_hi:[1,0,1]
	v_cvt_scalef32_pk_f32_fp4 v[128:129], v27, 1.0
	v_cvt_scalef32_pk_f32_fp4 v[206:207], v109, 1.0 op_sel:[0,1,0]
	v_pk_fma_f32 v[8:9], v[122:123], s[28:29], v[8:9] op_sel_hi:[1,0,1]
	v_pk_fma_f32 v[14:15], v[112:113], s[26:27], v[14:15] op_sel_hi:[1,0,1]
	v_pk_fma_f32 v[16:17], v[166:167], s[34:35], v[16:17] op_sel_hi:[1,0,1]
	v_cvt_scalef32_pk_f32_fp4 v[232:233], v119, 1.0 op_sel:[0,1,0]
	v_pk_fma_f32 v[8:9], v[138:139], s[30:31], v[8:9] op_sel_hi:[1,0,1]
	v_pk_fma_f32 v[14:15], v[128:129], s[28:29], v[14:15] op_sel_hi:[1,0,1]
	v_pk_fma_f32 v[16:17], v[206:207], s[36:37], v[16:17] op_sel_hi:[1,0,1]
	v_cvt_scalef32_pk_f32_fp4 v[44:45], v106, 1.0 op_sel:[0,1,0]
	v_cvt_scalef32_pk_f32_fp4 v[196:197], v108, 1.0 op_sel:[1,0,0]
	v_cvt_scalef32_pk_f32_fp4 v[246:247], v133, 1.0 op_sel:[0,1,0]
	v_pk_fma_f32 v[8:9], v[156:157], s[34:35], v[8:9] op_sel_hi:[1,0,1]
	v_pk_fma_f32 v[14:15], v[146:147], s[30:31], v[14:15] op_sel_hi:[1,0,1]
	v_pk_fma_f32 v[16:17], v[232:233], s[38:39], v[16:17] op_sel_hi:[1,0,1]
	v_cvt_scalef32_pk_f32_fp4 v[22:23], v107, 1.0 op_sel:[1,1,0]
	v_cvt_scalef32_pk_f32_fp4 v[202:203], v109, 1.0
	v_cvt_scalef32_pk_f32_fp4 v[210:211], v118, 1.0 op_sel:[1,0,0]
	v_pk_fma_f32 v[8:9], v[196:197], s[36:37], v[8:9] op_sel_hi:[1,0,1]
	v_pk_fma_f32 v[10:11], v[44:45], s[20:21], v[10:11] op_sel_hi:[1,0,1]
	v_cvt_scalef32_pk_f32_fp4 v[44:45], v143, 1.0 op_sel:[0,1,0]
	v_pk_fma_f32 v[14:15], v[162:163], s[34:35], v[14:15] op_sel_hi:[1,0,1]
	v_pk_fma_f32 v[16:17], v[246:247], s[56:57], v[16:17] op_sel_hi:[1,0,1]
	v_cvt_scalef32_pk_f32_fp4 v[40:41], v106, 1.0
	v_cvt_scalef32_pk_f32_fp4 v[228:229], v119, 1.0
	v_cvt_scalef32_pk_f32_fp4 v[236:237], v132, 1.0 op_sel:[1,0,0]
	v_pk_fma_f32 v[8:9], v[210:211], s[38:39], v[8:9] op_sel_hi:[1,0,1]
	v_pk_fma_f32 v[14:15], v[202:203], s[36:37], v[14:15] op_sel_hi:[1,0,1]
	v_pk_fma_f32 v[18:19], v[44:45], s[62:63], v[16:17] op_sel_hi:[1,0,1]
	v_pk_fma_f32 v[16:17], v[22:23], s[20:21], v[20:21] op_sel_hi:[1,0,1]
	v_cvt_scalef32_pk_f32_fp4 v[32:33], v111, 1.0 op_sel:[1,1,0]
	v_cvt_scalef32_pk_f32_fp4 v[242:243], v133, 1.0
	v_pk_fma_f32 v[24:25], v[40:41], s[20:21], v[24:25] op_sel_hi:[1,0,1]
	v_cvt_scalef32_pk_f32_fp4 v[40:41], v142, 1.0 op_sel:[1,0,0]
	v_pk_fma_f32 v[8:9], v[236:237], s[56:57], v[8:9] op_sel_hi:[1,0,1]
	v_pk_fma_f32 v[14:15], v[228:229], s[38:39], v[14:15] op_sel_hi:[1,0,1]
	v_pk_fma_f32 v[16:17], v[28:29], s[22:23], v[16:17] op_sel_hi:[1,0,1]
	v_cvt_scalef32_pk_f32_fp4 v[50:51], v106, 1.0 op_sel:[1,1,0]
	v_cvt_scalef32_pk_f32_fp4 v[88:89], v110, 1.0
	v_cvt_scalef32_pk_f32_fp4 v[92:93], v110, 1.0 op_sel:[0,1,0]
	v_cvt_scalef32_pk_f32_fp4 v[94:95], v110, 1.0 op_sel:[1,1,0]
	v_cvt_scalef32_pk_f32_fp4 v[102:103], v34, 1.0
	v_cvt_scalef32_pk_f32_fp4 v[106:107], v34, 1.0 op_sel:[0,1,0]
	v_cvt_scalef32_pk_f32_fp4 v[110:111], v34, 1.0 op_sel:[1,1,0]
	v_cvt_scalef32_pk_f32_fp4 v[34:35], v35, 1.0 op_sel:[1,1,0]
	v_pk_fma_f32 v[8:9], v[40:41], s[62:63], v[8:9] op_sel_hi:[1,0,1]
	v_cvt_scalef32_pk_f32_fp4 v[40:41], v143, 1.0
	v_pk_fma_f32 v[14:15], v[242:243], s[56:57], v[14:15] op_sel_hi:[1,0,1]
	v_pk_fma_f32 v[16:17], v[32:33], s[24:25], v[16:17] op_sel_hi:[1,0,1]
	v_cvt_scalef32_pk_f32_fp4 v[120:121], v26, 1.0
	v_cvt_scalef32_pk_f32_fp4 v[124:125], v26, 1.0 op_sel:[0,1,0]
	v_cvt_scalef32_pk_f32_fp4 v[126:127], v26, 1.0 op_sel:[1,1,0]
	v_cvt_scalef32_pk_f32_fp4 v[26:27], v27, 1.0 op_sel:[1,1,0]
	v_pk_fma_f32 v[12:13], v[50:51], s[20:21], v[12:13] op_sel_hi:[1,0,1]
	v_pk_fma_f32 v[14:15], v[40:41], s[62:63], v[14:15] op_sel_hi:[1,0,1]
	v_pk_fma_f32 v[16:17], v[34:35], s[26:27], v[16:17] op_sel_hi:[1,0,1]
	v_readlane_b32 s20, v2, 4
	s_waitcnt vmcnt(11)
	v_cvt_scalef32_pk_f32_fp4 v[30:31], v171, 1.0
	v_pk_fma_f32 v[24:25], v[54:55], s[22:23], v[24:25] op_sel_hi:[1,0,1]
	v_pk_fma_f32 v[10:11], v[80:81], s[22:23], v[10:11] op_sel_hi:[1,0,1]
	v_pk_fma_f32 v[12:13], v[82:83], s[22:23], v[12:13] op_sel_hi:[1,0,1]
	v_pk_fma_f32 v[16:17], v[26:27], s[28:29], v[16:17] op_sel_hi:[1,0,1]
	v_readlane_b32 s22, v2, 5
	s_waitcnt vmcnt(10)
	v_cvt_scalef32_pk_f32_fp4 v[52:53], v173, 1.0
	v_pk_fma_f32 v[14:15], v[30:31], s[20:21], v[14:15] op_sel_hi:[1,0,1]
	v_pk_fma_f32 v[24:25], v[88:89], s[24:25], v[24:25] op_sel_hi:[1,0,1]
	v_pk_fma_f32 v[10:11], v[92:93], s[24:25], v[10:11] op_sel_hi:[1,0,1]
	v_pk_fma_f32 v[12:13], v[94:95], s[24:25], v[12:13] op_sel_hi:[1,0,1]
	v_pk_fma_f32 v[16:17], v[152:153], s[30:31], v[16:17] op_sel_hi:[1,0,1]
	v_readlane_b32 s24, v2, 6
	s_waitcnt vmcnt(9)
	v_cvt_scalef32_pk_f32_fp4 v[90:91], v175, 1.0
	v_pk_fma_f32 v[14:15], v[52:53], s[22:23], v[14:15] op_sel_hi:[1,0,1]
	v_cvt_scalef32_pk_f32_fp4 v[190:191], v108, 1.0
	v_cvt_scalef32_pk_f32_fp4 v[198:199], v108, 1.0 op_sel:[0,1,0]
	v_cvt_scalef32_pk_f32_fp4 v[200:201], v108, 1.0 op_sel:[1,1,0]
	v_cvt_scalef32_pk_f32_fp4 v[108:109], v109, 1.0 op_sel:[1,1,0]
	v_pk_fma_f32 v[24:25], v[102:103], s[26:27], v[24:25] op_sel_hi:[1,0,1]
	v_pk_fma_f32 v[10:11], v[106:107], s[26:27], v[10:11] op_sel_hi:[1,0,1]
	v_pk_fma_f32 v[12:13], v[110:111], s[26:27], v[12:13] op_sel_hi:[1,0,1]
	v_pk_fma_f32 v[16:17], v[168:169], s[34:35], v[16:17] op_sel_hi:[1,0,1]
	v_readlane_b32 s26, v2, 7
	s_waitcnt vmcnt(8)
	v_cvt_scalef32_pk_f32_fp4 v[106:107], v177, 1.0
	v_pk_fma_f32 v[14:15], v[90:91], s[24:25], v[14:15] op_sel_hi:[1,0,1]
	v_cvt_scalef32_pk_f32_fp4 v[208:209], v118, 1.0
	v_cvt_scalef32_pk_f32_fp4 v[214:215], v118, 1.0 op_sel:[0,1,0]
	v_cvt_scalef32_pk_f32_fp4 v[216:217], v118, 1.0 op_sel:[1,1,0]
	v_cvt_scalef32_pk_f32_fp4 v[118:119], v119, 1.0 op_sel:[1,1,0]
	v_pk_fma_f32 v[24:25], v[120:121], s[28:29], v[24:25] op_sel_hi:[1,0,1]
	v_pk_fma_f32 v[10:11], v[124:125], s[28:29], v[10:11] op_sel_hi:[1,0,1]
	v_pk_fma_f32 v[12:13], v[126:127], s[28:29], v[12:13] op_sel_hi:[1,0,1]
	v_pk_fma_f32 v[16:17], v[108:109], s[36:37], v[16:17] op_sel_hi:[1,0,1]
	v_readlane_b32 s28, v2, 8
	s_waitcnt vmcnt(7)
	v_cvt_scalef32_pk_f32_fp4 v[122:123], v179, 1.0
	v_pk_fma_f32 v[14:15], v[106:107], s[26:27], v[14:15] op_sel_hi:[1,0,1]
	v_cvt_scalef32_pk_f32_fp4 v[234:235], v132, 1.0
	v_cvt_scalef32_pk_f32_fp4 v[238:239], v132, 1.0 op_sel:[0,1,0]
	v_cvt_scalef32_pk_f32_fp4 v[240:241], v132, 1.0 op_sel:[1,1,0]
	v_cvt_scalef32_pk_f32_fp4 v[132:133], v133, 1.0 op_sel:[1,1,0]
	v_pk_fma_f32 v[24:25], v[136:137], s[30:31], v[24:25] op_sel_hi:[1,0,1]
	v_pk_fma_f32 v[10:11], v[140:141], s[30:31], v[10:11] op_sel_hi:[1,0,1]
	v_pk_fma_f32 v[12:13], v[144:145], s[30:31], v[12:13] op_sel_hi:[1,0,1]
	v_pk_fma_f32 v[16:17], v[118:119], s[38:39], v[16:17] op_sel_hi:[1,0,1]
	v_readlane_b32 s30, v2, 9
	s_waitcnt vmcnt(6)
	v_cvt_scalef32_pk_f32_fp4 v[138:139], v181, 1.0
	v_pk_fma_f32 v[14:15], v[122:123], s[28:29], v[14:15] op_sel_hi:[1,0,1]
	v_pk_fma_f32 v[24:25], v[154:155], s[34:35], v[24:25] op_sel_hi:[1,0,1]
	v_pk_fma_f32 v[10:11], v[158:159], s[34:35], v[10:11] op_sel_hi:[1,0,1]
	v_pk_fma_f32 v[12:13], v[160:161], s[34:35], v[12:13] op_sel_hi:[1,0,1]
	v_cvt_scalef32_pk_f32_fp4 v[50:51], v143, 1.0 op_sel:[1,1,0]
	v_pk_fma_f32 v[16:17], v[132:133], s[56:57], v[16:17] op_sel_hi:[1,0,1]
	v_readlane_b32 s34, v2, 10
	s_waitcnt vmcnt(5)
	v_cvt_scalef32_pk_f32_fp4 v[154:155], v183, 1.0
	v_pk_fma_f32 v[14:15], v[138:139], s[30:31], v[14:15] op_sel_hi:[1,0,1]
	v_pk_fma_f32 v[24:25], v[190:191], s[36:37], v[24:25] op_sel_hi:[1,0,1]
	v_pk_fma_f32 v[10:11], v[198:199], s[36:37], v[10:11] op_sel_hi:[1,0,1]
	v_pk_fma_f32 v[12:13], v[200:201], s[36:37], v[12:13] op_sel_hi:[1,0,1]
	v_pk_fma_f32 v[20:21], v[50:51], s[62:63], v[16:17] op_sel_hi:[1,0,1]
	v_cvt_scalef32_pk_f32_fp4 v[16:17], v170, 1.0
	v_cvt_scalef32_pk_f32_fp4 v[22:23], v170, 1.0 op_sel:[1,0,0]
	v_cvt_scalef32_pk_f32_fp4 v[26:27], v170, 1.0 op_sel:[0,1,0]
	v_cvt_scalef32_pk_f32_fp4 v[28:29], v170, 1.0 op_sel:[1,1,0]
	v_cvt_scalef32_pk_f32_fp4 v[32:33], v171, 1.0 op_sel:[1,0,0]
	v_cvt_scalef32_pk_f32_fp4 v[34:35], v171, 1.0 op_sel:[0,1,0]
	v_cvt_scalef32_pk_f32_fp4 v[36:37], v171, 1.0 op_sel:[1,1,0]
	v_readlane_b32 s36, v2, 11
	s_waitcnt vmcnt(4)
	v_cvt_scalef32_pk_f32_fp4 v[170:171], v185, 1.0
	v_pk_fma_f32 v[14:15], v[154:155], s[34:35], v[14:15] op_sel_hi:[1,0,1]
	v_pk_fma_f32 v[24:25], v[208:209], s[38:39], v[24:25] op_sel_hi:[1,0,1]
	v_pk_fma_f32 v[10:11], v[214:215], s[38:39], v[10:11] op_sel_hi:[1,0,1]
	v_pk_fma_f32 v[12:13], v[216:217], s[38:39], v[12:13] op_sel_hi:[1,0,1]
	v_readlane_b32 s38, v2, 12
	s_waitcnt vmcnt(3)
	v_cvt_scalef32_pk_f32_fp4 v[190:191], v187, 1.0
	v_pk_fma_f32 v[14:15], v[170:171], s[36:37], v[14:15] op_sel_hi:[1,0,1]
	v_cvt_scalef32_pk_f32_fp4 v[248:249], v142, 1.0
	v_cvt_scalef32_pk_f32_fp4 v[54:55], v142, 1.0 op_sel:[0,1,0]
	v_cvt_scalef32_pk_f32_fp4 v[88:89], v142, 1.0 op_sel:[1,1,0]
	v_pk_fma_f32 v[24:25], v[234:235], s[56:57], v[24:25] op_sel_hi:[1,0,1]
	v_pk_fma_f32 v[10:11], v[238:239], s[56:57], v[10:11] op_sel_hi:[1,0,1]
	v_pk_fma_f32 v[12:13], v[240:241], s[56:57], v[12:13] op_sel_hi:[1,0,1]
	v_readlane_b32 s56, v2, 13
	s_waitcnt vmcnt(2)
	v_cvt_scalef32_pk_f32_fp4 v[208:209], v189, 1.0
	v_pk_fma_f32 v[14:15], v[190:191], s[38:39], v[14:15] op_sel_hi:[1,0,1]
	v_pk_fma_f32 v[24:25], v[248:249], s[62:63], v[24:25] op_sel_hi:[1,0,1]
	v_pk_fma_f32 v[10:11], v[54:55], s[62:63], v[10:11] op_sel_hi:[1,0,1]
	v_pk_fma_f32 v[12:13], v[88:89], s[62:63], v[12:13] op_sel_hi:[1,0,1]
	v_readlane_b32 s62, v2, 14
	v_pk_fma_f32 v[8:9], v[22:23], s[20:21], v[8:9] op_sel_hi:[1,0,1]
	s_waitcnt vmcnt(1)
	v_cvt_scalef32_pk_f32_fp4 v[22:23], v7, 1.0
	v_pk_fma_f32 v[14:15], v[208:209], s[56:57], v[14:15] op_sel_hi:[1,0,1]
	v_cvt_scalef32_pk_f32_fp4 v[54:55], v173, 1.0 op_sel:[1,0,0]
	v_pk_fma_f32 v[14:15], v[22:23], s[62:63], v[14:15] op_sel_hi:[1,0,1]
	v_pk_fma_f32 v[22:23], v[32:33], s[20:21], v[38:39] op_sel_hi:[1,0,1]
	v_cvt_scalef32_pk_f32_fp4 v[92:93], v175, 1.0 op_sel:[1,0,0]
	v_pk_fma_f32 v[22:23], v[54:55], s[22:23], v[22:23] op_sel_hi:[1,0,1]
	v_cvt_scalef32_pk_f32_fp4 v[40:41], v172, 1.0
	v_cvt_scalef32_pk_f32_fp4 v[42:43], v172, 1.0 op_sel:[1,0,0]
	v_cvt_scalef32_pk_f32_fp4 v[44:45], v172, 1.0 op_sel:[0,1,0]
	v_cvt_scalef32_pk_f32_fp4 v[50:51], v172, 1.0 op_sel:[1,1,0]
	v_cvt_scalef32_pk_f32_fp4 v[108:109], v177, 1.0 op_sel:[1,0,0]
	v_pk_fma_f32 v[16:17], v[16:17], s[20:21], v[24:25] op_sel_hi:[1,0,1]
	v_pk_fma_f32 v[10:11], v[26:27], s[20:21], v[10:11] op_sel_hi:[1,0,1]
	v_pk_fma_f32 v[12:13], v[28:29], s[20:21], v[12:13] op_sel_hi:[1,0,1]
	v_pk_fma_f32 v[22:23], v[92:93], s[24:25], v[22:23] op_sel_hi:[1,0,1]
	v_cvt_scalef32_pk_f32_fp4 v[124:125], v179, 1.0 op_sel:[1,0,0]
	v_pk_fma_f32 v[16:17], v[40:41], s[22:23], v[16:17] op_sel_hi:[1,0,1]
	v_pk_fma_f32 v[8:9], v[42:43], s[22:23], v[8:9] op_sel_hi:[1,0,1]
	v_pk_fma_f32 v[10:11], v[44:45], s[22:23], v[10:11] op_sel_hi:[1,0,1]
	v_pk_fma_f32 v[12:13], v[50:51], s[22:23], v[12:13] op_sel_hi:[1,0,1]
	v_pk_fma_f32 v[22:23], v[108:109], s[26:27], v[22:23] op_sel_hi:[1,0,1]
	v_readlane_b32 s23, v48, 0
	v_cvt_scalef32_pk_f32_fp4 v[56:57], v173, 1.0 op_sel:[0,1,0]
	v_cvt_scalef32_pk_f32_fp4 v[140:141], v181, 1.0 op_sel:[1,0,0]
	v_pk_fma_f32 v[22:23], v[124:125], s[28:29], v[22:23] op_sel_hi:[1,0,1]
	v_pk_fma_f32 v[18:19], v[34:35], s[20:21], v[18:19] op_sel_hi:[1,0,1]
	v_cvt_scalef32_pk_f32_fp4 v[94:95], v175, 1.0 op_sel:[0,1,0]
	v_cvt_scalef32_pk_f32_fp4 v[156:157], v183, 1.0 op_sel:[1,0,0]
	v_pk_fma_f32 v[22:23], v[140:141], s[30:31], v[22:23] op_sel_hi:[1,0,1]
	v_pk_fma_f32 v[18:19], v[56:57], s[22:23], v[18:19] op_sel_hi:[1,0,1]
	v_cvt_scalef32_pk_f32_fp4 v[80:81], v173, 1.0 op_sel:[1,1,0]
	v_cvt_scalef32_pk_f32_fp4 v[110:111], v177, 1.0 op_sel:[0,1,0]
	v_cvt_scalef32_pk_f32_fp4 v[172:173], v185, 1.0 op_sel:[1,0,0]
	v_pk_fma_f32 v[22:23], v[156:157], s[34:35], v[22:23] op_sel_hi:[1,0,1]
	v_pk_fma_f32 v[18:19], v[94:95], s[24:25], v[18:19] op_sel_hi:[1,0,1]
	v_cvt_scalef32_pk_f32_fp4 v[126:127], v179, 1.0 op_sel:[0,1,0]
	v_cvt_scalef32_pk_f32_fp4 v[196:197], v187, 1.0 op_sel:[1,0,0]
	v_pk_fma_f32 v[22:23], v[172:173], s[36:37], v[22:23] op_sel_hi:[1,0,1]
	v_pk_fma_f32 v[18:19], v[110:111], s[26:27], v[18:19] op_sel_hi:[1,0,1]
	v_cvt_scalef32_pk_f32_fp4 v[142:143], v181, 1.0 op_sel:[0,1,0]
	v_cvt_scalef32_pk_f32_fp4 v[210:211], v189, 1.0 op_sel:[1,0,0]
	v_pk_fma_f32 v[22:23], v[196:197], s[38:39], v[22:23] op_sel_hi:[1,0,1]
	buffer_load_dwordx2 v[28:29], v192, s[4:7], s23 offen
	v_readlane_b32 s23, v48, 1
	v_pk_fma_f32 v[18:19], v[126:127], s[28:29], v[18:19] op_sel_hi:[1,0,1]
	v_cvt_scalef32_pk_f32_fp4 v[158:159], v183, 1.0 op_sel:[0,1,0]
	v_cvt_scalef32_pk_f32_fp4 v[24:25], v7, 1.0 op_sel:[1,0,0]
	v_pk_fma_f32 v[22:23], v[210:211], s[56:57], v[22:23] op_sel_hi:[1,0,1]
	v_pk_fma_f32 v[18:19], v[142:143], s[30:31], v[18:19] op_sel_hi:[1,0,1]
	v_cvt_scalef32_pk_f32_fp4 v[82:83], v174, 1.0
	v_cvt_scalef32_pk_f32_fp4 v[84:85], v174, 1.0 op_sel:[1,0,0]
	v_cvt_scalef32_pk_f32_fp4 v[86:87], v174, 1.0 op_sel:[0,1,0]
	v_cvt_scalef32_pk_f32_fp4 v[88:89], v174, 1.0 op_sel:[1,1,0]
	v_cvt_scalef32_pk_f32_fp4 v[96:97], v175, 1.0 op_sel:[1,1,0]
	v_cvt_scalef32_pk_f32_fp4 v[174:175], v185, 1.0 op_sel:[0,1,0]
	v_pk_fma_f32 v[30:31], v[24:25], s[62:63], v[22:23] op_sel_hi:[1,0,1]
	buffer_load_dwordx2 v[24:25], v192, s[4:7], s23 offen
	v_pk_fma_f32 v[18:19], v[158:159], s[34:35], v[18:19] op_sel_hi:[1,0,1]
	v_readlane_b32 s23, v48, 2
	v_cvt_scalef32_pk_f32_fp4 v[198:199], v187, 1.0 op_sel:[0,1,0]
	v_pk_fma_f32 v[18:19], v[174:175], s[36:37], v[18:19] op_sel_hi:[1,0,1]
	v_pk_fma_f32 v[20:21], v[36:37], s[20:21], v[20:21] op_sel_hi:[1,0,1]
	v_cvt_scalef32_pk_f32_fp4 v[214:215], v189, 1.0 op_sel:[0,1,0]
	v_pk_fma_f32 v[18:19], v[198:199], s[38:39], v[18:19] op_sel_hi:[1,0,1]
	v_pk_fma_f32 v[20:21], v[80:81], s[22:23], v[20:21] op_sel_hi:[1,0,1]
	v_readlane_b32 s20, v48, 3
	v_readlane_b32 s22, v48, 5
	v_cvt_scalef32_pk_f32_fp4 v[26:27], v7, 1.0 op_sel:[0,1,0]
	v_pk_fma_f32 v[18:19], v[214:215], s[56:57], v[18:19] op_sel_hi:[1,0,1]
	buffer_load_dwordx2 v[34:35], v192, s[4:7], s23 offen
	v_pk_fma_f32 v[18:19], v[26:27], s[62:63], v[18:19] op_sel_hi:[1,0,1]
	buffer_load_dwordx2 v[26:27], v192, s[4:7], s20 offen
	buffer_load_dwordx2 v[52:53], v192, s[4:7], s22 offen
	v_readlane_b32 s20, v48, 4
	v_readlane_b32 s22, v48, 6
	v_pk_fma_f32 v[16:17], v[82:83], s[24:25], v[16:17] op_sel_hi:[1,0,1]
	v_pk_fma_f32 v[8:9], v[84:85], s[24:25], v[8:9] op_sel_hi:[1,0,1]
	s_nop 1
	buffer_load_dwordx2 v[36:37], v192, s[4:7], s20 offen
	v_readlane_b32 s23, v48, 7
	s_nop 0
	buffer_load_dwordx2 v[82:83], v192, s[4:7], s22 offen
	s_nop 2
	s_nop 0
	buffer_load_dwordx2 v[84:85], v192, s[4:7], s23 offen
	v_readlane_b32 s22, v48, 8
	v_pk_fma_f32 v[10:11], v[86:87], s[24:25], v[10:11] op_sel_hi:[1,0,1]
	v_pk_fma_f32 v[12:13], v[88:89], s[24:25], v[12:13] op_sel_hi:[1,0,1]
	v_pk_fma_f32 v[20:21], v[96:97], s[24:25], v[20:21] op_sel_hi:[1,0,1]
	v_readlane_b32 s23, v48, 9
	v_readlane_b32 s24, v48, 10
	v_readlane_b32 s25, v48, 11
	buffer_load_dwordx2 v[86:87], v192, s[4:7], s22 offen
	s_nop 1
	buffer_load_dwordx2 v[88:89], v192, s[4:7], s23 offen
	s_nop 1
	buffer_load_dwordx2 v[90:91], v192, s[4:7], s24 offen
	s_nop 1
	buffer_load_dwordx2 v[92:93], v192, s[4:7], s25 offen
	v_cvt_scalef32_pk_f32_fp4 v[112:113], v177, 1.0 op_sel:[1,1,0]
	v_cvt_scalef32_pk_f32_fp4 v[128:129], v179, 1.0 op_sel:[1,1,0]
	v_pk_fma_f32 v[20:21], v[112:113], s[26:27], v[20:21] op_sel_hi:[1,0,1]
	v_cvt_scalef32_pk_f32_fp4 v[144:145], v181, 1.0 op_sel:[1,1,0]
	v_pk_fma_f32 v[20:21], v[128:129], s[28:29], v[20:21] op_sel_hi:[1,0,1]
	v_cvt_scalef32_pk_f32_fp4 v[160:161], v183, 1.0 op_sel:[1,1,0]
	v_pk_fma_f32 v[20:21], v[144:145], s[30:31], v[20:21] op_sel_hi:[1,0,1]
	v_cvt_scalef32_pk_f32_fp4 v[98:99], v176, 1.0
	v_cvt_scalef32_pk_f32_fp4 v[100:101], v176, 1.0 op_sel:[1,0,0]
	v_cvt_scalef32_pk_f32_fp4 v[102:103], v176, 1.0 op_sel:[0,1,0]
	v_cvt_scalef32_pk_f32_fp4 v[104:105], v176, 1.0 op_sel:[1,1,0]
	v_cvt_scalef32_pk_f32_fp4 v[176:177], v185, 1.0 op_sel:[1,1,0]
	v_pk_fma_f32 v[20:21], v[160:161], s[34:35], v[20:21] op_sel_hi:[1,0,1]
	v_cvt_scalef32_pk_f32_fp4 v[114:115], v178, 1.0
	v_cvt_scalef32_pk_f32_fp4 v[116:117], v178, 1.0 op_sel:[1,0,0]
	v_cvt_scalef32_pk_f32_fp4 v[118:119], v178, 1.0 op_sel:[0,1,0]
	v_cvt_scalef32_pk_f32_fp4 v[120:121], v178, 1.0 op_sel:[1,1,0]
	v_cvt_scalef32_pk_f32_fp4 v[130:131], v180, 1.0
	v_cvt_scalef32_pk_f32_fp4 v[132:133], v180, 1.0 op_sel:[1,0,0]
	v_cvt_scalef32_pk_f32_fp4 v[134:135], v180, 1.0 op_sel:[0,1,0]
	v_cvt_scalef32_pk_f32_fp4 v[136:137], v180, 1.0 op_sel:[1,1,0]
	v_cvt_scalef32_pk_f32_fp4 v[146:147], v182, 1.0
	v_cvt_scalef32_pk_f32_fp4 v[148:149], v182, 1.0 op_sel:[1,0,0]
	v_cvt_scalef32_pk_f32_fp4 v[150:151], v182, 1.0 op_sel:[0,1,0]
	v_cvt_scalef32_pk_f32_fp4 v[152:153], v182, 1.0 op_sel:[1,1,0]
	v_cvt_scalef32_pk_f32_fp4 v[162:163], v184, 1.0
	v_cvt_scalef32_pk_f32_fp4 v[164:165], v184, 1.0 op_sel:[1,0,0]
	v_cvt_scalef32_pk_f32_fp4 v[166:167], v184, 1.0 op_sel:[0,1,0]
	v_cvt_scalef32_pk_f32_fp4 v[168:169], v184, 1.0 op_sel:[1,1,0]
	v_cvt_scalef32_pk_f32_fp4 v[178:179], v186, 1.0
	v_cvt_scalef32_pk_f32_fp4 v[180:181], v186, 1.0 op_sel:[1,0,0]
	v_cvt_scalef32_pk_f32_fp4 v[182:183], v186, 1.0 op_sel:[0,1,0]
	v_cvt_scalef32_pk_f32_fp4 v[184:185], v186, 1.0 op_sel:[1,1,0]
	v_cvt_scalef32_pk_f32_fp4 v[186:187], v187, 1.0 op_sel:[1,1,0]
	v_pk_fma_f32 v[20:21], v[176:177], s[36:37], v[20:21] op_sel_hi:[1,0,1]
	v_cvt_scalef32_pk_f32_fp4 v[200:201], v188, 1.0
	v_cvt_scalef32_pk_f32_fp4 v[202:203], v188, 1.0 op_sel:[1,0,0]
	v_cvt_scalef32_pk_f32_fp4 v[204:205], v188, 1.0 op_sel:[0,1,0]
	v_cvt_scalef32_pk_f32_fp4 v[206:207], v188, 1.0 op_sel:[1,1,0]
	v_cvt_scalef32_pk_f32_fp4 v[188:189], v189, 1.0 op_sel:[1,1,0]
	v_pk_fma_f32 v[20:21], v[186:187], s[38:39], v[20:21] op_sel_hi:[1,0,1]
	v_readlane_b32 s22, v48, 12
	v_cvt_scalef32_pk_f32_fp4 v[216:217], v6, 1.0
	v_cvt_scalef32_pk_f32_fp4 v[228:229], v6, 1.0 op_sel:[1,0,0]
	v_cvt_scalef32_pk_f32_fp4 v[230:231], v6, 1.0 op_sel:[0,1,0]
	v_cvt_scalef32_pk_f32_fp4 v[232:233], v6, 1.0 op_sel:[1,1,0]
	v_cvt_scalef32_pk_f32_fp4 v[6:7], v7, 1.0 op_sel:[1,1,0]
	v_pk_fma_f32 v[20:21], v[188:189], s[56:57], v[20:21] op_sel_hi:[1,0,1]
	v_readlane_b32 s23, v48, 13
	v_readlane_b32 s24, v48, 14
	v_readlane_b32 s25, v48, 15
	v_pk_fma_f32 v[20:21], v[6:7], s[62:63], v[20:21] op_sel_hi:[1,0,1]
	s_waitcnt vmcnt(12)
	v_cvt_scalef32_pk_f32_fp4 v[38:39], v4, 1.0
	v_cvt_scalef32_pk_f32_fp4 v[40:41], v4, 1.0 op_sel:[1,0,0]
	v_cvt_scalef32_pk_f32_fp4 v[42:43], v4, 1.0 op_sel:[0,1,0]
	v_cvt_scalef32_pk_f32_fp4 v[44:45], v4, 1.0 op_sel:[1,1,0]
	v_cvt_scalef32_pk_f32_fp4 v[50:51], v5, 1.0
	v_cvt_scalef32_pk_f32_fp4 v[54:55], v5, 1.0 op_sel:[1,0,0]
	v_cvt_scalef32_pk_f32_fp4 v[56:57], v5, 1.0 op_sel:[0,1,0]
	v_cvt_scalef32_pk_f32_fp4 v[80:81], v5, 1.0 op_sel:[1,1,0]
	buffer_load_dwordx2 v[32:33], v192, s[4:7], s22 offen
	buffer_load_dwordx2 v[22:23], v192, s[4:7], s23 offen
	buffer_load_dwordx2 v[6:7], v192, s[4:7], s24 offen
	buffer_load_dwordx2 v[4:5], v192, s[4:7], s25 offen
	v_pk_fma_f32 v[16:17], v[98:99], s[26:27], v[16:17] op_sel_hi:[1,0,1]
	v_readlane_b32 s20, v2, 15
	v_pk_fma_f32 v[16:17], v[114:115], s[28:29], v[16:17] op_sel_hi:[1,0,1]
	v_readlane_b32 s22, v3, 0
	v_pk_fma_f32 v[16:17], v[130:131], s[30:31], v[16:17] op_sel_hi:[1,0,1]
	s_waitcnt vmcnt(15)
	v_cvt_scalef32_pk_f32_fp4 v[48:49], v28, 1.0
	v_pk_fma_f32 v[16:17], v[146:147], s[34:35], v[16:17] op_sel_hi:[1,0,1]
	v_pk_fma_f32 v[8:9], v[100:101], s[26:27], v[8:9] op_sel_hi:[1,0,1]
	v_pk_fma_f32 v[16:17], v[162:163], s[36:37], v[16:17] op_sel_hi:[1,0,1]
	v_pk_fma_f32 v[10:11], v[102:103], s[26:27], v[10:11] op_sel_hi:[1,0,1]
	v_pk_fma_f32 v[16:17], v[178:179], s[38:39], v[16:17] op_sel_hi:[1,0,1]
	v_pk_fma_f32 v[12:13], v[104:105], s[26:27], v[12:13] op_sel_hi:[1,0,1]
	v_pk_fma_f32 v[16:17], v[200:201], s[56:57], v[16:17] op_sel_hi:[1,0,1]
	v_cvt_scalef32_pk_f32_fp4 v[100:101], v29, 1.0
	v_pk_fma_f32 v[16:17], v[216:217], s[62:63], v[16:17] op_sel_hi:[1,0,1]
	v_readlane_b32 s24, v3, 1
	v_pk_fma_f32 v[16:17], v[38:39], s[20:21], v[16:17] op_sel_hi:[1,0,1]
	s_waitcnt vmcnt(14)
	v_cvt_scalef32_pk_f32_fp4 v[106:107], v24, 1.0
	v_pk_fma_f32 v[16:17], v[48:49], s[22:23], v[16:17] op_sel_hi:[1,0,1]
	v_pk_fma_f32 v[14:15], v[50:51], s[20:21], v[14:15] op_sel_hi:[1,0,1]
	v_pk_fma_f32 v[8:9], v[116:117], s[28:29], v[8:9] op_sel_hi:[1,0,1]
	v_pk_fma_f32 v[10:11], v[118:119], s[28:29], v[10:11] op_sel_hi:[1,0,1]
	v_pk_fma_f32 v[12:13], v[120:121], s[28:29], v[12:13] op_sel_hi:[1,0,1]
	v_cvt_scalef32_pk_f32_fp4 v[108:109], v24, 1.0 op_sel:[1,0,0]
	v_cvt_scalef32_pk_f32_fp4 v[110:111], v24, 1.0 op_sel:[0,1,0]
	v_cvt_scalef32_pk_f32_fp4 v[112:113], v24, 1.0 op_sel:[1,1,0]
	v_cvt_scalef32_pk_f32_fp4 v[114:115], v25, 1.0
	v_cvt_scalef32_pk_f32_fp4 v[116:117], v25, 1.0 op_sel:[1,0,0]
	v_cvt_scalef32_pk_f32_fp4 v[118:119], v25, 1.0 op_sel:[0,1,0]
	v_cvt_scalef32_pk_f32_fp4 v[120:121], v25, 1.0 op_sel:[1,1,0]
	v_readlane_b32 s26, v3, 2
	s_waitcnt vmcnt(13)
	v_cvt_scalef32_pk_f32_fp4 v[24:25], v34, 1.0
	v_pk_fma_f32 v[16:17], v[106:107], s[24:25], v[16:17] op_sel_hi:[1,0,1]
	v_pk_fma_f32 v[14:15], v[100:101], s[22:23], v[14:15] op_sel_hi:[1,0,1]
	v_pk_fma_f32 v[8:9], v[132:133], s[30:31], v[8:9] op_sel_hi:[1,0,1]
	v_pk_fma_f32 v[10:11], v[134:135], s[30:31], v[10:11] op_sel_hi:[1,0,1]
	v_cvt_scalef32_pk_f32_fp4 v[128:129], v35, 1.0
	v_readlane_b32 s28, v3, 3
	s_waitcnt vmcnt(12)
	v_cvt_scalef32_pk_f32_fp4 v[134:135], v26, 1.0
	v_pk_fma_f32 v[16:17], v[24:25], s[26:27], v[16:17] op_sel_hi:[1,0,1]
	v_pk_fma_f32 v[14:15], v[114:115], s[24:25], v[14:15] op_sel_hi:[1,0,1]
	v_pk_fma_f32 v[8:9], v[148:149], s[34:35], v[8:9] op_sel_hi:[1,0,1]
	v_pk_fma_f32 v[12:13], v[136:137], s[30:31], v[12:13] op_sel_hi:[1,0,1]
	v_cvt_scalef32_pk_f32_fp4 v[142:143], v27, 1.0
	v_readlane_b32 s30, v3, 4
	s_waitcnt vmcnt(10)
	v_cvt_scalef32_pk_f32_fp4 v[148:149], v36, 1.0
	v_pk_fma_f32 v[16:17], v[134:135], s[28:29], v[16:17] op_sel_hi:[1,0,1]
	v_pk_fma_f32 v[14:15], v[128:129], s[26:27], v[14:15] op_sel_hi:[1,0,1]
	v_pk_fma_f32 v[10:11], v[150:151], s[34:35], v[10:11] op_sel_hi:[1,0,1]
	v_pk_fma_f32 v[12:13], v[152:153], s[34:35], v[12:13] op_sel_hi:[1,0,1]
	v_cvt_scalef32_pk_f32_fp4 v[156:157], v37, 1.0
	v_readlane_b32 s34, v3, 5
	v_cvt_scalef32_pk_f32_fp4 v[162:163], v52, 1.0
	v_pk_fma_f32 v[16:17], v[148:149], s[30:31], v[16:17] op_sel_hi:[1,0,1]
	v_pk_fma_f32 v[14:15], v[142:143], s[28:29], v[14:15] op_sel_hi:[1,0,1]
	v_pk_fma_f32 v[8:9], v[164:165], s[36:37], v[8:9] op_sel_hi:[1,0,1]
	v_pk_fma_f32 v[10:11], v[166:167], s[36:37], v[10:11] op_sel_hi:[1,0,1]
	v_pk_fma_f32 v[12:13], v[168:169], s[36:37], v[12:13] op_sel_hi:[1,0,1]
	v_cvt_scalef32_pk_f32_fp4 v[170:171], v53, 1.0
	v_readlane_b32 s36, v3, 6
	s_waitcnt vmcnt(9)
	v_cvt_scalef32_pk_f32_fp4 v[176:177], v82, 1.0
	v_pk_fma_f32 v[16:17], v[162:163], s[34:35], v[16:17] op_sel_hi:[1,0,1]
	v_pk_fma_f32 v[14:15], v[156:157], s[30:31], v[14:15] op_sel_hi:[1,0,1]
	v_pk_fma_f32 v[8:9], v[180:181], s[38:39], v[8:9] op_sel_hi:[1,0,1]
	v_pk_fma_f32 v[10:11], v[182:183], s[38:39], v[10:11] op_sel_hi:[1,0,1]
	v_pk_fma_f32 v[12:13], v[184:185], s[38:39], v[12:13] op_sel_hi:[1,0,1]
	v_cvt_scalef32_pk_f32_fp4 v[184:185], v83, 1.0
	v_readlane_b32 s38, v3, 7
	s_waitcnt vmcnt(8)
	v_cvt_scalef32_pk_f32_fp4 v[190:191], v84, 1.0
	v_pk_fma_f32 v[16:17], v[176:177], s[36:37], v[16:17] op_sel_hi:[1,0,1]
	v_pk_fma_f32 v[14:15], v[170:171], s[34:35], v[14:15] op_sel_hi:[1,0,1]
	v_pk_fma_f32 v[8:9], v[202:203], s[56:57], v[8:9] op_sel_hi:[1,0,1]
	v_pk_fma_f32 v[10:11], v[204:205], s[56:57], v[10:11] op_sel_hi:[1,0,1]
	v_pk_fma_f32 v[12:13], v[206:207], s[56:57], v[12:13] op_sel_hi:[1,0,1]
	v_cvt_scalef32_pk_f32_fp4 v[202:203], v85, 1.0
	v_readlane_b32 s56, v3, 8
	s_waitcnt vmcnt(7)
	v_cvt_scalef32_pk_f32_fp4 v[208:209], v86, 1.0
	v_pk_fma_f32 v[16:17], v[190:191], s[38:39], v[16:17] op_sel_hi:[1,0,1]
	v_pk_fma_f32 v[14:15], v[184:185], s[36:37], v[14:15] op_sel_hi:[1,0,1]
	v_pk_fma_f32 v[8:9], v[228:229], s[62:63], v[8:9] op_sel_hi:[1,0,1]
	v_pk_fma_f32 v[10:11], v[230:231], s[62:63], v[10:11] op_sel_hi:[1,0,1]
	v_pk_fma_f32 v[12:13], v[232:233], s[62:63], v[12:13] op_sel_hi:[1,0,1]
	v_cvt_scalef32_pk_f32_fp4 v[228:229], v87, 1.0
	v_readlane_b32 s62, v3, 9
	s_waitcnt vmcnt(6)
	v_cvt_scalef32_pk_f32_fp4 v[234:235], v88, 1.0
	v_pk_fma_f32 v[16:17], v[208:209], s[56:57], v[16:17] op_sel_hi:[1,0,1]
	v_pk_fma_f32 v[14:15], v[202:203], s[38:39], v[14:15] op_sel_hi:[1,0,1]
	v_pk_fma_f32 v[24:25], v[234:235], s[62:63], v[16:17] op_sel_hi:[1,0,1]
	v_cvt_scalef32_pk_f32_fp4 v[16:17], v89, 1.0
	v_pk_fma_f32 v[14:15], v[228:229], s[56:57], v[14:15] op_sel_hi:[1,0,1]
	v_cvt_scalef32_pk_f32_fp4 v[94:95], v28, 1.0 op_sel:[1,0,0]
	v_cvt_scalef32_pk_f32_fp4 v[96:97], v28, 1.0 op_sel:[0,1,0]
	v_cvt_scalef32_pk_f32_fp4 v[98:99], v28, 1.0 op_sel:[1,1,0]
	v_cvt_scalef32_pk_f32_fp4 v[102:103], v29, 1.0 op_sel:[1,0,0]
	v_cvt_scalef32_pk_f32_fp4 v[104:105], v29, 1.0 op_sel:[0,1,0]
	v_cvt_scalef32_pk_f32_fp4 v[28:29], v29, 1.0 op_sel:[1,1,0]
	v_pk_fma_f32 v[14:15], v[16:17], s[62:63], v[14:15] op_sel_hi:[1,0,1]
	v_pk_fma_f32 v[16:17], v[54:55], s[20:21], v[30:31] op_sel_hi:[1,0,1]
	v_pk_fma_f32 v[18:19], v[56:57], s[20:21], v[18:19] op_sel_hi:[1,0,1]
	v_pk_fma_f32 v[20:21], v[80:81], s[20:21], v[20:21] op_sel_hi:[1,0,1]
	v_pk_fma_f32 v[16:17], v[102:103], s[22:23], v[16:17] op_sel_hi:[1,0,1]
	v_pk_fma_f32 v[18:19], v[104:105], s[22:23], v[18:19] op_sel_hi:[1,0,1]
	v_pk_fma_f32 v[20:21], v[28:29], s[22:23], v[20:21] op_sel_hi:[1,0,1]
	v_cvt_scalef32_pk_f32_fp4 v[122:123], v34, 1.0 op_sel:[1,0,0]
	v_cvt_scalef32_pk_f32_fp4 v[124:125], v34, 1.0 op_sel:[0,1,0]
	v_cvt_scalef32_pk_f32_fp4 v[126:127], v34, 1.0 op_sel:[1,1,0]
	v_cvt_scalef32_pk_f32_fp4 v[130:131], v35, 1.0 op_sel:[1,0,0]
	v_cvt_scalef32_pk_f32_fp4 v[132:133], v35, 1.0 op_sel:[0,1,0]
	v_cvt_scalef32_pk_f32_fp4 v[34:35], v35, 1.0 op_sel:[1,1,0]
	v_pk_fma_f32 v[16:17], v[116:117], s[24:25], v[16:17] op_sel_hi:[1,0,1]
	v_pk_fma_f32 v[18:19], v[118:119], s[24:25], v[18:19] op_sel_hi:[1,0,1]
	v_pk_fma_f32 v[20:21], v[120:121], s[24:25], v[20:21] op_sel_hi:[1,0,1]
	v_cvt_scalef32_pk_f32_fp4 v[136:137], v26, 1.0 op_sel:[1,0,0]
	v_cvt_scalef32_pk_f32_fp4 v[138:139], v26, 1.0 op_sel:[0,1,0]
	v_cvt_scalef32_pk_f32_fp4 v[140:141], v26, 1.0 op_sel:[1,1,0]
	v_cvt_scalef32_pk_f32_fp4 v[144:145], v27, 1.0 op_sel:[1,0,0]
	v_cvt_scalef32_pk_f32_fp4 v[146:147], v27, 1.0 op_sel:[0,1,0]
	v_cvt_scalef32_pk_f32_fp4 v[26:27], v27, 1.0 op_sel:[1,1,0]
	v_pk_fma_f32 v[16:17], v[130:131], s[26:27], v[16:17] op_sel_hi:[1,0,1]
	v_pk_fma_f32 v[18:19], v[132:133], s[26:27], v[18:19] op_sel_hi:[1,0,1]
	v_pk_fma_f32 v[20:21], v[34:35], s[26:27], v[20:21] op_sel_hi:[1,0,1]
	v_cvt_scalef32_pk_f32_fp4 v[150:151], v36, 1.0 op_sel:[1,0,0]
	v_cvt_scalef32_pk_f32_fp4 v[152:153], v36, 1.0 op_sel:[0,1,0]
	v_cvt_scalef32_pk_f32_fp4 v[154:155], v36, 1.0 op_sel:[1,1,0]
	v_cvt_scalef32_pk_f32_fp4 v[158:159], v37, 1.0 op_sel:[1,0,0]
	v_cvt_scalef32_pk_f32_fp4 v[160:161], v37, 1.0 op_sel:[0,1,0]
	v_cvt_scalef32_pk_f32_fp4 v[36:37], v37, 1.0 op_sel:[1,1,0]
	v_pk_fma_f32 v[16:17], v[144:145], s[28:29], v[16:17] op_sel_hi:[1,0,1]
	v_pk_fma_f32 v[18:19], v[146:147], s[28:29], v[18:19] op_sel_hi:[1,0,1]
	v_pk_fma_f32 v[20:21], v[26:27], s[28:29], v[20:21] op_sel_hi:[1,0,1]
	v_cvt_scalef32_pk_f32_fp4 v[164:165], v52, 1.0 op_sel:[1,0,0]
	v_cvt_scalef32_pk_f32_fp4 v[166:167], v52, 1.0 op_sel:[0,1,0]
	v_cvt_scalef32_pk_f32_fp4 v[168:169], v52, 1.0 op_sel:[1,1,0]
	v_cvt_scalef32_pk_f32_fp4 v[172:173], v53, 1.0 op_sel:[1,0,0]
	v_cvt_scalef32_pk_f32_fp4 v[174:175], v53, 1.0 op_sel:[0,1,0]
	v_cvt_scalef32_pk_f32_fp4 v[52:53], v53, 1.0 op_sel:[1,1,0]
	v_pk_fma_f32 v[16:17], v[158:159], s[30:31], v[16:17] op_sel_hi:[1,0,1]
	v_pk_fma_f32 v[18:19], v[160:161], s[30:31], v[18:19] op_sel_hi:[1,0,1]
	v_pk_fma_f32 v[20:21], v[36:37], s[30:31], v[20:21] op_sel_hi:[1,0,1]
	v_cvt_scalef32_pk_f32_fp4 v[178:179], v82, 1.0 op_sel:[1,0,0]
	v_cvt_scalef32_pk_f32_fp4 v[180:181], v82, 1.0 op_sel:[0,1,0]
	v_cvt_scalef32_pk_f32_fp4 v[182:183], v82, 1.0 op_sel:[1,1,0]
	v_cvt_scalef32_pk_f32_fp4 v[186:187], v83, 1.0 op_sel:[1,0,0]
	v_cvt_scalef32_pk_f32_fp4 v[188:189], v83, 1.0 op_sel:[0,1,0]
	v_cvt_scalef32_pk_f32_fp4 v[82:83], v83, 1.0 op_sel:[1,1,0]
	v_pk_fma_f32 v[16:17], v[172:173], s[34:35], v[16:17] op_sel_hi:[1,0,1]
	v_pk_fma_f32 v[18:19], v[174:175], s[34:35], v[18:19] op_sel_hi:[1,0,1]
	v_pk_fma_f32 v[20:21], v[52:53], s[34:35], v[20:21] op_sel_hi:[1,0,1]
	v_cvt_scalef32_pk_f32_fp4 v[196:197], v84, 1.0 op_sel:[1,0,0]
	v_cvt_scalef32_pk_f32_fp4 v[198:199], v84, 1.0 op_sel:[0,1,0]
	v_cvt_scalef32_pk_f32_fp4 v[200:201], v84, 1.0 op_sel:[1,1,0]
	v_cvt_scalef32_pk_f32_fp4 v[204:205], v85, 1.0 op_sel:[1,0,0]
	v_cvt_scalef32_pk_f32_fp4 v[206:207], v85, 1.0 op_sel:[0,1,0]
	v_cvt_scalef32_pk_f32_fp4 v[84:85], v85, 1.0 op_sel:[1,1,0]
	v_pk_fma_f32 v[8:9], v[40:41], s[20:21], v[8:9] op_sel_hi:[1,0,1]
	v_pk_fma_f32 v[10:11], v[42:43], s[20:21], v[10:11] op_sel_hi:[1,0,1]
	v_pk_fma_f32 v[12:13], v[44:45], s[20:21], v[12:13] op_sel_hi:[1,0,1]
	v_pk_fma_f32 v[16:17], v[186:187], s[36:37], v[16:17] op_sel_hi:[1,0,1]
	v_pk_fma_f32 v[18:19], v[188:189], s[36:37], v[18:19] op_sel_hi:[1,0,1]
	v_pk_fma_f32 v[20:21], v[82:83], s[36:37], v[20:21] op_sel_hi:[1,0,1]
	v_cvt_scalef32_pk_f32_fp4 v[210:211], v86, 1.0 op_sel:[1,0,0]
	v_cvt_scalef32_pk_f32_fp4 v[214:215], v86, 1.0 op_sel:[0,1,0]
	v_cvt_scalef32_pk_f32_fp4 v[216:217], v86, 1.0 op_sel:[1,1,0]
	v_cvt_scalef32_pk_f32_fp4 v[230:231], v87, 1.0 op_sel:[1,0,0]
	v_cvt_scalef32_pk_f32_fp4 v[232:233], v87, 1.0 op_sel:[0,1,0]
	v_cvt_scalef32_pk_f32_fp4 v[86:87], v87, 1.0 op_sel:[1,1,0]
	v_pk_fma_f32 v[8:9], v[94:95], s[22:23], v[8:9] op_sel_hi:[1,0,1]
	v_pk_fma_f32 v[10:11], v[96:97], s[22:23], v[10:11] op_sel_hi:[1,0,1]
	v_pk_fma_f32 v[12:13], v[98:99], s[22:23], v[12:13] op_sel_hi:[1,0,1]
	v_pk_fma_f32 v[16:17], v[204:205], s[38:39], v[16:17] op_sel_hi:[1,0,1]
	v_pk_fma_f32 v[18:19], v[206:207], s[38:39], v[18:19] op_sel_hi:[1,0,1]
	v_pk_fma_f32 v[20:21], v[84:85], s[38:39], v[20:21] op_sel_hi:[1,0,1]
	v_readlane_b32 s23, v46, 0
	v_cvt_scalef32_pk_f32_fp4 v[38:39], v89, 1.0 op_sel:[1,0,0]
	v_cvt_scalef32_pk_f32_fp4 v[40:41], v89, 1.0 op_sel:[0,1,0]
	v_cvt_scalef32_pk_f32_fp4 v[42:43], v89, 1.0 op_sel:[1,1,0]
	v_pk_fma_f32 v[16:17], v[230:231], s[56:57], v[16:17] op_sel_hi:[1,0,1]
	v_pk_fma_f32 v[18:19], v[232:233], s[56:57], v[18:19] op_sel_hi:[1,0,1]
	v_pk_fma_f32 v[20:21], v[86:87], s[56:57], v[20:21] op_sel_hi:[1,0,1]
	v_pk_fma_f32 v[16:17], v[38:39], s[62:63], v[16:17] op_sel_hi:[1,0,1]
	v_pk_fma_f32 v[18:19], v[40:41], s[62:63], v[18:19] op_sel_hi:[1,0,1]
	v_pk_fma_f32 v[20:21], v[42:43], s[62:63], v[20:21] op_sel_hi:[1,0,1]
	s_waitcnt vmcnt(5)
	v_cvt_scalef32_pk_f32_fp4 v[34:35], v90, 1.0
	v_cvt_scalef32_pk_f32_fp4 v[36:37], v90, 1.0 op_sel:[1,0,0]
	v_cvt_scalef32_pk_f32_fp4 v[38:39], v90, 1.0 op_sel:[0,1,0]
	v_cvt_scalef32_pk_f32_fp4 v[40:41], v90, 1.0 op_sel:[1,1,0]
	v_cvt_scalef32_pk_f32_fp4 v[42:43], v91, 1.0
	v_cvt_scalef32_pk_f32_fp4 v[44:45], v91, 1.0 op_sel:[1,0,0]
	v_cvt_scalef32_pk_f32_fp4 v[30:31], v91, 1.0 op_sel:[0,1,0]
	v_cvt_scalef32_pk_f32_fp4 v[26:27], v91, 1.0 op_sel:[1,1,0]
	buffer_load_dwordx2 v[90:91], v192, s[4:7], s23 offen
	v_readlane_b32 s23, v46, 1
	v_pk_fma_f32 v[10:11], v[110:111], s[24:25], v[10:11] op_sel_hi:[1,0,1]
	v_pk_fma_f32 v[8:9], v[108:109], s[24:25], v[8:9] op_sel_hi:[1,0,1]
	v_pk_fma_f32 v[10:11], v[124:125], s[26:27], v[10:11] op_sel_hi:[1,0,1]
	v_pk_fma_f32 v[8:9], v[122:123], s[26:27], v[8:9] op_sel_hi:[1,0,1]
	s_nop 0
	buffer_load_dwordx2 v[96:97], v192, s[4:7], s23 offen
	v_readlane_b32 s23, v46, 2
	v_pk_fma_f32 v[8:9], v[136:137], s[28:29], v[8:9] op_sel_hi:[1,0,1]
	v_pk_fma_f32 v[12:13], v[112:113], s[24:25], v[12:13] op_sel_hi:[1,0,1]
	v_pk_fma_f32 v[10:11], v[138:139], s[28:29], v[10:11] op_sel_hi:[1,0,1]
	v_pk_fma_f32 v[12:13], v[126:127], s[26:27], v[12:13] op_sel_hi:[1,0,1]
	s_nop 0
	buffer_load_dwordx2 v[114:115], v192, s[4:7], s23 offen
	v_readlane_b32 s23, v46, 3
	v_pk_fma_f32 v[12:13], v[140:141], s[28:29], v[12:13] op_sel_hi:[1,0,1]
	v_readlane_b32 s25, v46, 6
	v_readlane_b32 s27, v46, 7
	v_pk_fma_f32 v[10:11], v[152:153], s[30:31], v[10:11] op_sel_hi:[1,0,1]
	s_nop 0
	buffer_load_dwordx2 v[124:125], v192, s[4:7], s23 offen
	v_readlane_b32 s23, v46, 4
	v_pk_fma_f32 v[12:13], v[154:155], s[30:31], v[12:13] op_sel_hi:[1,0,1]
	v_pk_fma_f32 v[8:9], v[150:151], s[30:31], v[8:9] op_sel_hi:[1,0,1]
	s_nop 2
	buffer_load_dwordx2 v[136:137], v192, s[4:7], s23 offen
	v_readlane_b32 s23, v46, 5
	s_nop 3
	s_nop 0
	buffer_load_dwordx2 v[152:153], v192, s[4:7], s23 offen
	buffer_load_dwordx2 v[154:155], v192, s[4:7], s25 offen
	buffer_load_dwordx2 v[158:159], v192, s[4:7], s27 offen
	v_readlane_b32 s23, v46, 8
	v_readlane_b32 s25, v46, 9
	v_readlane_b32 s27, v46, 10
	v_readlane_b32 s29, v46, 11
	v_pk_fma_f32 v[8:9], v[164:165], s[34:35], v[8:9] op_sel_hi:[1,0,1]
	v_pk_fma_f32 v[10:11], v[166:167], s[34:35], v[10:11] op_sel_hi:[1,0,1]
	buffer_load_dwordx2 v[160:161], v192, s[4:7], s23 offen
	buffer_load_dwordx2 v[162:163], v192, s[4:7], s25 offen
	buffer_load_dwordx2 v[164:165], v192, s[4:7], s27 offen
	buffer_load_dwordx2 v[166:167], v192, s[4:7], s29 offen
	v_readlane_b32 s23, v46, 12
	v_readlane_b32 s25, v46, 13
	v_readlane_b32 s27, v46, 14
	v_readlane_b32 s29, v46, 15
	v_readlane_b32 s20, v3, 10
	v_readlane_b32 s22, v3, 11
	v_readlane_b32 s24, v3, 12
	v_readlane_b32 s26, v3, 13
	v_readlane_b32 s28, v3, 14
	s_waitcnt vmcnt(13)
	v_cvt_scalef32_pk_f32_fp4 v[116:117], v6, 1.0
	v_cvt_scalef32_pk_f32_fp4 v[120:121], v6, 1.0 op_sel:[1,0,0]
	v_cvt_scalef32_pk_f32_fp4 v[122:123], v6, 1.0 op_sel:[0,1,0]
	v_cvt_scalef32_pk_f32_fp4 v[126:127], v6, 1.0 op_sel:[1,1,0]
	v_cvt_scalef32_pk_f32_fp4 v[128:129], v7, 1.0
	v_cvt_scalef32_pk_f32_fp4 v[130:131], v7, 1.0 op_sel:[1,0,0]
	v_cvt_scalef32_pk_f32_fp4 v[132:133], v7, 1.0 op_sel:[0,1,0]
	v_cvt_scalef32_pk_f32_fp4 v[134:135], v7, 1.0 op_sel:[1,1,0]
	v_readlane_b32 s30, v3, 15
	ds_read2_b32 v[2:3], v47 offset0:96 offset1:112
	buffer_load_dwordx2 v[46:47], v192, s[4:7], s23 offen
	buffer_load_dwordx2 v[170:171], v192, s[4:7], s25 offen
	buffer_load_dwordx2 v[172:173], v192, s[4:7], s27 offen
	buffer_load_dwordx2 v[6:7], v192, s[4:7], s29 offen
	v_pk_fma_f32 v[8:9], v[178:179], s[36:37], v[8:9] op_sel_hi:[1,0,1]
	v_cvt_scalef32_pk_f32_fp4 v[236:237], v88, 1.0 op_sel:[1,0,0]
	v_pk_fma_f32 v[8:9], v[196:197], s[38:39], v[8:9] op_sel_hi:[1,0,1]
	v_cvt_scalef32_pk_f32_fp4 v[50:51], v92, 1.0 op_sel:[1,0,0]
	v_pk_fma_f32 v[8:9], v[210:211], s[56:57], v[8:9] op_sel_hi:[1,0,1]
	v_cvt_scalef32_pk_f32_fp4 v[56:57], v93, 1.0
	v_pk_fma_f32 v[8:9], v[236:237], s[62:63], v[8:9] op_sel_hi:[1,0,1]
	v_cvt_scalef32_pk_f32_fp4 v[86:87], v32, 1.0 op_sel:[1,0,0]
	v_pk_fma_f32 v[8:9], v[36:37], s[20:21], v[8:9] op_sel_hi:[1,0,1]
	v_pk_fma_f32 v[14:15], v[42:43], s[20:21], v[14:15] op_sel_hi:[1,0,1]
	v_pk_fma_f32 v[8:9], v[50:51], s[22:23], v[8:9] op_sel_hi:[1,0,1]
	v_cvt_scalef32_pk_f32_fp4 v[94:95], v33, 1.0
	v_cvt_scalef32_pk_f32_fp4 v[104:105], v22, 1.0 op_sel:[1,0,0]
	v_pk_fma_f32 v[8:9], v[86:87], s[24:25], v[8:9] op_sel_hi:[1,0,1]
	v_pk_fma_f32 v[14:15], v[56:57], s[22:23], v[14:15] op_sel_hi:[1,0,1]
	v_cvt_scalef32_pk_f32_fp4 v[48:49], v92, 1.0
	v_cvt_scalef32_pk_f32_fp4 v[110:111], v23, 1.0
	v_pk_fma_f32 v[24:25], v[34:35], s[20:21], v[24:25] op_sel_hi:[1,0,1]
	v_pk_fma_f32 v[8:9], v[104:105], s[26:27], v[8:9] op_sel_hi:[1,0,1]
	v_pk_fma_f32 v[14:15], v[94:95], s[24:25], v[14:15] op_sel_hi:[1,0,1]
	v_cvt_scalef32_pk_f32_fp4 v[84:85], v32, 1.0
	s_waitcnt vmcnt(16)
	v_cvt_scalef32_pk_f32_fp4 v[140:141], v4, 1.0 op_sel:[1,0,0]
	v_pk_fma_f32 v[24:25], v[48:49], s[22:23], v[24:25] op_sel_hi:[1,0,1]
	v_pk_fma_f32 v[8:9], v[120:121], s[28:29], v[8:9] op_sel_hi:[1,0,1]
	v_pk_fma_f32 v[14:15], v[110:111], s[26:27], v[14:15] op_sel_hi:[1,0,1]
	v_pk_fma_f32 v[12:13], v[168:169], s[34:35], v[12:13] op_sel_hi:[1,0,1]
	v_cvt_scalef32_pk_f32_fp4 v[102:103], v22, 1.0
	v_cvt_scalef32_pk_f32_fp4 v[146:147], v5, 1.0
	s_waitcnt lgkmcnt(0)
	v_readlane_b32 s34, v2, 0
	s_waitcnt vmcnt(15)
	v_cvt_scalef32_pk_f32_fp4 v[168:169], v90, 1.0 op_sel:[1,0,0]
	v_pk_fma_f32 v[24:25], v[84:85], s[24:25], v[24:25] op_sel_hi:[1,0,1]
	v_pk_fma_f32 v[8:9], v[140:141], s[30:31], v[8:9] op_sel_hi:[1,0,1]
	v_pk_fma_f32 v[14:15], v[128:129], s[28:29], v[14:15] op_sel_hi:[1,0,1]
	v_pk_fma_f32 v[10:11], v[180:181], s[36:37], v[10:11] op_sel_hi:[1,0,1]
	v_pk_fma_f32 v[12:13], v[182:183], s[36:37], v[12:13] op_sel_hi:[1,0,1]
	v_cvt_scalef32_pk_f32_fp4 v[178:179], v91, 1.0
	v_readlane_b32 s36, v2, 1
	s_waitcnt vmcnt(14)
	v_cvt_scalef32_pk_f32_fp4 v[186:187], v96, 1.0 op_sel:[1,0,0]
	v_pk_fma_f32 v[24:25], v[102:103], s[26:27], v[24:25] op_sel_hi:[1,0,1]
	v_pk_fma_f32 v[8:9], v[168:169], s[34:35], v[8:9] op_sel_hi:[1,0,1]
	v_pk_fma_f32 v[14:15], v[146:147], s[30:31], v[14:15] op_sel_hi:[1,0,1]
	v_pk_fma_f32 v[10:11], v[198:199], s[38:39], v[10:11] op_sel_hi:[1,0,1]
	v_pk_fma_f32 v[12:13], v[200:201], s[38:39], v[12:13] op_sel_hi:[1,0,1]
	v_cvt_scalef32_pk_f32_fp4 v[138:139], v4, 1.0
	v_cvt_scalef32_pk_f32_fp4 v[196:197], v97, 1.0
	v_readlane_b32 s38, v2, 2
	s_waitcnt vmcnt(13)
	v_cvt_scalef32_pk_f32_fp4 v[204:205], v114, 1.0 op_sel:[1,0,0]
	v_pk_fma_f32 v[24:25], v[116:117], s[28:29], v[24:25] op_sel_hi:[1,0,1]
	v_pk_fma_f32 v[8:9], v[186:187], s[36:37], v[8:9] op_sel_hi:[1,0,1]
	v_pk_fma_f32 v[14:15], v[178:179], s[34:35], v[14:15] op_sel_hi:[1,0,1]
	v_cvt_scalef32_pk_f32_fp4 v[238:239], v88, 1.0 op_sel:[0,1,0]
	v_cvt_scalef32_pk_f32_fp4 v[240:241], v88, 1.0 op_sel:[1,1,0]
	v_pk_fma_f32 v[10:11], v[214:215], s[56:57], v[10:11] op_sel_hi:[1,0,1]
	v_pk_fma_f32 v[12:13], v[216:217], s[56:57], v[12:13] op_sel_hi:[1,0,1]
	v_cvt_scalef32_pk_f32_fp4 v[156:157], v90, 1.0
	v_cvt_scalef32_pk_f32_fp4 v[210:211], v115, 1.0
	v_readlane_b32 s56, v2, 3
	s_waitcnt vmcnt(12)
	v_cvt_scalef32_pk_f32_fp4 v[230:231], v124, 1.0 op_sel:[1,0,0]
	v_pk_fma_f32 v[24:25], v[138:139], s[30:31], v[24:25] op_sel_hi:[1,0,1]
	v_pk_fma_f32 v[8:9], v[204:205], s[38:39], v[8:9] op_sel_hi:[1,0,1]
	v_pk_fma_f32 v[14:15], v[196:197], s[36:37], v[14:15] op_sel_hi:[1,0,1]
	v_pk_fma_f32 v[10:11], v[238:239], s[62:63], v[10:11] op_sel_hi:[1,0,1]
	v_pk_fma_f32 v[12:13], v[240:241], s[62:63], v[12:13] op_sel_hi:[1,0,1]
	v_cvt_scalef32_pk_f32_fp4 v[184:185], v96, 1.0
	v_cvt_scalef32_pk_f32_fp4 v[236:237], v125, 1.0
	v_readlane_b32 s62, v2, 4
	s_waitcnt vmcnt(11)
	v_cvt_scalef32_pk_f32_fp4 v[244:245], v136, 1.0 op_sel:[1,0,0]
	v_pk_fma_f32 v[24:25], v[156:157], s[34:35], v[24:25] op_sel_hi:[1,0,1]
	v_pk_fma_f32 v[8:9], v[230:231], s[56:57], v[8:9] op_sel_hi:[1,0,1]
	v_pk_fma_f32 v[14:15], v[210:211], s[38:39], v[14:15] op_sel_hi:[1,0,1]
	v_cvt_scalef32_pk_f32_fp4 v[52:53], v92, 1.0 op_sel:[0,1,0]
	v_cvt_scalef32_pk_f32_fp4 v[188:189], v96, 1.0 op_sel:[0,1,0]
	v_cvt_scalef32_pk_f32_fp4 v[190:191], v96, 1.0 op_sel:[1,1,0]
	v_cvt_scalef32_pk_f32_fp4 v[198:199], v97, 1.0 op_sel:[1,0,0]
	v_cvt_scalef32_pk_f32_fp4 v[200:201], v97, 1.0 op_sel:[0,1,0]
	v_cvt_scalef32_pk_f32_fp4 v[202:203], v97, 1.0 op_sel:[1,1,0]
	v_cvt_scalef32_pk_f32_fp4 v[96:97], v114, 1.0
	v_pk_fma_f32 v[24:25], v[184:185], s[36:37], v[24:25] op_sel_hi:[1,0,1]
	v_pk_fma_f32 v[120:121], v[244:245], s[62:63], v[8:9] op_sel_hi:[1,0,1]
	v_pk_fma_f32 v[8:9], v[38:39], s[20:21], v[10:11] op_sel_hi:[1,0,1]
	v_cvt_scalef32_pk_f32_fp4 v[10:11], v137, 1.0
	v_pk_fma_f32 v[14:15], v[236:237], s[56:57], v[14:15] op_sel_hi:[1,0,1]
	v_cvt_scalef32_pk_f32_fp4 v[80:81], v93, 1.0 op_sel:[1,0,0]
	v_cvt_scalef32_pk_f32_fp4 v[88:89], v32, 1.0 op_sel:[0,1,0]
	v_pk_fma_f32 v[24:25], v[96:97], s[38:39], v[24:25] op_sel_hi:[1,0,1]
	v_pk_fma_f32 v[8:9], v[52:53], s[22:23], v[8:9] op_sel_hi:[1,0,1]
	v_pk_fma_f32 v[96:97], v[10:11], s[62:63], v[14:15] op_sel_hi:[1,0,1]
	v_pk_fma_f32 v[10:11], v[44:45], s[20:21], v[16:17] op_sel_hi:[1,0,1]
	v_cvt_scalef32_pk_f32_fp4 v[98:99], v33, 1.0 op_sel:[1,0,0]
	v_cvt_scalef32_pk_f32_fp4 v[106:107], v22, 1.0 op_sel:[0,1,0]
	v_pk_fma_f32 v[8:9], v[88:89], s[24:25], v[8:9] op_sel_hi:[1,0,1]
	v_pk_fma_f32 v[10:11], v[80:81], s[22:23], v[10:11] op_sel_hi:[1,0,1]
	v_cvt_scalef32_pk_f32_fp4 v[112:113], v23, 1.0 op_sel:[1,0,0]
	v_pk_fma_f32 v[8:9], v[106:107], s[26:27], v[8:9] op_sel_hi:[1,0,1]
	v_pk_fma_f32 v[10:11], v[98:99], s[24:25], v[10:11] op_sel_hi:[1,0,1]
	v_cvt_scalef32_pk_f32_fp4 v[28:29], v93, 1.0 op_sel:[1,1,0]
	v_cvt_scalef32_pk_f32_fp4 v[142:143], v4, 1.0 op_sel:[0,1,0]
	v_pk_fma_f32 v[8:9], v[122:123], s[28:29], v[8:9] op_sel_hi:[1,0,1]
	v_pk_fma_f32 v[10:11], v[112:113], s[26:27], v[10:11] op_sel_hi:[1,0,1]
	v_pk_fma_f32 v[14:15], v[26:27], s[20:21], v[20:21] op_sel_hi:[1,0,1]
	v_cvt_scalef32_pk_f32_fp4 v[54:55], v92, 1.0 op_sel:[1,1,0]
	v_cvt_scalef32_pk_f32_fp4 v[82:83], v93, 1.0 op_sel:[0,1,0]
	v_cvt_scalef32_pk_f32_fp4 v[92:93], v32, 1.0 op_sel:[1,1,0]
	v_cvt_scalef32_pk_f32_fp4 v[100:101], v33, 1.0 op_sel:[0,1,0]
	v_cvt_scalef32_pk_f32_fp4 v[32:33], v33, 1.0 op_sel:[1,1,0]
	v_cvt_scalef32_pk_f32_fp4 v[148:149], v5, 1.0 op_sel:[1,0,0]
	v_cvt_scalef32_pk_f32_fp4 v[174:175], v90, 1.0 op_sel:[0,1,0]
	v_pk_fma_f32 v[8:9], v[142:143], s[30:31], v[8:9] op_sel_hi:[1,0,1]
	v_pk_fma_f32 v[10:11], v[130:131], s[28:29], v[10:11] op_sel_hi:[1,0,1]
	v_pk_fma_f32 v[14:15], v[28:29], s[22:23], v[14:15] op_sel_hi:[1,0,1]
	v_cvt_scalef32_pk_f32_fp4 v[108:109], v22, 1.0 op_sel:[1,1,0]
	v_cvt_scalef32_pk_f32_fp4 v[118:119], v23, 1.0 op_sel:[0,1,0]
	v_cvt_scalef32_pk_f32_fp4 v[22:23], v23, 1.0 op_sel:[1,1,0]
	v_cvt_scalef32_pk_f32_fp4 v[180:181], v91, 1.0 op_sel:[1,0,0]
	v_pk_fma_f32 v[8:9], v[174:175], s[34:35], v[8:9] op_sel_hi:[1,0,1]
	v_pk_fma_f32 v[10:11], v[148:149], s[30:31], v[10:11] op_sel_hi:[1,0,1]
	v_pk_fma_f32 v[14:15], v[32:33], s[24:25], v[14:15] op_sel_hi:[1,0,1]
	v_cvt_scalef32_pk_f32_fp4 v[206:207], v114, 1.0 op_sel:[0,1,0]
	v_pk_fma_f32 v[8:9], v[188:189], s[36:37], v[8:9] op_sel_hi:[1,0,1]
	v_pk_fma_f32 v[10:11], v[180:181], s[34:35], v[10:11] op_sel_hi:[1,0,1]
	v_pk_fma_f32 v[14:15], v[22:23], s[26:27], v[14:15] op_sel_hi:[1,0,1]
	v_cvt_scalef32_pk_f32_fp4 v[144:145], v4, 1.0 op_sel:[1,1,0]
	v_cvt_scalef32_pk_f32_fp4 v[150:151], v5, 1.0 op_sel:[0,1,0]
	v_cvt_scalef32_pk_f32_fp4 v[4:5], v5, 1.0 op_sel:[1,1,0]
	v_cvt_scalef32_pk_f32_fp4 v[214:215], v115, 1.0 op_sel:[1,0,0]
	v_cvt_scalef32_pk_f32_fp4 v[232:233], v124, 1.0 op_sel:[0,1,0]
	v_pk_fma_f32 v[8:9], v[206:207], s[38:39], v[8:9] op_sel_hi:[1,0,1]
	v_pk_fma_f32 v[10:11], v[198:199], s[36:37], v[10:11] op_sel_hi:[1,0,1]
	v_pk_fma_f32 v[14:15], v[134:135], s[28:29], v[14:15] op_sel_hi:[1,0,1]
	v_cvt_scalef32_pk_f32_fp4 v[176:177], v90, 1.0 op_sel:[1,1,0]
	v_cvt_scalef32_pk_f32_fp4 v[182:183], v91, 1.0 op_sel:[0,1,0]
	v_cvt_scalef32_pk_f32_fp4 v[90:91], v91, 1.0 op_sel:[1,1,0]
	v_cvt_scalef32_pk_f32_fp4 v[228:229], v124, 1.0
	v_cvt_scalef32_pk_f32_fp4 v[238:239], v125, 1.0 op_sel:[1,0,0]
	v_cvt_scalef32_pk_f32_fp4 v[246:247], v136, 1.0 op_sel:[0,1,0]
	v_pk_fma_f32 v[8:9], v[232:233], s[56:57], v[8:9] op_sel_hi:[1,0,1]
	v_pk_fma_f32 v[10:11], v[214:215], s[38:39], v[10:11] op_sel_hi:[1,0,1]
	v_pk_fma_f32 v[4:5], v[4:5], s[30:31], v[14:15] op_sel_hi:[1,0,1]
	v_cvt_scalef32_pk_f32_fp4 v[242:243], v136, 1.0
	v_pk_fma_f32 v[24:25], v[228:229], s[56:57], v[24:25] op_sel_hi:[1,0,1]
	v_pk_fma_f32 v[116:117], v[246:247], s[62:63], v[8:9] op_sel_hi:[1,0,1]
	v_pk_fma_f32 v[8:9], v[40:41], s[20:21], v[12:13] op_sel_hi:[1,0,1]
	v_cvt_scalef32_pk_f32_fp4 v[12:13], v137, 1.0 op_sel:[1,0,0]
	v_pk_fma_f32 v[10:11], v[238:239], s[56:57], v[10:11] op_sel_hi:[1,0,1]
	v_pk_fma_f32 v[4:5], v[90:91], s[34:35], v[4:5] op_sel_hi:[1,0,1]
	v_cvt_scalef32_pk_f32_fp4 v[208:209], v114, 1.0 op_sel:[1,1,0]
	v_cvt_scalef32_pk_f32_fp4 v[216:217], v115, 1.0 op_sel:[0,1,0]
	v_cvt_scalef32_pk_f32_fp4 v[114:115], v115, 1.0 op_sel:[1,1,0]
	v_pk_fma_f32 v[138:139], v[242:243], s[62:63], v[24:25] op_sel_hi:[1,0,1]
	v_pk_fma_f32 v[8:9], v[54:55], s[22:23], v[8:9] op_sel_hi:[1,0,1]
	v_pk_fma_f32 v[10:11], v[12:13], s[62:63], v[10:11] op_sel_hi:[1,0,1]
	v_pk_fma_f32 v[12:13], v[30:31], s[20:21], v[18:19] op_sel_hi:[1,0,1]
	v_pk_fma_f32 v[4:5], v[202:203], s[36:37], v[4:5] op_sel_hi:[1,0,1]
	v_readlane_b32 s20, v2, 5
	s_waitcnt vmcnt(10)
	v_cvt_scalef32_pk_f32_fp4 v[110:111], v152, 1.0
	v_pk_fma_f32 v[8:9], v[92:93], s[24:25], v[8:9] op_sel_hi:[1,0,1]
	v_pk_fma_f32 v[12:13], v[82:83], s[22:23], v[12:13] op_sel_hi:[1,0,1]
	v_pk_fma_f32 v[4:5], v[114:115], s[38:39], v[4:5] op_sel_hi:[1,0,1]
	v_readlane_b32 s22, v2, 6
	s_waitcnt vmcnt(9)
	v_cvt_scalef32_pk_f32_fp4 v[114:115], v154, 1.0
	v_pk_fma_f32 v[110:111], v[110:111], s[20:21], v[138:139] op_sel_hi:[1,0,1]
	v_pk_fma_f32 v[8:9], v[108:109], s[26:27], v[8:9] op_sel_hi:[1,0,1]
	v_pk_fma_f32 v[12:13], v[100:101], s[24:25], v[12:13] op_sel_hi:[1,0,1]
	v_readlane_b32 s24, v2, 7
	s_waitcnt vmcnt(8)
	v_cvt_scalef32_pk_f32_fp4 v[122:123], v158, 1.0
	v_pk_fma_f32 v[110:111], v[114:115], s[22:23], v[110:111] op_sel_hi:[1,0,1]
	v_pk_fma_f32 v[8:9], v[126:127], s[28:29], v[8:9] op_sel_hi:[1,0,1]
	v_pk_fma_f32 v[12:13], v[118:119], s[26:27], v[12:13] op_sel_hi:[1,0,1]
	v_readlane_b32 s26, v2, 8
	s_waitcnt vmcnt(7)
	v_cvt_scalef32_pk_f32_fp4 v[126:127], v160, 1.0
	v_pk_fma_f32 v[110:111], v[122:123], s[24:25], v[110:111] op_sel_hi:[1,0,1]
	v_pk_fma_f32 v[12:13], v[132:133], s[28:29], v[12:13] op_sel_hi:[1,0,1]
	v_readlane_b32 s28, v2, 9
	s_waitcnt vmcnt(6)
	v_cvt_scalef32_pk_f32_fp4 v[132:133], v162, 1.0
	v_pk_fma_f32 v[110:111], v[126:127], s[26:27], v[110:111] op_sel_hi:[1,0,1]
	v_cvt_scalef32_pk_f32_fp4 v[248:249], v136, 1.0 op_sel:[1,1,0]
	v_pk_fma_f32 v[8:9], v[144:145], s[30:31], v[8:9] op_sel_hi:[1,0,1]
	v_cvt_scalef32_pk_f32_fp4 v[24:25], v137, 1.0 op_sel:[0,1,0]
	v_cvt_scalef32_pk_f32_fp4 v[34:35], v137, 1.0 op_sel:[1,1,0]
	v_pk_fma_f32 v[12:13], v[150:151], s[30:31], v[12:13] op_sel_hi:[1,0,1]
	v_readlane_b32 s30, v2, 10
	s_waitcnt vmcnt(5)
	v_cvt_scalef32_pk_f32_fp4 v[136:137], v164, 1.0
	v_pk_fma_f32 v[110:111], v[132:133], s[28:29], v[110:111] op_sel_hi:[1,0,1]
	v_pk_fma_f32 v[8:9], v[176:177], s[34:35], v[8:9] op_sel_hi:[1,0,1]
	v_pk_fma_f32 v[12:13], v[182:183], s[34:35], v[12:13] op_sel_hi:[1,0,1]
	v_readlane_b32 s34, v2, 11
	s_waitcnt vmcnt(4)
	v_cvt_scalef32_pk_f32_fp4 v[180:181], v166, 1.0
	v_pk_fma_f32 v[110:111], v[136:137], s[30:31], v[110:111] op_sel_hi:[1,0,1]
	v_pk_fma_f32 v[8:9], v[190:191], s[36:37], v[8:9] op_sel_hi:[1,0,1]
	v_pk_fma_f32 v[12:13], v[200:201], s[36:37], v[12:13] op_sel_hi:[1,0,1]
	v_readlane_b32 s36, v2, 12
	s_waitcnt vmcnt(3)
	v_cvt_scalef32_pk_f32_fp4 v[200:201], v46, 1.0
	v_pk_fma_f32 v[110:111], v[180:181], s[34:35], v[110:111] op_sel_hi:[1,0,1]
	v_cvt_scalef32_pk_f32_fp4 v[234:235], v124, 1.0 op_sel:[1,1,0]
	v_cvt_scalef32_pk_f32_fp4 v[240:241], v125, 1.0 op_sel:[0,1,0]
	v_cvt_scalef32_pk_f32_fp4 v[124:125], v125, 1.0 op_sel:[1,1,0]
	v_pk_fma_f32 v[8:9], v[208:209], s[38:39], v[8:9] op_sel_hi:[1,0,1]
	v_pk_fma_f32 v[12:13], v[216:217], s[38:39], v[12:13] op_sel_hi:[1,0,1]
	v_readlane_b32 s38, v2, 13
	s_waitcnt vmcnt(2)
	v_cvt_scalef32_pk_f32_fp4 v[204:205], v170, 1.0
	v_pk_fma_f32 v[110:111], v[200:201], s[36:37], v[110:111] op_sel_hi:[1,0,1]
	v_pk_fma_f32 v[8:9], v[234:235], s[56:57], v[8:9] op_sel_hi:[1,0,1]
	v_pk_fma_f32 v[12:13], v[240:241], s[56:57], v[12:13] op_sel_hi:[1,0,1]
	v_pk_fma_f32 v[4:5], v[124:125], s[56:57], v[4:5] op_sel_hi:[1,0,1]
	v_readlane_b32 s56, v2, 14
	s_waitcnt vmcnt(1)
	v_cvt_scalef32_pk_f32_fp4 v[208:209], v172, 1.0
	v_pk_fma_f32 v[110:111], v[204:205], s[38:39], v[110:111] op_sel_hi:[1,0,1]
	v_pk_fma_f32 v[8:9], v[248:249], s[62:63], v[8:9] op_sel_hi:[1,0,1]
	v_pk_fma_f32 v[12:13], v[24:25], s[62:63], v[12:13] op_sel_hi:[1,0,1]
	v_pk_fma_f32 v[14:15], v[34:35], s[62:63], v[4:5] op_sel_hi:[1,0,1]
	v_cvt_scalef32_pk_f32_fp4 v[112:113], v152, 1.0 op_sel:[1,0,0]
	v_readlane_b32 s62, v2, 15
	s_waitcnt vmcnt(0)
	v_cvt_scalef32_pk_f32_fp4 v[214:215], v6, 1.0
	v_pk_fma_f32 v[110:111], v[208:209], s[56:57], v[110:111] op_sel_hi:[1,0,1]
	v_cvt_scalef32_pk_f32_fp4 v[118:119], v154, 1.0 op_sel:[1,0,0]
	v_pk_fma_f32 v[180:181], v[214:215], s[62:63], v[110:111] op_sel_hi:[1,0,1]
	v_pk_fma_f32 v[110:111], v[112:113], s[20:21], v[120:121] op_sel_hi:[1,0,1]
	v_cvt_scalef32_pk_f32_fp4 v[124:125], v158, 1.0 op_sel:[1,0,0]
	v_pk_fma_f32 v[110:111], v[118:119], s[22:23], v[110:111] op_sel_hi:[1,0,1]
	v_readlane_b32 s23, v0, 0
	v_cvt_scalef32_pk_f32_fp4 v[130:131], v160, 1.0 op_sel:[1,0,0]
	v_pk_fma_f32 v[110:111], v[124:125], s[24:25], v[110:111] op_sel_hi:[1,0,1]
	v_pk_fma_f32 v[138:139], v[130:131], s[26:27], v[110:111] op_sel_hi:[1,0,1]
	v_cvt_scalef32_pk_f32_fp4 v[134:135], v152, 1.0 op_sel:[0,1,0]
	s_nop 0
	buffer_load_dwordx2 v[110:111], v192, s[4:7], s23 offen
	v_readlane_b32 s23, v0, 1
	v_cvt_scalef32_pk_f32_fp4 v[140:141], v154, 1.0 op_sel:[0,1,0]
	v_cvt_scalef32_pk_f32_fp4 v[184:185], v162, 1.0 op_sel:[1,0,0]
	v_pk_fma_f32 v[116:117], v[134:135], s[20:21], v[116:117] op_sel_hi:[1,0,1]
	v_cvt_scalef32_pk_f32_fp4 v[142:143], v158, 1.0 op_sel:[0,1,0]
	s_nop 0
	buffer_load_dwordx2 v[112:113], v192, s[4:7], s23 offen
	v_readlane_b32 s23, v0, 2
	v_cvt_scalef32_pk_f32_fp4 v[190:191], v164, 1.0 op_sel:[1,0,0]
	v_pk_fma_f32 v[138:139], v[184:185], s[28:29], v[138:139] op_sel_hi:[1,0,1]
	v_cvt_scalef32_pk_f32_fp4 v[186:187], v160, 1.0 op_sel:[0,1,0]
	v_cvt_scalef32_pk_f32_fp4 v[198:199], v166, 1.0 op_sel:[1,0,0]
	s_nop 0
	buffer_load_dwordx2 v[114:115], v192, s[4:7], s23 offen
	v_readlane_b32 s23, v0, 3
	v_pk_fma_f32 v[138:139], v[190:191], s[30:31], v[138:139] op_sel_hi:[1,0,1]
	v_cvt_scalef32_pk_f32_fp4 v[188:189], v162, 1.0 op_sel:[0,1,0]
	v_cvt_scalef32_pk_f32_fp4 v[202:203], v46, 1.0 op_sel:[1,0,0]
	v_pk_fma_f32 v[138:139], v[198:199], s[34:35], v[138:139] op_sel_hi:[1,0,1]
	s_nop 0
	buffer_load_dwordx2 v[118:119], v192, s[4:7], s23 offen
	v_readlane_b32 s23, v0, 4
	v_cvt_scalef32_pk_f32_fp4 v[196:197], v164, 1.0 op_sel:[0,1,0]
	v_cvt_scalef32_pk_f32_fp4 v[206:207], v170, 1.0 op_sel:[1,0,0]
	v_pk_fma_f32 v[138:139], v[202:203], s[36:37], v[138:139] op_sel_hi:[1,0,1]
	v_cvt_scalef32_pk_f32_fp4 v[210:211], v172, 1.0 op_sel:[1,0,0]
	s_nop 0
	buffer_load_dwordx2 v[120:121], v192, s[4:7], s23 offen
	v_readlane_b32 s23, v0, 5
	v_pk_fma_f32 v[138:139], v[206:207], s[38:39], v[138:139] op_sel_hi:[1,0,1]
	v_cvt_scalef32_pk_f32_fp4 v[216:217], v6, 1.0 op_sel:[1,0,0]
	v_pk_fma_f32 v[138:139], v[210:211], s[56:57], v[138:139] op_sel_hi:[1,0,1]
	v_lshlrev_b64 v[204:205], 12, v[78:79]
	s_nop 0
	buffer_load_dwordx2 v[122:123], v192, s[4:7], s23 offen
	v_readlane_b32 s23, v0, 6
	v_pk_fma_f32 v[184:185], v[216:217], s[62:63], v[138:139] op_sel_hi:[1,0,1]
	v_cvt_scalef32_pk_f32_fp4 v[4:5], v166, 1.0 op_sel:[0,1,0]
	v_cvt_scalef32_pk_f32_fp4 v[176:177], v46, 1.0 op_sel:[0,1,0]
	v_cvt_scalef32_pk_f32_fp4 v[178:179], v170, 1.0 op_sel:[0,1,0]
	s_nop 0
	buffer_load_dwordx2 v[124:125], v192, s[4:7], s23 offen
	v_readlane_b32 s23, v0, 7
	v_cvt_scalef32_pk_f32_fp4 v[182:183], v172, 1.0 op_sel:[0,1,0]
	v_readlane_b32 s64, v3, 1
	v_readlane_b32 s66, v3, 2
	v_readlane_b32 s68, v3, 3
	s_nop 0
	buffer_load_dwordx2 v[126:127], v192, s[4:7], s23 offen
	v_readlane_b32 s23, v0, 8
	v_readlane_b32 s70, v3, 4
	v_readlane_b32 s72, v3, 5
	v_readlane_b32 s74, v3, 6
	v_readlane_b32 s76, v3, 7
	s_nop 0
	buffer_load_dwordx2 v[130:131], v192, s[4:7], s23 offen
	v_readlane_b32 s23, v0, 9
	v_readlane_b32 s78, v3, 8
	v_readlane_b32 s80, v3, 9
	v_readlane_b32 s82, v3, 10
	v_readlane_b32 s84, v3, 11
	s_nop 0
	buffer_load_dwordx2 v[132:133], v192, s[4:7], s23 offen
	v_readlane_b32 s23, v0, 10
	v_readlane_b32 s86, v3, 12
	s_nop 0
	v_pk_fma_f32 v[116:117], v[140:141], s[22:23], v[116:117] op_sel_hi:[1,0,1]
	v_readlane_b32 s88, v3, 13
	v_pk_fma_f32 v[116:117], v[142:143], s[24:25], v[116:117] op_sel_hi:[1,0,1]
	s_nop 0
	buffer_load_dwordx2 v[136:137], v192, s[4:7], s23 offen
	v_pk_fma_f32 v[116:117], v[186:187], s[26:27], v[116:117] op_sel_hi:[1,0,1]
	v_readlane_b32 s23, v0, 11
	v_pk_fma_f32 v[116:117], v[188:189], s[28:29], v[116:117] op_sel_hi:[1,0,1]
	v_pk_fma_f32 v[190:191], v[196:197], s[30:31], v[116:117] op_sel_hi:[1,0,1]
	v_readlane_b32 s25, v0, 13
	v_readlane_b32 s27, v0, 14
	s_nop 0
	buffer_load_dwordx2 v[116:117], v192, s[4:7], s23 offen
	v_readlane_b32 s23, v0, 12
	v_readlane_b32 s29, v0, 15
	v_add_u32_e32 v0, 0xffffe000, v78
	s_nop 2
	buffer_load_dwordx2 v[142:143], v192, s[4:7], s23 offen
	buffer_load_dwordx2 v[140:141], v192, s[4:7], s25 offen
	buffer_load_dwordx2 v[138:139], v192, s[4:7], s27 offen
	s_nop 0
	buffer_load_dwordx2 v[134:135], v192, s[4:7], s29 offen
	v_lshrrev_b32_e32 v0, 12, v0
	s_movk_i32 s6, 0x1fff
	v_add_u32_e32 v0, 1, v0
	v_cmp_lt_i32_e32 vcc, s6, v78
	s_mul_i32 s6, s60, 3
	v_mov_b64_e32 v[186:187], s[94:95]
	v_cndmask_b32_e32 v195, 0, v0, vcc
	v_add_u32_e32 v0, s6, v195
	v_mad_i64_i32 v[186:187], s[6:7], v0, s67, v[186:187]
	s_mov_b64 s[6:7], 0x9665000
	s_nop 0
	v_lshl_add_u64 v[188:189], v[186:187], 0, s[6:7]
	v_lshlrev_b32_e32 v0, 2, v58
	v_lshl_add_u64 v[186:187], v[68:69], 0, v[204:205]
	v_lshl_add_u64 v[200:201], v[188:189], 0, v[0:1]
	global_load_dwordx4 v[196:199], v[186:187], off
	s_nop 0
	global_load_dwordx4 v[200:203], v[200:201], off
	v_pk_fma_f32 v[4:5], v[4:5], s[34:35], v[190:191] op_sel_hi:[1,0,1]
	v_readlane_b32 s6, v3, 0
	v_pk_fma_f32 v[4:5], v[176:177], s[36:37], v[4:5] op_sel_hi:[1,0,1]
	s_waitcnt vmcnt(17)
	v_cvt_scalef32_pk_f32_fp4 v[176:177], v110, 1.0 op_sel:[1,0,0]
	v_pk_fma_f32 v[4:5], v[178:179], s[38:39], v[4:5] op_sel_hi:[1,0,1]
	s_waitcnt vmcnt(16)
	v_cvt_scalef32_pk_f32_fp4 v[178:179], v112, 1.0
	v_pk_fma_f32 v[190:191], v[182:183], s[56:57], v[4:5] op_sel_hi:[1,0,1]
	v_cvt_scalef32_pk_f32_fp4 v[4:5], v110, 1.0
	v_cvt_scalef32_pk_f32_fp4 v[182:183], v112, 1.0 op_sel:[1,0,0]
	v_pk_fma_f32 v[4:5], v[4:5], s[6:7], v[180:181] op_sel_hi:[1,0,1]
	v_pk_fma_f32 v[176:177], v[176:177], s[6:7], v[184:185] op_sel_hi:[1,0,1]
	s_waitcnt vmcnt(15)
	v_cvt_scalef32_pk_f32_fp4 v[206:207], v114, 1.0
	v_cvt_scalef32_pk_f32_fp4 v[208:209], v114, 1.0 op_sel:[1,0,0]
	v_pk_fma_f32 v[4:5], v[178:179], s[64:65], v[4:5] op_sel_hi:[1,0,1]
	v_pk_fma_f32 v[176:177], v[182:183], s[64:65], v[176:177] op_sel_hi:[1,0,1]
	s_waitcnt vmcnt(14)
	v_cvt_scalef32_pk_f32_fp4 v[210:211], v118, 1.0
	v_cvt_scalef32_pk_f32_fp4 v[214:215], v118, 1.0 op_sel:[1,0,0]
	v_pk_fma_f32 v[4:5], v[206:207], s[66:67], v[4:5] op_sel_hi:[1,0,1]
	v_pk_fma_f32 v[176:177], v[208:209], s[66:67], v[176:177] op_sel_hi:[1,0,1]
	s_waitcnt vmcnt(13)
	v_cvt_scalef32_pk_f32_fp4 v[216:217], v120, 1.0
	v_cvt_scalef32_pk_f32_fp4 v[228:229], v120, 1.0 op_sel:[1,0,0]
	v_pk_fma_f32 v[4:5], v[210:211], s[68:69], v[4:5] op_sel_hi:[1,0,1]
	v_pk_fma_f32 v[176:177], v[214:215], s[68:69], v[176:177] op_sel_hi:[1,0,1]
	s_waitcnt vmcnt(12)
	v_cvt_scalef32_pk_f32_fp4 v[230:231], v122, 1.0
	v_cvt_scalef32_pk_f32_fp4 v[232:233], v122, 1.0 op_sel:[1,0,0]
	v_pk_fma_f32 v[4:5], v[216:217], s[70:71], v[4:5] op_sel_hi:[1,0,1]
	v_pk_fma_f32 v[176:177], v[228:229], s[70:71], v[176:177] op_sel_hi:[1,0,1]
	s_waitcnt vmcnt(11)
	v_cvt_scalef32_pk_f32_fp4 v[234:235], v124, 1.0
	v_cvt_scalef32_pk_f32_fp4 v[236:237], v124, 1.0 op_sel:[1,0,0]
	v_pk_fma_f32 v[4:5], v[230:231], s[72:73], v[4:5] op_sel_hi:[1,0,1]
	v_pk_fma_f32 v[176:177], v[232:233], s[72:73], v[176:177] op_sel_hi:[1,0,1]
	s_waitcnt vmcnt(10)
	v_cvt_scalef32_pk_f32_fp4 v[238:239], v126, 1.0
	v_cvt_scalef32_pk_f32_fp4 v[240:241], v126, 1.0 op_sel:[1,0,0]
	v_pk_fma_f32 v[4:5], v[234:235], s[74:75], v[4:5] op_sel_hi:[1,0,1]
	v_pk_fma_f32 v[176:177], v[236:237], s[74:75], v[176:177] op_sel_hi:[1,0,1]
	s_waitcnt vmcnt(9)
	v_cvt_scalef32_pk_f32_fp4 v[242:243], v130, 1.0
	v_cvt_scalef32_pk_f32_fp4 v[244:245], v130, 1.0 op_sel:[1,0,0]
	v_pk_fma_f32 v[4:5], v[238:239], s[76:77], v[4:5] op_sel_hi:[1,0,1]
	v_pk_fma_f32 v[176:177], v[240:241], s[76:77], v[176:177] op_sel_hi:[1,0,1]
	v_pk_fma_f32 v[4:5], v[242:243], s[78:79], v[4:5] op_sel_hi:[1,0,1]
	s_waitcnt vmcnt(8)
	v_cvt_scalef32_pk_f32_fp4 v[246:247], v132, 1.0
	v_cvt_scalef32_pk_f32_fp4 v[248:249], v132, 1.0 op_sel:[1,0,0]
	v_pk_fma_f32 v[176:177], v[244:245], s[78:79], v[176:177] op_sel_hi:[1,0,1]
	v_pk_fma_f32 v[4:5], v[246:247], s[80:81], v[4:5] op_sel_hi:[1,0,1]
	v_pk_fma_f32 v[176:177], v[248:249], s[80:81], v[176:177] op_sel_hi:[1,0,1]
	v_readlane_b32 s90, v3, 14
	v_readlane_b32 s92, v3, 15
	s_waitcnt vmcnt(7)
	v_cvt_scalef32_pk_f32_fp4 v[180:181], v136, 1.0
	v_cvt_scalef32_pk_f32_fp4 v[178:179], v136, 1.0 op_sel:[1,0,0]
	v_pk_fma_f32 v[4:5], v[180:181], s[82:83], v[4:5] op_sel_hi:[1,0,1]
	v_pk_fma_f32 v[176:177], v[178:179], s[82:83], v[176:177] op_sel_hi:[1,0,1]
	v_mov_b32_e32 v73, v1
	v_cvt_scalef32_pk_f32_fp4 v[148:149], v152, 1.0 op_sel:[1,1,0]
	v_cvt_scalef32_pk_f32_fp4 v[144:145], v153, 1.0
	v_cvt_scalef32_pk_f32_fp4 v[56:57], v153, 1.0 op_sel:[1,0,0]
	s_waitcnt vmcnt(6)
	v_cvt_scalef32_pk_f32_fp4 v[178:179], v116, 1.0
	v_pk_fma_f32 v[4:5], v[178:179], s[84:85], v[4:5] op_sel_hi:[1,0,1]
	v_cvt_scalef32_pk_f32_fp4 v[180:181], v116, 1.0 op_sel:[1,0,0]
	v_cvt_scalef32_pk_f32_fp4 v[52:53], v153, 1.0 op_sel:[0,1,0]
	v_cvt_scalef32_pk_f32_fp4 v[16:17], v153, 1.0 op_sel:[1,1,0]
	s_waitcnt vmcnt(5)
	v_cvt_scalef32_pk_f32_fp4 v[182:183], v142, 1.0
	s_waitcnt vmcnt(4)
	v_cvt_scalef32_pk_f32_fp4 v[206:207], v140, 1.0
	v_pk_fma_f32 v[4:5], v[182:183], s[86:87], v[4:5] op_sel_hi:[1,0,1]
	s_waitcnt vmcnt(3)
	v_cvt_scalef32_pk_f32_fp4 v[210:211], v138, 1.0
	v_pk_fma_f32 v[4:5], v[206:207], s[88:89], v[4:5] op_sel_hi:[1,0,1]
	s_waitcnt vmcnt(2)
	v_cvt_scalef32_pk_f32_fp4 v[2:3], v134, 1.0
	v_pk_fma_f32 v[4:5], v[210:211], s[90:91], v[4:5] op_sel_hi:[1,0,1]
	v_cvt_scalef32_pk_f32_fp4 v[184:185], v142, 1.0 op_sel:[1,0,0]
	v_pk_fma_f32 v[2:3], v[2:3], s[92:93], v[4:5] op_sel_hi:[1,0,1]
	v_pk_fma_f32 v[4:5], v[180:181], s[84:85], v[176:177] op_sel_hi:[1,0,1]
	v_cvt_scalef32_pk_f32_fp4 v[208:209], v140, 1.0 op_sel:[1,0,0]
	v_pk_fma_f32 v[4:5], v[184:185], s[86:87], v[4:5] op_sel_hi:[1,0,1]
	v_cvt_scalef32_pk_f32_fp4 v[214:215], v138, 1.0 op_sel:[1,0,0]
	v_pk_fma_f32 v[4:5], v[208:209], s[88:89], v[4:5] op_sel_hi:[1,0,1]
	v_cvt_scalef32_pk_f32_fp4 v[216:217], v134, 1.0 op_sel:[1,0,0]
	v_pk_fma_f32 v[4:5], v[214:215], s[90:91], v[4:5] op_sel_hi:[1,0,1]
	v_lshl_add_u64 v[176:177], v[70:71], 0, v[204:205]
	v_pk_fma_f32 v[4:5], v[216:217], s[92:93], v[4:5] op_sel_hi:[1,0,1]
	v_lshl_add_u64 v[182:183], v[188:189], 0, v[72:73]
	s_waitcnt vmcnt(0)
	v_pk_fma_f32 v[2:3], v[2:3], v[200:201], v[196:197]
	v_pk_fma_f32 v[4:5], v[4:5], v[202:203], v[198:199]
	global_store_dwordx4 v[176:177], v[2:5], off
	global_load_dwordx4 v[178:181], v[186:187], off offset:16
	s_nop 0
	global_load_dwordx4 v[182:185], v[182:183], off
	v_cvt_scalef32_pk_f32_fp4 v[152:153], v154, 1.0 op_sel:[1,1,0]
	v_pk_fma_f32 v[8:9], v[148:149], s[20:21], v[8:9] op_sel_hi:[1,0,1]
	v_cvt_scalef32_pk_f32_fp4 v[156:157], v158, 1.0 op_sel:[1,1,0]
	v_pk_fma_f32 v[8:9], v[152:153], s[22:23], v[8:9] op_sel_hi:[1,0,1]
	v_cvt_scalef32_pk_f32_fp4 v[150:151], v159, 1.0
	v_cvt_scalef32_pk_f32_fp4 v[82:83], v159, 1.0 op_sel:[1,0,0]
	v_cvt_scalef32_pk_f32_fp4 v[24:25], v159, 1.0 op_sel:[0,1,0]
	v_cvt_scalef32_pk_f32_fp4 v[20:21], v159, 1.0 op_sel:[1,1,0]
	v_cvt_scalef32_pk_f32_fp4 v[158:159], v160, 1.0 op_sel:[1,1,0]
	v_pk_fma_f32 v[8:9], v[156:157], s[24:25], v[8:9] op_sel_hi:[1,0,1]
	v_cvt_scalef32_pk_f32_fp4 v[146:147], v155, 1.0
	v_cvt_scalef32_pk_f32_fp4 v[80:81], v155, 1.0 op_sel:[1,0,0]
	v_cvt_scalef32_pk_f32_fp4 v[54:55], v155, 1.0 op_sel:[0,1,0]
	v_cvt_scalef32_pk_f32_fp4 v[18:19], v155, 1.0 op_sel:[1,1,0]
	v_cvt_scalef32_pk_f32_fp4 v[154:155], v161, 1.0
	v_cvt_scalef32_pk_f32_fp4 v[84:85], v161, 1.0 op_sel:[1,0,0]
	v_cvt_scalef32_pk_f32_fp4 v[28:29], v161, 1.0 op_sel:[0,1,0]
	v_cvt_scalef32_pk_f32_fp4 v[22:23], v161, 1.0 op_sel:[1,1,0]
	v_cvt_scalef32_pk_f32_fp4 v[160:161], v162, 1.0 op_sel:[1,1,0]
	v_pk_fma_f32 v[8:9], v[158:159], s[26:27], v[8:9] op_sel_hi:[1,0,1]
	v_cvt_scalef32_pk_f32_fp4 v[90:91], v163, 1.0
	v_cvt_scalef32_pk_f32_fp4 v[86:87], v163, 1.0 op_sel:[1,0,0]
	v_cvt_scalef32_pk_f32_fp4 v[32:33], v163, 1.0 op_sel:[0,1,0]
	v_cvt_scalef32_pk_f32_fp4 v[26:27], v163, 1.0 op_sel:[1,1,0]
	v_cvt_scalef32_pk_f32_fp4 v[162:163], v164, 1.0 op_sel:[1,1,0]
	v_pk_fma_f32 v[8:9], v[160:161], s[28:29], v[8:9] op_sel_hi:[1,0,1]
	v_cvt_scalef32_pk_f32_fp4 v[94:95], v165, 1.0
	v_cvt_scalef32_pk_f32_fp4 v[88:89], v165, 1.0 op_sel:[1,0,0]
	v_cvt_scalef32_pk_f32_fp4 v[36:37], v165, 1.0 op_sel:[0,1,0]
	v_cvt_scalef32_pk_f32_fp4 v[30:31], v165, 1.0 op_sel:[1,1,0]
	v_cvt_scalef32_pk_f32_fp4 v[164:165], v166, 1.0 op_sel:[1,1,0]
	v_pk_fma_f32 v[8:9], v[162:163], s[30:31], v[8:9] op_sel_hi:[1,0,1]
	v_cvt_scalef32_pk_f32_fp4 v[100:101], v167, 1.0
	v_cvt_scalef32_pk_f32_fp4 v[92:93], v167, 1.0 op_sel:[1,0,0]
	v_cvt_scalef32_pk_f32_fp4 v[40:41], v167, 1.0 op_sel:[0,1,0]
	v_cvt_scalef32_pk_f32_fp4 v[34:35], v167, 1.0 op_sel:[1,1,0]
	v_cvt_scalef32_pk_f32_fp4 v[166:167], v46, 1.0 op_sel:[1,1,0]
	v_pk_fma_f32 v[8:9], v[164:165], s[34:35], v[8:9] op_sel_hi:[1,0,1]
	v_cvt_scalef32_pk_f32_fp4 v[104:105], v47, 1.0
	v_cvt_scalef32_pk_f32_fp4 v[98:99], v47, 1.0 op_sel:[1,0,0]
	v_cvt_scalef32_pk_f32_fp4 v[44:45], v47, 1.0 op_sel:[0,1,0]
	v_cvt_scalef32_pk_f32_fp4 v[38:39], v47, 1.0 op_sel:[1,1,0]
	v_cvt_scalef32_pk_f32_fp4 v[168:169], v170, 1.0 op_sel:[1,1,0]
	v_cvt_scalef32_pk_f32_fp4 v[108:109], v171, 1.0
	v_cvt_scalef32_pk_f32_fp4 v[102:103], v171, 1.0 op_sel:[1,0,0]
	v_cvt_scalef32_pk_f32_fp4 v[48:49], v171, 1.0 op_sel:[0,1,0]
	v_cvt_scalef32_pk_f32_fp4 v[42:43], v171, 1.0 op_sel:[1,1,0]
	v_cvt_scalef32_pk_f32_fp4 v[170:171], v172, 1.0 op_sel:[1,1,0]
	v_cvt_scalef32_pk_f32_fp4 v[128:129], v173, 1.0
	v_cvt_scalef32_pk_f32_fp4 v[106:107], v173, 1.0 op_sel:[1,0,0]
	v_cvt_scalef32_pk_f32_fp4 v[50:51], v173, 1.0 op_sel:[0,1,0]
	v_cvt_scalef32_pk_f32_fp4 v[46:47], v173, 1.0 op_sel:[1,1,0]
	v_cvt_scalef32_pk_f32_fp4 v[174:175], v6, 1.0 op_sel:[0,1,0]
	v_cvt_scalef32_pk_f32_fp4 v[172:173], v6, 1.0 op_sel:[1,1,0]
	v_pk_fma_f32 v[8:9], v[166:167], s[36:37], v[8:9] op_sel_hi:[1,0,1]
	v_cvt_scalef32_pk_f32_fp4 v[152:153], v7, 1.0
	v_cvt_scalef32_pk_f32_fp4 v[156:157], v7, 1.0 op_sel:[1,0,0]
	v_cvt_scalef32_pk_f32_fp4 v[158:159], v7, 1.0 op_sel:[0,1,0]
	v_cvt_scalef32_pk_f32_fp4 v[160:161], v7, 1.0 op_sel:[1,1,0]
	v_pk_fma_f32 v[6:7], v[144:145], s[20:21], v[96:97] op_sel_hi:[1,0,1]
	v_pk_fma_f32 v[8:9], v[168:169], s[38:39], v[8:9] op_sel_hi:[1,0,1]
	v_pk_fma_f32 v[6:7], v[146:147], s[22:23], v[6:7] op_sel_hi:[1,0,1]
	v_pk_fma_f32 v[8:9], v[170:171], s[56:57], v[8:9] op_sel_hi:[1,0,1]
	v_pk_fma_f32 v[6:7], v[150:151], s[24:25], v[6:7] op_sel_hi:[1,0,1]
	v_pk_fma_f32 v[174:175], v[174:175], s[62:63], v[190:191] op_sel_hi:[1,0,1]
	v_pk_fma_f32 v[8:9], v[172:173], s[62:63], v[8:9] op_sel_hi:[1,0,1]
	v_pk_fma_f32 v[96:97], v[154:155], s[26:27], v[6:7] op_sel_hi:[1,0,1]
	v_cvt_scalef32_pk_f32_fp4 v[6:7], v110, 1.0 op_sel:[0,1,0]
	v_cvt_scalef32_pk_f32_fp4 v[144:145], v110, 1.0 op_sel:[1,1,0]
	v_cvt_scalef32_pk_f32_fp4 v[146:147], v112, 1.0 op_sel:[0,1,0]
	v_cvt_scalef32_pk_f32_fp4 v[148:149], v112, 1.0 op_sel:[1,1,0]
	v_pk_fma_f32 v[6:7], v[6:7], s[6:7], v[174:175] op_sel_hi:[1,0,1]
	v_pk_fma_f32 v[8:9], v[144:145], s[6:7], v[8:9] op_sel_hi:[1,0,1]
	v_cvt_scalef32_pk_f32_fp4 v[150:151], v114, 1.0 op_sel:[0,1,0]
	v_cvt_scalef32_pk_f32_fp4 v[154:155], v114, 1.0 op_sel:[1,1,0]
	v_pk_fma_f32 v[6:7], v[146:147], s[64:65], v[6:7] op_sel_hi:[1,0,1]
	v_pk_fma_f32 v[8:9], v[148:149], s[64:65], v[8:9] op_sel_hi:[1,0,1]
	v_cvt_scalef32_pk_f32_fp4 v[162:163], v118, 1.0 op_sel:[0,1,0]
	v_cvt_scalef32_pk_f32_fp4 v[164:165], v118, 1.0 op_sel:[1,1,0]
	v_pk_fma_f32 v[6:7], v[150:151], s[66:67], v[6:7] op_sel_hi:[1,0,1]
	v_pk_fma_f32 v[8:9], v[154:155], s[66:67], v[8:9] op_sel_hi:[1,0,1]
	v_cvt_scalef32_pk_f32_fp4 v[166:167], v120, 1.0 op_sel:[0,1,0]
	v_cvt_scalef32_pk_f32_fp4 v[168:169], v120, 1.0 op_sel:[1,1,0]
	v_pk_fma_f32 v[6:7], v[162:163], s[68:69], v[6:7] op_sel_hi:[1,0,1]
	v_pk_fma_f32 v[8:9], v[164:165], s[68:69], v[8:9] op_sel_hi:[1,0,1]
	v_cvt_scalef32_pk_f32_fp4 v[170:171], v122, 1.0 op_sel:[0,1,0]
	v_cvt_scalef32_pk_f32_fp4 v[172:173], v122, 1.0 op_sel:[1,1,0]
	v_pk_fma_f32 v[6:7], v[166:167], s[70:71], v[6:7] op_sel_hi:[1,0,1]
	v_pk_fma_f32 v[8:9], v[168:169], s[70:71], v[8:9] op_sel_hi:[1,0,1]
	v_cvt_scalef32_pk_f32_fp4 v[190:191], v124, 1.0 op_sel:[0,1,0]
	v_cvt_scalef32_pk_f32_fp4 v[196:197], v124, 1.0 op_sel:[1,1,0]
	v_pk_fma_f32 v[6:7], v[170:171], s[72:73], v[6:7] op_sel_hi:[1,0,1]
	v_pk_fma_f32 v[8:9], v[172:173], s[72:73], v[8:9] op_sel_hi:[1,0,1]
	v_cvt_scalef32_pk_f32_fp4 v[198:199], v126, 1.0 op_sel:[0,1,0]
	v_cvt_scalef32_pk_f32_fp4 v[200:201], v126, 1.0 op_sel:[1,1,0]
	v_pk_fma_f32 v[6:7], v[190:191], s[74:75], v[6:7] op_sel_hi:[1,0,1]
	v_pk_fma_f32 v[8:9], v[196:197], s[74:75], v[8:9] op_sel_hi:[1,0,1]
	v_cvt_scalef32_pk_f32_fp4 v[202:203], v130, 1.0 op_sel:[0,1,0]
	v_cvt_scalef32_pk_f32_fp4 v[204:205], v130, 1.0 op_sel:[1,1,0]
	v_pk_fma_f32 v[6:7], v[198:199], s[76:77], v[6:7] op_sel_hi:[1,0,1]
	v_pk_fma_f32 v[8:9], v[200:201], s[76:77], v[8:9] op_sel_hi:[1,0,1]
	v_cvt_scalef32_pk_f32_fp4 v[206:207], v132, 1.0 op_sel:[0,1,0]
	v_cvt_scalef32_pk_f32_fp4 v[208:209], v132, 1.0 op_sel:[1,1,0]
	v_pk_fma_f32 v[6:7], v[202:203], s[78:79], v[6:7] op_sel_hi:[1,0,1]
	v_pk_fma_f32 v[8:9], v[204:205], s[78:79], v[8:9] op_sel_hi:[1,0,1]
	v_cvt_scalef32_pk_f32_fp4 v[210:211], v136, 1.0 op_sel:[0,1,0]
	v_cvt_scalef32_pk_f32_fp4 v[214:215], v136, 1.0 op_sel:[1,1,0]
	v_pk_fma_f32 v[6:7], v[206:207], s[80:81], v[6:7] op_sel_hi:[1,0,1]
	v_pk_fma_f32 v[8:9], v[208:209], s[80:81], v[8:9] op_sel_hi:[1,0,1]
	v_pk_fma_f32 v[6:7], v[210:211], s[82:83], v[6:7] op_sel_hi:[1,0,1]
	v_pk_fma_f32 v[8:9], v[214:215], s[82:83], v[8:9] op_sel_hi:[1,0,1]
	v_cvt_scalef32_pk_f32_fp4 v[144:145], v116, 1.0 op_sel:[0,1,0]
	v_cvt_scalef32_pk_f32_fp4 v[146:147], v116, 1.0 op_sel:[1,1,0]
	v_cvt_scalef32_pk_f32_fp4 v[148:149], v142, 1.0 op_sel:[0,1,0]
	v_cvt_scalef32_pk_f32_fp4 v[150:151], v142, 1.0 op_sel:[1,1,0]
	v_pk_fma_f32 v[6:7], v[144:145], s[84:85], v[6:7] op_sel_hi:[1,0,1]
	v_pk_fma_f32 v[8:9], v[146:147], s[84:85], v[8:9] op_sel_hi:[1,0,1]
	v_cvt_scalef32_pk_f32_fp4 v[154:155], v140, 1.0 op_sel:[0,1,0]
	v_cvt_scalef32_pk_f32_fp4 v[162:163], v140, 1.0 op_sel:[1,1,0]
	v_pk_fma_f32 v[6:7], v[148:149], s[86:87], v[6:7] op_sel_hi:[1,0,1]
	v_pk_fma_f32 v[8:9], v[150:151], s[86:87], v[8:9] op_sel_hi:[1,0,1]
	v_cvt_scalef32_pk_f32_fp4 v[164:165], v138, 1.0 op_sel:[0,1,0]
	v_cvt_scalef32_pk_f32_fp4 v[166:167], v138, 1.0 op_sel:[1,1,0]
	v_pk_fma_f32 v[6:7], v[154:155], s[88:89], v[6:7] op_sel_hi:[1,0,1]
	v_pk_fma_f32 v[8:9], v[162:163], s[88:89], v[8:9] op_sel_hi:[1,0,1]
	v_cvt_scalef32_pk_f32_fp4 v[168:169], v134, 1.0 op_sel:[0,1,0]
	v_cvt_scalef32_pk_f32_fp4 v[170:171], v134, 1.0 op_sel:[1,1,0]
	v_pk_fma_f32 v[6:7], v[164:165], s[90:91], v[6:7] op_sel_hi:[1,0,1]
	v_pk_fma_f32 v[8:9], v[166:167], s[90:91], v[8:9] op_sel_hi:[1,0,1]
	v_pk_fma_f32 v[6:7], v[168:169], s[92:93], v[6:7] op_sel_hi:[1,0,1]
	v_pk_fma_f32 v[8:9], v[170:171], s[92:93], v[8:9] op_sel_hi:[1,0,1]
	s_waitcnt vmcnt(0)
	v_pk_fma_f32 v[6:7], v[6:7], v[182:183], v[178:179]
	v_pk_fma_f32 v[8:9], v[8:9], v[184:185], v[180:181]
	global_store_dwordx4 v[176:177], v[6:9], off offset:16
	v_lshl_add_u64 v[148:149], v[188:189], 0, v[74:75]
	global_load_dwordx4 v[144:147], v[186:187], off offset:32
	s_nop 0
	global_load_dwordx4 v[148:151], v[148:149], off
	v_pk_fma_f32 v[10:11], v[56:57], s[20:21], v[10:11] op_sel_hi:[1,0,1]
	v_pk_fma_f32 v[90:91], v[90:91], s[28:29], v[96:97] op_sel_hi:[1,0,1]
	v_pk_fma_f32 v[10:11], v[80:81], s[22:23], v[10:11] op_sel_hi:[1,0,1]
	v_pk_fma_f32 v[90:91], v[94:95], s[30:31], v[90:91] op_sel_hi:[1,0,1]
	v_pk_fma_f32 v[10:11], v[82:83], s[24:25], v[10:11] op_sel_hi:[1,0,1]
	v_pk_fma_f32 v[90:91], v[100:101], s[34:35], v[90:91] op_sel_hi:[1,0,1]
	v_pk_fma_f32 v[10:11], v[84:85], s[26:27], v[10:11] op_sel_hi:[1,0,1]
	v_pk_fma_f32 v[90:91], v[104:105], s[36:37], v[90:91] op_sel_hi:[1,0,1]
	v_pk_fma_f32 v[10:11], v[86:87], s[28:29], v[10:11] op_sel_hi:[1,0,1]
	v_pk_fma_f32 v[90:91], v[108:109], s[38:39], v[90:91] op_sel_hi:[1,0,1]
	v_pk_fma_f32 v[10:11], v[88:89], s[30:31], v[10:11] op_sel_hi:[1,0,1]
	v_pk_fma_f32 v[90:91], v[128:129], s[56:57], v[90:91] op_sel_hi:[1,0,1]
	v_pk_fma_f32 v[10:11], v[92:93], s[34:35], v[10:11] op_sel_hi:[1,0,1]
	v_pk_fma_f32 v[12:13], v[52:53], s[20:21], v[12:13] op_sel_hi:[1,0,1]
	v_pk_fma_f32 v[10:11], v[98:99], s[36:37], v[10:11] op_sel_hi:[1,0,1]
	v_pk_fma_f32 v[90:91], v[152:153], s[62:63], v[90:91] op_sel_hi:[1,0,1]
	v_pk_fma_f32 v[10:11], v[102:103], s[38:39], v[10:11] op_sel_hi:[1,0,1]
	v_pk_fma_f32 v[56:57], v[54:55], s[22:23], v[12:13] op_sel_hi:[1,0,1]
	v_pk_fma_f32 v[10:11], v[106:107], s[56:57], v[10:11] op_sel_hi:[1,0,1]
	v_cvt_scalef32_pk_f32_fp4 v[12:13], v111, 1.0
	v_pk_fma_f32 v[10:11], v[156:157], s[62:63], v[10:11] op_sel_hi:[1,0,1]
	v_cvt_scalef32_pk_f32_fp4 v[52:53], v111, 1.0 op_sel:[1,0,0]
	v_cvt_scalef32_pk_f32_fp4 v[54:55], v113, 1.0
	v_cvt_scalef32_pk_f32_fp4 v[80:81], v113, 1.0 op_sel:[1,0,0]
	v_pk_fma_f32 v[12:13], v[12:13], s[6:7], v[90:91] op_sel_hi:[1,0,1]
	v_pk_fma_f32 v[10:11], v[52:53], s[6:7], v[10:11] op_sel_hi:[1,0,1]
	v_cvt_scalef32_pk_f32_fp4 v[82:83], v115, 1.0
	v_cvt_scalef32_pk_f32_fp4 v[84:85], v115, 1.0 op_sel:[1,0,0]
	v_pk_fma_f32 v[12:13], v[54:55], s[64:65], v[12:13] op_sel_hi:[1,0,1]
	v_pk_fma_f32 v[10:11], v[80:81], s[64:65], v[10:11] op_sel_hi:[1,0,1]
	v_cvt_scalef32_pk_f32_fp4 v[86:87], v119, 1.0
	v_cvt_scalef32_pk_f32_fp4 v[88:89], v119, 1.0 op_sel:[1,0,0]
	v_pk_fma_f32 v[12:13], v[82:83], s[66:67], v[12:13] op_sel_hi:[1,0,1]
	v_pk_fma_f32 v[10:11], v[84:85], s[66:67], v[10:11] op_sel_hi:[1,0,1]
	v_cvt_scalef32_pk_f32_fp4 v[92:93], v121, 1.0
	v_cvt_scalef32_pk_f32_fp4 v[94:95], v121, 1.0 op_sel:[1,0,0]
	v_pk_fma_f32 v[12:13], v[86:87], s[68:69], v[12:13] op_sel_hi:[1,0,1]
	v_pk_fma_f32 v[10:11], v[88:89], s[68:69], v[10:11] op_sel_hi:[1,0,1]
	v_cvt_scalef32_pk_f32_fp4 v[96:97], v123, 1.0
	v_cvt_scalef32_pk_f32_fp4 v[98:99], v123, 1.0 op_sel:[1,0,0]
	v_pk_fma_f32 v[12:13], v[92:93], s[70:71], v[12:13] op_sel_hi:[1,0,1]
	v_pk_fma_f32 v[10:11], v[94:95], s[70:71], v[10:11] op_sel_hi:[1,0,1]
	v_cvt_scalef32_pk_f32_fp4 v[100:101], v125, 1.0
	v_cvt_scalef32_pk_f32_fp4 v[102:103], v125, 1.0 op_sel:[1,0,0]
	v_pk_fma_f32 v[12:13], v[96:97], s[72:73], v[12:13] op_sel_hi:[1,0,1]
	v_pk_fma_f32 v[10:11], v[98:99], s[72:73], v[10:11] op_sel_hi:[1,0,1]
	v_cvt_scalef32_pk_f32_fp4 v[104:105], v127, 1.0
	v_cvt_scalef32_pk_f32_fp4 v[106:107], v127, 1.0 op_sel:[1,0,0]
	v_pk_fma_f32 v[12:13], v[100:101], s[74:75], v[12:13] op_sel_hi:[1,0,1]
	v_pk_fma_f32 v[10:11], v[102:103], s[74:75], v[10:11] op_sel_hi:[1,0,1]
	v_cvt_scalef32_pk_f32_fp4 v[108:109], v131, 1.0
	v_cvt_scalef32_pk_f32_fp4 v[128:129], v131, 1.0 op_sel:[1,0,0]
	v_pk_fma_f32 v[12:13], v[104:105], s[76:77], v[12:13] op_sel_hi:[1,0,1]
	v_pk_fma_f32 v[10:11], v[106:107], s[76:77], v[10:11] op_sel_hi:[1,0,1]
	v_cvt_scalef32_pk_f32_fp4 v[152:153], v133, 1.0
	v_cvt_scalef32_pk_f32_fp4 v[154:155], v133, 1.0 op_sel:[1,0,0]
	v_pk_fma_f32 v[12:13], v[108:109], s[78:79], v[12:13] op_sel_hi:[1,0,1]
	v_pk_fma_f32 v[10:11], v[128:129], s[78:79], v[10:11] op_sel_hi:[1,0,1]
	v_cvt_scalef32_pk_f32_fp4 v[156:157], v137, 1.0
	v_cvt_scalef32_pk_f32_fp4 v[162:163], v137, 1.0 op_sel:[1,0,0]
	v_pk_fma_f32 v[12:13], v[152:153], s[80:81], v[12:13] op_sel_hi:[1,0,1]
	v_pk_fma_f32 v[10:11], v[154:155], s[80:81], v[10:11] op_sel_hi:[1,0,1]
	v_pk_fma_f32 v[12:13], v[156:157], s[82:83], v[12:13] op_sel_hi:[1,0,1]
	v_pk_fma_f32 v[52:53], v[162:163], s[82:83], v[10:11] op_sel_hi:[1,0,1]
	v_cvt_scalef32_pk_f32_fp4 v[10:11], v117, 1.0
	v_cvt_scalef32_pk_f32_fp4 v[54:55], v117, 1.0 op_sel:[1,0,0]
	v_cvt_scalef32_pk_f32_fp4 v[80:81], v143, 1.0
	v_cvt_scalef32_pk_f32_fp4 v[82:83], v143, 1.0 op_sel:[1,0,0]
	v_pk_fma_f32 v[10:11], v[10:11], s[84:85], v[12:13] op_sel_hi:[1,0,1]
	v_pk_fma_f32 v[12:13], v[54:55], s[84:85], v[52:53] op_sel_hi:[1,0,1]
	v_cvt_scalef32_pk_f32_fp4 v[84:85], v141, 1.0
	v_cvt_scalef32_pk_f32_fp4 v[86:87], v141, 1.0 op_sel:[1,0,0]
	v_pk_fma_f32 v[10:11], v[80:81], s[86:87], v[10:11] op_sel_hi:[1,0,1]
	v_pk_fma_f32 v[12:13], v[82:83], s[86:87], v[12:13] op_sel_hi:[1,0,1]
	v_cvt_scalef32_pk_f32_fp4 v[88:89], v139, 1.0
	v_cvt_scalef32_pk_f32_fp4 v[90:91], v139, 1.0 op_sel:[1,0,0]
	v_pk_fma_f32 v[10:11], v[84:85], s[88:89], v[10:11] op_sel_hi:[1,0,1]
	v_pk_fma_f32 v[12:13], v[86:87], s[88:89], v[12:13] op_sel_hi:[1,0,1]
	v_cvt_scalef32_pk_f32_fp4 v[92:93], v135, 1.0
	v_cvt_scalef32_pk_f32_fp4 v[94:95], v135, 1.0 op_sel:[1,0,0]
	v_pk_fma_f32 v[10:11], v[88:89], s[90:91], v[10:11] op_sel_hi:[1,0,1]
	v_pk_fma_f32 v[12:13], v[90:91], s[90:91], v[12:13] op_sel_hi:[1,0,1]
	v_pk_fma_f32 v[10:11], v[92:93], s[92:93], v[10:11] op_sel_hi:[1,0,1]
	v_pk_fma_f32 v[12:13], v[94:95], s[92:93], v[12:13] op_sel_hi:[1,0,1]
	s_waitcnt vmcnt(0)
	v_pk_fma_f32 v[10:11], v[10:11], v[148:149], v[144:145]
	v_pk_fma_f32 v[12:13], v[12:13], v[150:151], v[146:147]
	global_store_dwordx4 v[176:177], v[10:13], off offset:32
	v_lshl_add_u64 v[80:81], v[188:189], 0, v[76:77]
	global_load_dwordx4 v[52:55], v[186:187], off offset:48
	s_nop 0
	global_load_dwordx4 v[80:83], v[80:81], off
	v_pk_fma_f32 v[14:15], v[16:17], s[20:21], v[14:15] op_sel_hi:[1,0,1]
	v_pk_fma_f32 v[24:25], v[24:25], s[24:25], v[56:57] op_sel_hi:[1,0,1]
	v_pk_fma_f32 v[14:15], v[18:19], s[22:23], v[14:15] op_sel_hi:[1,0,1]
	v_pk_fma_f32 v[24:25], v[28:29], s[26:27], v[24:25] op_sel_hi:[1,0,1]
	v_pk_fma_f32 v[14:15], v[20:21], s[24:25], v[14:15] op_sel_hi:[1,0,1]
	v_pk_fma_f32 v[24:25], v[32:33], s[28:29], v[24:25] op_sel_hi:[1,0,1]
	v_pk_fma_f32 v[14:15], v[22:23], s[26:27], v[14:15] op_sel_hi:[1,0,1]
	v_pk_fma_f32 v[24:25], v[36:37], s[30:31], v[24:25] op_sel_hi:[1,0,1]
	v_pk_fma_f32 v[14:15], v[26:27], s[28:29], v[14:15] op_sel_hi:[1,0,1]
	v_pk_fma_f32 v[24:25], v[40:41], s[34:35], v[24:25] op_sel_hi:[1,0,1]
	v_pk_fma_f32 v[14:15], v[30:31], s[30:31], v[14:15] op_sel_hi:[1,0,1]
	v_pk_fma_f32 v[24:25], v[44:45], s[36:37], v[24:25] op_sel_hi:[1,0,1]
	v_pk_fma_f32 v[14:15], v[34:35], s[34:35], v[14:15] op_sel_hi:[1,0,1]
	v_pk_fma_f32 v[24:25], v[48:49], s[38:39], v[24:25] op_sel_hi:[1,0,1]
	v_pk_fma_f32 v[14:15], v[38:39], s[36:37], v[14:15] op_sel_hi:[1,0,1]
	v_pk_fma_f32 v[24:25], v[50:51], s[56:57], v[24:25] op_sel_hi:[1,0,1]
	v_pk_fma_f32 v[14:15], v[42:43], s[38:39], v[14:15] op_sel_hi:[1,0,1]
	v_pk_fma_f32 v[24:25], v[158:159], s[62:63], v[24:25] op_sel_hi:[1,0,1]
	v_pk_fma_f32 v[14:15], v[46:47], s[56:57], v[14:15] op_sel_hi:[1,0,1]
	v_cvt_scalef32_pk_f32_fp4 v[16:17], v111, 1.0 op_sel:[0,1,0]
	v_pk_fma_f32 v[14:15], v[160:161], s[62:63], v[14:15] op_sel_hi:[1,0,1]
	v_cvt_scalef32_pk_f32_fp4 v[18:19], v111, 1.0 op_sel:[1,1,0]
	v_cvt_scalef32_pk_f32_fp4 v[20:21], v113, 1.0 op_sel:[0,1,0]
	v_cvt_scalef32_pk_f32_fp4 v[22:23], v113, 1.0 op_sel:[1,1,0]
	v_pk_fma_f32 v[16:17], v[16:17], s[6:7], v[24:25] op_sel_hi:[1,0,1]
	v_pk_fma_f32 v[14:15], v[18:19], s[6:7], v[14:15] op_sel_hi:[1,0,1]
	v_cvt_scalef32_pk_f32_fp4 v[26:27], v115, 1.0 op_sel:[0,1,0]
	v_cvt_scalef32_pk_f32_fp4 v[28:29], v115, 1.0 op_sel:[1,1,0]
	v_pk_fma_f32 v[16:17], v[20:21], s[64:65], v[16:17] op_sel_hi:[1,0,1]
	v_pk_fma_f32 v[14:15], v[22:23], s[64:65], v[14:15] op_sel_hi:[1,0,1]
	v_cvt_scalef32_pk_f32_fp4 v[30:31], v119, 1.0 op_sel:[0,1,0]
	v_cvt_scalef32_pk_f32_fp4 v[32:33], v119, 1.0 op_sel:[1,1,0]
	v_pk_fma_f32 v[16:17], v[26:27], s[66:67], v[16:17] op_sel_hi:[1,0,1]
	v_pk_fma_f32 v[14:15], v[28:29], s[66:67], v[14:15] op_sel_hi:[1,0,1]
	v_cvt_scalef32_pk_f32_fp4 v[34:35], v121, 1.0 op_sel:[0,1,0]
	v_cvt_scalef32_pk_f32_fp4 v[36:37], v121, 1.0 op_sel:[1,1,0]
	v_pk_fma_f32 v[16:17], v[30:31], s[68:69], v[16:17] op_sel_hi:[1,0,1]
	v_pk_fma_f32 v[14:15], v[32:33], s[68:69], v[14:15] op_sel_hi:[1,0,1]
	v_cvt_scalef32_pk_f32_fp4 v[38:39], v123, 1.0 op_sel:[0,1,0]
	v_cvt_scalef32_pk_f32_fp4 v[40:41], v123, 1.0 op_sel:[1,1,0]
	v_pk_fma_f32 v[16:17], v[34:35], s[70:71], v[16:17] op_sel_hi:[1,0,1]
	v_pk_fma_f32 v[14:15], v[36:37], s[70:71], v[14:15] op_sel_hi:[1,0,1]
	v_cvt_scalef32_pk_f32_fp4 v[42:43], v125, 1.0 op_sel:[0,1,0]
	v_cvt_scalef32_pk_f32_fp4 v[44:45], v125, 1.0 op_sel:[1,1,0]
	v_pk_fma_f32 v[16:17], v[38:39], s[72:73], v[16:17] op_sel_hi:[1,0,1]
	v_pk_fma_f32 v[14:15], v[40:41], s[72:73], v[14:15] op_sel_hi:[1,0,1]
	v_cvt_scalef32_pk_f32_fp4 v[46:47], v127, 1.0 op_sel:[0,1,0]
	v_cvt_scalef32_pk_f32_fp4 v[48:49], v127, 1.0 op_sel:[1,1,0]
	v_pk_fma_f32 v[16:17], v[42:43], s[74:75], v[16:17] op_sel_hi:[1,0,1]
	v_pk_fma_f32 v[14:15], v[44:45], s[74:75], v[14:15] op_sel_hi:[1,0,1]
	v_cvt_scalef32_pk_f32_fp4 v[50:51], v131, 1.0 op_sel:[0,1,0]
	v_cvt_scalef32_pk_f32_fp4 v[56:57], v131, 1.0 op_sel:[1,1,0]
	v_pk_fma_f32 v[16:17], v[46:47], s[76:77], v[16:17] op_sel_hi:[1,0,1]
	v_pk_fma_f32 v[14:15], v[48:49], s[76:77], v[14:15] op_sel_hi:[1,0,1]
	v_cvt_scalef32_pk_f32_fp4 v[84:85], v133, 1.0 op_sel:[0,1,0]
	v_cvt_scalef32_pk_f32_fp4 v[86:87], v133, 1.0 op_sel:[1,1,0]
	v_pk_fma_f32 v[16:17], v[50:51], s[78:79], v[16:17] op_sel_hi:[1,0,1]
	v_pk_fma_f32 v[14:15], v[56:57], s[78:79], v[14:15] op_sel_hi:[1,0,1]
	v_cvt_scalef32_pk_f32_fp4 v[88:89], v137, 1.0 op_sel:[0,1,0]
	v_cvt_scalef32_pk_f32_fp4 v[90:91], v137, 1.0 op_sel:[1,1,0]
	v_pk_fma_f32 v[16:17], v[84:85], s[80:81], v[16:17] op_sel_hi:[1,0,1]
	v_pk_fma_f32 v[14:15], v[86:87], s[80:81], v[14:15] op_sel_hi:[1,0,1]
	v_pk_fma_f32 v[16:17], v[88:89], s[82:83], v[16:17] op_sel_hi:[1,0,1]
	v_pk_fma_f32 v[18:19], v[90:91], s[82:83], v[14:15] op_sel_hi:[1,0,1]
	v_cvt_scalef32_pk_f32_fp4 v[14:15], v117, 1.0 op_sel:[0,1,0]
	v_cvt_scalef32_pk_f32_fp4 v[20:21], v117, 1.0 op_sel:[1,1,0]
	v_cvt_scalef32_pk_f32_fp4 v[22:23], v143, 1.0 op_sel:[0,1,0]
	v_cvt_scalef32_pk_f32_fp4 v[24:25], v143, 1.0 op_sel:[1,1,0]
	v_pk_fma_f32 v[14:15], v[14:15], s[84:85], v[16:17] op_sel_hi:[1,0,1]
	v_pk_fma_f32 v[16:17], v[20:21], s[84:85], v[18:19] op_sel_hi:[1,0,1]
	v_cvt_scalef32_pk_f32_fp4 v[26:27], v141, 1.0 op_sel:[0,1,0]
	v_cvt_scalef32_pk_f32_fp4 v[28:29], v141, 1.0 op_sel:[1,1,0]
	v_pk_fma_f32 v[14:15], v[22:23], s[86:87], v[14:15] op_sel_hi:[1,0,1]
	v_pk_fma_f32 v[16:17], v[24:25], s[86:87], v[16:17] op_sel_hi:[1,0,1]
	v_cvt_scalef32_pk_f32_fp4 v[30:31], v139, 1.0 op_sel:[0,1,0]
	v_cvt_scalef32_pk_f32_fp4 v[32:33], v139, 1.0 op_sel:[1,1,0]
	v_pk_fma_f32 v[14:15], v[26:27], s[88:89], v[14:15] op_sel_hi:[1,0,1]
	v_pk_fma_f32 v[16:17], v[28:29], s[88:89], v[16:17] op_sel_hi:[1,0,1]
	v_cvt_scalef32_pk_f32_fp4 v[34:35], v135, 1.0 op_sel:[0,1,0]
	v_cvt_scalef32_pk_f32_fp4 v[36:37], v135, 1.0 op_sel:[1,1,0]
	v_pk_fma_f32 v[14:15], v[30:31], s[90:91], v[14:15] op_sel_hi:[1,0,1]
	v_pk_fma_f32 v[16:17], v[32:33], s[90:91], v[16:17] op_sel_hi:[1,0,1]
	v_pk_fma_f32 v[14:15], v[34:35], s[92:93], v[14:15] op_sel_hi:[1,0,1]
	v_pk_fma_f32 v[16:17], v[36:37], s[92:93], v[16:17] op_sel_hi:[1,0,1]
	s_waitcnt vmcnt(0)
	v_pk_fma_f32 v[14:15], v[14:15], v[80:81], v[52:53]
	v_pk_fma_f32 v[16:17], v[16:17], v[82:83], v[54:55]
	s_andn2_b64 vcc, exec, s[12:13]
	global_store_dwordx4 v[176:177], v[14:17], off offset:48
	s_cbranch_vccnz .LBB0_556
	v_mov_b32_e32 v24, v3
	v_mov_b32_e32 v25, v7
	v_mov_b32_e32 v22, v2
	v_mov_b32_e32 v23, v6
	v_pk_mul_f32 v[24:25], v[24:25], v[24:25]
	v_mov_b32_e32 v26, v11
	v_mov_b32_e32 v27, v15
	v_mov_b32_e32 v20, v4
	v_mov_b32_e32 v21, v8
	v_pk_fma_f32 v[22:23], v[22:23], v[22:23], v[24:25]
	v_mov_b32_e32 v24, v10
	v_mov_b32_e32 v25, v14
	v_pk_mul_f32 v[26:27], v[26:27], v[26:27]
	v_mov_b32_e32 v18, v5
	v_mov_b32_e32 v19, v9
	v_pk_fma_f32 v[20:21], v[20:21], v[20:21], v[22:23]
	v_mov_b32_e32 v22, v12
	v_mov_b32_e32 v23, v16
	v_pk_fma_f32 v[24:25], v[24:25], v[24:25], v[26:27]
	v_pk_fma_f32 v[18:19], v[18:19], v[18:19], v[20:21]
	v_mov_b32_e32 v20, v13
	v_mov_b32_e32 v21, v17
	v_pk_fma_f32 v[22:23], v[22:23], v[22:23], v[24:25]
	v_add_f32_e32 v18, v18, v19
	v_pk_fma_f32 v[20:21], v[20:21], v[20:21], v[22:23]
	v_and_b32_e32 v19, 64, v219
	v_add_f32_e32 v18, v18, v20
	v_add_u32_e32 v19, 64, v19
	v_xor_b32_e32 v20, 32, v219
	v_cmp_lt_i32_e32 vcc, v20, v19
	v_add_f32_e32 v18, v18, v21
	v_readlane_b32 s6, v250, 40
	v_cndmask_b32_e32 v20, v219, v20, vcc
	v_lshlrev_b32_e32 v20, 2, v20
	ds_bpermute_b32 v20, v20, v18
	v_readlane_b32 s7, v250, 41
	v_lshlrev_b64 v[80:81], 10, v[78:79]
	s_waitcnt lgkmcnt(0)
	v_add_f32_e32 v18, v18, v20
	v_xor_b32_e32 v20, 16, v219
	v_cmp_lt_i32_e32 vcc, v20, v19
	s_nop 1
	v_cndmask_b32_e32 v20, v219, v20, vcc
	v_lshlrev_b32_e32 v20, 2, v20
	ds_bpermute_b32 v20, v20, v18
	s_waitcnt lgkmcnt(0)
	v_add_f32_e32 v18, v18, v20
	v_xor_b32_e32 v20, 8, v219
	v_cmp_lt_i32_e32 vcc, v20, v19
	s_nop 1
	v_cndmask_b32_e32 v20, v219, v20, vcc
	v_lshlrev_b32_e32 v20, 2, v20
	ds_bpermute_b32 v20, v20, v18
	s_waitcnt lgkmcnt(0)
	v_add_f32_e32 v18, v18, v20
	v_xor_b32_e32 v20, 4, v219
	v_cmp_lt_i32_e32 vcc, v20, v19
	s_nop 1
	v_cndmask_b32_e32 v20, v219, v20, vcc
	v_lshlrev_b32_e32 v20, 2, v20
	ds_bpermute_b32 v20, v20, v18
	s_waitcnt lgkmcnt(0)
	v_add_f32_e32 v18, v18, v20
	v_xor_b32_e32 v20, 2, v219
	v_cmp_lt_i32_e32 vcc, v20, v19
	s_nop 1
	v_cndmask_b32_e32 v20, v219, v20, vcc
	v_lshlrev_b32_e32 v20, 2, v20
	ds_bpermute_b32 v20, v20, v18
	s_waitcnt lgkmcnt(0)
	v_add_f32_e32 v18, v18, v20
	v_xor_b32_e32 v20, 1, v219
	v_cmp_lt_i32_e32 vcc, v20, v19
	s_nop 1
	v_cndmask_b32_e32 v19, v219, v20, vcc
	v_lshlrev_b32_e32 v19, 2, v19
	ds_bpermute_b32 v19, v19, v18
	v_add_u32_e32 v20, 3, v195
	s_waitcnt lgkmcnt(0)
	v_add_f32_e32 v18, v18, v19
	v_fmamk_f32 v18, v18, 0x3a800000, v213
	v_cmp_gt_f32_e32 vcc, s54, v18
	v_mul_f32_e32 v19, 0x4b800000, v18
	s_nop 0
	v_cndmask_b32_e32 v18, v18, v19, vcc
	v_rsq_f32_e32 v18, v18
	s_nop 0
	v_mul_f32_e32 v19, 0x45800000, v18
	v_cndmask_b32_e32 v82, v18, v19, vcc
	v_mov_b64_e32 v[18:19], s[6:7]
	v_mad_u64_u32 v[18:19], s[6:7], v20, s67, v[18:19]
	v_lshl_add_u64 v[50:51], v[18:19], 0, v[0:1]
	s_mov_b64 s[6:7], 0x1000
	v_lshl_add_u64 v[88:89], v[50:51], 0, s[6:7]
	s_movk_i32 s6, 0x1000
	global_load_dwordx4 v[18:21], v[66:67], off offset:48
	global_load_dwordx4 v[22:25], v[66:67], off offset:32
	global_load_dwordx4 v[30:33], v[66:67], off offset:16
	global_load_dwordx4 v[42:45], v[66:67], off
	global_load_dwordx4 v[26:29], v[50:51], off offset:48
	global_load_dwordx4 v[34:37], v[50:51], off offset:32
	global_load_dwordx4 v[38:41], v[50:51], off offset:16
	global_load_dwordx4 v[46:49], v[50:51], off
	v_add_co_u32_e32 v50, vcc, s6, v50
	v_pk_mul_f32 v[2:3], v[2:3], v[82:83] op_sel_hi:[1,0]
	s_nop 0
	v_addc_co_u32_e32 v51, vcc, 0, v51, vcc
	global_load_dwordx4 v[84:87], v[50:51], off
	s_nop 0
	global_load_dwordx4 v[50:53], v[88:89], off offset:48
	global_load_dwordx4 v[54:57], v[88:89], off offset:32
	s_nop 0
	global_load_dwordx4 v[88:91], v[88:89], off offset:16
	v_pk_mul_f32 v[6:7], v[6:7], v[82:83] op_sel_hi:[1,0]
	v_pk_mul_f32 v[4:5], v[4:5], v[82:83] op_sel_hi:[1,0]
	v_pk_mul_f32 v[8:9], v[8:9], v[82:83] op_sel_hi:[1,0]
	v_pk_mul_f32 v[10:11], v[10:11], v[82:83] op_sel_hi:[1,0]
	v_pk_mul_f32 v[14:15], v[14:15], v[82:83] op_sel_hi:[1,0]
	v_pk_mul_f32 v[12:13], v[12:13], v[82:83] op_sel_hi:[1,0]
	v_pk_mul_f32 v[16:17], v[16:17], v[82:83] op_sel_hi:[1,0]
	s_waitcnt vmcnt(11)
	v_pk_mul_f32 v[14:15], v[14:15], v[18:19]
	s_waitcnt vmcnt(10)
	v_pk_mul_f32 v[10:11], v[10:11], v[22:23]
	s_waitcnt vmcnt(9)
	v_pk_mul_f32 v[6:7], v[6:7], v[30:31]
	s_waitcnt vmcnt(8)
	v_pk_mul_f32 v[2:3], v[42:43], v[2:3]
	v_pk_mul_f32 v[4:5], v[44:45], v[4:5]
	v_pk_mul_f32 v[8:9], v[8:9], v[32:33]
	v_pk_mul_f32 v[12:13], v[12:13], v[24:25]
	v_pk_mul_f32 v[16:17], v[16:17], v[20:21]
	s_waitcnt vmcnt(3)
	v_pk_add_f32 v[42:43], v[84:85], 1.0 op_sel_hi:[1,0]
	s_nop 0
	v_pk_fma_f32 v[2:3], v[42:43], v[2:3], v[46:47]
	v_pk_add_f32 v[42:43], v[86:87], 1.0 op_sel_hi:[1,0]
	s_waitcnt vmcnt(0)
	v_pk_add_f32 v[30:31], v[88:89], 1.0 op_sel_hi:[1,0]
	v_pk_add_f32 v[22:23], v[54:55], 1.0 op_sel_hi:[1,0]
	v_pk_fma_f32 v[6:7], v[6:7], v[30:31], v[38:39]
	v_pk_add_f32 v[30:31], v[90:91], 1.0 op_sel_hi:[1,0]
	v_pk_add_f32 v[18:19], v[50:51], 1.0 op_sel_hi:[1,0]
	v_pk_fma_f32 v[4:5], v[4:5], v[42:43], v[48:49]
	v_pk_fma_f32 v[8:9], v[8:9], v[30:31], v[40:41]
	v_pk_fma_f32 v[10:11], v[10:11], v[22:23], v[34:35]
	v_pk_add_f32 v[22:23], v[56:57], 1.0 op_sel_hi:[1,0]
	v_pk_fma_f32 v[14:15], v[14:15], v[18:19], v[26:27]
	v_pk_add_f32 v[18:19], v[52:53], 1.0 op_sel_hi:[1,0]
	v_pk_fma_f32 v[12:13], v[12:13], v[22:23], v[36:37]
	v_pk_fma_f32 v[16:17], v[16:17], v[18:19], v[28:29]
	v_lshl_add_u64 v[18:19], v[80:81], 1, v[60:61]
	v_cvt_pk_bf16_f32 v2, v2, v3
	v_cvt_pk_bf16_f32 v3, v4, v5
	v_cvt_pk_bf16_f32 v4, v6, v7
	v_cvt_pk_bf16_f32 v5, v8, v9
	global_store_dwordx4 v[18:19], v[2:5], off
	s_nop 1
	v_cvt_pk_bf16_f32 v2, v10, v11
	v_cvt_pk_bf16_f32 v3, v12, v13
	v_cvt_pk_bf16_f32 v4, v14, v15
	v_cvt_pk_bf16_f32 v5, v16, v17
	global_store_dwordx4 v[18:19], v[2:5], off offset:16
	s_branch .LBB0_556
